# write-through (sc1) for all 16-byte stores ahead of a grid barrier or arrival counter, so the release writeback has nothing to flush
# baseline (speedup 1.0000x reference)
; #define LAS __attribute__((address_space(3)))
; template <bool QKPERM, bool BIAS>
; __device__ __forceinline__ void transpose_item(const float* W, int K, int N, bf16* WT, int row_off, LAS float* scr, int item, int lane, const float* sh2 = nullptr, float* bias2 = nullptr) {
;     const int nblk = N / 32, kb = item / nblk, nb = item % nblk, k0 = 64 * kb, n0 = 32 * nb;
;     if (BIAS) row_off += (n0 >> 7) * 128;
;     float wv[32];
; #pragma unroll
;     for (int i = 0; i < 32; ++i) wv[i] = __builtin_nontemporal_load(W + (size_t)(k0 + 2 * i + (lane >> 5)) * N + n0 + (lane & 31));
; __device__ __forceinline__ void phase_wconv_in(const Params& p, LAS unsigned char* lds, int gw, int NGW) {
;     ...
;     for (int it = gw; it < I_IN; it += NGW) transpose_item<true, false>(p.w_in, D_MODEL, IN_COLS, (bf16*)(p.ws + WS_WINT), 0, scr, it, lane);
.LBB0_45:
	s_mul_hi_i32 s4, s12, 0x2aaaaaab
	s_lshr_b32 s5, s4, 31
	s_ashr_i32 s4, s4, 6
	s_add_i32 s5, s4, s5
	s_lshl_b32 s4, s5, 6
	s_mulk_i32 s5, 0xd000
	s_add_i32 s6, s8, s5
	v_add_u32_e32 v19, s4, v4
	s_ashr_i32 s7, s6, 31
	s_ashr_i32 s5, s4, 31
	v_add_u32_e32 v30, 6, v19
	v_add_u32_e32 v32, 8, v19
	v_add_u32_e32 v34, 10, v19
	v_add_u32_e32 v44, 20, v19
	v_add_u32_e32 v46, 22, v19
	v_add_u32_e32 v48, 24, v19
	v_add_u32_e32 v50, 26, v19
	v_add_u32_e32 v52, 28, v19
	v_add_u32_e32 v54, 30, v19
	v_lshl_add_u64 v[22:23], s[6:7], 2, v[0:1]
	v_add_u32_e32 v26, 2, v19
	v_add_u32_e32 v28, 4, v19
	v_add_u32_e32 v36, 12, v19
	v_add_u32_e32 v38, 14, v19
	v_add_u32_e32 v40, 16, v19
	v_add_u32_e32 v42, 18, v19
	v_add_u32_e32 v56, 32, v19
	v_add_u32_e32 v58, 34, v19
	v_add_u32_e32 v60, 36, v19
	v_add_u32_e32 v62, 38, v19
	v_add_u32_e32 v64, 40, v19
	v_add_u32_e32 v66, 42, v19
	v_add_u32_e32 v68, 44, v19
	v_add_u32_e32 v70, 46, v19
	v_add_u32_e32 v72, 48, v19
	v_add_u32_e32 v74, 50, v19
	v_add_u32_e32 v76, 52, v19
	v_add_u32_e32 v78, 54, v19
	v_add_u32_e32 v80, 56, v19
	v_add_u32_e32 v82, 58, v19
	v_add_u32_e32 v84, 60, v19
	v_add_u32_e32 v86, 62, v19
	v_lshl_add_u64 v[20:21], s[4:5], 1, v[2:3]
	v_mad_i64_i32 v[24:25], s[4:5], v19, s10, v[22:23]
	v_mad_i64_i32 v[30:31], s[4:5], v30, s10, v[22:23]
	v_mad_i64_i32 v[32:33], s[4:5], v32, s10, v[22:23]
	v_mad_i64_i32 v[34:35], s[4:5], v34, s10, v[22:23]
	v_mad_i64_i32 v[44:45], s[4:5], v44, s10, v[22:23]
	v_mad_i64_i32 v[46:47], s[4:5], v46, s10, v[22:23]
	v_mad_i64_i32 v[48:49], s[4:5], v48, s10, v[22:23]
	v_mad_i64_i32 v[50:51], s[4:5], v50, s10, v[22:23]
	v_mad_i64_i32 v[52:53], s[4:5], v52, s10, v[22:23]
	v_mad_i64_i32 v[54:55], s[4:5], v54, s10, v[22:23]
	v_mad_i64_i32 v[26:27], s[4:5], v26, s10, v[22:23]
	v_mad_i64_i32 v[28:29], s[4:5], v28, s10, v[22:23]
	v_mad_i64_i32 v[36:37], s[4:5], v36, s10, v[22:23]
	v_mad_i64_i32 v[38:39], s[4:5], v38, s10, v[22:23]
	v_mad_i64_i32 v[40:41], s[4:5], v40, s10, v[22:23]
	v_mad_i64_i32 v[42:43], s[4:5], v42, s10, v[22:23]
	v_mad_i64_i32 v[56:57], s[4:5], v56, s10, v[22:23]
	v_mad_i64_i32 v[58:59], s[4:5], v58, s10, v[22:23]
	v_mad_i64_i32 v[60:61], s[4:5], v60, s10, v[22:23]
	v_mad_i64_i32 v[62:63], s[4:5], v62, s10, v[22:23]
	v_mad_i64_i32 v[64:65], s[4:5], v64, s10, v[22:23]
	v_mad_i64_i32 v[66:67], s[4:5], v66, s10, v[22:23]
	v_mad_i64_i32 v[68:69], s[4:5], v68, s10, v[22:23]
	v_mad_i64_i32 v[70:71], s[4:5], v70, s10, v[22:23]
	v_mad_i64_i32 v[72:73], s[4:5], v72, s10, v[22:23]
	v_mad_i64_i32 v[74:75], s[4:5], v74, s10, v[22:23]
	v_mad_i64_i32 v[76:77], s[4:5], v76, s10, v[22:23]
	v_mad_i64_i32 v[78:79], s[4:5], v78, s10, v[22:23]
	v_mad_i64_i32 v[80:81], s[4:5], v80, s10, v[22:23]
	v_mad_i64_i32 v[82:83], s[4:5], v82, s10, v[22:23]
	v_mad_i64_i32 v[84:85], s[4:5], v84, s10, v[22:23]
	v_mad_i64_i32 v[22:23], s[4:5], v86, s10, v[22:23]
	global_load_dword v19, v[24:25], off nt
	global_load_dword v86, v[26:27], off nt
	global_load_dword v96, v[28:29], off nt
	global_load_dword v97, v[30:31], off nt
	global_load_dword v98, v[32:33], off nt
	global_load_dword v99, v[34:35], off nt
	global_load_dword v100, v[36:37], off nt
	global_load_dword v101, v[38:39], off nt
	global_load_dword v102, v[40:41], off nt
	global_load_dword v103, v[42:43], off nt
	global_load_dword v104, v[44:45], off nt
	global_load_dword v105, v[46:47], off nt
	global_load_dword v106, v[48:49], off nt
	global_load_dword v107, v[50:51], off nt
	global_load_dword v108, v[52:53], off nt
	global_load_dword v30, v[54:55], off nt
	global_load_dword v31, v[56:57], off nt
	global_load_dword v32, v[58:59], off nt
	global_load_dword v33, v[60:61], off nt
	global_load_dword v34, v[62:63], off nt
	global_load_dword v35, v[64:65], off nt
	global_load_dword v44, v[66:67], off nt
	global_load_dword v45, v[68:69], off nt
	global_load_dword v46, v[70:71], off nt
	global_load_dword v47, v[72:73], off nt
	global_load_dword v48, v[74:75], off nt
	global_load_dword v49, v[76:77], off nt
	global_load_dword v50, v[78:79], off nt
	global_load_dword v51, v[80:81], off nt
	global_load_dword v52, v[82:83], off nt
	global_load_dword v53, v[84:85], off nt
	global_load_dword v54, v[22:23], off nt
	v_add_u32_e32 v87, s6, v5
	v_lshrrev_b32_e32 v90, 1, v87
	v_add_u32_e32 v91, 8, v87
	v_add_u32_e32 v93, 16, v87
	v_add_u32_e32 v95, 24, v87
	v_add_u32_e32 v88, 0xffffec00, v87
	v_and_b32_e32 v89, 0x1fcf, v87
	v_and_b32_e32 v22, 16, v90
	v_lshrrev_b32_e32 v25, 1, v91
	v_lshrrev_b32_e32 v27, 1, v93
	v_lshrrev_b32_e32 v29, 1, v95
	v_add_u32_e32 v92, 0xffffec08, v87
	v_add_u32_e32 v94, 0xffffec10, v87
	v_add_u32_e32 v23, 0xffffec18, v87
	v_and_b32_e32 v24, 0x1fcf, v91
	v_and_b32_e32 v26, 0x1fcf, v93
	v_and_b32_e32 v28, 0x1fcf, v95
	v_or3_b32 v22, v89, v7, v22
	v_and_b32_e32 v25, 16, v25
	v_and_b32_e32 v27, 16, v27
	v_and_b32_e32 v29, 16, v29
	v_cmp_gt_u32_e32 vcc, s11, v88
	v_or3_b32 v24, v24, v8, v25
	v_or3_b32 v25, v26, v9, v27
	v_cndmask_b32_e32 v22, v87, v22, vcc
	v_cmp_gt_u32_e32 vcc, s11, v92
	v_cmp_gt_u32_e64 s[4:5], s11, v94
	v_or3_b32 v27, v28, v10, v29
	v_cmp_gt_u32_e64 s[6:7], s11, v23
	v_ashrrev_i32_e32 v23, 31, v22
	v_cndmask_b32_e32 v24, v91, v24, vcc
	v_cndmask_b32_e64 v26, v93, v25, s[4:5]
	v_cndmask_b32_e64 v28, v95, v27, s[6:7]
	v_lshlrev_b64 v[22:23], 12, v[22:23]
	v_ashrrev_i32_e32 v25, 31, v24
	v_ashrrev_i32_e32 v27, 31, v26
	v_ashrrev_i32_e32 v29, 31, v28
	s_waitcnt vmcnt(30)
; #define LAS __attribute__((address_space(3)))
; __device__ __forceinline__ unsigned pk2(float lo, float hi) { const f32x2_t v = {lo, hi}; const bf16x2_t b = __builtin_convertvector(v, bf16x2_t); return __builtin_bit_cast(unsigned, b); }
; template <bool QKPERM, bool BIAS>
; __device__ __forceinline__ void transpose_item(const float* W, int K, int N, bf16* WT, int row_off, LAS float* scr, int item, int lane, const float* sh2 = nullptr, float* bias2 = nullptr) {
;     ...
;     for (int i = 0; i < 32; ++i) scr[(2 * i + (lane >> 5)) * 33 + (lane & 31)] = wv[i];
;     if (BIAS) {
;         float a0 = 0.f, a1 = 0.f, a2 = 0.f, a3 = 0.f;
; #pragma unroll
;         for (int i = 0; i < 32; ++i) { const int k = k0 + 2 * i + (lane >> 5); const float w = wv[i];
;             a0 += w * sh2[0 * IN_COLS + k]; a1 += w * sh2[1 * IN_COLS + k]; a2 += w * sh2[2 * IN_COLS + k]; a3 += w * sh2[3 * IN_COLS + k]; }
;         a0 = half_swap_sum(a0); a1 = half_swap_sum(a1); a2 = half_swap_sum(a2); a3 = half_swap_sum(a3);
;         if (lane < 32) { float* bp = bias2 + row_off + n0 + lane; atomicAdd(bp, a0); atomicAdd(bp + 2 * FFN, a1); atomicAdd(bp + 4 * FFN, a2); atomicAdd(bp + 6 * FFN, a3); }
;     }
;     asm volatile("s_waitcnt lgkmcnt(0)" ::: "memory");
;     const int c = lane & 7;
; #pragma unroll
;     for (int j = 0; j < 4; ++j) { const int n = (lane >> 3) + 8 * j; const LAS float* s = scr + (8 * c) * 33 + n;
;         u32x4 o; o.x = pk2(s[0 * 33], s[1 * 33]); o.y = pk2(s[2 * 33], s[3 * 33]); o.z = pk2(s[4 * 33], s[5 * 33]); o.w = pk2(s[6 * 33], s[7 * 33]);
;         int cdst = n0 + n;
;         if (QKPERM && cdst >= 5 * WA && cdst < 7 * WA) cdst = (cdst & ~0x30) | ((cdst & 0x10) << 1) | ((cdst & 0x20) >> 1);
;         *(u32x4*)(WT + (size_t)(row_off + cdst) * K + k0 + 8 * c) = o; }
;     asm volatile("s_waitcnt lgkmcnt(0)" ::: "memory");
; __device__ __forceinline__ void phase_wconv_in(const Params& p, LAS unsigned char* lds, int gw, int NGW) {
;     ...
;     for (int it = gw; it < I_IN; it += NGW) transpose_item<true, false>(p.w_in, D_MODEL, IN_COLS, (bf16*)(p.ws + WS_WINT), 0, scr, it, lane);
	ds_write2_b32 v11, v19, v86 offset1:66
	s_waitcnt vmcnt(28)
	ds_write2_b32 v11, v96, v97 offset0:132 offset1:198
	s_waitcnt vmcnt(26)
	ds_write2_b32 v12, v98, v99 offset0:8 offset1:74
	s_waitcnt vmcnt(24)
	ds_write2_b32 v12, v100, v101 offset0:140 offset1:206
	s_waitcnt vmcnt(22)
	ds_write2_b32 v13, v102, v103 offset0:16 offset1:82
	s_waitcnt vmcnt(20)
	ds_write2_b32 v13, v104, v105 offset0:148 offset1:214
	s_waitcnt vmcnt(18)
	ds_write2_b32 v14, v106, v107 offset0:24 offset1:90
	s_waitcnt vmcnt(16)
	ds_write2_b32 v14, v108, v30 offset0:156 offset1:222
	s_waitcnt vmcnt(14)
	ds_write2_b32 v15, v31, v32 offset0:32 offset1:98
	s_waitcnt vmcnt(12)
	ds_write2_b32 v15, v33, v34 offset0:164 offset1:230
	s_waitcnt vmcnt(10)
	ds_write2_b32 v16, v35, v44 offset0:40 offset1:106
	s_waitcnt vmcnt(8)
	ds_write2_b32 v16, v45, v46 offset0:172 offset1:238
	s_waitcnt vmcnt(6)
	ds_write2_b32 v17, v47, v48 offset0:48 offset1:114
	s_waitcnt vmcnt(4)
	ds_write2_b32 v17, v49, v50 offset0:180 offset1:246
	s_waitcnt vmcnt(2)
	ds_write2_b32 v18, v51, v52 offset0:56 offset1:122
	s_waitcnt vmcnt(0)
	ds_write2_b32 v18, v53, v54 offset0:188 offset1:254
	v_lshl_add_u64 v[36:37], v[20:21], 0, v[22:23]
	v_lshlrev_b64 v[22:23], 12, v[24:25]
	v_lshlrev_b64 v[24:25], 12, v[26:27]
	v_lshlrev_b64 v[26:27], 12, v[28:29]
	s_waitcnt lgkmcnt(0)
	v_lshl_add_u64 v[40:41], v[20:21], 0, v[24:25]
	v_lshl_add_u64 v[42:43], v[20:21], 0, v[26:27]
	ds_read2_b32 v[24:25], v6 offset0:33 offset1:41
	ds_read2_b32 v[26:27], v6 offset1:8
	ds_read2_b32 v[28:29], v6 offset0:66 offset1:74
	ds_read2_b32 v[30:31], v6 offset0:99 offset1:107
	ds_read2_b32 v[32:33], v6 offset0:132 offset1:140
	ds_read2_b32 v[34:35], v6 offset0:165 offset1:173
	ds_read2_b32 v[44:45], v6 offset0:198 offset1:206
	ds_read2_b32 v[46:47], v6 offset0:231 offset1:239
	ds_read2_b32 v[48:49], v6 offset0:16 offset1:24
	ds_read2_b32 v[50:51], v6 offset0:49 offset1:57
	ds_read2_b32 v[52:53], v6 offset0:82 offset1:90
	ds_read2_b32 v[54:55], v6 offset0:115 offset1:123
	ds_read2_b32 v[56:57], v6 offset0:148 offset1:156
	ds_read2_b32 v[58:59], v6 offset0:181 offset1:189
	ds_read2_b32 v[60:61], v6 offset0:214 offset1:222
	ds_read2_b32 v[62:63], v6 offset0:247 offset1:255
	v_lshl_add_u64 v[38:39], v[20:21], 0, v[22:23]
	s_waitcnt lgkmcnt(14)
	v_cvt_pk_bf16_f32 v20, v26, v24
	s_waitcnt lgkmcnt(12)
	v_cvt_pk_bf16_f32 v21, v28, v30
	s_waitcnt lgkmcnt(10)
	v_cvt_pk_bf16_f32 v22, v32, v34
	s_waitcnt lgkmcnt(8)
	v_cvt_pk_bf16_f32 v23, v44, v46
	v_cvt_pk_bf16_f32 v24, v27, v25
	v_cvt_pk_bf16_f32 v25, v29, v31
	v_cvt_pk_bf16_f32 v26, v33, v35
	v_cvt_pk_bf16_f32 v27, v45, v47
	s_waitcnt lgkmcnt(6)
	v_cvt_pk_bf16_f32 v28, v48, v50
	s_waitcnt lgkmcnt(4)
	v_cvt_pk_bf16_f32 v29, v52, v54
	s_waitcnt lgkmcnt(2)
	v_cvt_pk_bf16_f32 v30, v56, v58
	s_waitcnt lgkmcnt(0)
	v_cvt_pk_bf16_f32 v31, v60, v62
	v_cvt_pk_bf16_f32 v32, v49, v51
	v_cvt_pk_bf16_f32 v33, v53, v55
	v_cvt_pk_bf16_f32 v34, v57, v59
	v_cvt_pk_bf16_f32 v35, v61, v63
	global_store_dwordx4 v[36:37], v[20:23], off sc1
	global_store_dwordx4 v[38:39], v[24:27], off sc1
	global_store_dwordx4 v[40:41], v[28:31], off sc1
	global_store_dwordx4 v[42:43], v[32:35], off sc1
	s_waitcnt lgkmcnt(0)
	s_add_i32 s12, s12, s46
	s_add_i32 s8, s8, s9
	s_cmpk_lt_i32 s12, 0x3000
	s_cbranch_scc1 .LBB0_45

; __device__ __forceinline__ float sigmoidf_(float x) { return __builtin_amdgcn_rcpf(1.0f + __expf(-x)); }
;     __device__ __forceinline__ void operator()(const f32x4 (&acc)[2][2][4][2], const pg8::Unit& u, int wr, int wc, int fr, int fq) const {
;     ...
;         if (seg == 1 || seg == 2) {
;             float* F = (float*)(ws + (seg == 1 ? WS_FW : WS_FB)); const float* lbd = lb + (seg - 1) * WA;
;             f32x4 lbv[2][2];
; #pragma unroll
;             for (int bj = 0; bj < 2; ++bj)
; #pragma unroll
;                 for (int n = 0; n < 2; ++n) lbv[bj][n] = *(const f32x4*)(lbd + u.pn * 256 + bj * 128 + wc * 32 + n * 16 + fq * 4 - seg * WA);
;             EPI_LOOP_BEGIN
;                 const int c = col - seg * WA; const f32x4 l = lbv[bj][n]; f32x4 o;
;                 o.x = l.x + (1.0f - l.x) * sigmoidf_(v.x); o.y = l.y + (1.0f - l.y) * sigmoidf_(v.y);
;                 o.z = l.z + (1.0f - l.z) * sigmoidf_(v.z); o.w = l.w + (1.0f - l.w) * sigmoidf_(v.w);
;                 *(f32x4*)(F + (size_t)row * WA + c) = o;
;             EPI_LOOP_END
.LBB0_208:
	s_cmp_eq_u32 s25, 1
	s_mov_b32 s6, 0x6542000
	s_cselect_b32 s40, s6, 0x8942000
	s_lshl_b32 s26, s25, 10
	s_lshl_b64 s[6:7], s[26:27], 2
	s_add_u32 s25, s22, s6
	s_addc_u32 s41, s23, s7
	s_lshl_b32 s38, s66, 8
	s_ashr_i32 s39, s38, 31
	s_lshl_b64 s[42:43], s[38:39], 2
	s_add_u32 s25, s25, s42
	s_addc_u32 s39, s41, s43
	s_lshl_b32 s41, s85, 2
	s_add_u32 s42, s25, s41
	v_lshlrev_b32_e32 v146, 2, v226
	s_addc_u32 s43, s39, 0
	v_ashrrev_i32_e32 v147, 31, v146
	v_lshl_add_u64 v[128:129], v[146:147], 2, s[42:43]
	s_mov_b64 s[42:43], 0x13b000
	v_lshl_add_u64 v[128:129], v[128:129], 0, s[42:43]
	v_subrev_co_u32_e32 v128, vcc, s6, v128
	v_mov_b32_e32 v130, s7
	s_nop 0
	v_subb_co_u32_e32 v129, vcc, v129, v130, vcc
	global_load_dwordx4 v[140:143], v[128:129], off
	global_load_dwordx4 v[136:139], v[128:129], off offset:64
	global_load_dwordx4 v[132:135], v[128:129], off offset:512
	s_nop 0
	global_load_dwordx4 v[128:131], v[128:129], off offset:576
	v_mul_f32_e32 v124, 0xbfb8aa3b, v124
	v_mul_f32_e32 v126, 0xbfb8aa3b, v126
	v_exp_f32_e32 v124, v124
	v_exp_f32_e32 v126, v126
	v_or_b32_e32 v144, s84, v225
	s_add_u32 s6, s22, s40
	v_lshl_add_u32 v144, s64, 8, v144
	s_addc_u32 s7, s23, 0
	s_sub_i32 s25, s85, s26
	v_ashrrev_i32_e32 v145, 31, v144
	v_lshlrev_b64 v[148:149], 12, v[144:145]
	s_add_i32 s25, s38, s25
	v_add_f32_e32 v124, 1.0, v124
	v_add_f32_e32 v126, 1.0, v126
	v_lshl_add_u64 v[154:155], s[6:7], 0, v[148:149]
	v_add_u32_e32 v152, s25, v146
	v_rcp_f32_e32 v146, v124
	v_mul_f32_e32 v124, 0xbfb8aa3b, v125
	v_rcp_f32_e32 v148, v126
	v_mul_f32_e32 v126, 0xbfb8aa3b, v127
	v_exp_f32_e32 v124, v124
	v_exp_f32_e32 v126, v126
	v_mul_f32_e32 v120, 0xbfb8aa3b, v120
	v_mul_f32_e32 v122, 0xbfb8aa3b, v122
	v_add_f32_e32 v124, 1.0, v124
	v_add_f32_e32 v126, 1.0, v126
	v_rcp_f32_e32 v147, v124
	v_rcp_f32_e32 v149, v126
	v_exp_f32_e32 v120, v120
	v_exp_f32_e32 v122, v122
	v_ashrrev_i32_e32 v153, 31, v152
	v_mul_f32_e32 v116, 0xbfb8aa3b, v116
	v_add_f32_e32 v120, 1.0, v120
	v_add_f32_e32 v122, 1.0, v122
	v_mul_f32_e32 v118, 0xbfb8aa3b, v118
	v_exp_f32_e32 v116, v116
	v_exp_f32_e32 v118, v118
	v_mul_f32_e32 v112, 0xbfb8aa3b, v112
	v_mul_f32_e32 v114, 0xbfb8aa3b, v114
	v_add_f32_e32 v116, 1.0, v116
	v_add_f32_e32 v118, 1.0, v118
	v_exp_f32_e32 v112, v112
	v_exp_f32_e32 v114, v114
	v_mul_f32_e32 v108, 0xbfb8aa3b, v108
	v_mul_f32_e32 v109, 0xbfb8aa3b, v109
	v_add_f32_e32 v112, 1.0, v112
	v_add_f32_e32 v114, 1.0, v114
	v_mul_f32_e32 v110, 0xbfb8aa3b, v110
	v_mul_f32_e32 v111, 0xbfb8aa3b, v111
	v_exp_f32_e32 v108, v108
	v_exp_f32_e32 v109, v109
	v_exp_f32_e32 v110, v110
	v_exp_f32_e32 v111, v111
	v_mul_f32_e32 v104, 0xbfb8aa3b, v104
	v_mul_f32_e32 v105, 0xbfb8aa3b, v105
	v_mul_f32_e32 v106, 0xbfb8aa3b, v106
	v_mul_f32_e32 v107, 0xbfb8aa3b, v107
	v_exp_f32_e32 v104, v104
	v_exp_f32_e32 v105, v105
	v_exp_f32_e32 v106, v106
	v_exp_f32_e32 v107, v107
	v_mul_f32_e32 v100, 0xbfb8aa3b, v100
	v_mul_f32_e32 v101, 0xbfb8aa3b, v101
	v_mul_f32_e32 v102, 0xbfb8aa3b, v102
	v_mul_f32_e32 v103, 0xbfb8aa3b, v103
	v_exp_f32_e32 v100, v100
	v_exp_f32_e32 v101, v101
	v_exp_f32_e32 v102, v102
	v_exp_f32_e32 v103, v103
	v_mul_f32_e32 v96, 0xbfb8aa3b, v96
	v_mul_f32_e32 v97, 0xbfb8aa3b, v97
	v_mul_f32_e32 v98, 0xbfb8aa3b, v98
	v_mul_f32_e32 v99, 0xbfb8aa3b, v99
	v_exp_f32_e32 v96, v96
	v_exp_f32_e32 v97, v97
	v_exp_f32_e32 v98, v98
	s_waitcnt vmcnt(0)
	v_pk_add_f32 v[124:125], v[140:141], 1.0 op_sel_hi:[1,0] neg_lo:[1,0] neg_hi:[1,0]
	v_pk_add_f32 v[126:127], v[142:143], 1.0 op_sel_hi:[1,0] neg_lo:[1,0] neg_hi:[1,0]
	v_exp_f32_e32 v99, v99
	v_pk_fma_f32 v[150:151], v[148:149], v[126:127], v[142:143]
	v_pk_fma_f32 v[148:149], v[146:147], v[124:125], v[140:141]
	v_lshlrev_b64 v[146:147], 2, v[152:153]
	v_lshl_add_u64 v[156:157], v[154:155], 0, v[146:147]
	global_store_dwordx4 v[156:157], v[148:151], off sc1
	v_rcp_f32_e32 v156, v122
	v_mul_f32_e32 v122, 0xbfb8aa3b, v123
	v_rcp_f32_e32 v150, v120
	v_mul_f32_e32 v120, 0xbfb8aa3b, v121
	v_exp_f32_e32 v120, v120
	v_exp_f32_e32 v122, v122
	v_add_u32_e32 v148, 16, v152
	v_ashrrev_i32_e32 v149, 31, v148
	v_add_f32_e32 v120, 1.0, v120
	v_add_f32_e32 v122, 1.0, v122
	v_rcp_f32_e32 v151, v120
	v_rcp_f32_e32 v157, v122
	v_pk_add_f32 v[120:121], v[136:137], 1.0 op_sel_hi:[1,0] neg_lo:[1,0] neg_hi:[1,0]
	v_pk_add_f32 v[122:123], v[138:139], 1.0 op_sel_hi:[1,0] neg_lo:[1,0] neg_hi:[1,0]
	v_lshlrev_b64 v[148:149], 2, v[148:149]
	v_pk_fma_f32 v[158:159], v[156:157], v[122:123], v[138:139]
	v_pk_fma_f32 v[156:157], v[150:151], v[120:121], v[136:137]
	v_lshl_add_u64 v[150:151], v[154:155], 0, v[148:149]
	global_store_dwordx4 v[150:151], v[156:159], off sc1
	v_add_u32_e32 v150, 0x80, v152
	v_ashrrev_i32_e32 v151, 31, v150
	v_rcp_f32_e32 v156, v116
	v_mul_f32_e32 v116, 0xbfb8aa3b, v117
	v_rcp_f32_e32 v158, v118
	v_mul_f32_e32 v118, 0xbfb8aa3b, v119
	v_exp_f32_e32 v116, v116
	v_exp_f32_e32 v118, v118
	v_lshlrev_b64 v[150:151], 2, v[150:151]
	v_lshl_add_u64 v[160:161], v[154:155], 0, v[150:151]
	v_add_f32_e32 v116, 1.0, v116
	v_add_f32_e32 v118, 1.0, v118
	v_rcp_f32_e32 v157, v116
	v_rcp_f32_e32 v159, v118
	v_pk_add_f32 v[116:117], v[132:133], 1.0 op_sel_hi:[1,0] neg_lo:[1,0] neg_hi:[1,0]
	v_pk_add_f32 v[118:119], v[134:135], 1.0 op_sel_hi:[1,0] neg_lo:[1,0] neg_hi:[1,0]
	v_pk_fma_f32 v[156:157], v[156:157], v[116:117], v[132:133]
	v_pk_fma_f32 v[158:159], v[158:159], v[118:119], v[134:135]
	global_store_dwordx4 v[160:161], v[156:159], off sc1
	v_add_u32_e32 v152, 0x90, v152
	v_ashrrev_i32_e32 v153, 31, v152
	v_rcp_f32_e32 v156, v112
	v_mul_f32_e32 v112, 0xbfb8aa3b, v113
	v_rcp_f32_e32 v158, v114
	v_mul_f32_e32 v114, 0xbfb8aa3b, v115
	v_exp_f32_e32 v112, v112
; __device__ __forceinline__ float sigmoidf_(float x) { return __builtin_amdgcn_rcpf(1.0f + __expf(-x)); }
;     __device__ __forceinline__ void operator()(const f32x4 (&acc)[2][2][4][2], const pg8::Unit& u, int wr, int wc, int fr, int fq) const {
;     ...
;         if (seg == 1 || seg == 2) {
;             float* F = (float*)(ws + (seg == 1 ? WS_FW : WS_FB)); const float* lbd = lb + (seg - 1) * WA;
;             f32x4 lbv[2][2];
; #pragma unroll
;             for (int bj = 0; bj < 2; ++bj)
; #pragma unroll
;                 for (int n = 0; n < 2; ++n) lbv[bj][n] = *(const f32x4*)(lbd + u.pn * 256 + bj * 128 + wc * 32 + n * 16 + fq * 4 - seg * WA);
;             EPI_LOOP_BEGIN
;                 const int c = col - seg * WA; const f32x4 l = lbv[bj][n]; f32x4 o;
;                 o.x = l.x + (1.0f - l.x) * sigmoidf_(v.x); o.y = l.y + (1.0f - l.y) * sigmoidf_(v.y);
;                 o.z = l.z + (1.0f - l.z) * sigmoidf_(v.z); o.w = l.w + (1.0f - l.w) * sigmoidf_(v.w);
;                 *(f32x4*)(F + (size_t)row * WA + c) = o;
;             EPI_LOOP_END
	v_exp_f32_e32 v114, v114
	v_lshlrev_b64 v[152:153], 2, v[152:153]
	v_lshl_add_u64 v[154:155], v[154:155], 0, v[152:153]
	v_add_f32_e32 v112, 1.0, v112
	v_add_f32_e32 v114, 1.0, v114
	v_rcp_f32_e32 v157, v112
	v_rcp_f32_e32 v159, v114
	v_pk_add_f32 v[112:113], v[128:129], 1.0 op_sel_hi:[1,0] neg_lo:[1,0] neg_hi:[1,0]
	v_pk_add_f32 v[114:115], v[130:131], 1.0 op_sel_hi:[1,0] neg_lo:[1,0] neg_hi:[1,0]
	v_pk_fma_f32 v[156:157], v[156:157], v[112:113], v[128:129]
	v_pk_fma_f32 v[158:159], v[158:159], v[114:115], v[130:131]
	v_add_f32_e32 v108, 1.0, v108
	v_add_f32_e32 v109, 1.0, v109
	v_add_f32_e32 v110, 1.0, v110
	v_add_f32_e32 v111, 1.0, v111
	global_store_dwordx4 v[154:155], v[156:159], off sc1
	v_or_b32_e32 v154, 16, v144
	v_rcp_f32_e32 v108, v108
	v_rcp_f32_e32 v109, v109
	v_rcp_f32_e32 v110, v110
	v_rcp_f32_e32 v111, v111
	v_add_f32_e32 v104, 1.0, v104
	v_add_f32_e32 v105, 1.0, v105
	v_add_f32_e32 v106, 1.0, v106
	v_add_f32_e32 v107, 1.0, v107
	v_ashrrev_i32_e32 v155, 31, v154
	v_rcp_f32_e32 v104, v104
	v_rcp_f32_e32 v105, v105
	v_rcp_f32_e32 v106, v106
	v_rcp_f32_e32 v107, v107
	v_add_f32_e32 v100, 1.0, v100
	v_add_f32_e32 v101, 1.0, v101
	v_add_f32_e32 v102, 1.0, v102
	v_add_f32_e32 v103, 1.0, v103
	v_lshlrev_b64 v[154:155], 12, v[154:155]
	v_rcp_f32_e32 v100, v100
	v_rcp_f32_e32 v101, v101
	v_rcp_f32_e32 v102, v102
	v_rcp_f32_e32 v103, v103
	v_add_f32_e32 v96, 1.0, v96
	v_add_f32_e32 v97, 1.0, v97
	v_add_f32_e32 v98, 1.0, v98
	v_add_f32_e32 v99, 1.0, v99
	v_mul_f32_e32 v92, 0xbfb8aa3b, v92
	v_mul_f32_e32 v93, 0xbfb8aa3b, v93
	v_mul_f32_e32 v94, 0xbfb8aa3b, v94
	v_mul_f32_e32 v95, 0xbfb8aa3b, v95
	v_lshl_add_u64 v[154:155], s[6:7], 0, v[154:155]
	v_rcp_f32_e32 v96, v96
	v_rcp_f32_e32 v97, v97
	v_rcp_f32_e32 v98, v98
	v_rcp_f32_e32 v99, v99
	v_exp_f32_e32 v92, v92
	v_exp_f32_e32 v93, v93
	v_exp_f32_e32 v94, v94
	v_exp_f32_e32 v95, v95
	v_mul_f32_e32 v88, 0xbfb8aa3b, v88
	v_mul_f32_e32 v89, 0xbfb8aa3b, v89
	v_mul_f32_e32 v90, 0xbfb8aa3b, v90
	v_mul_f32_e32 v91, 0xbfb8aa3b, v91
	v_pk_fma_f32 v[110:111], v[110:111], v[126:127], v[142:143]
	v_pk_fma_f32 v[108:109], v[108:109], v[124:125], v[140:141]
	v_lshl_add_u64 v[156:157], v[154:155], 0, v[146:147]
	v_exp_f32_e32 v88, v88
	v_exp_f32_e32 v89, v89
	v_exp_f32_e32 v90, v90
	v_exp_f32_e32 v91, v91
	v_mul_f32_e32 v84, 0xbfb8aa3b, v84
	v_mul_f32_e32 v85, 0xbfb8aa3b, v85
	v_mul_f32_e32 v86, 0xbfb8aa3b, v86
	v_mul_f32_e32 v87, 0xbfb8aa3b, v87
	global_store_dwordx4 v[156:157], v[108:111], off sc1
	v_pk_fma_f32 v[106:107], v[106:107], v[122:123], v[138:139]
	v_pk_fma_f32 v[104:105], v[104:105], v[120:121], v[136:137]
	v_lshl_add_u64 v[108:109], v[154:155], 0, v[148:149]
	v_exp_f32_e32 v84, v84
	v_exp_f32_e32 v85, v85
	v_exp_f32_e32 v86, v86
	v_exp_f32_e32 v87, v87
	v_mul_f32_e32 v80, 0xbfb8aa3b, v80
	v_mul_f32_e32 v81, 0xbfb8aa3b, v81
	v_mul_f32_e32 v82, 0xbfb8aa3b, v82
	v_mul_f32_e32 v83, 0xbfb8aa3b, v83
	global_store_dwordx4 v[108:109], v[104:107], off sc1
	v_pk_fma_f32 v[102:103], v[102:103], v[118:119], v[134:135]
	v_pk_fma_f32 v[100:101], v[100:101], v[116:117], v[132:133]
	v_lshl_add_u64 v[104:105], v[154:155], 0, v[150:151]
	v_exp_f32_e32 v80, v80
	v_exp_f32_e32 v81, v81
	v_exp_f32_e32 v82, v82
	v_exp_f32_e32 v83, v83
	global_store_dwordx4 v[104:105], v[100:103], off sc1
	v_pk_fma_f32 v[98:99], v[98:99], v[114:115], v[130:131]
	v_pk_fma_f32 v[96:97], v[96:97], v[112:113], v[128:129]
	v_lshl_add_u64 v[100:101], v[154:155], 0, v[152:153]
	v_add_f32_e32 v92, 1.0, v92
	v_add_f32_e32 v93, 1.0, v93
	v_add_f32_e32 v94, 1.0, v94
	v_add_f32_e32 v95, 1.0, v95
	global_store_dwordx4 v[100:101], v[96:99], off sc1
	v_rcp_f32_e32 v92, v92
	v_rcp_f32_e32 v93, v93
	v_or_b32_e32 v96, 32, v144
	v_rcp_f32_e32 v94, v94
	v_rcp_f32_e32 v95, v95
	v_add_f32_e32 v88, 1.0, v88
	v_add_f32_e32 v89, 1.0, v89
	v_add_f32_e32 v90, 1.0, v90
	v_add_f32_e32 v91, 1.0, v91
	v_ashrrev_i32_e32 v97, 31, v96
	v_rcp_f32_e32 v88, v88
	v_rcp_f32_e32 v89, v89
	v_rcp_f32_e32 v90, v90
	v_rcp_f32_e32 v91, v91
	v_add_f32_e32 v84, 1.0, v84
	v_add_f32_e32 v85, 1.0, v85
	v_add_f32_e32 v86, 1.0, v86
	v_add_f32_e32 v87, 1.0, v87
	v_lshlrev_b64 v[96:97], 12, v[96:97]
	v_rcp_f32_e32 v84, v84
	v_rcp_f32_e32 v85, v85
	v_rcp_f32_e32 v86, v86
	v_rcp_f32_e32 v87, v87
	v_add_f32_e32 v80, 1.0, v80
	v_add_f32_e32 v81, 1.0, v81
	v_add_f32_e32 v82, 1.0, v82
	v_add_f32_e32 v83, 1.0, v83
	v_mul_f32_e32 v76, 0xbfb8aa3b, v76
	v_mul_f32_e32 v77, 0xbfb8aa3b, v77
	v_mul_f32_e32 v78, 0xbfb8aa3b, v78
	v_mul_f32_e32 v79, 0xbfb8aa3b, v79
	v_lshl_add_u64 v[96:97], s[6:7], 0, v[96:97]
	v_rcp_f32_e32 v80, v80
	v_rcp_f32_e32 v81, v81
	v_rcp_f32_e32 v82, v82
	v_rcp_f32_e32 v83, v83
	v_exp_f32_e32 v76, v76
	v_exp_f32_e32 v77, v77
	v_exp_f32_e32 v78, v78
	v_exp_f32_e32 v79, v79
	v_mul_f32_e32 v72, 0xbfb8aa3b, v72
	v_mul_f32_e32 v73, 0xbfb8aa3b, v73
	v_mul_f32_e32 v74, 0xbfb8aa3b, v74
	v_mul_f32_e32 v75, 0xbfb8aa3b, v75
	v_pk_fma_f32 v[94:95], v[94:95], v[126:127], v[142:143]
	v_pk_fma_f32 v[92:93], v[92:93], v[124:125], v[140:141]
	v_lshl_add_u64 v[98:99], v[96:97], 0, v[146:147]
	v_exp_f32_e32 v72, v72
	v_exp_f32_e32 v73, v73
	v_exp_f32_e32 v74, v74
	v_exp_f32_e32 v75, v75
	v_mul_f32_e32 v68, 0xbfb8aa3b, v68
	v_mul_f32_e32 v69, 0xbfb8aa3b, v69
	v_mul_f32_e32 v70, 0xbfb8aa3b, v70
	v_mul_f32_e32 v71, 0xbfb8aa3b, v71
	global_store_dwordx4 v[98:99], v[92:95], off sc1
	v_pk_fma_f32 v[90:91], v[90:91], v[122:123], v[138:139]
	v_pk_fma_f32 v[88:89], v[88:89], v[120:121], v[136:137]
	v_lshl_add_u64 v[92:93], v[96:97], 0, v[148:149]
	v_exp_f32_e32 v68, v68
	v_exp_f32_e32 v69, v69
	v_exp_f32_e32 v70, v70
	v_exp_f32_e32 v71, v71
	v_mul_f32_e32 v64, 0xbfb8aa3b, v64
; __device__ __forceinline__ float sigmoidf_(float x) { return __builtin_amdgcn_rcpf(1.0f + __expf(-x)); }
;     __device__ __forceinline__ void operator()(const f32x4 (&acc)[2][2][4][2], const pg8::Unit& u, int wr, int wc, int fr, int fq) const {
;     ...
;         if (seg == 1 || seg == 2) {
;             float* F = (float*)(ws + (seg == 1 ? WS_FW : WS_FB)); const float* lbd = lb + (seg - 1) * WA;
;             f32x4 lbv[2][2];
; #pragma unroll
;             for (int bj = 0; bj < 2; ++bj)
; #pragma unroll
;                 for (int n = 0; n < 2; ++n) lbv[bj][n] = *(const f32x4*)(lbd + u.pn * 256 + bj * 128 + wc * 32 + n * 16 + fq * 4 - seg * WA);
;             EPI_LOOP_BEGIN
;                 const int c = col - seg * WA; const f32x4 l = lbv[bj][n]; f32x4 o;
;                 o.x = l.x + (1.0f - l.x) * sigmoidf_(v.x); o.y = l.y + (1.0f - l.y) * sigmoidf_(v.y);
;                 o.z = l.z + (1.0f - l.z) * sigmoidf_(v.z); o.w = l.w + (1.0f - l.w) * sigmoidf_(v.w);
;                 *(f32x4*)(F + (size_t)row * WA + c) = o;
;             EPI_LOOP_END
	v_mul_f32_e32 v65, 0xbfb8aa3b, v65
	v_mul_f32_e32 v66, 0xbfb8aa3b, v66
	v_mul_f32_e32 v67, 0xbfb8aa3b, v67
	global_store_dwordx4 v[92:93], v[88:91], off sc1
	v_pk_fma_f32 v[86:87], v[86:87], v[118:119], v[134:135]
	v_pk_fma_f32 v[84:85], v[84:85], v[116:117], v[132:133]
	v_lshl_add_u64 v[88:89], v[96:97], 0, v[150:151]
	v_exp_f32_e32 v64, v64
	v_exp_f32_e32 v65, v65
	v_exp_f32_e32 v66, v66
	v_exp_f32_e32 v67, v67
	global_store_dwordx4 v[88:89], v[84:87], off sc1
	v_pk_fma_f32 v[82:83], v[82:83], v[114:115], v[130:131]
	v_pk_fma_f32 v[80:81], v[80:81], v[112:113], v[128:129]
	v_lshl_add_u64 v[84:85], v[96:97], 0, v[152:153]
	v_add_f32_e32 v76, 1.0, v76
	v_add_f32_e32 v77, 1.0, v77
	v_add_f32_e32 v78, 1.0, v78
	v_add_f32_e32 v79, 1.0, v79
	global_store_dwordx4 v[84:85], v[80:83], off sc1
	v_rcp_f32_e32 v76, v76
	v_rcp_f32_e32 v77, v77
	v_or_b32_e32 v80, 48, v144
	v_rcp_f32_e32 v78, v78
	v_rcp_f32_e32 v79, v79
	v_add_f32_e32 v72, 1.0, v72
	v_add_f32_e32 v73, 1.0, v73
	v_add_f32_e32 v74, 1.0, v74
	v_add_f32_e32 v75, 1.0, v75
	v_ashrrev_i32_e32 v81, 31, v80
	v_rcp_f32_e32 v72, v72
	v_rcp_f32_e32 v73, v73
	v_rcp_f32_e32 v74, v74
	v_rcp_f32_e32 v75, v75
	v_add_f32_e32 v68, 1.0, v68
	v_add_f32_e32 v69, 1.0, v69
	v_add_f32_e32 v70, 1.0, v70
	v_add_f32_e32 v71, 1.0, v71
	v_lshlrev_b64 v[80:81], 12, v[80:81]
	v_rcp_f32_e32 v68, v68
	v_rcp_f32_e32 v69, v69
	v_rcp_f32_e32 v70, v70
	v_rcp_f32_e32 v71, v71
	v_add_f32_e32 v64, 1.0, v64
	v_add_f32_e32 v65, 1.0, v65
	v_add_f32_e32 v66, 1.0, v66
	v_add_f32_e32 v67, 1.0, v67
	v_mul_f32_e32 v60, 0xbfb8aa3b, v60
	v_mul_f32_e32 v61, 0xbfb8aa3b, v61
	v_mul_f32_e32 v62, 0xbfb8aa3b, v62
	v_mul_f32_e32 v63, 0xbfb8aa3b, v63
	v_lshl_add_u64 v[80:81], s[6:7], 0, v[80:81]
	v_rcp_f32_e32 v64, v64
	v_rcp_f32_e32 v65, v65
	v_rcp_f32_e32 v66, v66
	v_rcp_f32_e32 v67, v67
	v_exp_f32_e32 v60, v60
	v_exp_f32_e32 v61, v61
	v_exp_f32_e32 v62, v62
	v_exp_f32_e32 v63, v63
	v_mul_f32_e32 v56, 0xbfb8aa3b, v56
	v_mul_f32_e32 v57, 0xbfb8aa3b, v57
	v_mul_f32_e32 v58, 0xbfb8aa3b, v58
	v_mul_f32_e32 v59, 0xbfb8aa3b, v59
	v_pk_fma_f32 v[78:79], v[78:79], v[126:127], v[142:143]
	v_pk_fma_f32 v[76:77], v[76:77], v[124:125], v[140:141]
	v_lshl_add_u64 v[82:83], v[80:81], 0, v[146:147]
	v_exp_f32_e32 v56, v56
	v_exp_f32_e32 v57, v57
	v_exp_f32_e32 v58, v58
	v_exp_f32_e32 v59, v59
	v_mul_f32_e32 v52, 0xbfb8aa3b, v52
	v_mul_f32_e32 v53, 0xbfb8aa3b, v53
	v_mul_f32_e32 v54, 0xbfb8aa3b, v54
	v_mul_f32_e32 v55, 0xbfb8aa3b, v55
	global_store_dwordx4 v[82:83], v[76:79], off sc1
	v_pk_fma_f32 v[74:75], v[74:75], v[122:123], v[138:139]
	v_pk_fma_f32 v[72:73], v[72:73], v[120:121], v[136:137]
	v_lshl_add_u64 v[76:77], v[80:81], 0, v[148:149]
	v_exp_f32_e32 v52, v52
	v_exp_f32_e32 v53, v53
	v_exp_f32_e32 v54, v54
	v_exp_f32_e32 v55, v55
	v_mul_f32_e32 v48, 0xbfb8aa3b, v48
	v_mul_f32_e32 v49, 0xbfb8aa3b, v49
	v_mul_f32_e32 v50, 0xbfb8aa3b, v50
	v_mul_f32_e32 v51, 0xbfb8aa3b, v51
	global_store_dwordx4 v[76:77], v[72:75], off sc1
	v_pk_fma_f32 v[70:71], v[70:71], v[118:119], v[134:135]
	v_pk_fma_f32 v[68:69], v[68:69], v[116:117], v[132:133]
	v_lshl_add_u64 v[72:73], v[80:81], 0, v[150:151]
	v_exp_f32_e32 v48, v48
	v_exp_f32_e32 v49, v49
	v_exp_f32_e32 v50, v50
	v_exp_f32_e32 v51, v51
	global_store_dwordx4 v[72:73], v[68:71], off sc1
	v_pk_fma_f32 v[66:67], v[66:67], v[114:115], v[130:131]
	v_pk_fma_f32 v[64:65], v[64:65], v[112:113], v[128:129]
	v_lshl_add_u64 v[68:69], v[80:81], 0, v[152:153]
	v_add_f32_e32 v60, 1.0, v60
	v_add_f32_e32 v61, 1.0, v61
	v_add_f32_e32 v62, 1.0, v62
	v_add_f32_e32 v63, 1.0, v63
	global_store_dwordx4 v[68:69], v[64:67], off sc1
	v_rcp_f32_e32 v60, v60
	v_rcp_f32_e32 v61, v61
	v_add_u32_e32 v64, 0x80, v144
	v_rcp_f32_e32 v62, v62
	v_rcp_f32_e32 v63, v63
	v_add_f32_e32 v56, 1.0, v56
	v_add_f32_e32 v57, 1.0, v57
	v_add_f32_e32 v58, 1.0, v58
	v_add_f32_e32 v59, 1.0, v59
	v_ashrrev_i32_e32 v65, 31, v64
	v_rcp_f32_e32 v56, v56
	v_rcp_f32_e32 v57, v57
	v_rcp_f32_e32 v58, v58
	v_rcp_f32_e32 v59, v59
	v_add_f32_e32 v52, 1.0, v52
	v_add_f32_e32 v53, 1.0, v53
	v_add_f32_e32 v54, 1.0, v54
	v_add_f32_e32 v55, 1.0, v55
	v_lshlrev_b64 v[64:65], 12, v[64:65]
	v_rcp_f32_e32 v52, v52
	v_rcp_f32_e32 v53, v53
	v_rcp_f32_e32 v54, v54
	v_rcp_f32_e32 v55, v55
	v_add_f32_e32 v48, 1.0, v48
	v_add_f32_e32 v49, 1.0, v49
	v_add_f32_e32 v50, 1.0, v50
	v_add_f32_e32 v51, 1.0, v51
	v_mul_f32_e32 v44, 0xbfb8aa3b, v44
	v_mul_f32_e32 v45, 0xbfb8aa3b, v45
	v_mul_f32_e32 v46, 0xbfb8aa3b, v46
	v_mul_f32_e32 v47, 0xbfb8aa3b, v47
	v_lshl_add_u64 v[64:65], s[6:7], 0, v[64:65]
	v_rcp_f32_e32 v48, v48
	v_rcp_f32_e32 v49, v49
	v_rcp_f32_e32 v50, v50
	v_rcp_f32_e32 v51, v51
	v_exp_f32_e32 v44, v44
	v_exp_f32_e32 v45, v45
	v_exp_f32_e32 v46, v46
	v_exp_f32_e32 v47, v47
	v_mul_f32_e32 v40, 0xbfb8aa3b, v40
	v_mul_f32_e32 v41, 0xbfb8aa3b, v41
	v_mul_f32_e32 v42, 0xbfb8aa3b, v42
	v_mul_f32_e32 v43, 0xbfb8aa3b, v43
	v_pk_fma_f32 v[62:63], v[62:63], v[126:127], v[142:143]
	v_pk_fma_f32 v[60:61], v[60:61], v[124:125], v[140:141]
	v_lshl_add_u64 v[66:67], v[64:65], 0, v[146:147]
	v_exp_f32_e32 v40, v40
	v_exp_f32_e32 v41, v41
	v_exp_f32_e32 v42, v42
	v_exp_f32_e32 v43, v43
	v_mul_f32_e32 v36, 0xbfb8aa3b, v36
	v_mul_f32_e32 v37, 0xbfb8aa3b, v37
	v_mul_f32_e32 v38, 0xbfb8aa3b, v38
	v_mul_f32_e32 v39, 0xbfb8aa3b, v39
	global_store_dwordx4 v[66:67], v[60:63], off sc1
	v_pk_fma_f32 v[58:59], v[58:59], v[122:123], v[138:139]
	v_pk_fma_f32 v[56:57], v[56:57], v[120:121], v[136:137]
	v_lshl_add_u64 v[60:61], v[64:65], 0, v[148:149]
	v_exp_f32_e32 v36, v36
	v_exp_f32_e32 v37, v37
	v_exp_f32_e32 v38, v38
	v_exp_f32_e32 v39, v39
	v_mul_f32_e32 v32, 0xbfb8aa3b, v32
	v_mul_f32_e32 v33, 0xbfb8aa3b, v33
; __device__ __forceinline__ float sigmoidf_(float x) { return __builtin_amdgcn_rcpf(1.0f + __expf(-x)); }
;     __device__ __forceinline__ void operator()(const f32x4 (&acc)[2][2][4][2], const pg8::Unit& u, int wr, int wc, int fr, int fq) const {
;     ...
;         if (seg == 1 || seg == 2) {
;             float* F = (float*)(ws + (seg == 1 ? WS_FW : WS_FB)); const float* lbd = lb + (seg - 1) * WA;
;             f32x4 lbv[2][2];
; #pragma unroll
;             for (int bj = 0; bj < 2; ++bj)
; #pragma unroll
;                 for (int n = 0; n < 2; ++n) lbv[bj][n] = *(const f32x4*)(lbd + u.pn * 256 + bj * 128 + wc * 32 + n * 16 + fq * 4 - seg * WA);
;             EPI_LOOP_BEGIN
;                 const int c = col - seg * WA; const f32x4 l = lbv[bj][n]; f32x4 o;
;                 o.x = l.x + (1.0f - l.x) * sigmoidf_(v.x); o.y = l.y + (1.0f - l.y) * sigmoidf_(v.y);
;                 o.z = l.z + (1.0f - l.z) * sigmoidf_(v.z); o.w = l.w + (1.0f - l.w) * sigmoidf_(v.w);
;                 *(f32x4*)(F + (size_t)row * WA + c) = o;
;             EPI_LOOP_END
	v_mul_f32_e32 v34, 0xbfb8aa3b, v34
	v_mul_f32_e32 v35, 0xbfb8aa3b, v35
	global_store_dwordx4 v[60:61], v[56:59], off sc1
	v_pk_fma_f32 v[54:55], v[54:55], v[118:119], v[134:135]
	v_pk_fma_f32 v[52:53], v[52:53], v[116:117], v[132:133]
	v_lshl_add_u64 v[56:57], v[64:65], 0, v[150:151]
	v_exp_f32_e32 v32, v32
	v_exp_f32_e32 v33, v33
	v_exp_f32_e32 v34, v34
	v_exp_f32_e32 v35, v35
	global_store_dwordx4 v[56:57], v[52:55], off sc1
	v_pk_fma_f32 v[50:51], v[50:51], v[114:115], v[130:131]
	v_pk_fma_f32 v[48:49], v[48:49], v[112:113], v[128:129]
	v_lshl_add_u64 v[52:53], v[64:65], 0, v[152:153]
	v_add_f32_e32 v44, 1.0, v44
	v_add_f32_e32 v45, 1.0, v45
	v_add_f32_e32 v46, 1.0, v46
	v_add_f32_e32 v47, 1.0, v47
	global_store_dwordx4 v[52:53], v[48:51], off sc1
	v_rcp_f32_e32 v44, v44
	v_rcp_f32_e32 v45, v45
	v_add_u32_e32 v48, 0x90, v144
	v_rcp_f32_e32 v46, v46
	v_rcp_f32_e32 v47, v47
	v_add_f32_e32 v40, 1.0, v40
	v_add_f32_e32 v41, 1.0, v41
	v_add_f32_e32 v42, 1.0, v42
	v_add_f32_e32 v43, 1.0, v43
	v_ashrrev_i32_e32 v49, 31, v48
	v_rcp_f32_e32 v40, v40
	v_rcp_f32_e32 v41, v41
	v_rcp_f32_e32 v42, v42
	v_rcp_f32_e32 v43, v43
	v_add_f32_e32 v36, 1.0, v36
	v_add_f32_e32 v37, 1.0, v37
	v_add_f32_e32 v38, 1.0, v38
	v_add_f32_e32 v39, 1.0, v39
	v_lshlrev_b64 v[48:49], 12, v[48:49]
	v_rcp_f32_e32 v36, v36
	v_rcp_f32_e32 v37, v37
	v_rcp_f32_e32 v38, v38
	v_rcp_f32_e32 v39, v39
	v_add_f32_e32 v32, 1.0, v32
	v_add_f32_e32 v33, 1.0, v33
	v_add_f32_e32 v34, 1.0, v34
	v_add_f32_e32 v35, 1.0, v35
	v_mul_f32_e32 v28, 0xbfb8aa3b, v28
	v_mul_f32_e32 v29, 0xbfb8aa3b, v29
	v_mul_f32_e32 v30, 0xbfb8aa3b, v30
	v_mul_f32_e32 v31, 0xbfb8aa3b, v31
	v_lshl_add_u64 v[48:49], s[6:7], 0, v[48:49]
	v_rcp_f32_e32 v32, v32
	v_rcp_f32_e32 v33, v33
	v_rcp_f32_e32 v34, v34
	v_rcp_f32_e32 v35, v35
	v_exp_f32_e32 v28, v28
	v_exp_f32_e32 v29, v29
	v_exp_f32_e32 v30, v30
	v_exp_f32_e32 v31, v31
	v_mul_f32_e32 v24, 0xbfb8aa3b, v24
	v_mul_f32_e32 v25, 0xbfb8aa3b, v25
	v_mul_f32_e32 v26, 0xbfb8aa3b, v26
	v_mul_f32_e32 v27, 0xbfb8aa3b, v27
	v_pk_fma_f32 v[46:47], v[46:47], v[126:127], v[142:143]
	v_pk_fma_f32 v[44:45], v[44:45], v[124:125], v[140:141]
	v_lshl_add_u64 v[50:51], v[48:49], 0, v[146:147]
	v_exp_f32_e32 v24, v24
	v_exp_f32_e32 v25, v25
	v_exp_f32_e32 v26, v26
	v_exp_f32_e32 v27, v27
	v_mul_f32_e32 v20, 0xbfb8aa3b, v20
	v_mul_f32_e32 v21, 0xbfb8aa3b, v21
	v_mul_f32_e32 v22, 0xbfb8aa3b, v22
	v_mul_f32_e32 v23, 0xbfb8aa3b, v23
	global_store_dwordx4 v[50:51], v[44:47], off sc1
	v_pk_fma_f32 v[42:43], v[42:43], v[122:123], v[138:139]
	v_pk_fma_f32 v[40:41], v[40:41], v[120:121], v[136:137]
	v_lshl_add_u64 v[44:45], v[48:49], 0, v[148:149]
	v_exp_f32_e32 v20, v20
	v_exp_f32_e32 v21, v21
	v_exp_f32_e32 v22, v22
	v_exp_f32_e32 v23, v23
	v_mul_f32_e32 v16, 0xbfb8aa3b, v16
	v_mul_f32_e32 v17, 0xbfb8aa3b, v17
	v_mul_f32_e32 v18, 0xbfb8aa3b, v18
	v_mul_f32_e32 v19, 0xbfb8aa3b, v19
	global_store_dwordx4 v[44:45], v[40:43], off sc1
	v_pk_fma_f32 v[38:39], v[38:39], v[118:119], v[134:135]
	v_pk_fma_f32 v[36:37], v[36:37], v[116:117], v[132:133]
	v_lshl_add_u64 v[40:41], v[48:49], 0, v[150:151]
	v_exp_f32_e32 v16, v16
	v_exp_f32_e32 v17, v17
	v_exp_f32_e32 v18, v18
	v_exp_f32_e32 v19, v19
	global_store_dwordx4 v[40:41], v[36:39], off sc1
	v_pk_fma_f32 v[34:35], v[34:35], v[114:115], v[130:131]
	v_pk_fma_f32 v[32:33], v[32:33], v[112:113], v[128:129]
	v_lshl_add_u64 v[36:37], v[48:49], 0, v[152:153]
	v_add_f32_e32 v28, 1.0, v28
	v_add_f32_e32 v29, 1.0, v29
	v_add_f32_e32 v30, 1.0, v30
	v_add_f32_e32 v31, 1.0, v31
	global_store_dwordx4 v[36:37], v[32:35], off sc1
	v_rcp_f32_e32 v28, v28
	v_rcp_f32_e32 v29, v29
	v_add_u32_e32 v32, 0xa0, v144
	v_rcp_f32_e32 v30, v30
	v_rcp_f32_e32 v31, v31
	v_add_f32_e32 v24, 1.0, v24
	v_add_f32_e32 v25, 1.0, v25
	v_add_f32_e32 v26, 1.0, v26
	v_add_f32_e32 v27, 1.0, v27
	v_ashrrev_i32_e32 v33, 31, v32
	v_rcp_f32_e32 v24, v24
	v_rcp_f32_e32 v25, v25
	v_rcp_f32_e32 v26, v26
	v_rcp_f32_e32 v27, v27
	v_add_f32_e32 v20, 1.0, v20
	v_add_f32_e32 v21, 1.0, v21
	v_add_f32_e32 v22, 1.0, v22
; __device__ __forceinline__ float sigmoidf_(float x) { return __builtin_amdgcn_rcpf(1.0f + __expf(-x)); }
;     __device__ __forceinline__ void operator()(const f32x4 (&acc)[2][2][4][2], const pg8::Unit& u, int wr, int wc, int fr, int fq) const {
;     ...
;         if (seg == 1 || seg == 2) {
;             float* F = (float*)(ws + (seg == 1 ? WS_FW : WS_FB)); const float* lbd = lb + (seg - 1) * WA;
;             f32x4 lbv[2][2];
; #pragma unroll
;             for (int bj = 0; bj < 2; ++bj)
; #pragma unroll
;                 for (int n = 0; n < 2; ++n) lbv[bj][n] = *(const f32x4*)(lbd + u.pn * 256 + bj * 128 + wc * 32 + n * 16 + fq * 4 - seg * WA);
;             EPI_LOOP_BEGIN
;                 const int c = col - seg * WA; const f32x4 l = lbv[bj][n]; f32x4 o;
;                 o.x = l.x + (1.0f - l.x) * sigmoidf_(v.x); o.y = l.y + (1.0f - l.y) * sigmoidf_(v.y);
;                 o.z = l.z + (1.0f - l.z) * sigmoidf_(v.z); o.w = l.w + (1.0f - l.w) * sigmoidf_(v.w);
;                 *(f32x4*)(F + (size_t)row * WA + c) = o;
;             EPI_LOOP_END
	v_add_f32_e32 v23, 1.0, v23
	v_lshlrev_b64 v[32:33], 12, v[32:33]
	v_rcp_f32_e32 v20, v20
	v_rcp_f32_e32 v21, v21
	v_rcp_f32_e32 v22, v22
	v_rcp_f32_e32 v23, v23
	v_add_f32_e32 v16, 1.0, v16
	v_add_f32_e32 v17, 1.0, v17
	v_add_f32_e32 v18, 1.0, v18
	v_add_f32_e32 v19, 1.0, v19
	v_mul_f32_e32 v12, 0xbfb8aa3b, v12
	v_mul_f32_e32 v13, 0xbfb8aa3b, v13
	v_mul_f32_e32 v14, 0xbfb8aa3b, v14
	v_mul_f32_e32 v15, 0xbfb8aa3b, v15
	v_lshl_add_u64 v[32:33], s[6:7], 0, v[32:33]
	v_rcp_f32_e32 v16, v16
	v_rcp_f32_e32 v17, v17
	v_rcp_f32_e32 v18, v18
	v_rcp_f32_e32 v19, v19
	v_exp_f32_e32 v12, v12
	v_exp_f32_e32 v13, v13
	v_exp_f32_e32 v14, v14
	v_exp_f32_e32 v15, v15
	v_mul_f32_e32 v8, 0xbfb8aa3b, v8
	v_mul_f32_e32 v9, 0xbfb8aa3b, v9
	v_mul_f32_e32 v10, 0xbfb8aa3b, v10
	v_mul_f32_e32 v11, 0xbfb8aa3b, v11
	v_pk_fma_f32 v[30:31], v[30:31], v[126:127], v[142:143]
	v_pk_fma_f32 v[28:29], v[28:29], v[124:125], v[140:141]
	v_lshl_add_u64 v[34:35], v[32:33], 0, v[146:147]
	v_exp_f32_e32 v8, v8
	v_exp_f32_e32 v9, v9
	v_exp_f32_e32 v10, v10
	v_exp_f32_e32 v11, v11
	v_mul_f32_e32 v4, 0xbfb8aa3b, v4
	v_mul_f32_e32 v5, 0xbfb8aa3b, v5
	v_mul_f32_e32 v6, 0xbfb8aa3b, v6
	v_mul_f32_e32 v7, 0xbfb8aa3b, v7
	global_store_dwordx4 v[34:35], v[28:31], off sc1
	v_pk_fma_f32 v[26:27], v[26:27], v[122:123], v[138:139]
	v_pk_fma_f32 v[24:25], v[24:25], v[120:121], v[136:137]
	v_lshl_add_u64 v[28:29], v[32:33], 0, v[148:149]
	v_exp_f32_e32 v4, v4
	v_exp_f32_e32 v5, v5
	v_exp_f32_e32 v6, v6
	v_exp_f32_e32 v7, v7
	v_mul_f32_e32 v0, 0xbfb8aa3b, v0
	v_mul_f32_e32 v1, 0xbfb8aa3b, v1
	v_mul_f32_e32 v2, 0xbfb8aa3b, v2
	v_mul_f32_e32 v3, 0xbfb8aa3b, v3
	global_store_dwordx4 v[28:29], v[24:27], off sc1
	v_pk_fma_f32 v[22:23], v[22:23], v[118:119], v[134:135]
	v_pk_fma_f32 v[20:21], v[20:21], v[116:117], v[132:133]
	v_lshl_add_u64 v[24:25], v[32:33], 0, v[150:151]
	v_exp_f32_e32 v0, v0
	v_exp_f32_e32 v1, v1
	v_exp_f32_e32 v2, v2
	v_exp_f32_e32 v3, v3
	global_store_dwordx4 v[24:25], v[20:23], off sc1
	v_pk_fma_f32 v[18:19], v[18:19], v[114:115], v[130:131]
	v_pk_fma_f32 v[16:17], v[16:17], v[112:113], v[128:129]
	v_lshl_add_u64 v[20:21], v[32:33], 0, v[152:153]
	v_add_f32_e32 v12, 1.0, v12
	v_add_f32_e32 v13, 1.0, v13
	v_add_f32_e32 v14, 1.0, v14
	v_add_f32_e32 v15, 1.0, v15
	global_store_dwordx4 v[20:21], v[16:19], off sc1
	v_rcp_f32_e32 v12, v12
	v_rcp_f32_e32 v13, v13
	v_add_u32_e32 v16, 0xb0, v144
	v_rcp_f32_e32 v14, v14
	v_rcp_f32_e32 v15, v15
	v_add_f32_e32 v8, 1.0, v8
	v_add_f32_e32 v9, 1.0, v9
	v_add_f32_e32 v10, 1.0, v10
	v_add_f32_e32 v11, 1.0, v11
	v_ashrrev_i32_e32 v17, 31, v16
	v_rcp_f32_e32 v8, v8
	v_rcp_f32_e32 v9, v9
	v_rcp_f32_e32 v10, v10
	v_rcp_f32_e32 v11, v11
	v_add_f32_e32 v4, 1.0, v4
	v_add_f32_e32 v5, 1.0, v5
	v_add_f32_e32 v6, 1.0, v6
	v_add_f32_e32 v7, 1.0, v7
	v_lshlrev_b64 v[16:17], 12, v[16:17]
	v_rcp_f32_e32 v4, v4
	v_rcp_f32_e32 v5, v5
	v_rcp_f32_e32 v6, v6
	v_rcp_f32_e32 v7, v7
	v_add_f32_e32 v0, 1.0, v0
	v_add_f32_e32 v1, 1.0, v1
	v_add_f32_e32 v2, 1.0, v2
	v_add_f32_e32 v3, 1.0, v3
	v_lshl_add_u64 v[16:17], s[6:7], 0, v[16:17]
	v_rcp_f32_e32 v0, v0
	v_rcp_f32_e32 v1, v1
	v_rcp_f32_e32 v2, v2
	v_rcp_f32_e32 v3, v3
	v_pk_fma_f32 v[14:15], v[14:15], v[126:127], v[142:143]
	v_pk_fma_f32 v[12:13], v[12:13], v[124:125], v[140:141]
	v_lshl_add_u64 v[18:19], v[16:17], 0, v[146:147]
	global_store_dwordx4 v[18:19], v[12:15], off sc1
	v_pk_fma_f32 v[10:11], v[10:11], v[122:123], v[138:139]
	v_pk_fma_f32 v[8:9], v[8:9], v[120:121], v[136:137]
	v_lshl_add_u64 v[12:13], v[16:17], 0, v[148:149]
	global_store_dwordx4 v[12:13], v[8:11], off sc1
	v_pk_fma_f32 v[6:7], v[6:7], v[118:119], v[134:135]
	v_pk_fma_f32 v[4:5], v[4:5], v[116:117], v[132:133]
	v_lshl_add_u64 v[8:9], v[16:17], 0, v[150:151]
	global_store_dwordx4 v[8:9], v[4:7], off sc1
	v_pk_fma_f32 v[2:3], v[2:3], v[114:115], v[130:131]
	v_pk_fma_f32 v[0:1], v[0:1], v[112:113], v[128:129]
	v_lshl_add_u64 v[4:5], v[16:17], 0, v[152:153]
	global_store_dwordx4 v[4:5], v[0:3], off sc1
	s_andn2_b64 vcc, exec, s[58:59]
	s_mov_b64 s[6:7], -1
	s_cbranch_vccnz .LBB0_125

; template <bool QKPERM, bool BIAS>
; __device__ __forceinline__ void transpose_item(const float* W, int K, int N, bf16* WT, int row_off, LAS float* scr, int item, int lane, const float* sh2 = nullptr, float* bias2 = nullptr) {
;     ...
;     for (int i = 0; i < 32; ++i) wv[i] = __builtin_nontemporal_load(W + (size_t)(k0 + 2 * i + (lane >> 5)) * N + n0 + (lane & 31));
; __device__ __forceinline__ void phase_wconv_rest(const Params& p, LAS unsigned char* lds, int gw, int NGW) {
;     ...
;     for (int it = gw; it < NITEMS; it += NGW) {
;         int r = it;
;         if (r < I_A) { transpose_item<false, false>(p.w_a, WA, D_MODEL, (bf16*)(ws + WS_WAT), 0, scr, r, lane); continue; } r -= I_A;
;         if (r < I_A) { transpose_item<false, false>(p.w_b, WA, D_MODEL, (bf16*)(ws + WS_WBT), 0, scr, r, lane); continue; } r -= I_A;
;         if (r < I_O) { transpose_item<false, false>(p.w_o, D_MODEL, D_MODEL, (bf16*)(ws + WS_WOT), 0, scr, r, lane); continue; } r -= I_O;
;         if (r < I_1) { transpose_item<false, true>(p.w1, D_MODEL, FFN, (bf16*)(ws + WS_W13T), 0, scr, r, lane, sh2, b2); continue; } r -= I_1;
;         if (r < I_1) { transpose_item<false, true>(p.w3, D_MODEL, FFN, (bf16*)(ws + WS_W13T), 128, scr, r, lane, sh2, b2); continue; } r -= I_1;
;         transpose_item<false, false>(p.w2, FFN, D_MODEL, (bf16*)(ws + WS_W2T), 0, scr, r, lane);
.LBB0_217:
	s_cmpk_gt_u32 s20, 0x7ff
	s_cbranch_scc0 .LBB0_235
	s_cmpk_gt_u32 s20, 0xfff
	s_cbranch_scc0 .LBB0_232
	s_cmpk_gt_u32 s20, 0x25ff
	s_cbranch_scc0 .LBB0_227
	s_cmpk_gt_u32 s20, 0x3bff
	s_cbranch_scc0 .LBB0_222
	s_add_i32 s18, s20, 0xc400
	s_and_b32 s27, s18, 0xffc0
	s_and_b32 s26, s21, 0x7e0
	v_add_u32_e32 v26, s27, v34
	s_lshl_b32 s18, s26, 2
	v_ashrrev_i32_e32 v27, 31, v26
	v_lshl_add_u64 v[28:29], v[12:13], 0, s[18:19]
	v_lshlrev_b64 v[26:27], 13, v[26:27]
	v_lshl_add_u64 v[26:27], v[28:29], 0, v[26:27]
	v_add_co_u32_e32 v28, vcc, 0x4000, v26
	s_lshl_b32 s18, s27, 1
	s_nop 0
	v_addc_co_u32_e32 v29, vcc, 0, v27, vcc
	v_add_co_u32_e32 v30, vcc, 0x8000, v26
	s_nop 1
	v_addc_co_u32_e32 v31, vcc, 0, v27, vcc
	v_add_co_u32_e32 v32, vcc, 0xc000, v26
	s_nop 1
	v_addc_co_u32_e32 v33, vcc, 0, v27, vcc
	v_add_co_u32_e32 v48, vcc, 0x10000, v26
	s_nop 1
	v_addc_co_u32_e32 v49, vcc, 0, v27, vcc
	v_add_co_u32_e32 v50, vcc, 0x14000, v26
	s_nop 1
	v_addc_co_u32_e32 v51, vcc, 0, v27, vcc
	v_add_co_u32_e32 v52, vcc, 0x18000, v26
	s_nop 1
	v_addc_co_u32_e32 v53, vcc, 0, v27, vcc
	v_add_co_u32_e32 v54, vcc, 0x1c000, v26
	s_nop 1
	v_addc_co_u32_e32 v55, vcc, 0, v27, vcc
	global_load_dword v58, v[26:27], off nt
	global_load_dword v59, v[28:29], off nt
	global_load_dword v60, v[30:31], off nt
	global_load_dword v61, v[32:33], off nt
	global_load_dword v62, v[48:49], off nt
	global_load_dword v63, v[50:51], off nt
	global_load_dword v64, v[52:53], off nt
	global_load_dword v65, v[54:55], off nt
	v_add_co_u32_e32 v28, vcc, 0x20000, v26
	s_nop 1
	v_addc_co_u32_e32 v29, vcc, 0, v27, vcc
	v_add_co_u32_e32 v30, vcc, 0x24000, v26
	s_nop 1
	v_addc_co_u32_e32 v31, vcc, 0, v27, vcc
	v_add_co_u32_e32 v32, vcc, 0x28000, v26
	s_nop 1
	v_addc_co_u32_e32 v33, vcc, 0, v27, vcc
	v_add_co_u32_e32 v48, vcc, 0x2c000, v26
	s_nop 1
	v_addc_co_u32_e32 v49, vcc, 0, v27, vcc
	v_add_co_u32_e32 v50, vcc, 0x30000, v26
	s_nop 1
	v_addc_co_u32_e32 v51, vcc, 0, v27, vcc
	v_add_co_u32_e32 v52, vcc, 0x34000, v26
	s_nop 1
	v_addc_co_u32_e32 v53, vcc, 0, v27, vcc
	v_add_co_u32_e32 v54, vcc, 0x38000, v26
	s_nop 1
	v_addc_co_u32_e32 v55, vcc, 0, v27, vcc
	v_add_co_u32_e32 v56, vcc, 0x3c000, v26
	s_nop 1
	v_addc_co_u32_e32 v57, vcc, 0, v27, vcc
	global_load_dword v66, v[28:29], off nt
	global_load_dword v67, v[30:31], off nt
	global_load_dword v68, v[32:33], off nt
	global_load_dword v69, v[48:49], off nt
	global_load_dword v70, v[50:51], off nt
	global_load_dword v71, v[52:53], off nt
	global_load_dword v72, v[54:55], off nt
	global_load_dword v73, v[56:57], off nt
	v_add_co_u32_e32 v28, vcc, 0x40000, v26
	s_nop 1
	v_addc_co_u32_e32 v29, vcc, 0, v27, vcc
	v_add_co_u32_e32 v30, vcc, 0x44000, v26
	s_nop 1
	v_addc_co_u32_e32 v31, vcc, 0, v27, vcc
	v_add_co_u32_e32 v32, vcc, 0x48000, v26
	s_nop 1
	v_addc_co_u32_e32 v33, vcc, 0, v27, vcc
	v_add_co_u32_e32 v48, vcc, 0x4c000, v26
	s_nop 1
	v_addc_co_u32_e32 v49, vcc, 0, v27, vcc
	v_add_co_u32_e32 v50, vcc, 0x50000, v26
	s_nop 1
	v_addc_co_u32_e32 v51, vcc, 0, v27, vcc
	v_add_co_u32_e32 v52, vcc, 0x54000, v26
	s_nop 1
	v_addc_co_u32_e32 v53, vcc, 0, v27, vcc
	v_add_co_u32_e32 v54, vcc, 0x58000, v26
	s_nop 1
	v_addc_co_u32_e32 v55, vcc, 0, v27, vcc
	v_add_co_u32_e32 v56, vcc, 0x5c000, v26
	s_nop 1
	v_addc_co_u32_e32 v57, vcc, 0, v27, vcc
	global_load_dword v74, v[28:29], off nt
	global_load_dword v75, v[30:31], off nt
	global_load_dword v76, v[32:33], off nt
	global_load_dword v77, v[48:49], off nt
	global_load_dword v78, v[50:51], off nt
	global_load_dword v79, v[52:53], off nt
	global_load_dword v80, v[54:55], off nt
	global_load_dword v81, v[56:57], off nt
	v_add_co_u32_e32 v28, vcc, 0x60000, v26
	s_nop 1
	v_addc_co_u32_e32 v29, vcc, 0, v27, vcc
	v_add_co_u32_e32 v30, vcc, 0x64000, v26
	s_nop 1
	v_addc_co_u32_e32 v31, vcc, 0, v27, vcc
	v_add_co_u32_e32 v32, vcc, 0x68000, v26
	s_nop 1
	v_addc_co_u32_e32 v33, vcc, 0, v27, vcc
	v_add_co_u32_e32 v48, vcc, 0x6c000, v26
	s_nop 1
	v_addc_co_u32_e32 v49, vcc, 0, v27, vcc
	v_add_co_u32_e32 v50, vcc, 0x70000, v26
	s_nop 1
	v_addc_co_u32_e32 v51, vcc, 0, v27, vcc
	v_add_co_u32_e32 v52, vcc, 0x74000, v26
	s_nop 1
	v_addc_co_u32_e32 v53, vcc, 0, v27, vcc
	v_add_co_u32_e32 v54, vcc, 0x78000, v26
	s_nop 1
	v_addc_co_u32_e32 v55, vcc, 0, v27, vcc
	v_add_co_u32_e32 v26, vcc, 0x7c000, v26
	s_nop 1
	v_addc_co_u32_e32 v27, vcc, 0, v27, vcc
	global_load_dword v28, v[28:29], off nt
	s_nop 0
	global_load_dword v29, v[30:31], off nt
	global_load_dword v56, v[32:33], off nt
	global_load_dword v57, v[48:49], off nt
	global_load_dword v82, v[50:51], off nt
	global_load_dword v83, v[52:53], off nt
	global_load_dword v84, v[54:55], off nt
	global_load_dword v85, v[26:27], off nt
	s_waitcnt vmcnt(0)
; #define LAS __attribute__((address_space(3)))
; __device__ __forceinline__ unsigned pk2(float lo, float hi) { const f32x2_t v = {lo, hi}; const bf16x2_t b = __builtin_convertvector(v, bf16x2_t); return __builtin_bit_cast(unsigned, b); }
; template <bool QKPERM, bool BIAS>
; __device__ __forceinline__ void transpose_item(const float* W, int K, int N, bf16* WT, int row_off, LAS float* scr, int item, int lane, const float* sh2 = nullptr, float* bias2 = nullptr) {
;     ...
;     for (int i = 0; i < 32; ++i) scr[(2 * i + (lane >> 5)) * 33 + (lane & 31)] = wv[i];
;     if (BIAS) {
;         float a0 = 0.f, a1 = 0.f, a2 = 0.f, a3 = 0.f;
; #pragma unroll
;         for (int i = 0; i < 32; ++i) { const int k = k0 + 2 * i + (lane >> 5); const float w = wv[i];
;             a0 += w * sh2[0 * IN_COLS + k]; a1 += w * sh2[1 * IN_COLS + k]; a2 += w * sh2[2 * IN_COLS + k]; a3 += w * sh2[3 * IN_COLS + k]; }
;         a0 = half_swap_sum(a0); a1 = half_swap_sum(a1); a2 = half_swap_sum(a2); a3 = half_swap_sum(a3);
;         if (lane < 32) { float* bp = bias2 + row_off + n0 + lane; atomicAdd(bp, a0); atomicAdd(bp + 2 * FFN, a1); atomicAdd(bp + 4 * FFN, a2); atomicAdd(bp + 6 * FFN, a3); }
;     }
;     asm volatile("s_waitcnt lgkmcnt(0)" ::: "memory");
;     const int c = lane & 7;
; #pragma unroll
;     for (int j = 0; j < 4; ++j) { const int n = (lane >> 3) + 8 * j; const LAS float* s = scr + (8 * c) * 33 + n;
;         u32x4 o; o.x = pk2(s[0 * 33], s[1 * 33]); o.y = pk2(s[2 * 33], s[3 * 33]); o.z = pk2(s[4 * 33], s[5 * 33]); o.w = pk2(s[6 * 33], s[7 * 33]);
;         int cdst = n0 + n;
;         if (QKPERM && cdst >= 5 * WA && cdst < 7 * WA) cdst = (cdst & ~0x30) | ((cdst & 0x10) << 1) | ((cdst & 0x20) >> 1);
;         *(u32x4*)(WT + (size_t)(row_off + cdst) * K + k0 + 8 * c) = o; }
;     asm volatile("s_waitcnt lgkmcnt(0)" ::: "memory");
; __device__ __forceinline__ void phase_wconv_rest(const Params& p, LAS unsigned char* lds, int gw, int NGW) {
;     ...
;         transpose_item<false, false>(p.w2, FFN, D_MODEL, (bf16*)(ws + WS_W2T), 0, scr, r, lane);
	ds_write2_b32 v39, v58, v59 offset1:66
	ds_write2_b32 v39, v60, v61 offset0:132 offset1:198
	ds_write2_b32 v40, v62, v63 offset0:8 offset1:74
	ds_write2_b32 v40, v64, v65 offset0:140 offset1:206
	ds_write2_b32 v41, v66, v67 offset0:16 offset1:82
	ds_write2_b32 v41, v68, v69 offset0:148 offset1:214
	ds_write2_b32 v42, v70, v71 offset0:24 offset1:90
	ds_write2_b32 v42, v72, v73 offset0:156 offset1:222
	ds_write2_b32 v43, v74, v75 offset0:32 offset1:98
	ds_write2_b32 v43, v76, v77 offset0:164 offset1:230
	ds_write2_b32 v44, v78, v79 offset0:40 offset1:106
	ds_write2_b32 v44, v80, v81 offset0:172 offset1:238
	ds_write2_b32 v45, v28, v29 offset0:48 offset1:114
	ds_write2_b32 v45, v56, v57 offset0:180 offset1:246
	ds_write2_b32 v46, v82, v83 offset0:56 offset1:122
	ds_write2_b32 v46, v84, v85 offset0:188 offset1:254
	s_waitcnt lgkmcnt(0)
	ds_read2_b32 v[30:31], v47 offset0:33 offset1:41
	ds_read2_b32 v[32:33], v47 offset1:8
	ds_read2_b32 v[48:49], v47 offset0:66 offset1:74
	ds_read2_b32 v[50:51], v47 offset0:99 offset1:107
	ds_read2_b32 v[52:53], v47 offset0:132 offset1:140
	ds_read2_b32 v[54:55], v47 offset0:165 offset1:173
	ds_read2_b32 v[56:57], v47 offset0:198 offset1:206
	ds_read2_b32 v[58:59], v47 offset0:231 offset1:239
	v_lshl_add_u64 v[60:61], v[2:3], 0, s[18:19]
	s_waitcnt lgkmcnt(6)
	v_cvt_pk_bf16_f32 v26, v32, v30
	v_add_u32_e32 v30, s26, v35
	s_waitcnt lgkmcnt(4)
	v_cvt_pk_bf16_f32 v27, v48, v50
	s_waitcnt lgkmcnt(2)
	v_cvt_pk_bf16_f32 v28, v52, v54
	s_waitcnt lgkmcnt(0)
	v_cvt_pk_bf16_f32 v29, v56, v58
	v_mad_i64_i32 v[62:63], s[28:29], v30, s34, v[60:61]
	global_store_dwordx4 v[62:63], v[26:29], off sc1
	v_add_u32_e32 v30, s26, v36
	s_nop 0
	v_cvt_pk_bf16_f32 v26, v33, v31
	v_cvt_pk_bf16_f32 v27, v49, v51
	v_cvt_pk_bf16_f32 v28, v53, v55
	v_cvt_pk_bf16_f32 v29, v57, v59
	ds_read2_b32 v[32:33], v47 offset0:49 offset1:57
	ds_read2_b32 v[48:49], v47 offset0:16 offset1:24
	ds_read2_b32 v[50:51], v47 offset0:82 offset1:90
	ds_read2_b32 v[52:53], v47 offset0:115 offset1:123
	ds_read2_b32 v[54:55], v47 offset0:148 offset1:156
	ds_read2_b32 v[56:57], v47 offset0:181 offset1:189
	ds_read2_b32 v[58:59], v47 offset0:214 offset1:222
	ds_read2_b32 v[62:63], v47 offset0:247 offset1:255
	v_mad_i64_i32 v[30:31], s[28:29], v30, s34, v[60:61]
	global_store_dwordx4 v[30:31], v[26:29], off sc1
	v_add_u32_e32 v30, s26, v37
	v_mad_i64_i32 v[30:31], s[28:29], v30, s34, v[60:61]
	s_waitcnt lgkmcnt(6)
	v_cvt_pk_bf16_f32 v26, v48, v32
	s_waitcnt lgkmcnt(4)
	v_cvt_pk_bf16_f32 v27, v50, v52
	s_waitcnt lgkmcnt(2)
	v_cvt_pk_bf16_f32 v28, v54, v56
	s_waitcnt lgkmcnt(0)
	v_cvt_pk_bf16_f32 v29, v58, v62
	global_store_dwordx4 v[30:31], v[26:29], off sc1
	v_add_u32_e32 v30, s26, v38
	v_mad_i64_i32 v[30:31], s[26:27], v30, s34, v[60:61]
	v_cvt_pk_bf16_f32 v26, v49, v33
	v_cvt_pk_bf16_f32 v27, v51, v53
	v_cvt_pk_bf16_f32 v28, v55, v57
	v_cvt_pk_bf16_f32 v29, v59, v63
	global_store_dwordx4 v[30:31], v[26:29], off sc1
	s_waitcnt lgkmcnt(0)
	s_mov_b64 s[26:27], 0

; #define LAS __attribute__((address_space(3)))
; __device__ __forceinline__ unsigned pk2(float lo, float hi) { const f32x2_t v = {lo, hi}; const bf16x2_t b = __builtin_convertvector(v, bf16x2_t); return __builtin_bit_cast(unsigned, b); }
; template <bool QKPERM, bool BIAS>
; __device__ __forceinline__ void transpose_item(const float* W, int K, int N, bf16* WT, int row_off, LAS float* scr, int item, int lane, const float* sh2 = nullptr, float* bias2 = nullptr) {
;     ...
;         if (lane < 32) { float* bp = bias2 + row_off + n0 + lane; atomicAdd(bp, a0); atomicAdd(bp + 2 * FFN, a1); atomicAdd(bp + 4 * FFN, a2); atomicAdd(bp + 6 * FFN, a3); }
;     }
;     asm volatile("s_waitcnt lgkmcnt(0)" ::: "memory");
;     const int c = lane & 7;
; #pragma unroll
;     for (int j = 0; j < 4; ++j) { const int n = (lane >> 3) + 8 * j; const LAS float* s = scr + (8 * c) * 33 + n;
;         u32x4 o; o.x = pk2(s[0 * 33], s[1 * 33]); o.y = pk2(s[2 * 33], s[3 * 33]); o.z = pk2(s[4 * 33], s[5 * 33]); o.w = pk2(s[6 * 33], s[7 * 33]);
;         int cdst = n0 + n;
;         if (QKPERM && cdst >= 5 * WA && cdst < 7 * WA) cdst = (cdst & ~0x30) | ((cdst & 0x10) << 1) | ((cdst & 0x20) >> 1);
;         *(u32x4*)(WT + (size_t)(row_off + cdst) * K + k0 + 8 * c) = o; }
;     asm volatile("s_waitcnt lgkmcnt(0)" ::: "memory");
; __device__ __forceinline__ void phase_wconv_rest(const Params& p, LAS unsigned char* lds, int gw, int NGW) {
;     ...
;         if (r < I_1) { transpose_item<false, true>(p.w1, D_MODEL, FFN, (bf16*)(ws + WS_W13T), 0, scr, r, lane, sh2, b2); continue; } r -= I_1;
;         if (r < I_1) { transpose_item<false, true>(p.w3, D_MODEL, FFN, (bf16*)(ws + WS_W13T), 128, scr, r, lane, sh2, b2); continue; } r -= I_1;
.LBB0_225:
	s_or_b64 exec, exec, s[26:27]
	s_waitcnt lgkmcnt(0)
	ds_read2_b32 v[30:31], v47 offset0:33 offset1:41
	ds_read2_b32 v[32:33], v47 offset1:8
	ds_read2_b32 v[48:49], v47 offset0:66 offset1:74
	ds_read2_b32 v[50:51], v47 offset0:99 offset1:107
	ds_read2_b32 v[52:53], v47 offset0:132 offset1:140
	ds_read2_b32 v[54:55], v47 offset0:165 offset1:173
	ds_read2_b32 v[56:57], v47 offset0:198 offset1:206
	ds_read2_b32 v[58:59], v47 offset0:231 offset1:239
	s_add_i32 s36, s36, s29
	s_and_b32 s18, 0xffff, s28
	v_add_u32_e32 v62, s36, v35
	s_lshl_b32 s18, s18, 1
	v_ashrrev_i32_e32 v63, 31, v62
	v_lshl_add_u64 v[60:61], v[4:5], 0, s[18:19]
	v_lshlrev_b64 v[62:63], 12, v[62:63]
	s_waitcnt lgkmcnt(6)
	v_cvt_pk_bf16_f32 v26, v32, v30
	s_waitcnt lgkmcnt(4)
	v_cvt_pk_bf16_f32 v27, v48, v50
	s_waitcnt lgkmcnt(2)
	v_cvt_pk_bf16_f32 v28, v52, v54
	s_waitcnt lgkmcnt(0)
	v_cvt_pk_bf16_f32 v29, v56, v58
	v_lshl_add_u64 v[62:63], v[60:61], 0, v[62:63]
	v_add_u32_e32 v30, s36, v36
	global_store_dwordx4 v[62:63], v[26:29], off sc1
	s_nop 1
	v_cvt_pk_bf16_f32 v26, v33, v31
	v_ashrrev_i32_e32 v31, 31, v30
	v_cvt_pk_bf16_f32 v27, v49, v51
	v_cvt_pk_bf16_f32 v28, v53, v55
	v_cvt_pk_bf16_f32 v29, v57, v59
	v_lshlrev_b64 v[30:31], 12, v[30:31]
	ds_read2_b32 v[32:33], v47 offset0:49 offset1:57
	ds_read2_b32 v[48:49], v47 offset0:16 offset1:24
	ds_read2_b32 v[50:51], v47 offset0:82 offset1:90
	ds_read2_b32 v[52:53], v47 offset0:115 offset1:123
	ds_read2_b32 v[54:55], v47 offset0:148 offset1:156
	ds_read2_b32 v[56:57], v47 offset0:181 offset1:189
	ds_read2_b32 v[58:59], v47 offset0:214 offset1:222
	ds_read2_b32 v[62:63], v47 offset0:247 offset1:255
	v_lshl_add_u64 v[30:31], v[60:61], 0, v[30:31]
	global_store_dwordx4 v[30:31], v[26:29], off sc1
	v_add_u32_e32 v30, s36, v37
	v_ashrrev_i32_e32 v31, 31, v30
	v_lshlrev_b64 v[30:31], 12, v[30:31]
	s_waitcnt lgkmcnt(6)
	v_cvt_pk_bf16_f32 v26, v48, v32
	s_waitcnt lgkmcnt(4)
	v_cvt_pk_bf16_f32 v27, v50, v52
	s_waitcnt lgkmcnt(2)
	v_cvt_pk_bf16_f32 v28, v54, v56
	s_waitcnt lgkmcnt(0)
	v_cvt_pk_bf16_f32 v29, v58, v62
	v_lshl_add_u64 v[30:31], v[60:61], 0, v[30:31]
	global_store_dwordx4 v[30:31], v[26:29], off sc1
	v_add_u32_e32 v30, s36, v38
	v_ashrrev_i32_e32 v31, 31, v30
	v_lshlrev_b64 v[30:31], 12, v[30:31]
	v_cvt_pk_bf16_f32 v26, v49, v33
	v_cvt_pk_bf16_f32 v27, v51, v53
	v_cvt_pk_bf16_f32 v28, v55, v57
	v_cvt_pk_bf16_f32 v29, v59, v63
	v_lshl_add_u64 v[30:31], v[60:61], 0, v[30:31]
	global_store_dwordx4 v[30:31], v[26:29], off sc1
	s_waitcnt lgkmcnt(0)

; template <bool QKPERM, bool BIAS>
; __device__ __forceinline__ void transpose_item(const float* W, int K, int N, bf16* WT, int row_off, LAS float* scr, int item, int lane, const float* sh2 = nullptr, float* bias2 = nullptr) {
;     ...
;     for (int i = 0; i < 32; ++i) wv[i] = __builtin_nontemporal_load(W + (size_t)(k0 + 2 * i + (lane >> 5)) * N + n0 + (lane & 31));
; __device__ __forceinline__ void phase_wconv_rest(const Params& p, LAS unsigned char* lds, int gw, int NGW) {
;     ...
;         if (r < I_O) { transpose_item<false, false>(p.w_o, D_MODEL, D_MODEL, (bf16*)(ws + WS_WOT), 0, scr, r, lane); continue; } r -= I_O;
.LBB0_232:
	s_andn2_b64 vcc, exec, s[26:27]
	s_cbranch_vccnz .LBB0_234
	s_add_i32 s18, s20, 0xf800
	s_and_b32 s27, s18, 0xffc0
	s_and_b32 s26, s21, 0x7e0
	v_add_u32_e32 v26, s27, v34
	s_lshl_b32 s18, s26, 2
	v_ashrrev_i32_e32 v27, 31, v26
	v_lshl_add_u64 v[28:29], v[18:19], 0, s[18:19]
	v_lshlrev_b64 v[26:27], 13, v[26:27]
	v_lshl_add_u64 v[26:27], v[28:29], 0, v[26:27]
	v_add_co_u32_e32 v28, vcc, 0x4000, v26
	s_lshl_b32 s18, s27, 1
	s_nop 0
	v_addc_co_u32_e32 v29, vcc, 0, v27, vcc
	v_add_co_u32_e32 v30, vcc, 0x8000, v26
	s_nop 1
	v_addc_co_u32_e32 v31, vcc, 0, v27, vcc
	v_add_co_u32_e32 v32, vcc, 0xc000, v26
	s_nop 1
	v_addc_co_u32_e32 v33, vcc, 0, v27, vcc
	v_add_co_u32_e32 v48, vcc, 0x10000, v26
	s_nop 1
	v_addc_co_u32_e32 v49, vcc, 0, v27, vcc
	v_add_co_u32_e32 v50, vcc, 0x14000, v26
	s_nop 1
	v_addc_co_u32_e32 v51, vcc, 0, v27, vcc
	v_add_co_u32_e32 v52, vcc, 0x18000, v26
	s_nop 1
	v_addc_co_u32_e32 v53, vcc, 0, v27, vcc
	v_add_co_u32_e32 v54, vcc, 0x1c000, v26
	s_nop 1
	v_addc_co_u32_e32 v55, vcc, 0, v27, vcc
	global_load_dword v58, v[26:27], off nt
	global_load_dword v59, v[28:29], off nt
	global_load_dword v60, v[30:31], off nt
	global_load_dword v61, v[32:33], off nt
	global_load_dword v62, v[48:49], off nt
	global_load_dword v63, v[50:51], off nt
	global_load_dword v64, v[52:53], off nt
	global_load_dword v65, v[54:55], off nt
	v_add_co_u32_e32 v28, vcc, 0x20000, v26
	s_nop 1
	v_addc_co_u32_e32 v29, vcc, 0, v27, vcc
	v_add_co_u32_e32 v30, vcc, 0x24000, v26
	s_nop 1
	v_addc_co_u32_e32 v31, vcc, 0, v27, vcc
	v_add_co_u32_e32 v32, vcc, 0x28000, v26
	s_nop 1
	v_addc_co_u32_e32 v33, vcc, 0, v27, vcc
	v_add_co_u32_e32 v48, vcc, 0x2c000, v26
	s_nop 1
	v_addc_co_u32_e32 v49, vcc, 0, v27, vcc
	v_add_co_u32_e32 v50, vcc, 0x30000, v26
	s_nop 1
	v_addc_co_u32_e32 v51, vcc, 0, v27, vcc
	v_add_co_u32_e32 v52, vcc, 0x34000, v26
	s_nop 1
	v_addc_co_u32_e32 v53, vcc, 0, v27, vcc
	v_add_co_u32_e32 v54, vcc, 0x38000, v26
	s_nop 1
	v_addc_co_u32_e32 v55, vcc, 0, v27, vcc
	v_add_co_u32_e32 v56, vcc, 0x3c000, v26
	s_nop 1
	v_addc_co_u32_e32 v57, vcc, 0, v27, vcc
	global_load_dword v66, v[28:29], off nt
	global_load_dword v67, v[30:31], off nt
	global_load_dword v68, v[32:33], off nt
	global_load_dword v69, v[48:49], off nt
	global_load_dword v70, v[50:51], off nt
	global_load_dword v71, v[52:53], off nt
	global_load_dword v72, v[54:55], off nt
	global_load_dword v73, v[56:57], off nt
	v_add_co_u32_e32 v28, vcc, 0x40000, v26
	s_nop 1
	v_addc_co_u32_e32 v29, vcc, 0, v27, vcc
	v_add_co_u32_e32 v30, vcc, 0x44000, v26
	s_nop 1
	v_addc_co_u32_e32 v31, vcc, 0, v27, vcc
	v_add_co_u32_e32 v32, vcc, 0x48000, v26
	s_nop 1
	v_addc_co_u32_e32 v33, vcc, 0, v27, vcc
	v_add_co_u32_e32 v48, vcc, 0x4c000, v26
	s_nop 1
	v_addc_co_u32_e32 v49, vcc, 0, v27, vcc
	v_add_co_u32_e32 v50, vcc, 0x50000, v26
	s_nop 1
	v_addc_co_u32_e32 v51, vcc, 0, v27, vcc
	v_add_co_u32_e32 v52, vcc, 0x54000, v26
	s_nop 1
	v_addc_co_u32_e32 v53, vcc, 0, v27, vcc
	v_add_co_u32_e32 v54, vcc, 0x58000, v26
	s_nop 1
	v_addc_co_u32_e32 v55, vcc, 0, v27, vcc
	v_add_co_u32_e32 v56, vcc, 0x5c000, v26
	s_nop 1
	v_addc_co_u32_e32 v57, vcc, 0, v27, vcc
	global_load_dword v74, v[28:29], off nt
	global_load_dword v75, v[30:31], off nt
	global_load_dword v76, v[32:33], off nt
	global_load_dword v77, v[48:49], off nt
	global_load_dword v78, v[50:51], off nt
	global_load_dword v79, v[52:53], off nt
	global_load_dword v80, v[54:55], off nt
	global_load_dword v81, v[56:57], off nt
	v_add_co_u32_e32 v28, vcc, 0x60000, v26
	s_nop 1
	v_addc_co_u32_e32 v29, vcc, 0, v27, vcc
	v_add_co_u32_e32 v30, vcc, 0x64000, v26
	s_nop 1
	v_addc_co_u32_e32 v31, vcc, 0, v27, vcc
	v_add_co_u32_e32 v32, vcc, 0x68000, v26
	s_nop 1
	v_addc_co_u32_e32 v33, vcc, 0, v27, vcc
	v_add_co_u32_e32 v48, vcc, 0x6c000, v26
	s_nop 1
	v_addc_co_u32_e32 v49, vcc, 0, v27, vcc
	v_add_co_u32_e32 v50, vcc, 0x70000, v26
	s_nop 1
	v_addc_co_u32_e32 v51, vcc, 0, v27, vcc
	v_add_co_u32_e32 v52, vcc, 0x74000, v26
	s_nop 1
	v_addc_co_u32_e32 v53, vcc, 0, v27, vcc
	v_add_co_u32_e32 v54, vcc, 0x78000, v26
	s_nop 1
	v_addc_co_u32_e32 v55, vcc, 0, v27, vcc
	v_add_co_u32_e32 v26, vcc, 0x7c000, v26
	s_nop 1
	v_addc_co_u32_e32 v27, vcc, 0, v27, vcc
	global_load_dword v28, v[28:29], off nt
	s_nop 0
	global_load_dword v29, v[30:31], off nt
	global_load_dword v56, v[32:33], off nt
	global_load_dword v57, v[48:49], off nt
	global_load_dword v82, v[50:51], off nt
	global_load_dword v83, v[52:53], off nt
	global_load_dword v84, v[54:55], off nt
	global_load_dword v85, v[26:27], off nt
	s_waitcnt vmcnt(0)
; #define LAS __attribute__((address_space(3)))
; __device__ __forceinline__ unsigned pk2(float lo, float hi) { const f32x2_t v = {lo, hi}; const bf16x2_t b = __builtin_convertvector(v, bf16x2_t); return __builtin_bit_cast(unsigned, b); }
; template <bool QKPERM, bool BIAS>
; __device__ __forceinline__ void transpose_item(const float* W, int K, int N, bf16* WT, int row_off, LAS float* scr, int item, int lane, const float* sh2 = nullptr, float* bias2 = nullptr) {
;     ...
;     for (int i = 0; i < 32; ++i) scr[(2 * i + (lane >> 5)) * 33 + (lane & 31)] = wv[i];
;     if (BIAS) {
;         float a0 = 0.f, a1 = 0.f, a2 = 0.f, a3 = 0.f;
; #pragma unroll
;         for (int i = 0; i < 32; ++i) { const int k = k0 + 2 * i + (lane >> 5); const float w = wv[i];
;             a0 += w * sh2[0 * IN_COLS + k]; a1 += w * sh2[1 * IN_COLS + k]; a2 += w * sh2[2 * IN_COLS + k]; a3 += w * sh2[3 * IN_COLS + k]; }
;         a0 = half_swap_sum(a0); a1 = half_swap_sum(a1); a2 = half_swap_sum(a2); a3 = half_swap_sum(a3);
;         if (lane < 32) { float* bp = bias2 + row_off + n0 + lane; atomicAdd(bp, a0); atomicAdd(bp + 2 * FFN, a1); atomicAdd(bp + 4 * FFN, a2); atomicAdd(bp + 6 * FFN, a3); }
;     }
;     asm volatile("s_waitcnt lgkmcnt(0)" ::: "memory");
;     const int c = lane & 7;
; #pragma unroll
;     for (int j = 0; j < 4; ++j) { const int n = (lane >> 3) + 8 * j; const LAS float* s = scr + (8 * c) * 33 + n;
;         u32x4 o; o.x = pk2(s[0 * 33], s[1 * 33]); o.y = pk2(s[2 * 33], s[3 * 33]); o.z = pk2(s[4 * 33], s[5 * 33]); o.w = pk2(s[6 * 33], s[7 * 33]);
;         int cdst = n0 + n;
;         if (QKPERM && cdst >= 5 * WA && cdst < 7 * WA) cdst = (cdst & ~0x30) | ((cdst & 0x10) << 1) | ((cdst & 0x20) >> 1);
;         *(u32x4*)(WT + (size_t)(row_off + cdst) * K + k0 + 8 * c) = o; }
;     asm volatile("s_waitcnt lgkmcnt(0)" ::: "memory");
; __device__ __forceinline__ void phase_wconv_rest(const Params& p, LAS unsigned char* lds, int gw, int NGW) {
;     ...
;         if (r < I_O) { transpose_item<false, false>(p.w_o, D_MODEL, D_MODEL, (bf16*)(ws + WS_WOT), 0, scr, r, lane); continue; } r -= I_O;
	ds_write2_b32 v39, v58, v59 offset1:66
	ds_write2_b32 v39, v60, v61 offset0:132 offset1:198
	ds_write2_b32 v40, v62, v63 offset0:8 offset1:74
	ds_write2_b32 v40, v64, v65 offset0:140 offset1:206
	ds_write2_b32 v41, v66, v67 offset0:16 offset1:82
	ds_write2_b32 v41, v68, v69 offset0:148 offset1:214
	ds_write2_b32 v42, v70, v71 offset0:24 offset1:90
	ds_write2_b32 v42, v72, v73 offset0:156 offset1:222
	ds_write2_b32 v43, v74, v75 offset0:32 offset1:98
	ds_write2_b32 v43, v76, v77 offset0:164 offset1:230
	ds_write2_b32 v44, v78, v79 offset0:40 offset1:106
	ds_write2_b32 v44, v80, v81 offset0:172 offset1:238
	ds_write2_b32 v45, v28, v29 offset0:48 offset1:114
	ds_write2_b32 v45, v56, v57 offset0:180 offset1:246
	ds_write2_b32 v46, v82, v83 offset0:56 offset1:122
	ds_write2_b32 v46, v84, v85 offset0:188 offset1:254
	s_waitcnt lgkmcnt(0)
	ds_read2_b32 v[30:31], v47 offset0:33 offset1:41
	ds_read2_b32 v[32:33], v47 offset1:8
	ds_read2_b32 v[48:49], v47 offset0:66 offset1:74
	ds_read2_b32 v[50:51], v47 offset0:99 offset1:107
	ds_read2_b32 v[52:53], v47 offset0:132 offset1:140
	ds_read2_b32 v[54:55], v47 offset0:165 offset1:173
	ds_read2_b32 v[56:57], v47 offset0:198 offset1:206
	ds_read2_b32 v[58:59], v47 offset0:231 offset1:239
	v_add_u32_e32 v62, s26, v35
	v_ashrrev_i32_e32 v63, 31, v62
	v_lshl_add_u64 v[60:61], v[6:7], 0, s[18:19]
	v_lshlrev_b64 v[62:63], 12, v[62:63]
	s_waitcnt lgkmcnt(6)
	v_cvt_pk_bf16_f32 v26, v32, v30
	s_waitcnt lgkmcnt(4)
	v_cvt_pk_bf16_f32 v27, v48, v50
	s_waitcnt lgkmcnt(2)
	v_cvt_pk_bf16_f32 v28, v52, v54
	s_waitcnt lgkmcnt(0)
	v_cvt_pk_bf16_f32 v29, v56, v58
	v_lshl_add_u64 v[62:63], v[60:61], 0, v[62:63]
	v_add_u32_e32 v30, s26, v36
	global_store_dwordx4 v[62:63], v[26:29], off sc1
	s_nop 1
	v_cvt_pk_bf16_f32 v26, v33, v31
	v_ashrrev_i32_e32 v31, 31, v30
	v_cvt_pk_bf16_f32 v27, v49, v51
	v_cvt_pk_bf16_f32 v28, v53, v55
	v_cvt_pk_bf16_f32 v29, v57, v59
	v_lshlrev_b64 v[30:31], 12, v[30:31]
	ds_read2_b32 v[32:33], v47 offset0:49 offset1:57
	ds_read2_b32 v[48:49], v47 offset0:16 offset1:24
	ds_read2_b32 v[50:51], v47 offset0:82 offset1:90
	ds_read2_b32 v[52:53], v47 offset0:115 offset1:123
	ds_read2_b32 v[54:55], v47 offset0:148 offset1:156
	ds_read2_b32 v[56:57], v47 offset0:181 offset1:189
	ds_read2_b32 v[58:59], v47 offset0:214 offset1:222
	ds_read2_b32 v[62:63], v47 offset0:247 offset1:255
	v_lshl_add_u64 v[30:31], v[60:61], 0, v[30:31]
	global_store_dwordx4 v[30:31], v[26:29], off sc1
	v_add_u32_e32 v30, s26, v37
	v_ashrrev_i32_e32 v31, 31, v30
	v_lshlrev_b64 v[30:31], 12, v[30:31]
	s_waitcnt lgkmcnt(6)
	v_cvt_pk_bf16_f32 v26, v48, v32
	s_waitcnt lgkmcnt(4)
	v_cvt_pk_bf16_f32 v27, v50, v52
	s_waitcnt lgkmcnt(2)
	v_cvt_pk_bf16_f32 v28, v54, v56
	s_waitcnt lgkmcnt(0)
	v_cvt_pk_bf16_f32 v29, v58, v62
	v_lshl_add_u64 v[30:31], v[60:61], 0, v[30:31]
	global_store_dwordx4 v[30:31], v[26:29], off sc1
	v_add_u32_e32 v30, s26, v38
	v_ashrrev_i32_e32 v31, 31, v30
	v_lshlrev_b64 v[30:31], 12, v[30:31]
	v_cvt_pk_bf16_f32 v26, v49, v33
	v_cvt_pk_bf16_f32 v27, v51, v53
	v_cvt_pk_bf16_f32 v28, v55, v57
	v_cvt_pk_bf16_f32 v29, v59, v63
	v_lshl_add_u64 v[30:31], v[60:61], 0, v[30:31]
	global_store_dwordx4 v[30:31], v[26:29], off sc1
	s_waitcnt lgkmcnt(0)

; template <bool QKPERM, bool BIAS>
; __device__ __forceinline__ void transpose_item(const float* W, int K, int N, bf16* WT, int row_off, LAS float* scr, int item, int lane, const float* sh2 = nullptr, float* bias2 = nullptr) {
;     ...
;     for (int i = 0; i < 32; ++i) wv[i] = __builtin_nontemporal_load(W + (size_t)(k0 + 2 * i + (lane >> 5)) * N + n0 + (lane & 31));
; __device__ __forceinline__ void phase_wconv_rest(const Params& p, LAS unsigned char* lds, int gw, int NGW) {
;     ...
;         if (r < I_A) { transpose_item<false, false>(p.w_b, WA, D_MODEL, (bf16*)(ws + WS_WBT), 0, scr, r, lane); continue; } r -= I_A;
.LBB0_235:
	s_andn2_b64 vcc, exec, s[26:27]
	s_cbranch_vccnz .LBB0_237
	s_add_i32 s18, s20, 0xfc00
	s_and_b32 s27, s18, 0xffc0
	s_and_b32 s26, s21, 0x7e0
	v_add_u32_e32 v26, s27, v34
	s_lshl_b32 s18, s26, 2
	v_ashrrev_i32_e32 v27, 31, v26
	v_lshl_add_u64 v[28:29], v[20:21], 0, s[18:19]
	v_lshlrev_b64 v[26:27], 13, v[26:27]
	v_lshl_add_u64 v[26:27], v[28:29], 0, v[26:27]
	v_add_co_u32_e32 v28, vcc, 0x4000, v26
	s_lshl_b32 s18, s27, 1
	s_nop 0
	v_addc_co_u32_e32 v29, vcc, 0, v27, vcc
	v_add_co_u32_e32 v30, vcc, 0x8000, v26
	s_nop 1
	v_addc_co_u32_e32 v31, vcc, 0, v27, vcc
	v_add_co_u32_e32 v32, vcc, 0xc000, v26
	s_nop 1
	v_addc_co_u32_e32 v33, vcc, 0, v27, vcc
	v_add_co_u32_e32 v48, vcc, 0x10000, v26
	s_nop 1
	v_addc_co_u32_e32 v49, vcc, 0, v27, vcc
	v_add_co_u32_e32 v50, vcc, 0x14000, v26
	s_nop 1
	v_addc_co_u32_e32 v51, vcc, 0, v27, vcc
	v_add_co_u32_e32 v52, vcc, 0x18000, v26
	s_nop 1
	v_addc_co_u32_e32 v53, vcc, 0, v27, vcc
	v_add_co_u32_e32 v54, vcc, 0x1c000, v26
	s_nop 1
	v_addc_co_u32_e32 v55, vcc, 0, v27, vcc
	global_load_dword v58, v[26:27], off nt
	global_load_dword v59, v[28:29], off nt
	global_load_dword v60, v[30:31], off nt
	global_load_dword v61, v[32:33], off nt
	global_load_dword v62, v[48:49], off nt
	global_load_dword v63, v[50:51], off nt
	global_load_dword v64, v[52:53], off nt
	global_load_dword v65, v[54:55], off nt
	v_add_co_u32_e32 v28, vcc, 0x20000, v26
	s_nop 1
	v_addc_co_u32_e32 v29, vcc, 0, v27, vcc
	v_add_co_u32_e32 v30, vcc, 0x24000, v26
	s_nop 1
	v_addc_co_u32_e32 v31, vcc, 0, v27, vcc
	v_add_co_u32_e32 v32, vcc, 0x28000, v26
	s_nop 1
	v_addc_co_u32_e32 v33, vcc, 0, v27, vcc
	v_add_co_u32_e32 v48, vcc, 0x2c000, v26
	s_nop 1
	v_addc_co_u32_e32 v49, vcc, 0, v27, vcc
	v_add_co_u32_e32 v50, vcc, 0x30000, v26
	s_nop 1
	v_addc_co_u32_e32 v51, vcc, 0, v27, vcc
	v_add_co_u32_e32 v52, vcc, 0x34000, v26
	s_nop 1
	v_addc_co_u32_e32 v53, vcc, 0, v27, vcc
	v_add_co_u32_e32 v54, vcc, 0x38000, v26
	s_nop 1
	v_addc_co_u32_e32 v55, vcc, 0, v27, vcc
	v_add_co_u32_e32 v56, vcc, 0x3c000, v26
	s_nop 1
	v_addc_co_u32_e32 v57, vcc, 0, v27, vcc
	global_load_dword v66, v[28:29], off nt
	global_load_dword v67, v[30:31], off nt
	global_load_dword v68, v[32:33], off nt
	global_load_dword v69, v[48:49], off nt
	global_load_dword v70, v[50:51], off nt
	global_load_dword v71, v[52:53], off nt
	global_load_dword v72, v[54:55], off nt
	global_load_dword v73, v[56:57], off nt
	v_add_co_u32_e32 v28, vcc, 0x40000, v26
	s_nop 1
	v_addc_co_u32_e32 v29, vcc, 0, v27, vcc
	v_add_co_u32_e32 v30, vcc, 0x44000, v26
	s_nop 1
	v_addc_co_u32_e32 v31, vcc, 0, v27, vcc
	v_add_co_u32_e32 v32, vcc, 0x48000, v26
	s_nop 1
	v_addc_co_u32_e32 v33, vcc, 0, v27, vcc
	v_add_co_u32_e32 v48, vcc, 0x4c000, v26
	s_nop 1
	v_addc_co_u32_e32 v49, vcc, 0, v27, vcc
	v_add_co_u32_e32 v50, vcc, 0x50000, v26
	s_nop 1
	v_addc_co_u32_e32 v51, vcc, 0, v27, vcc
	v_add_co_u32_e32 v52, vcc, 0x54000, v26
	s_nop 1
	v_addc_co_u32_e32 v53, vcc, 0, v27, vcc
	v_add_co_u32_e32 v54, vcc, 0x58000, v26
	s_nop 1
	v_addc_co_u32_e32 v55, vcc, 0, v27, vcc
	v_add_co_u32_e32 v56, vcc, 0x5c000, v26
	s_nop 1
	v_addc_co_u32_e32 v57, vcc, 0, v27, vcc
	global_load_dword v74, v[28:29], off nt
	global_load_dword v75, v[30:31], off nt
	global_load_dword v76, v[32:33], off nt
	global_load_dword v77, v[48:49], off nt
	global_load_dword v78, v[50:51], off nt
	global_load_dword v79, v[52:53], off nt
	global_load_dword v80, v[54:55], off nt
	global_load_dword v81, v[56:57], off nt
	v_add_co_u32_e32 v28, vcc, 0x60000, v26
	s_nop 1
	v_addc_co_u32_e32 v29, vcc, 0, v27, vcc
	v_add_co_u32_e32 v30, vcc, 0x64000, v26
	s_nop 1
	v_addc_co_u32_e32 v31, vcc, 0, v27, vcc
	v_add_co_u32_e32 v32, vcc, 0x68000, v26
	s_nop 1
	v_addc_co_u32_e32 v33, vcc, 0, v27, vcc
	v_add_co_u32_e32 v48, vcc, 0x6c000, v26
	s_nop 1
	v_addc_co_u32_e32 v49, vcc, 0, v27, vcc
	v_add_co_u32_e32 v50, vcc, 0x70000, v26
	s_nop 1
	v_addc_co_u32_e32 v51, vcc, 0, v27, vcc
	v_add_co_u32_e32 v52, vcc, 0x74000, v26
	s_nop 1
	v_addc_co_u32_e32 v53, vcc, 0, v27, vcc
	v_add_co_u32_e32 v54, vcc, 0x78000, v26
	s_nop 1
	v_addc_co_u32_e32 v55, vcc, 0, v27, vcc
	v_add_co_u32_e32 v26, vcc, 0x7c000, v26
	s_nop 1
	v_addc_co_u32_e32 v27, vcc, 0, v27, vcc
	global_load_dword v28, v[28:29], off nt
	s_nop 0
	global_load_dword v29, v[30:31], off nt
	global_load_dword v56, v[32:33], off nt
	global_load_dword v57, v[48:49], off nt
	global_load_dword v82, v[50:51], off nt
	global_load_dword v83, v[52:53], off nt
	global_load_dword v84, v[54:55], off nt
	global_load_dword v85, v[26:27], off nt
	s_waitcnt vmcnt(0)
; #define LAS __attribute__((address_space(3)))
; __device__ __forceinline__ unsigned pk2(float lo, float hi) { const f32x2_t v = {lo, hi}; const bf16x2_t b = __builtin_convertvector(v, bf16x2_t); return __builtin_bit_cast(unsigned, b); }
; template <bool QKPERM, bool BIAS>
; __device__ __forceinline__ void transpose_item(const float* W, int K, int N, bf16* WT, int row_off, LAS float* scr, int item, int lane, const float* sh2 = nullptr, float* bias2 = nullptr) {
;     ...
;     for (int i = 0; i < 32; ++i) scr[(2 * i + (lane >> 5)) * 33 + (lane & 31)] = wv[i];
;     if (BIAS) {
;         float a0 = 0.f, a1 = 0.f, a2 = 0.f, a3 = 0.f;
; #pragma unroll
;         for (int i = 0; i < 32; ++i) { const int k = k0 + 2 * i + (lane >> 5); const float w = wv[i];
;             a0 += w * sh2[0 * IN_COLS + k]; a1 += w * sh2[1 * IN_COLS + k]; a2 += w * sh2[2 * IN_COLS + k]; a3 += w * sh2[3 * IN_COLS + k]; }
;         a0 = half_swap_sum(a0); a1 = half_swap_sum(a1); a2 = half_swap_sum(a2); a3 = half_swap_sum(a3);
;         if (lane < 32) { float* bp = bias2 + row_off + n0 + lane; atomicAdd(bp, a0); atomicAdd(bp + 2 * FFN, a1); atomicAdd(bp + 4 * FFN, a2); atomicAdd(bp + 6 * FFN, a3); }
;     }
;     asm volatile("s_waitcnt lgkmcnt(0)" ::: "memory");
;     const int c = lane & 7;
; #pragma unroll
;     for (int j = 0; j < 4; ++j) { const int n = (lane >> 3) + 8 * j; const LAS float* s = scr + (8 * c) * 33 + n;
;         u32x4 o; o.x = pk2(s[0 * 33], s[1 * 33]); o.y = pk2(s[2 * 33], s[3 * 33]); o.z = pk2(s[4 * 33], s[5 * 33]); o.w = pk2(s[6 * 33], s[7 * 33]);
;         int cdst = n0 + n;
;         if (QKPERM && cdst >= 5 * WA && cdst < 7 * WA) cdst = (cdst & ~0x30) | ((cdst & 0x10) << 1) | ((cdst & 0x20) >> 1);
;         *(u32x4*)(WT + (size_t)(row_off + cdst) * K + k0 + 8 * c) = o; }
;     asm volatile("s_waitcnt lgkmcnt(0)" ::: "memory");
; __device__ __forceinline__ void phase_wconv_rest(const Params& p, LAS unsigned char* lds, int gw, int NGW) {
;     ...
;         if (r < I_A) { transpose_item<false, false>(p.w_b, WA, D_MODEL, (bf16*)(ws + WS_WBT), 0, scr, r, lane); continue; } r -= I_A;
	ds_write2_b32 v39, v58, v59 offset1:66
	ds_write2_b32 v39, v60, v61 offset0:132 offset1:198
	ds_write2_b32 v40, v62, v63 offset0:8 offset1:74
	ds_write2_b32 v40, v64, v65 offset0:140 offset1:206
	ds_write2_b32 v41, v66, v67 offset0:16 offset1:82
	ds_write2_b32 v41, v68, v69 offset0:148 offset1:214
	ds_write2_b32 v42, v70, v71 offset0:24 offset1:90
	ds_write2_b32 v42, v72, v73 offset0:156 offset1:222
	ds_write2_b32 v43, v74, v75 offset0:32 offset1:98
	ds_write2_b32 v43, v76, v77 offset0:164 offset1:230
	ds_write2_b32 v44, v78, v79 offset0:40 offset1:106
	ds_write2_b32 v44, v80, v81 offset0:172 offset1:238
	ds_write2_b32 v45, v28, v29 offset0:48 offset1:114
	ds_write2_b32 v45, v56, v57 offset0:180 offset1:246
	ds_write2_b32 v46, v82, v83 offset0:56 offset1:122
	ds_write2_b32 v46, v84, v85 offset0:188 offset1:254
	s_waitcnt lgkmcnt(0)
	ds_read2_b32 v[30:31], v47 offset0:33 offset1:41
	ds_read2_b32 v[32:33], v47 offset1:8
	ds_read2_b32 v[48:49], v47 offset0:66 offset1:74
	ds_read2_b32 v[50:51], v47 offset0:99 offset1:107
	ds_read2_b32 v[52:53], v47 offset0:132 offset1:140
	ds_read2_b32 v[54:55], v47 offset0:165 offset1:173
	ds_read2_b32 v[56:57], v47 offset0:198 offset1:206
	ds_read2_b32 v[58:59], v47 offset0:231 offset1:239
	v_add_u32_e32 v62, s26, v35
	v_ashrrev_i32_e32 v63, 31, v62
	v_lshl_add_u64 v[60:61], v[8:9], 0, s[18:19]
	v_lshlrev_b64 v[62:63], 11, v[62:63]
	s_waitcnt lgkmcnt(6)
	v_cvt_pk_bf16_f32 v26, v32, v30
	s_waitcnt lgkmcnt(4)
	v_cvt_pk_bf16_f32 v27, v48, v50
	s_waitcnt lgkmcnt(2)
	v_cvt_pk_bf16_f32 v28, v52, v54
	s_waitcnt lgkmcnt(0)
	v_cvt_pk_bf16_f32 v29, v56, v58
	v_lshl_add_u64 v[62:63], v[60:61], 0, v[62:63]
	v_add_u32_e32 v30, s26, v36
	global_store_dwordx4 v[62:63], v[26:29], off sc1
	s_nop 1
	v_cvt_pk_bf16_f32 v26, v33, v31
	v_ashrrev_i32_e32 v31, 31, v30
	v_cvt_pk_bf16_f32 v27, v49, v51
	v_cvt_pk_bf16_f32 v28, v53, v55
	v_cvt_pk_bf16_f32 v29, v57, v59
	v_lshlrev_b64 v[30:31], 11, v[30:31]
	ds_read2_b32 v[32:33], v47 offset0:49 offset1:57
	ds_read2_b32 v[48:49], v47 offset0:16 offset1:24
	ds_read2_b32 v[50:51], v47 offset0:82 offset1:90
	ds_read2_b32 v[52:53], v47 offset0:115 offset1:123
	ds_read2_b32 v[54:55], v47 offset0:148 offset1:156
	ds_read2_b32 v[56:57], v47 offset0:181 offset1:189
	ds_read2_b32 v[58:59], v47 offset0:214 offset1:222
	ds_read2_b32 v[62:63], v47 offset0:247 offset1:255
	v_lshl_add_u64 v[30:31], v[60:61], 0, v[30:31]
	global_store_dwordx4 v[30:31], v[26:29], off sc1
	v_add_u32_e32 v30, s26, v37
	v_ashrrev_i32_e32 v31, 31, v30
	v_lshlrev_b64 v[30:31], 11, v[30:31]
	s_waitcnt lgkmcnt(6)
	v_cvt_pk_bf16_f32 v26, v48, v32
	s_waitcnt lgkmcnt(4)
	v_cvt_pk_bf16_f32 v27, v50, v52
	s_waitcnt lgkmcnt(2)
	v_cvt_pk_bf16_f32 v28, v54, v56
	s_waitcnt lgkmcnt(0)
	v_cvt_pk_bf16_f32 v29, v58, v62
	v_lshl_add_u64 v[30:31], v[60:61], 0, v[30:31]
	global_store_dwordx4 v[30:31], v[26:29], off sc1
	v_add_u32_e32 v30, s26, v38
	v_ashrrev_i32_e32 v31, 31, v30
	v_lshlrev_b64 v[30:31], 11, v[30:31]
	v_cvt_pk_bf16_f32 v26, v49, v33
	v_cvt_pk_bf16_f32 v27, v51, v53
	v_cvt_pk_bf16_f32 v28, v55, v57
	v_cvt_pk_bf16_f32 v29, v59, v63
	v_lshl_add_u64 v[30:31], v[60:61], 0, v[30:31]
	global_store_dwordx4 v[30:31], v[26:29], off sc1
	s_waitcnt lgkmcnt(0)

; template <bool QKPERM, bool BIAS>
; __device__ __forceinline__ void transpose_item(const float* W, int K, int N, bf16* WT, int row_off, LAS float* scr, int item, int lane, const float* sh2 = nullptr, float* bias2 = nullptr) {
;     ...
;     for (int i = 0; i < 32; ++i) wv[i] = __builtin_nontemporal_load(W + (size_t)(k0 + 2 * i + (lane >> 5)) * N + n0 + (lane & 31));
; __device__ __forceinline__ void phase_wconv_rest(const Params& p, LAS unsigned char* lds, int gw, int NGW) {
;     ...
;         if (r < I_A) { transpose_item<false, false>(p.w_a, WA, D_MODEL, (bf16*)(ws + WS_WAT), 0, scr, r, lane); continue; } r -= I_A;
.LBB0_238:
	s_ashr_i32 s18, s20, 31
	s_lshr_b32 s18, s18, 26
	s_add_i32 s18, s20, s18
	s_and_b32 s28, s18, 0xffffffc0
	s_lshl_b32 s18, s18, 5
	s_and_b32 s18, s18, 0xfffff800
	s_sub_i32 s26, s21, s18
	v_add_u32_e32 v28, s28, v34
	s_ashr_i32 s27, s26, 31
	v_ashrrev_i32_e32 v29, 31, v28
	v_add_u32_e32 v32, 2, v28
	v_add_u32_e32 v48, 4, v28
	v_add_u32_e32 v50, 6, v28
	v_add_u32_e32 v52, 8, v28
	v_add_u32_e32 v54, 10, v28
	v_add_u32_e32 v56, 12, v28
	v_add_u32_e32 v58, 14, v28
	v_lshl_add_u64 v[26:27], s[26:27], 2, v[22:23]
	v_lshlrev_b64 v[30:31], 13, v[28:29]
	v_ashrrev_i32_e32 v33, 31, v32
	v_ashrrev_i32_e32 v49, 31, v48
	v_ashrrev_i32_e32 v51, 31, v50
	v_ashrrev_i32_e32 v53, 31, v52
	v_ashrrev_i32_e32 v55, 31, v54
	v_ashrrev_i32_e32 v57, 31, v56
	v_ashrrev_i32_e32 v59, 31, v58
	v_lshl_add_u64 v[30:31], v[26:27], 0, v[30:31]
	v_lshlrev_b64 v[32:33], 13, v[32:33]
	v_lshlrev_b64 v[48:49], 13, v[48:49]
	v_lshlrev_b64 v[50:51], 13, v[50:51]
	v_lshlrev_b64 v[52:53], 13, v[52:53]
	v_lshlrev_b64 v[54:55], 13, v[54:55]
	v_lshlrev_b64 v[56:57], 13, v[56:57]
	v_lshlrev_b64 v[58:59], 13, v[58:59]
	v_lshl_add_u64 v[32:33], v[26:27], 0, v[32:33]
	v_lshl_add_u64 v[48:49], v[26:27], 0, v[48:49]
	v_lshl_add_u64 v[50:51], v[26:27], 0, v[50:51]
	v_lshl_add_u64 v[52:53], v[26:27], 0, v[52:53]
	v_lshl_add_u64 v[54:55], v[26:27], 0, v[54:55]
	v_lshl_add_u64 v[56:57], v[26:27], 0, v[56:57]
	v_lshl_add_u64 v[58:59], v[26:27], 0, v[58:59]
	global_load_dword v60, v[30:31], off nt
	global_load_dword v61, v[32:33], off nt
	global_load_dword v62, v[48:49], off nt
	global_load_dword v63, v[50:51], off nt
	global_load_dword v64, v[52:53], off nt
	global_load_dword v65, v[54:55], off nt
	global_load_dword v66, v[56:57], off nt
	global_load_dword v67, v[58:59], off nt
	v_add_u32_e32 v30, 16, v28
	v_ashrrev_i32_e32 v31, 31, v30
	v_add_u32_e32 v32, 18, v28
	v_add_u32_e32 v48, 20, v28
	v_add_u32_e32 v50, 22, v28
	v_add_u32_e32 v52, 24, v28
	v_add_u32_e32 v54, 26, v28
	v_add_u32_e32 v56, 28, v28
	v_add_u32_e32 v58, 30, v28
	v_lshlrev_b64 v[30:31], 13, v[30:31]
	v_ashrrev_i32_e32 v33, 31, v32
	v_ashrrev_i32_e32 v49, 31, v48
	v_ashrrev_i32_e32 v51, 31, v50
	v_ashrrev_i32_e32 v53, 31, v52
	v_ashrrev_i32_e32 v55, 31, v54
	v_ashrrev_i32_e32 v57, 31, v56
	v_ashrrev_i32_e32 v59, 31, v58
	v_lshl_add_u64 v[30:31], v[26:27], 0, v[30:31]
	v_lshlrev_b64 v[32:33], 13, v[32:33]
	v_lshlrev_b64 v[48:49], 13, v[48:49]
	v_lshlrev_b64 v[50:51], 13, v[50:51]
	v_lshlrev_b64 v[52:53], 13, v[52:53]
	v_lshlrev_b64 v[54:55], 13, v[54:55]
	v_lshlrev_b64 v[56:57], 13, v[56:57]
	v_lshlrev_b64 v[58:59], 13, v[58:59]
	v_lshl_add_u64 v[32:33], v[26:27], 0, v[32:33]
	v_lshl_add_u64 v[48:49], v[26:27], 0, v[48:49]
	v_lshl_add_u64 v[50:51], v[26:27], 0, v[50:51]
	v_lshl_add_u64 v[52:53], v[26:27], 0, v[52:53]
	v_lshl_add_u64 v[54:55], v[26:27], 0, v[54:55]
	v_lshl_add_u64 v[56:57], v[26:27], 0, v[56:57]
	v_lshl_add_u64 v[58:59], v[26:27], 0, v[58:59]
	global_load_dword v68, v[30:31], off nt
	global_load_dword v69, v[32:33], off nt
	global_load_dword v70, v[48:49], off nt
	global_load_dword v71, v[50:51], off nt
	global_load_dword v72, v[52:53], off nt
	global_load_dword v73, v[54:55], off nt
	global_load_dword v74, v[56:57], off nt
	global_load_dword v75, v[58:59], off nt
	v_add_u32_e32 v30, 32, v28
	v_ashrrev_i32_e32 v31, 31, v30
	v_add_u32_e32 v32, 34, v28
	v_add_u32_e32 v48, 36, v28
	v_add_u32_e32 v50, 38, v28
	v_add_u32_e32 v52, 40, v28
	v_add_u32_e32 v54, 42, v28
	v_add_u32_e32 v56, 44, v28
	v_add_u32_e32 v58, 46, v28
	v_lshlrev_b64 v[30:31], 13, v[30:31]
	v_ashrrev_i32_e32 v33, 31, v32
	v_ashrrev_i32_e32 v49, 31, v48
	v_ashrrev_i32_e32 v51, 31, v50
	v_ashrrev_i32_e32 v53, 31, v52
	v_ashrrev_i32_e32 v55, 31, v54
	v_ashrrev_i32_e32 v57, 31, v56
	v_ashrrev_i32_e32 v59, 31, v58
	v_lshl_add_u64 v[30:31], v[26:27], 0, v[30:31]
	v_lshlrev_b64 v[32:33], 13, v[32:33]
	v_lshlrev_b64 v[48:49], 13, v[48:49]
	v_lshlrev_b64 v[50:51], 13, v[50:51]
	v_lshlrev_b64 v[52:53], 13, v[52:53]
	v_lshlrev_b64 v[54:55], 13, v[54:55]
	v_lshlrev_b64 v[56:57], 13, v[56:57]
	v_lshlrev_b64 v[58:59], 13, v[58:59]
	v_lshl_add_u64 v[32:33], v[26:27], 0, v[32:33]
	v_lshl_add_u64 v[48:49], v[26:27], 0, v[48:49]
	v_lshl_add_u64 v[50:51], v[26:27], 0, v[50:51]
	v_lshl_add_u64 v[52:53], v[26:27], 0, v[52:53]
	v_lshl_add_u64 v[54:55], v[26:27], 0, v[54:55]
	v_lshl_add_u64 v[56:57], v[26:27], 0, v[56:57]
	v_lshl_add_u64 v[58:59], v[26:27], 0, v[58:59]
	global_load_dword v76, v[30:31], off nt
	global_load_dword v77, v[32:33], off nt
	global_load_dword v78, v[48:49], off nt
	global_load_dword v79, v[50:51], off nt
	global_load_dword v80, v[52:53], off nt
	global_load_dword v81, v[54:55], off nt
	global_load_dword v82, v[56:57], off nt
	global_load_dword v83, v[58:59], off nt
	v_add_u32_e32 v30, 48, v28
	v_ashrrev_i32_e32 v31, 31, v30
	v_add_u32_e32 v32, 50, v28
	v_add_u32_e32 v48, 52, v28
	v_add_u32_e32 v50, 54, v28
	v_add_u32_e32 v52, 56, v28
	v_add_u32_e32 v54, 58, v28
	v_add_u32_e32 v56, 60, v28
	v_add_u32_e32 v28, 62, v28
	v_lshlrev_b64 v[30:31], 13, v[30:31]
	v_ashrrev_i32_e32 v33, 31, v32
	v_ashrrev_i32_e32 v49, 31, v48
	v_ashrrev_i32_e32 v51, 31, v50
	v_ashrrev_i32_e32 v53, 31, v52
	v_ashrrev_i32_e32 v55, 31, v54
	v_ashrrev_i32_e32 v57, 31, v56
	v_ashrrev_i32_e32 v29, 31, v28
	v_lshl_add_u64 v[30:31], v[26:27], 0, v[30:31]
	v_lshlrev_b64 v[32:33], 13, v[32:33]
	v_lshlrev_b64 v[48:49], 13, v[48:49]
	v_lshlrev_b64 v[50:51], 13, v[50:51]
	v_lshlrev_b64 v[52:53], 13, v[52:53]
	v_lshlrev_b64 v[54:55], 13, v[54:55]
	v_lshlrev_b64 v[56:57], 13, v[56:57]
	v_lshlrev_b64 v[28:29], 13, v[28:29]
	v_lshl_add_u64 v[32:33], v[26:27], 0, v[32:33]
	v_lshl_add_u64 v[48:49], v[26:27], 0, v[48:49]
	v_lshl_add_u64 v[50:51], v[26:27], 0, v[50:51]
	v_lshl_add_u64 v[52:53], v[26:27], 0, v[52:53]
	v_lshl_add_u64 v[54:55], v[26:27], 0, v[54:55]
	v_lshl_add_u64 v[56:57], v[26:27], 0, v[56:57]
	v_lshl_add_u64 v[26:27], v[26:27], 0, v[28:29]
	global_load_dword v28, v[30:31], off nt
	global_load_dword v29, v[32:33], off nt
	global_load_dword v58, v[48:49], off nt
	global_load_dword v59, v[50:51], off nt
	global_load_dword v84, v[52:53], off nt
	global_load_dword v85, v[54:55], off nt
	global_load_dword v86, v[56:57], off nt
	global_load_dword v87, v[26:27], off nt
	s_waitcnt vmcnt(0)
; #define LAS __attribute__((address_space(3)))
; __device__ __forceinline__ unsigned pk2(float lo, float hi) { const f32x2_t v = {lo, hi}; const bf16x2_t b = __builtin_convertvector(v, bf16x2_t); return __builtin_bit_cast(unsigned, b); }
; template <bool QKPERM, bool BIAS>
; __device__ __forceinline__ void transpose_item(const float* W, int K, int N, bf16* WT, int row_off, LAS float* scr, int item, int lane, const float* sh2 = nullptr, float* bias2 = nullptr) {
;     ...
;     for (int i = 0; i < 32; ++i) scr[(2 * i + (lane >> 5)) * 33 + (lane & 31)] = wv[i];
;     if (BIAS) {
;         float a0 = 0.f, a1 = 0.f, a2 = 0.f, a3 = 0.f;
; #pragma unroll
;         for (int i = 0; i < 32; ++i) { const int k = k0 + 2 * i + (lane >> 5); const float w = wv[i];
;             a0 += w * sh2[0 * IN_COLS + k]; a1 += w * sh2[1 * IN_COLS + k]; a2 += w * sh2[2 * IN_COLS + k]; a3 += w * sh2[3 * IN_COLS + k]; }
;         a0 = half_swap_sum(a0); a1 = half_swap_sum(a1); a2 = half_swap_sum(a2); a3 = half_swap_sum(a3);
;         if (lane < 32) { float* bp = bias2 + row_off + n0 + lane; atomicAdd(bp, a0); atomicAdd(bp + 2 * FFN, a1); atomicAdd(bp + 4 * FFN, a2); atomicAdd(bp + 6 * FFN, a3); }
;     }
;     asm volatile("s_waitcnt lgkmcnt(0)" ::: "memory");
;     const int c = lane & 7;
; #pragma unroll
;     for (int j = 0; j < 4; ++j) { const int n = (lane >> 3) + 8 * j; const LAS float* s = scr + (8 * c) * 33 + n;
;         u32x4 o; o.x = pk2(s[0 * 33], s[1 * 33]); o.y = pk2(s[2 * 33], s[3 * 33]); o.z = pk2(s[4 * 33], s[5 * 33]); o.w = pk2(s[6 * 33], s[7 * 33]);
;         int cdst = n0 + n;
;         if (QKPERM && cdst >= 5 * WA && cdst < 7 * WA) cdst = (cdst & ~0x30) | ((cdst & 0x10) << 1) | ((cdst & 0x20) >> 1);
;         *(u32x4*)(WT + (size_t)(row_off + cdst) * K + k0 + 8 * c) = o; }
;     asm volatile("s_waitcnt lgkmcnt(0)" ::: "memory");
; __device__ __forceinline__ void phase_wconv_rest(const Params& p, LAS unsigned char* lds, int gw, int NGW) {
;     ...
;         if (r < I_A) { transpose_item<false, false>(p.w_a, WA, D_MODEL, (bf16*)(ws + WS_WAT), 0, scr, r, lane); continue; } r -= I_A;
	ds_write2_b32 v39, v60, v61 offset1:66
	ds_write2_b32 v39, v62, v63 offset0:132 offset1:198
	ds_write2_b32 v40, v64, v65 offset0:8 offset1:74
	ds_write2_b32 v40, v66, v67 offset0:140 offset1:206
	ds_write2_b32 v41, v68, v69 offset0:16 offset1:82
	ds_write2_b32 v41, v70, v71 offset0:148 offset1:214
	ds_write2_b32 v42, v72, v73 offset0:24 offset1:90
	ds_write2_b32 v42, v74, v75 offset0:156 offset1:222
	ds_write2_b32 v43, v76, v77 offset0:32 offset1:98
	ds_write2_b32 v43, v78, v79 offset0:164 offset1:230
	ds_write2_b32 v44, v80, v81 offset0:40 offset1:106
	ds_write2_b32 v44, v82, v83 offset0:172 offset1:238
	ds_write2_b32 v45, v28, v29 offset0:48 offset1:114
	ds_write2_b32 v45, v58, v59 offset0:180 offset1:246
	ds_write2_b32 v46, v84, v85 offset0:56 offset1:122
	ds_write2_b32 v46, v86, v87 offset0:188 offset1:254
	s_waitcnt lgkmcnt(0)
	ds_read2_b32 v[30:31], v47 offset0:33 offset1:41
	ds_read2_b32 v[32:33], v47 offset1:8
	ds_read2_b32 v[48:49], v47 offset0:66 offset1:74
	ds_read2_b32 v[50:51], v47 offset0:99 offset1:107
	ds_read2_b32 v[52:53], v47 offset0:132 offset1:140
	ds_read2_b32 v[54:55], v47 offset0:165 offset1:173
	ds_read2_b32 v[56:57], v47 offset0:198 offset1:206
	ds_read2_b32 v[58:59], v47 offset0:231 offset1:239
	v_add_u32_e32 v62, s26, v35
	s_ashr_i32 s29, s28, 31
	v_ashrrev_i32_e32 v63, 31, v62
	v_lshl_add_u64 v[60:61], s[28:29], 1, v[10:11]
	v_lshlrev_b64 v[64:65], 11, v[62:63]
	s_waitcnt lgkmcnt(6)
	v_cvt_pk_bf16_f32 v26, v32, v30
	s_waitcnt lgkmcnt(4)
	v_cvt_pk_bf16_f32 v27, v48, v50
	s_waitcnt lgkmcnt(2)
	v_cvt_pk_bf16_f32 v28, v52, v54
	s_waitcnt lgkmcnt(0)
	v_cvt_pk_bf16_f32 v29, v56, v58
	v_lshl_add_u64 v[64:65], v[60:61], 0, v[64:65]
	v_add_u32_e32 v30, 8, v62
	global_store_dwordx4 v[64:65], v[26:29], off sc1
	s_nop 1
	v_cvt_pk_bf16_f32 v26, v33, v31
	v_ashrrev_i32_e32 v31, 31, v30
	v_cvt_pk_bf16_f32 v27, v49, v51
	v_cvt_pk_bf16_f32 v28, v53, v55
	v_cvt_pk_bf16_f32 v29, v57, v59
	v_lshlrev_b64 v[30:31], 11, v[30:31]
	ds_read2_b32 v[32:33], v47 offset0:49 offset1:57
	ds_read2_b32 v[48:49], v47 offset0:16 offset1:24
	ds_read2_b32 v[50:51], v47 offset0:82 offset1:90
	ds_read2_b32 v[52:53], v47 offset0:115 offset1:123
	ds_read2_b32 v[54:55], v47 offset0:148 offset1:156
	ds_read2_b32 v[56:57], v47 offset0:181 offset1:189
	ds_read2_b32 v[58:59], v47 offset0:214 offset1:222
	ds_read2_b32 v[64:65], v47 offset0:247 offset1:255
	v_lshl_add_u64 v[30:31], v[60:61], 0, v[30:31]
	global_store_dwordx4 v[30:31], v[26:29], off sc1
	v_add_u32_e32 v30, 16, v62
	v_ashrrev_i32_e32 v31, 31, v30
	v_lshlrev_b64 v[30:31], 11, v[30:31]
	s_waitcnt lgkmcnt(6)
	v_cvt_pk_bf16_f32 v26, v48, v32
	s_waitcnt lgkmcnt(4)
	v_cvt_pk_bf16_f32 v27, v50, v52
	s_waitcnt lgkmcnt(2)
	v_cvt_pk_bf16_f32 v28, v54, v56
	s_waitcnt lgkmcnt(0)
	v_cvt_pk_bf16_f32 v29, v58, v64
	v_lshl_add_u64 v[30:31], v[60:61], 0, v[30:31]
	global_store_dwordx4 v[30:31], v[26:29], off sc1
	v_add_u32_e32 v30, 24, v62
	v_ashrrev_i32_e32 v31, 31, v30
	v_lshlrev_b64 v[30:31], 11, v[30:31]
	v_cvt_pk_bf16_f32 v26, v49, v33
	v_cvt_pk_bf16_f32 v27, v51, v53
	v_cvt_pk_bf16_f32 v28, v55, v57
	v_cvt_pk_bf16_f32 v29, v59, v65
	v_lshl_add_u64 v[30:31], v[60:61], 0, v[30:31]
	global_store_dwordx4 v[30:31], v[26:29], off sc1
	s_waitcnt lgkmcnt(0)
	s_branch .LBB0_214

; __device__ __forceinline__ void phase_wconv_rest(const Params& p, LAS unsigned char* lds, int gw, int NGW) {
;     ...
;     for (int it = gw; it < NITEMS; it += NGW) {
;         int r = it;
;         if (r < I_A) { transpose_item<false, false>(p.w_a, WA, D_MODEL, (bf16*)(ws + WS_WAT), 0, scr, r, lane); continue; } r -= I_A;
;         if (r < I_A) { transpose_item<false, false>(p.w_b, WA, D_MODEL, (bf16*)(ws + WS_WBT), 0, scr, r, lane); continue; } r -= I_A;
;         if (r < I_O) { transpose_item<false, false>(p.w_o, D_MODEL, D_MODEL, (bf16*)(ws + WS_WOT), 0, scr, r, lane); continue; } r -= I_O;
;         if (r < I_1) { transpose_item<false, true>(p.w1, D_MODEL, FFN, (bf16*)(ws + WS_W13T), 0, scr, r, lane, sh2, b2); continue; } r -= I_1;
;         if (r < I_1) { transpose_item<false, true>(p.w3, D_MODEL, FFN, (bf16*)(ws + WS_W13T), 128, scr, r, lane, sh2, b2); continue; } r -= I_1;
;         transpose_item<false, false>(p.w2, FFN, D_MODEL, (bf16*)(ws + WS_W2T), 0, scr, r, lane);
; __global__ void __launch_bounds__(NTHREADS, 2) mega_fwd(Params p_in) {
;     ...
;       if (nfree >= 64) { if (bx >= CTX_UNITS) phase_wconv_rest(p, lds, (bx - CTX_UNITS) * 8 + wave_id, nfree * 8); }
;       else phase_wconv_rest(p, lds, bx * 8 + wave_id, nb * 8); }
.LBB0_246:
	s_cmpk_gt_u32 s20, 0x7ff
	s_cbranch_scc0 .LBB0_264
	s_cmpk_gt_u32 s20, 0xfff
	s_cbranch_scc0 .LBB0_261
	s_cmpk_gt_u32 s20, 0x25ff
	s_cbranch_scc0 .LBB0_256
	s_cmpk_gt_u32 s20, 0x3bff
	s_cbranch_scc0 .LBB0_251
	s_add_i32 s8, s20, 0xc400
	s_and_b32 s9, s8, 0xffc0
	s_and_b32 s8, s3, 0x7e0
	v_add_u32_e32 v26, s9, v34
	s_lshl_b32 s18, s8, 2
	v_ashrrev_i32_e32 v27, 31, v26
	v_lshl_add_u64 v[28:29], v[12:13], 0, s[18:19]
	v_lshlrev_b64 v[26:27], 13, v[26:27]
	v_lshl_add_u64 v[26:27], v[28:29], 0, v[26:27]
	v_add_co_u32_e32 v28, vcc, 0x4000, v26
	s_lshl_b32 s18, s9, 1
	s_nop 0
	v_addc_co_u32_e32 v29, vcc, 0, v27, vcc
	v_add_co_u32_e32 v30, vcc, 0x8000, v26
	s_nop 1
	v_addc_co_u32_e32 v31, vcc, 0, v27, vcc
	v_add_co_u32_e32 v32, vcc, 0xc000, v26
	s_nop 1
	v_addc_co_u32_e32 v33, vcc, 0, v27, vcc
	v_add_co_u32_e32 v48, vcc, 0x10000, v26
	s_nop 1
	v_addc_co_u32_e32 v49, vcc, 0, v27, vcc
	v_add_co_u32_e32 v50, vcc, 0x14000, v26
	s_nop 1
	v_addc_co_u32_e32 v51, vcc, 0, v27, vcc
	v_add_co_u32_e32 v52, vcc, 0x18000, v26
	s_nop 1
	v_addc_co_u32_e32 v53, vcc, 0, v27, vcc
	v_add_co_u32_e32 v54, vcc, 0x1c000, v26
	s_nop 1
	v_addc_co_u32_e32 v55, vcc, 0, v27, vcc
	global_load_dword v58, v[26:27], off nt
	global_load_dword v59, v[28:29], off nt
	global_load_dword v60, v[30:31], off nt
	global_load_dword v61, v[32:33], off nt
	global_load_dword v62, v[48:49], off nt
	global_load_dword v63, v[50:51], off nt
	global_load_dword v64, v[52:53], off nt
	global_load_dword v65, v[54:55], off nt
	v_add_co_u32_e32 v28, vcc, 0x20000, v26
	s_nop 1
	v_addc_co_u32_e32 v29, vcc, 0, v27, vcc
	v_add_co_u32_e32 v30, vcc, 0x24000, v26
	s_nop 1
	v_addc_co_u32_e32 v31, vcc, 0, v27, vcc
	v_add_co_u32_e32 v32, vcc, 0x28000, v26
	s_nop 1
	v_addc_co_u32_e32 v33, vcc, 0, v27, vcc
	v_add_co_u32_e32 v48, vcc, 0x2c000, v26
	s_nop 1
	v_addc_co_u32_e32 v49, vcc, 0, v27, vcc
	v_add_co_u32_e32 v50, vcc, 0x30000, v26
	s_nop 1
	v_addc_co_u32_e32 v51, vcc, 0, v27, vcc
	v_add_co_u32_e32 v52, vcc, 0x34000, v26
	s_nop 1
	v_addc_co_u32_e32 v53, vcc, 0, v27, vcc
	v_add_co_u32_e32 v54, vcc, 0x38000, v26
	s_nop 1
	v_addc_co_u32_e32 v55, vcc, 0, v27, vcc
	v_add_co_u32_e32 v56, vcc, 0x3c000, v26
	s_nop 1
	v_addc_co_u32_e32 v57, vcc, 0, v27, vcc
	global_load_dword v66, v[28:29], off nt
	global_load_dword v67, v[30:31], off nt
	global_load_dword v68, v[32:33], off nt
	global_load_dword v69, v[48:49], off nt
	global_load_dword v70, v[50:51], off nt
	global_load_dword v71, v[52:53], off nt
	global_load_dword v72, v[54:55], off nt
	global_load_dword v73, v[56:57], off nt
	v_add_co_u32_e32 v28, vcc, 0x40000, v26
	s_nop 1
	v_addc_co_u32_e32 v29, vcc, 0, v27, vcc
	v_add_co_u32_e32 v30, vcc, 0x44000, v26
	s_nop 1
	v_addc_co_u32_e32 v31, vcc, 0, v27, vcc
	v_add_co_u32_e32 v32, vcc, 0x48000, v26
	s_nop 1
	v_addc_co_u32_e32 v33, vcc, 0, v27, vcc
	v_add_co_u32_e32 v48, vcc, 0x4c000, v26
	s_nop 1
	v_addc_co_u32_e32 v49, vcc, 0, v27, vcc
	v_add_co_u32_e32 v50, vcc, 0x50000, v26
	s_nop 1
	v_addc_co_u32_e32 v51, vcc, 0, v27, vcc
	v_add_co_u32_e32 v52, vcc, 0x54000, v26
	s_nop 1
	v_addc_co_u32_e32 v53, vcc, 0, v27, vcc
	v_add_co_u32_e32 v54, vcc, 0x58000, v26
	s_nop 1
	v_addc_co_u32_e32 v55, vcc, 0, v27, vcc
	v_add_co_u32_e32 v56, vcc, 0x5c000, v26
	s_nop 1
	v_addc_co_u32_e32 v57, vcc, 0, v27, vcc
	global_load_dword v74, v[28:29], off nt
	global_load_dword v75, v[30:31], off nt
	global_load_dword v76, v[32:33], off nt
	global_load_dword v77, v[48:49], off nt
	global_load_dword v78, v[50:51], off nt
	global_load_dword v79, v[52:53], off nt
	global_load_dword v80, v[54:55], off nt
	global_load_dword v81, v[56:57], off nt
	v_add_co_u32_e32 v28, vcc, 0x60000, v26
	s_nop 1
	v_addc_co_u32_e32 v29, vcc, 0, v27, vcc
	v_add_co_u32_e32 v30, vcc, 0x64000, v26
	s_nop 1
	v_addc_co_u32_e32 v31, vcc, 0, v27, vcc
	v_add_co_u32_e32 v32, vcc, 0x68000, v26
	s_nop 1
	v_addc_co_u32_e32 v33, vcc, 0, v27, vcc
	v_add_co_u32_e32 v48, vcc, 0x6c000, v26
	s_nop 1
	v_addc_co_u32_e32 v49, vcc, 0, v27, vcc
	v_add_co_u32_e32 v50, vcc, 0x70000, v26
	s_nop 1
	v_addc_co_u32_e32 v51, vcc, 0, v27, vcc
	v_add_co_u32_e32 v52, vcc, 0x74000, v26
	s_nop 1
	v_addc_co_u32_e32 v53, vcc, 0, v27, vcc
	v_add_co_u32_e32 v54, vcc, 0x78000, v26
	s_nop 1
	v_addc_co_u32_e32 v55, vcc, 0, v27, vcc
	v_add_co_u32_e32 v26, vcc, 0x7c000, v26
	s_nop 1
	v_addc_co_u32_e32 v27, vcc, 0, v27, vcc
	global_load_dword v56, v[28:29], off nt
	global_load_dword v57, v[30:31], off nt
	global_load_dword v82, v[32:33], off nt
	global_load_dword v83, v[48:49], off nt
	global_load_dword v84, v[50:51], off nt
	global_load_dword v85, v[52:53], off nt
	global_load_dword v86, v[54:55], off nt
	global_load_dword v87, v[26:27], off nt
	s_waitcnt vmcnt(0)
; #define LAS __attribute__((address_space(3)))
; __device__ __forceinline__ unsigned pk2(float lo, float hi) { const f32x2_t v = {lo, hi}; const bf16x2_t b = __builtin_convertvector(v, bf16x2_t); return __builtin_bit_cast(unsigned, b); }
; template <bool QKPERM, bool BIAS>
; __device__ __forceinline__ void transpose_item(const float* W, int K, int N, bf16* WT, int row_off, LAS float* scr, int item, int lane, const float* sh2 = nullptr, float* bias2 = nullptr) {
;     ...
;     for (int i = 0; i < 32; ++i) scr[(2 * i + (lane >> 5)) * 33 + (lane & 31)] = wv[i];
;     if (BIAS) {
;         float a0 = 0.f, a1 = 0.f, a2 = 0.f, a3 = 0.f;
; #pragma unroll
;         for (int i = 0; i < 32; ++i) { const int k = k0 + 2 * i + (lane >> 5); const float w = wv[i];
;             a0 += w * sh2[0 * IN_COLS + k]; a1 += w * sh2[1 * IN_COLS + k]; a2 += w * sh2[2 * IN_COLS + k]; a3 += w * sh2[3 * IN_COLS + k]; }
;         a0 = half_swap_sum(a0); a1 = half_swap_sum(a1); a2 = half_swap_sum(a2); a3 = half_swap_sum(a3);
;         if (lane < 32) { float* bp = bias2 + row_off + n0 + lane; atomicAdd(bp, a0); atomicAdd(bp + 2 * FFN, a1); atomicAdd(bp + 4 * FFN, a2); atomicAdd(bp + 6 * FFN, a3); }
;     }
;     asm volatile("s_waitcnt lgkmcnt(0)" ::: "memory");
;     const int c = lane & 7;
; #pragma unroll
;     for (int j = 0; j < 4; ++j) { const int n = (lane >> 3) + 8 * j; const LAS float* s = scr + (8 * c) * 33 + n;
;         u32x4 o; o.x = pk2(s[0 * 33], s[1 * 33]); o.y = pk2(s[2 * 33], s[3 * 33]); o.z = pk2(s[4 * 33], s[5 * 33]); o.w = pk2(s[6 * 33], s[7 * 33]);
;         int cdst = n0 + n;
;         if (QKPERM && cdst >= 5 * WA && cdst < 7 * WA) cdst = (cdst & ~0x30) | ((cdst & 0x10) << 1) | ((cdst & 0x20) >> 1);
;         *(u32x4*)(WT + (size_t)(row_off + cdst) * K + k0 + 8 * c) = o; }
	ds_write2_b32 v39, v58, v59 offset1:66
	ds_write2_b32 v39, v60, v61 offset0:132 offset1:198
	ds_write2_b32 v40, v62, v63 offset0:8 offset1:74
	ds_write2_b32 v40, v64, v65 offset0:140 offset1:206
	ds_write2_b32 v41, v66, v67 offset0:16 offset1:82
	ds_write2_b32 v41, v68, v69 offset0:148 offset1:214
	ds_write2_b32 v42, v70, v71 offset0:24 offset1:90
	ds_write2_b32 v42, v72, v73 offset0:156 offset1:222
	ds_write2_b32 v43, v74, v75 offset0:32 offset1:98
	ds_write2_b32 v43, v76, v77 offset0:164 offset1:230
	ds_write2_b32 v44, v78, v79 offset0:40 offset1:106
	ds_write2_b32 v44, v80, v81 offset0:172 offset1:238
	ds_write2_b32 v45, v56, v57 offset0:48 offset1:114
	ds_write2_b32 v45, v82, v83 offset0:180 offset1:246
	ds_write2_b32 v46, v84, v85 offset0:56 offset1:122
	ds_write2_b32 v46, v86, v87 offset0:188 offset1:254
	s_waitcnt lgkmcnt(0)
	ds_read2_b32 v[30:31], v47 offset0:33 offset1:41
	ds_read2_b32 v[32:33], v47 offset1:8
	ds_read2_b32 v[48:49], v47 offset0:66 offset1:74
	ds_read2_b32 v[50:51], v47 offset0:99 offset1:107
	ds_read2_b32 v[52:53], v47 offset0:132 offset1:140
	ds_read2_b32 v[54:55], v47 offset0:165 offset1:173
	ds_read2_b32 v[56:57], v47 offset0:198 offset1:206
	ds_read2_b32 v[58:59], v47 offset0:231 offset1:239
	v_lshl_add_u64 v[60:61], v[2:3], 0, s[18:19]
	s_waitcnt lgkmcnt(6)
	v_cvt_pk_bf16_f32 v26, v32, v30
	v_add_u32_e32 v30, s8, v35
	s_waitcnt lgkmcnt(4)
	v_cvt_pk_bf16_f32 v27, v48, v50
	s_waitcnt lgkmcnt(2)
	v_cvt_pk_bf16_f32 v28, v52, v54
	s_waitcnt lgkmcnt(0)
	v_cvt_pk_bf16_f32 v29, v56, v58
	v_mad_i64_i32 v[62:63], s[10:11], v30, s22, v[60:61]
	global_store_dwordx4 v[62:63], v[26:29], off sc1
	v_add_u32_e32 v30, s8, v36
	s_nop 0
	v_cvt_pk_bf16_f32 v26, v33, v31
	v_cvt_pk_bf16_f32 v27, v49, v51
	v_cvt_pk_bf16_f32 v28, v53, v55
	v_cvt_pk_bf16_f32 v29, v57, v59
	ds_read2_b32 v[32:33], v47 offset0:49 offset1:57
	ds_read2_b32 v[48:49], v47 offset0:16 offset1:24
	ds_read2_b32 v[50:51], v47 offset0:82 offset1:90
	ds_read2_b32 v[52:53], v47 offset0:115 offset1:123
	ds_read2_b32 v[54:55], v47 offset0:148 offset1:156
	ds_read2_b32 v[56:57], v47 offset0:181 offset1:189
	ds_read2_b32 v[58:59], v47 offset0:214 offset1:222
	ds_read2_b32 v[62:63], v47 offset0:247 offset1:255
	v_mad_i64_i32 v[30:31], s[10:11], v30, s22, v[60:61]
	global_store_dwordx4 v[30:31], v[26:29], off sc1
	v_add_u32_e32 v30, s8, v37
	v_mad_i64_i32 v[30:31], s[10:11], v30, s22, v[60:61]
	s_waitcnt lgkmcnt(6)
	v_cvt_pk_bf16_f32 v26, v48, v32
	s_waitcnt lgkmcnt(4)
	v_cvt_pk_bf16_f32 v27, v50, v52
	s_waitcnt lgkmcnt(2)
	v_cvt_pk_bf16_f32 v28, v54, v56
	s_waitcnt lgkmcnt(0)
	v_cvt_pk_bf16_f32 v29, v58, v62
	global_store_dwordx4 v[30:31], v[26:29], off sc1
	v_add_u32_e32 v30, s8, v38
	v_mad_i64_i32 v[30:31], s[8:9], v30, s22, v[60:61]
	v_cvt_pk_bf16_f32 v26, v49, v33
	v_cvt_pk_bf16_f32 v27, v51, v53
	v_cvt_pk_bf16_f32 v28, v55, v57
	v_cvt_pk_bf16_f32 v29, v59, v63
	global_store_dwordx4 v[30:31], v[26:29], off sc1
	s_waitcnt lgkmcnt(0)
	s_mov_b64 s[8:9], 0

; #define LAS __attribute__((address_space(3)))
; __device__ __forceinline__ unsigned pk2(float lo, float hi) { const f32x2_t v = {lo, hi}; const bf16x2_t b = __builtin_convertvector(v, bf16x2_t); return __builtin_bit_cast(unsigned, b); }
; template <bool QKPERM, bool BIAS>
; __device__ __forceinline__ void transpose_item(const float* W, int K, int N, bf16* WT, int row_off, LAS float* scr, int item, int lane, const float* sh2 = nullptr, float* bias2 = nullptr) {
;     ...
;         if (lane < 32) { float* bp = bias2 + row_off + n0 + lane; atomicAdd(bp, a0); atomicAdd(bp + 2 * FFN, a1); atomicAdd(bp + 4 * FFN, a2); atomicAdd(bp + 6 * FFN, a3); }
;     }
;     asm volatile("s_waitcnt lgkmcnt(0)" ::: "memory");
;     const int c = lane & 7;
; #pragma unroll
;     for (int j = 0; j < 4; ++j) { const int n = (lane >> 3) + 8 * j; const LAS float* s = scr + (8 * c) * 33 + n;
;         u32x4 o; o.x = pk2(s[0 * 33], s[1 * 33]); o.y = pk2(s[2 * 33], s[3 * 33]); o.z = pk2(s[4 * 33], s[5 * 33]); o.w = pk2(s[6 * 33], s[7 * 33]);
;         int cdst = n0 + n;
;         if (QKPERM && cdst >= 5 * WA && cdst < 7 * WA) cdst = (cdst & ~0x30) | ((cdst & 0x10) << 1) | ((cdst & 0x20) >> 1);
;         *(u32x4*)(WT + (size_t)(row_off + cdst) * K + k0 + 8 * c) = o; }
.LBB0_254:
	s_or_b64 exec, exec, s[8:9]
	s_waitcnt lgkmcnt(0)
	ds_read2_b32 v[30:31], v47 offset0:33 offset1:41
	ds_read2_b32 v[32:33], v47 offset1:8
	ds_read2_b32 v[48:49], v47 offset0:66 offset1:74
	ds_read2_b32 v[50:51], v47 offset0:99 offset1:107
	ds_read2_b32 v[52:53], v47 offset0:132 offset1:140
	ds_read2_b32 v[54:55], v47 offset0:165 offset1:173
	ds_read2_b32 v[56:57], v47 offset0:198 offset1:206
	ds_read2_b32 v[58:59], v47 offset0:231 offset1:239
	s_add_i32 s24, s24, s11
	s_and_b32 s8, 0xffff, s10
	v_add_u32_e32 v62, s24, v35
	s_lshl_b32 s18, s8, 1
	v_ashrrev_i32_e32 v63, 31, v62
	v_lshl_add_u64 v[60:61], v[4:5], 0, s[18:19]
	v_lshlrev_b64 v[62:63], 12, v[62:63]
	s_waitcnt lgkmcnt(6)
	v_cvt_pk_bf16_f32 v26, v32, v30
	s_waitcnt lgkmcnt(4)
	v_cvt_pk_bf16_f32 v27, v48, v50
	s_waitcnt lgkmcnt(2)
	v_cvt_pk_bf16_f32 v28, v52, v54
	s_waitcnt lgkmcnt(0)
	v_cvt_pk_bf16_f32 v29, v56, v58
	v_lshl_add_u64 v[62:63], v[60:61], 0, v[62:63]
	v_add_u32_e32 v30, s24, v36
	global_store_dwordx4 v[62:63], v[26:29], off sc1
	s_nop 1
	v_cvt_pk_bf16_f32 v26, v33, v31
	v_ashrrev_i32_e32 v31, 31, v30
	v_cvt_pk_bf16_f32 v27, v49, v51
	v_cvt_pk_bf16_f32 v28, v53, v55
	v_cvt_pk_bf16_f32 v29, v57, v59
	v_lshlrev_b64 v[30:31], 12, v[30:31]
	ds_read2_b32 v[32:33], v47 offset0:49 offset1:57
	ds_read2_b32 v[48:49], v47 offset0:16 offset1:24
	ds_read2_b32 v[50:51], v47 offset0:82 offset1:90
	ds_read2_b32 v[52:53], v47 offset0:115 offset1:123
	ds_read2_b32 v[54:55], v47 offset0:148 offset1:156
	ds_read2_b32 v[56:57], v47 offset0:181 offset1:189
	ds_read2_b32 v[58:59], v47 offset0:214 offset1:222
	ds_read2_b32 v[62:63], v47 offset0:247 offset1:255
	v_lshl_add_u64 v[30:31], v[60:61], 0, v[30:31]
	global_store_dwordx4 v[30:31], v[26:29], off sc1
	v_add_u32_e32 v30, s24, v37
	v_ashrrev_i32_e32 v31, 31, v30
	v_lshlrev_b64 v[30:31], 12, v[30:31]
	s_waitcnt lgkmcnt(6)
	v_cvt_pk_bf16_f32 v26, v48, v32
	s_waitcnt lgkmcnt(4)
	v_cvt_pk_bf16_f32 v27, v50, v52
	s_waitcnt lgkmcnt(2)
	v_cvt_pk_bf16_f32 v28, v54, v56
	s_waitcnt lgkmcnt(0)
	v_cvt_pk_bf16_f32 v29, v58, v62
	v_lshl_add_u64 v[30:31], v[60:61], 0, v[30:31]
	global_store_dwordx4 v[30:31], v[26:29], off sc1
	v_add_u32_e32 v30, s24, v38
	v_ashrrev_i32_e32 v31, 31, v30
	v_lshlrev_b64 v[30:31], 12, v[30:31]
	v_cvt_pk_bf16_f32 v26, v49, v33
	v_cvt_pk_bf16_f32 v27, v51, v53
	v_cvt_pk_bf16_f32 v28, v55, v57
	v_cvt_pk_bf16_f32 v29, v59, v63
	v_lshl_add_u64 v[30:31], v[60:61], 0, v[30:31]
	global_store_dwordx4 v[30:31], v[26:29], off sc1
	s_waitcnt lgkmcnt(0)

; template <bool QKPERM, bool BIAS>
; __device__ __forceinline__ void transpose_item(const float* W, int K, int N, bf16* WT, int row_off, LAS float* scr, int item, int lane, const float* sh2 = nullptr, float* bias2 = nullptr) {
;     const int nblk = N / 32, kb = item / nblk, nb = item % nblk, k0 = 64 * kb, n0 = 32 * nb;
;     if (BIAS) row_off += (n0 >> 7) * 128;
;     float wv[32];
; #pragma unroll
;     for (int i = 0; i < 32; ++i) wv[i] = __builtin_nontemporal_load(W + (size_t)(k0 + 2 * i + (lane >> 5)) * N + n0 + (lane & 31));
; __device__ __forceinline__ void phase_wconv_rest(const Params& p, LAS unsigned char* lds, int gw, int NGW) {
;     ...
;         if (r < I_O) { transpose_item<false, false>(p.w_o, D_MODEL, D_MODEL, (bf16*)(ws + WS_WOT), 0, scr, r, lane); continue; } r -= I_O;
.LBB0_261:
	s_andn2_b64 vcc, exec, s[8:9]
	s_cbranch_vccnz .LBB0_263
	s_add_i32 s8, s20, 0xf800
	s_and_b32 s9, s8, 0xffc0
	s_and_b32 s8, s3, 0x7e0
	v_add_u32_e32 v26, s9, v34
	s_lshl_b32 s18, s8, 2
	v_ashrrev_i32_e32 v27, 31, v26
	v_lshl_add_u64 v[28:29], v[18:19], 0, s[18:19]
	v_lshlrev_b64 v[26:27], 13, v[26:27]
	v_lshl_add_u64 v[26:27], v[28:29], 0, v[26:27]
	v_add_co_u32_e32 v28, vcc, 0x4000, v26
	s_lshl_b32 s18, s9, 1
	s_nop 0
	v_addc_co_u32_e32 v29, vcc, 0, v27, vcc
	v_add_co_u32_e32 v30, vcc, 0x8000, v26
	s_nop 1
	v_addc_co_u32_e32 v31, vcc, 0, v27, vcc
	v_add_co_u32_e32 v32, vcc, 0xc000, v26
	s_nop 1
	v_addc_co_u32_e32 v33, vcc, 0, v27, vcc
	v_add_co_u32_e32 v48, vcc, 0x10000, v26
	s_nop 1
	v_addc_co_u32_e32 v49, vcc, 0, v27, vcc
	v_add_co_u32_e32 v50, vcc, 0x14000, v26
	s_nop 1
	v_addc_co_u32_e32 v51, vcc, 0, v27, vcc
	v_add_co_u32_e32 v52, vcc, 0x18000, v26
	s_nop 1
	v_addc_co_u32_e32 v53, vcc, 0, v27, vcc
	v_add_co_u32_e32 v54, vcc, 0x1c000, v26
	s_nop 1
	v_addc_co_u32_e32 v55, vcc, 0, v27, vcc
	global_load_dword v58, v[26:27], off nt
	global_load_dword v59, v[28:29], off nt
	global_load_dword v60, v[30:31], off nt
	global_load_dword v61, v[32:33], off nt
	global_load_dword v62, v[48:49], off nt
	global_load_dword v63, v[50:51], off nt
	global_load_dword v64, v[52:53], off nt
	global_load_dword v65, v[54:55], off nt
	v_add_co_u32_e32 v28, vcc, 0x20000, v26
	s_nop 1
	v_addc_co_u32_e32 v29, vcc, 0, v27, vcc
	v_add_co_u32_e32 v30, vcc, 0x24000, v26
	s_nop 1
	v_addc_co_u32_e32 v31, vcc, 0, v27, vcc
	v_add_co_u32_e32 v32, vcc, 0x28000, v26
	s_nop 1
	v_addc_co_u32_e32 v33, vcc, 0, v27, vcc
	v_add_co_u32_e32 v48, vcc, 0x2c000, v26
	s_nop 1
	v_addc_co_u32_e32 v49, vcc, 0, v27, vcc
	v_add_co_u32_e32 v50, vcc, 0x30000, v26
	s_nop 1
	v_addc_co_u32_e32 v51, vcc, 0, v27, vcc
	v_add_co_u32_e32 v52, vcc, 0x34000, v26
	s_nop 1
	v_addc_co_u32_e32 v53, vcc, 0, v27, vcc
	v_add_co_u32_e32 v54, vcc, 0x38000, v26
	s_nop 1
	v_addc_co_u32_e32 v55, vcc, 0, v27, vcc
	v_add_co_u32_e32 v56, vcc, 0x3c000, v26
	s_nop 1
	v_addc_co_u32_e32 v57, vcc, 0, v27, vcc
	global_load_dword v66, v[28:29], off nt
	global_load_dword v67, v[30:31], off nt
	global_load_dword v68, v[32:33], off nt
	global_load_dword v69, v[48:49], off nt
	global_load_dword v70, v[50:51], off nt
	global_load_dword v71, v[52:53], off nt
	global_load_dword v72, v[54:55], off nt
	global_load_dword v73, v[56:57], off nt
	v_add_co_u32_e32 v28, vcc, 0x40000, v26
	s_nop 1
	v_addc_co_u32_e32 v29, vcc, 0, v27, vcc
	v_add_co_u32_e32 v30, vcc, 0x44000, v26
	s_nop 1
	v_addc_co_u32_e32 v31, vcc, 0, v27, vcc
	v_add_co_u32_e32 v32, vcc, 0x48000, v26
	s_nop 1
	v_addc_co_u32_e32 v33, vcc, 0, v27, vcc
	v_add_co_u32_e32 v48, vcc, 0x4c000, v26
	s_nop 1
	v_addc_co_u32_e32 v49, vcc, 0, v27, vcc
	v_add_co_u32_e32 v50, vcc, 0x50000, v26
	s_nop 1
	v_addc_co_u32_e32 v51, vcc, 0, v27, vcc
	v_add_co_u32_e32 v52, vcc, 0x54000, v26
	s_nop 1
	v_addc_co_u32_e32 v53, vcc, 0, v27, vcc
	v_add_co_u32_e32 v54, vcc, 0x58000, v26
	s_nop 1
	v_addc_co_u32_e32 v55, vcc, 0, v27, vcc
	v_add_co_u32_e32 v56, vcc, 0x5c000, v26
	s_nop 1
	v_addc_co_u32_e32 v57, vcc, 0, v27, vcc
	global_load_dword v74, v[28:29], off nt
	global_load_dword v75, v[30:31], off nt
	global_load_dword v76, v[32:33], off nt
	global_load_dword v77, v[48:49], off nt
	global_load_dword v78, v[50:51], off nt
	global_load_dword v79, v[52:53], off nt
	global_load_dword v80, v[54:55], off nt
	global_load_dword v81, v[56:57], off nt
	v_add_co_u32_e32 v28, vcc, 0x60000, v26
	s_nop 1
	v_addc_co_u32_e32 v29, vcc, 0, v27, vcc
	v_add_co_u32_e32 v30, vcc, 0x64000, v26
	s_nop 1
	v_addc_co_u32_e32 v31, vcc, 0, v27, vcc
	v_add_co_u32_e32 v32, vcc, 0x68000, v26
	s_nop 1
	v_addc_co_u32_e32 v33, vcc, 0, v27, vcc
	v_add_co_u32_e32 v48, vcc, 0x6c000, v26
	s_nop 1
	v_addc_co_u32_e32 v49, vcc, 0, v27, vcc
	v_add_co_u32_e32 v50, vcc, 0x70000, v26
	s_nop 1
	v_addc_co_u32_e32 v51, vcc, 0, v27, vcc
	v_add_co_u32_e32 v52, vcc, 0x74000, v26
	s_nop 1
	v_addc_co_u32_e32 v53, vcc, 0, v27, vcc
	v_add_co_u32_e32 v54, vcc, 0x78000, v26
	s_nop 1
	v_addc_co_u32_e32 v55, vcc, 0, v27, vcc
	v_add_co_u32_e32 v26, vcc, 0x7c000, v26
	s_nop 1
	v_addc_co_u32_e32 v27, vcc, 0, v27, vcc
	global_load_dword v56, v[28:29], off nt
	global_load_dword v57, v[30:31], off nt
	global_load_dword v82, v[32:33], off nt
	global_load_dword v83, v[48:49], off nt
	global_load_dword v84, v[50:51], off nt
	global_load_dword v85, v[52:53], off nt
	global_load_dword v86, v[54:55], off nt
	global_load_dword v87, v[26:27], off nt
	s_waitcnt vmcnt(0)
; #define LAS __attribute__((address_space(3)))
; __device__ __forceinline__ unsigned pk2(float lo, float hi) { const f32x2_t v = {lo, hi}; const bf16x2_t b = __builtin_convertvector(v, bf16x2_t); return __builtin_bit_cast(unsigned, b); }
; template <bool QKPERM, bool BIAS>
; __device__ __forceinline__ void transpose_item(const float* W, int K, int N, bf16* WT, int row_off, LAS float* scr, int item, int lane, const float* sh2 = nullptr, float* bias2 = nullptr) {
;     ...
;     for (int i = 0; i < 32; ++i) scr[(2 * i + (lane >> 5)) * 33 + (lane & 31)] = wv[i];
;     if (BIAS) {
;         float a0 = 0.f, a1 = 0.f, a2 = 0.f, a3 = 0.f;
; #pragma unroll
;         for (int i = 0; i < 32; ++i) { const int k = k0 + 2 * i + (lane >> 5); const float w = wv[i];
;             a0 += w * sh2[0 * IN_COLS + k]; a1 += w * sh2[1 * IN_COLS + k]; a2 += w * sh2[2 * IN_COLS + k]; a3 += w * sh2[3 * IN_COLS + k]; }
;         a0 = half_swap_sum(a0); a1 = half_swap_sum(a1); a2 = half_swap_sum(a2); a3 = half_swap_sum(a3);
;         if (lane < 32) { float* bp = bias2 + row_off + n0 + lane; atomicAdd(bp, a0); atomicAdd(bp + 2 * FFN, a1); atomicAdd(bp + 4 * FFN, a2); atomicAdd(bp + 6 * FFN, a3); }
;     }
;     asm volatile("s_waitcnt lgkmcnt(0)" ::: "memory");
;     const int c = lane & 7;
; #pragma unroll
;     for (int j = 0; j < 4; ++j) { const int n = (lane >> 3) + 8 * j; const LAS float* s = scr + (8 * c) * 33 + n;
;         u32x4 o; o.x = pk2(s[0 * 33], s[1 * 33]); o.y = pk2(s[2 * 33], s[3 * 33]); o.z = pk2(s[4 * 33], s[5 * 33]); o.w = pk2(s[6 * 33], s[7 * 33]);
;         int cdst = n0 + n;
;         if (QKPERM && cdst >= 5 * WA && cdst < 7 * WA) cdst = (cdst & ~0x30) | ((cdst & 0x10) << 1) | ((cdst & 0x20) >> 1);
;         *(u32x4*)(WT + (size_t)(row_off + cdst) * K + k0 + 8 * c) = o; }
	ds_write2_b32 v39, v58, v59 offset1:66
	ds_write2_b32 v39, v60, v61 offset0:132 offset1:198
	ds_write2_b32 v40, v62, v63 offset0:8 offset1:74
	ds_write2_b32 v40, v64, v65 offset0:140 offset1:206
	ds_write2_b32 v41, v66, v67 offset0:16 offset1:82
	ds_write2_b32 v41, v68, v69 offset0:148 offset1:214
	ds_write2_b32 v42, v70, v71 offset0:24 offset1:90
	ds_write2_b32 v42, v72, v73 offset0:156 offset1:222
	ds_write2_b32 v43, v74, v75 offset0:32 offset1:98
	ds_write2_b32 v43, v76, v77 offset0:164 offset1:230
	ds_write2_b32 v44, v78, v79 offset0:40 offset1:106
	ds_write2_b32 v44, v80, v81 offset0:172 offset1:238
	ds_write2_b32 v45, v56, v57 offset0:48 offset1:114
	ds_write2_b32 v45, v82, v83 offset0:180 offset1:246
	ds_write2_b32 v46, v84, v85 offset0:56 offset1:122
	ds_write2_b32 v46, v86, v87 offset0:188 offset1:254
	s_waitcnt lgkmcnt(0)
	ds_read2_b32 v[30:31], v47 offset0:33 offset1:41
	ds_read2_b32 v[32:33], v47 offset1:8
	ds_read2_b32 v[48:49], v47 offset0:66 offset1:74
	ds_read2_b32 v[50:51], v47 offset0:99 offset1:107
	ds_read2_b32 v[52:53], v47 offset0:132 offset1:140
	ds_read2_b32 v[54:55], v47 offset0:165 offset1:173
	ds_read2_b32 v[56:57], v47 offset0:198 offset1:206
	ds_read2_b32 v[58:59], v47 offset0:231 offset1:239
	v_add_u32_e32 v62, s8, v35
	v_ashrrev_i32_e32 v63, 31, v62
	v_lshl_add_u64 v[60:61], v[6:7], 0, s[18:19]
	v_lshlrev_b64 v[62:63], 12, v[62:63]
	s_waitcnt lgkmcnt(6)
	v_cvt_pk_bf16_f32 v26, v32, v30
	s_waitcnt lgkmcnt(4)
	v_cvt_pk_bf16_f32 v27, v48, v50
	s_waitcnt lgkmcnt(2)
	v_cvt_pk_bf16_f32 v28, v52, v54
	s_waitcnt lgkmcnt(0)
	v_cvt_pk_bf16_f32 v29, v56, v58
	v_lshl_add_u64 v[62:63], v[60:61], 0, v[62:63]
	v_add_u32_e32 v30, s8, v36
	global_store_dwordx4 v[62:63], v[26:29], off sc1
	s_nop 1
	v_cvt_pk_bf16_f32 v26, v33, v31
	v_ashrrev_i32_e32 v31, 31, v30
	v_cvt_pk_bf16_f32 v27, v49, v51
	v_cvt_pk_bf16_f32 v28, v53, v55
	v_cvt_pk_bf16_f32 v29, v57, v59
	v_lshlrev_b64 v[30:31], 12, v[30:31]
	ds_read2_b32 v[32:33], v47 offset0:49 offset1:57
	ds_read2_b32 v[48:49], v47 offset0:16 offset1:24
	ds_read2_b32 v[50:51], v47 offset0:82 offset1:90
	ds_read2_b32 v[52:53], v47 offset0:115 offset1:123
	ds_read2_b32 v[54:55], v47 offset0:148 offset1:156
	ds_read2_b32 v[56:57], v47 offset0:181 offset1:189
	ds_read2_b32 v[58:59], v47 offset0:214 offset1:222
	ds_read2_b32 v[62:63], v47 offset0:247 offset1:255
	v_lshl_add_u64 v[30:31], v[60:61], 0, v[30:31]
	global_store_dwordx4 v[30:31], v[26:29], off sc1
	v_add_u32_e32 v30, s8, v37
	v_ashrrev_i32_e32 v31, 31, v30
	v_lshlrev_b64 v[30:31], 12, v[30:31]
	s_waitcnt lgkmcnt(6)
	v_cvt_pk_bf16_f32 v26, v48, v32
	s_waitcnt lgkmcnt(4)
	v_cvt_pk_bf16_f32 v27, v50, v52
	s_waitcnt lgkmcnt(2)
	v_cvt_pk_bf16_f32 v28, v54, v56
	s_waitcnt lgkmcnt(0)
	v_cvt_pk_bf16_f32 v29, v58, v62
	v_lshl_add_u64 v[30:31], v[60:61], 0, v[30:31]
	global_store_dwordx4 v[30:31], v[26:29], off sc1
	v_add_u32_e32 v30, s8, v38
	v_ashrrev_i32_e32 v31, 31, v30
	v_lshlrev_b64 v[30:31], 12, v[30:31]
	v_cvt_pk_bf16_f32 v26, v49, v33
	v_cvt_pk_bf16_f32 v27, v51, v53
	v_cvt_pk_bf16_f32 v28, v55, v57
	v_cvt_pk_bf16_f32 v29, v59, v63
	v_lshl_add_u64 v[30:31], v[60:61], 0, v[30:31]
	global_store_dwordx4 v[30:31], v[26:29], off sc1
	s_waitcnt lgkmcnt(0)

; template <bool QKPERM, bool BIAS>
; __device__ __forceinline__ void transpose_item(const float* W, int K, int N, bf16* WT, int row_off, LAS float* scr, int item, int lane, const float* sh2 = nullptr, float* bias2 = nullptr) {
;     const int nblk = N / 32, kb = item / nblk, nb = item % nblk, k0 = 64 * kb, n0 = 32 * nb;
;     if (BIAS) row_off += (n0 >> 7) * 128;
;     float wv[32];
; #pragma unroll
;     for (int i = 0; i < 32; ++i) wv[i] = __builtin_nontemporal_load(W + (size_t)(k0 + 2 * i + (lane >> 5)) * N + n0 + (lane & 31));
; __device__ __forceinline__ void phase_wconv_rest(const Params& p, LAS unsigned char* lds, int gw, int NGW) {
;     ...
;         if (r < I_A) { transpose_item<false, false>(p.w_b, WA, D_MODEL, (bf16*)(ws + WS_WBT), 0, scr, r, lane); continue; } r -= I_A;
.LBB0_264:
	s_andn2_b64 vcc, exec, s[8:9]
	s_cbranch_vccnz .LBB0_266
	s_add_i32 s8, s20, 0xfc00
	s_and_b32 s9, s8, 0xffc0
	s_and_b32 s8, s3, 0x7e0
	v_add_u32_e32 v26, s9, v34
	s_lshl_b32 s18, s8, 2
	v_ashrrev_i32_e32 v27, 31, v26
	v_lshl_add_u64 v[28:29], v[20:21], 0, s[18:19]
	v_lshlrev_b64 v[26:27], 13, v[26:27]
	v_lshl_add_u64 v[26:27], v[28:29], 0, v[26:27]
	v_add_co_u32_e32 v28, vcc, 0x4000, v26
	s_lshl_b32 s18, s9, 1
	s_nop 0
	v_addc_co_u32_e32 v29, vcc, 0, v27, vcc
	v_add_co_u32_e32 v30, vcc, 0x8000, v26
	s_nop 1
	v_addc_co_u32_e32 v31, vcc, 0, v27, vcc
	v_add_co_u32_e32 v32, vcc, 0xc000, v26
	s_nop 1
	v_addc_co_u32_e32 v33, vcc, 0, v27, vcc
	v_add_co_u32_e32 v48, vcc, 0x10000, v26
	s_nop 1
	v_addc_co_u32_e32 v49, vcc, 0, v27, vcc
	v_add_co_u32_e32 v50, vcc, 0x14000, v26
	s_nop 1
	v_addc_co_u32_e32 v51, vcc, 0, v27, vcc
	v_add_co_u32_e32 v52, vcc, 0x18000, v26
	s_nop 1
	v_addc_co_u32_e32 v53, vcc, 0, v27, vcc
	v_add_co_u32_e32 v54, vcc, 0x1c000, v26
	s_nop 1
	v_addc_co_u32_e32 v55, vcc, 0, v27, vcc
	global_load_dword v58, v[26:27], off nt
	global_load_dword v59, v[28:29], off nt
	global_load_dword v60, v[30:31], off nt
	global_load_dword v61, v[32:33], off nt
	global_load_dword v62, v[48:49], off nt
	global_load_dword v63, v[50:51], off nt
	global_load_dword v64, v[52:53], off nt
	global_load_dword v65, v[54:55], off nt
	v_add_co_u32_e32 v28, vcc, 0x20000, v26
	s_nop 1
	v_addc_co_u32_e32 v29, vcc, 0, v27, vcc
	v_add_co_u32_e32 v30, vcc, 0x24000, v26
	s_nop 1
	v_addc_co_u32_e32 v31, vcc, 0, v27, vcc
	v_add_co_u32_e32 v32, vcc, 0x28000, v26
	s_nop 1
	v_addc_co_u32_e32 v33, vcc, 0, v27, vcc
	v_add_co_u32_e32 v48, vcc, 0x2c000, v26
	s_nop 1
	v_addc_co_u32_e32 v49, vcc, 0, v27, vcc
	v_add_co_u32_e32 v50, vcc, 0x30000, v26
	s_nop 1
	v_addc_co_u32_e32 v51, vcc, 0, v27, vcc
	v_add_co_u32_e32 v52, vcc, 0x34000, v26
	s_nop 1
	v_addc_co_u32_e32 v53, vcc, 0, v27, vcc
	v_add_co_u32_e32 v54, vcc, 0x38000, v26
	s_nop 1
	v_addc_co_u32_e32 v55, vcc, 0, v27, vcc
	v_add_co_u32_e32 v56, vcc, 0x3c000, v26
	s_nop 1
	v_addc_co_u32_e32 v57, vcc, 0, v27, vcc
	global_load_dword v66, v[28:29], off nt
	global_load_dword v67, v[30:31], off nt
	global_load_dword v68, v[32:33], off nt
	global_load_dword v69, v[48:49], off nt
	global_load_dword v70, v[50:51], off nt
	global_load_dword v71, v[52:53], off nt
	global_load_dword v72, v[54:55], off nt
	global_load_dword v73, v[56:57], off nt
	v_add_co_u32_e32 v28, vcc, 0x40000, v26
	s_nop 1
	v_addc_co_u32_e32 v29, vcc, 0, v27, vcc
	v_add_co_u32_e32 v30, vcc, 0x44000, v26
	s_nop 1
	v_addc_co_u32_e32 v31, vcc, 0, v27, vcc
	v_add_co_u32_e32 v32, vcc, 0x48000, v26
	s_nop 1
	v_addc_co_u32_e32 v33, vcc, 0, v27, vcc
	v_add_co_u32_e32 v48, vcc, 0x4c000, v26
	s_nop 1
	v_addc_co_u32_e32 v49, vcc, 0, v27, vcc
	v_add_co_u32_e32 v50, vcc, 0x50000, v26
	s_nop 1
	v_addc_co_u32_e32 v51, vcc, 0, v27, vcc
	v_add_co_u32_e32 v52, vcc, 0x54000, v26
	s_nop 1
	v_addc_co_u32_e32 v53, vcc, 0, v27, vcc
	v_add_co_u32_e32 v54, vcc, 0x58000, v26
	s_nop 1
	v_addc_co_u32_e32 v55, vcc, 0, v27, vcc
	v_add_co_u32_e32 v56, vcc, 0x5c000, v26
	s_nop 1
	v_addc_co_u32_e32 v57, vcc, 0, v27, vcc
	global_load_dword v74, v[28:29], off nt
	global_load_dword v75, v[30:31], off nt
	global_load_dword v76, v[32:33], off nt
	global_load_dword v77, v[48:49], off nt
	global_load_dword v78, v[50:51], off nt
	global_load_dword v79, v[52:53], off nt
	global_load_dword v80, v[54:55], off nt
	global_load_dword v81, v[56:57], off nt
	v_add_co_u32_e32 v28, vcc, 0x60000, v26
	s_nop 1
	v_addc_co_u32_e32 v29, vcc, 0, v27, vcc
	v_add_co_u32_e32 v30, vcc, 0x64000, v26
	s_nop 1
	v_addc_co_u32_e32 v31, vcc, 0, v27, vcc
	v_add_co_u32_e32 v32, vcc, 0x68000, v26
	s_nop 1
	v_addc_co_u32_e32 v33, vcc, 0, v27, vcc
	v_add_co_u32_e32 v48, vcc, 0x6c000, v26
	s_nop 1
	v_addc_co_u32_e32 v49, vcc, 0, v27, vcc
	v_add_co_u32_e32 v50, vcc, 0x70000, v26
	s_nop 1
	v_addc_co_u32_e32 v51, vcc, 0, v27, vcc
	v_add_co_u32_e32 v52, vcc, 0x74000, v26
	s_nop 1
	v_addc_co_u32_e32 v53, vcc, 0, v27, vcc
	v_add_co_u32_e32 v54, vcc, 0x78000, v26
	s_nop 1
	v_addc_co_u32_e32 v55, vcc, 0, v27, vcc
	v_add_co_u32_e32 v26, vcc, 0x7c000, v26
	s_nop 1
	v_addc_co_u32_e32 v27, vcc, 0, v27, vcc
	global_load_dword v56, v[28:29], off nt
	global_load_dword v57, v[30:31], off nt
	global_load_dword v82, v[32:33], off nt
	global_load_dword v83, v[48:49], off nt
	global_load_dword v84, v[50:51], off nt
	global_load_dword v85, v[52:53], off nt
	global_load_dword v86, v[54:55], off nt
	global_load_dword v87, v[26:27], off nt
	s_waitcnt vmcnt(0)
; #define LAS __attribute__((address_space(3)))
; __device__ __forceinline__ unsigned pk2(float lo, float hi) { const f32x2_t v = {lo, hi}; const bf16x2_t b = __builtin_convertvector(v, bf16x2_t); return __builtin_bit_cast(unsigned, b); }
; template <bool QKPERM, bool BIAS>
; __device__ __forceinline__ void transpose_item(const float* W, int K, int N, bf16* WT, int row_off, LAS float* scr, int item, int lane, const float* sh2 = nullptr, float* bias2 = nullptr) {
;     ...
;     for (int i = 0; i < 32; ++i) scr[(2 * i + (lane >> 5)) * 33 + (lane & 31)] = wv[i];
;     if (BIAS) {
;         float a0 = 0.f, a1 = 0.f, a2 = 0.f, a3 = 0.f;
; #pragma unroll
;         for (int i = 0; i < 32; ++i) { const int k = k0 + 2 * i + (lane >> 5); const float w = wv[i];
;             a0 += w * sh2[0 * IN_COLS + k]; a1 += w * sh2[1 * IN_COLS + k]; a2 += w * sh2[2 * IN_COLS + k]; a3 += w * sh2[3 * IN_COLS + k]; }
;         a0 = half_swap_sum(a0); a1 = half_swap_sum(a1); a2 = half_swap_sum(a2); a3 = half_swap_sum(a3);
;         if (lane < 32) { float* bp = bias2 + row_off + n0 + lane; atomicAdd(bp, a0); atomicAdd(bp + 2 * FFN, a1); atomicAdd(bp + 4 * FFN, a2); atomicAdd(bp + 6 * FFN, a3); }
;     }
;     asm volatile("s_waitcnt lgkmcnt(0)" ::: "memory");
;     const int c = lane & 7;
; #pragma unroll
;     for (int j = 0; j < 4; ++j) { const int n = (lane >> 3) + 8 * j; const LAS float* s = scr + (8 * c) * 33 + n;
;         u32x4 o; o.x = pk2(s[0 * 33], s[1 * 33]); o.y = pk2(s[2 * 33], s[3 * 33]); o.z = pk2(s[4 * 33], s[5 * 33]); o.w = pk2(s[6 * 33], s[7 * 33]);
;         int cdst = n0 + n;
;         if (QKPERM && cdst >= 5 * WA && cdst < 7 * WA) cdst = (cdst & ~0x30) | ((cdst & 0x10) << 1) | ((cdst & 0x20) >> 1);
;         *(u32x4*)(WT + (size_t)(row_off + cdst) * K + k0 + 8 * c) = o; }
	ds_write2_b32 v39, v58, v59 offset1:66
	ds_write2_b32 v39, v60, v61 offset0:132 offset1:198
	ds_write2_b32 v40, v62, v63 offset0:8 offset1:74
	ds_write2_b32 v40, v64, v65 offset0:140 offset1:206
	ds_write2_b32 v41, v66, v67 offset0:16 offset1:82
	ds_write2_b32 v41, v68, v69 offset0:148 offset1:214
	ds_write2_b32 v42, v70, v71 offset0:24 offset1:90
	ds_write2_b32 v42, v72, v73 offset0:156 offset1:222
	ds_write2_b32 v43, v74, v75 offset0:32 offset1:98
	ds_write2_b32 v43, v76, v77 offset0:164 offset1:230
	ds_write2_b32 v44, v78, v79 offset0:40 offset1:106
	ds_write2_b32 v44, v80, v81 offset0:172 offset1:238
	ds_write2_b32 v45, v56, v57 offset0:48 offset1:114
	ds_write2_b32 v45, v82, v83 offset0:180 offset1:246
	ds_write2_b32 v46, v84, v85 offset0:56 offset1:122
	ds_write2_b32 v46, v86, v87 offset0:188 offset1:254
	s_waitcnt lgkmcnt(0)
	ds_read2_b32 v[30:31], v47 offset0:33 offset1:41
	ds_read2_b32 v[32:33], v47 offset1:8
	ds_read2_b32 v[48:49], v47 offset0:66 offset1:74
	ds_read2_b32 v[50:51], v47 offset0:99 offset1:107
	ds_read2_b32 v[52:53], v47 offset0:132 offset1:140
	ds_read2_b32 v[54:55], v47 offset0:165 offset1:173
	ds_read2_b32 v[56:57], v47 offset0:198 offset1:206
	ds_read2_b32 v[58:59], v47 offset0:231 offset1:239
	v_add_u32_e32 v62, s8, v35
	v_ashrrev_i32_e32 v63, 31, v62
	v_lshl_add_u64 v[60:61], v[8:9], 0, s[18:19]
	v_lshlrev_b64 v[62:63], 11, v[62:63]
	s_waitcnt lgkmcnt(6)
	v_cvt_pk_bf16_f32 v26, v32, v30
	s_waitcnt lgkmcnt(4)
	v_cvt_pk_bf16_f32 v27, v48, v50
	s_waitcnt lgkmcnt(2)
	v_cvt_pk_bf16_f32 v28, v52, v54
	s_waitcnt lgkmcnt(0)
	v_cvt_pk_bf16_f32 v29, v56, v58
	v_lshl_add_u64 v[62:63], v[60:61], 0, v[62:63]
	v_add_u32_e32 v30, s8, v36
	global_store_dwordx4 v[62:63], v[26:29], off sc1
	s_nop 1
	v_cvt_pk_bf16_f32 v26, v33, v31
	v_ashrrev_i32_e32 v31, 31, v30
	v_cvt_pk_bf16_f32 v27, v49, v51
	v_cvt_pk_bf16_f32 v28, v53, v55
	v_cvt_pk_bf16_f32 v29, v57, v59
	v_lshlrev_b64 v[30:31], 11, v[30:31]
	ds_read2_b32 v[32:33], v47 offset0:49 offset1:57
	ds_read2_b32 v[48:49], v47 offset0:16 offset1:24
	ds_read2_b32 v[50:51], v47 offset0:82 offset1:90
	ds_read2_b32 v[52:53], v47 offset0:115 offset1:123
	ds_read2_b32 v[54:55], v47 offset0:148 offset1:156
	ds_read2_b32 v[56:57], v47 offset0:181 offset1:189
	ds_read2_b32 v[58:59], v47 offset0:214 offset1:222
	ds_read2_b32 v[62:63], v47 offset0:247 offset1:255
	v_lshl_add_u64 v[30:31], v[60:61], 0, v[30:31]
	global_store_dwordx4 v[30:31], v[26:29], off sc1
	v_add_u32_e32 v30, s8, v37
	v_ashrrev_i32_e32 v31, 31, v30
	v_lshlrev_b64 v[30:31], 11, v[30:31]
	s_waitcnt lgkmcnt(6)
	v_cvt_pk_bf16_f32 v26, v48, v32
	s_waitcnt lgkmcnt(4)
	v_cvt_pk_bf16_f32 v27, v50, v52
	s_waitcnt lgkmcnt(2)
	v_cvt_pk_bf16_f32 v28, v54, v56
	s_waitcnt lgkmcnt(0)
	v_cvt_pk_bf16_f32 v29, v58, v62
	v_lshl_add_u64 v[30:31], v[60:61], 0, v[30:31]
	global_store_dwordx4 v[30:31], v[26:29], off sc1
	v_add_u32_e32 v30, s8, v38
	v_ashrrev_i32_e32 v31, 31, v30
	v_lshlrev_b64 v[30:31], 11, v[30:31]
	v_cvt_pk_bf16_f32 v26, v49, v33
	v_cvt_pk_bf16_f32 v27, v51, v53
	v_cvt_pk_bf16_f32 v28, v55, v57
	v_cvt_pk_bf16_f32 v29, v59, v63
	v_lshl_add_u64 v[30:31], v[60:61], 0, v[30:31]
	global_store_dwordx4 v[30:31], v[26:29], off sc1
	s_waitcnt lgkmcnt(0)

; template <bool QKPERM, bool BIAS>
; __device__ __forceinline__ void transpose_item(const float* W, int K, int N, bf16* WT, int row_off, LAS float* scr, int item, int lane, const float* sh2 = nullptr, float* bias2 = nullptr) {
;     const int nblk = N / 32, kb = item / nblk, nb = item % nblk, k0 = 64 * kb, n0 = 32 * nb;
;     if (BIAS) row_off += (n0 >> 7) * 128;
;     float wv[32];
; #pragma unroll
;     for (int i = 0; i < 32; ++i) wv[i] = __builtin_nontemporal_load(W + (size_t)(k0 + 2 * i + (lane >> 5)) * N + n0 + (lane & 31));
; __device__ __forceinline__ void phase_wconv_rest(const Params& p, LAS unsigned char* lds, int gw, int NGW) {
;     ...
;         if (r < I_A) { transpose_item<false, false>(p.w_a, WA, D_MODEL, (bf16*)(ws + WS_WAT), 0, scr, r, lane); continue; } r -= I_A;
.LBB0_267:
	s_ashr_i32 s8, s20, 31
	s_lshr_b32 s8, s8, 26
	s_add_i32 s8, s20, s8
	s_and_b32 s10, s8, 0xffffffc0
	s_lshl_b32 s8, s8, 5
	s_and_b32 s8, s8, 0xfffff800
	s_sub_i32 s8, s3, s8
	v_add_u32_e32 v28, s10, v34
	s_ashr_i32 s9, s8, 31
	v_ashrrev_i32_e32 v29, 31, v28
	v_add_u32_e32 v32, 2, v28
	v_add_u32_e32 v48, 4, v28
	v_add_u32_e32 v50, 6, v28
	v_add_u32_e32 v52, 8, v28
	v_add_u32_e32 v54, 10, v28
	v_add_u32_e32 v56, 12, v28
	v_add_u32_e32 v58, 14, v28
	v_lshl_add_u64 v[26:27], s[8:9], 2, v[22:23]
	v_lshlrev_b64 v[30:31], 13, v[28:29]
	v_ashrrev_i32_e32 v33, 31, v32
	v_ashrrev_i32_e32 v49, 31, v48
	v_ashrrev_i32_e32 v51, 31, v50
	v_ashrrev_i32_e32 v53, 31, v52
	v_ashrrev_i32_e32 v55, 31, v54
	v_ashrrev_i32_e32 v57, 31, v56
	v_ashrrev_i32_e32 v59, 31, v58
	v_lshl_add_u64 v[30:31], v[26:27], 0, v[30:31]
	v_lshlrev_b64 v[32:33], 13, v[32:33]
	v_lshlrev_b64 v[48:49], 13, v[48:49]
	v_lshlrev_b64 v[50:51], 13, v[50:51]
	v_lshlrev_b64 v[52:53], 13, v[52:53]
	v_lshlrev_b64 v[54:55], 13, v[54:55]
	v_lshlrev_b64 v[56:57], 13, v[56:57]
	v_lshlrev_b64 v[58:59], 13, v[58:59]
	v_lshl_add_u64 v[32:33], v[26:27], 0, v[32:33]
	v_lshl_add_u64 v[48:49], v[26:27], 0, v[48:49]
	v_lshl_add_u64 v[50:51], v[26:27], 0, v[50:51]
	v_lshl_add_u64 v[52:53], v[26:27], 0, v[52:53]
	v_lshl_add_u64 v[54:55], v[26:27], 0, v[54:55]
	v_lshl_add_u64 v[56:57], v[26:27], 0, v[56:57]
	v_lshl_add_u64 v[58:59], v[26:27], 0, v[58:59]
	global_load_dword v60, v[30:31], off nt
	global_load_dword v61, v[32:33], off nt
	global_load_dword v62, v[48:49], off nt
	global_load_dword v63, v[50:51], off nt
	global_load_dword v64, v[52:53], off nt
	global_load_dword v65, v[54:55], off nt
	global_load_dword v66, v[56:57], off nt
	global_load_dword v67, v[58:59], off nt
	v_add_u32_e32 v30, 16, v28
	v_ashrrev_i32_e32 v31, 31, v30
	v_add_u32_e32 v32, 18, v28
	v_add_u32_e32 v48, 20, v28
	v_add_u32_e32 v50, 22, v28
	v_add_u32_e32 v52, 24, v28
	v_add_u32_e32 v54, 26, v28
	v_add_u32_e32 v56, 28, v28
	v_add_u32_e32 v58, 30, v28
	v_lshlrev_b64 v[30:31], 13, v[30:31]
	v_ashrrev_i32_e32 v33, 31, v32
	v_ashrrev_i32_e32 v49, 31, v48
	v_ashrrev_i32_e32 v51, 31, v50
	v_ashrrev_i32_e32 v53, 31, v52
	v_ashrrev_i32_e32 v55, 31, v54
	v_ashrrev_i32_e32 v57, 31, v56
	v_ashrrev_i32_e32 v59, 31, v58
	v_lshl_add_u64 v[30:31], v[26:27], 0, v[30:31]
	v_lshlrev_b64 v[32:33], 13, v[32:33]
	v_lshlrev_b64 v[48:49], 13, v[48:49]
	v_lshlrev_b64 v[50:51], 13, v[50:51]
	v_lshlrev_b64 v[52:53], 13, v[52:53]
	v_lshlrev_b64 v[54:55], 13, v[54:55]
	v_lshlrev_b64 v[56:57], 13, v[56:57]
	v_lshlrev_b64 v[58:59], 13, v[58:59]
	v_lshl_add_u64 v[32:33], v[26:27], 0, v[32:33]
	v_lshl_add_u64 v[48:49], v[26:27], 0, v[48:49]
	v_lshl_add_u64 v[50:51], v[26:27], 0, v[50:51]
	v_lshl_add_u64 v[52:53], v[26:27], 0, v[52:53]
	v_lshl_add_u64 v[54:55], v[26:27], 0, v[54:55]
	v_lshl_add_u64 v[56:57], v[26:27], 0, v[56:57]
	v_lshl_add_u64 v[58:59], v[26:27], 0, v[58:59]
	global_load_dword v68, v[30:31], off nt
	global_load_dword v69, v[32:33], off nt
	global_load_dword v70, v[48:49], off nt
	global_load_dword v71, v[50:51], off nt
	global_load_dword v72, v[52:53], off nt
	global_load_dword v73, v[54:55], off nt
	global_load_dword v74, v[56:57], off nt
	global_load_dword v75, v[58:59], off nt
	v_add_u32_e32 v30, 32, v28
	v_ashrrev_i32_e32 v31, 31, v30
	v_add_u32_e32 v32, 34, v28
	v_add_u32_e32 v48, 36, v28
	v_add_u32_e32 v50, 38, v28
	v_add_u32_e32 v52, 40, v28
	v_add_u32_e32 v54, 42, v28
	v_add_u32_e32 v56, 44, v28
	v_add_u32_e32 v58, 46, v28
	v_lshlrev_b64 v[30:31], 13, v[30:31]
	v_ashrrev_i32_e32 v33, 31, v32
	v_ashrrev_i32_e32 v49, 31, v48
	v_ashrrev_i32_e32 v51, 31, v50
	v_ashrrev_i32_e32 v53, 31, v52
	v_ashrrev_i32_e32 v55, 31, v54
	v_ashrrev_i32_e32 v57, 31, v56
	v_ashrrev_i32_e32 v59, 31, v58
	v_lshl_add_u64 v[30:31], v[26:27], 0, v[30:31]
	v_lshlrev_b64 v[32:33], 13, v[32:33]
	v_lshlrev_b64 v[48:49], 13, v[48:49]
	v_lshlrev_b64 v[50:51], 13, v[50:51]
	v_lshlrev_b64 v[52:53], 13, v[52:53]
	v_lshlrev_b64 v[54:55], 13, v[54:55]
	v_lshlrev_b64 v[56:57], 13, v[56:57]
	v_lshlrev_b64 v[58:59], 13, v[58:59]
	v_lshl_add_u64 v[32:33], v[26:27], 0, v[32:33]
	v_lshl_add_u64 v[48:49], v[26:27], 0, v[48:49]
	v_lshl_add_u64 v[50:51], v[26:27], 0, v[50:51]
	v_lshl_add_u64 v[52:53], v[26:27], 0, v[52:53]
	v_lshl_add_u64 v[54:55], v[26:27], 0, v[54:55]
	v_lshl_add_u64 v[56:57], v[26:27], 0, v[56:57]
	v_lshl_add_u64 v[58:59], v[26:27], 0, v[58:59]
	global_load_dword v76, v[30:31], off nt
	global_load_dword v77, v[32:33], off nt
	global_load_dword v78, v[48:49], off nt
	global_load_dword v79, v[50:51], off nt
	global_load_dword v80, v[52:53], off nt
	global_load_dword v81, v[54:55], off nt
	global_load_dword v82, v[56:57], off nt
	global_load_dword v83, v[58:59], off nt
	v_add_u32_e32 v30, 48, v28
	v_ashrrev_i32_e32 v31, 31, v30
	v_add_u32_e32 v32, 50, v28
	v_add_u32_e32 v48, 52, v28
	v_add_u32_e32 v50, 54, v28
	v_add_u32_e32 v52, 56, v28
	v_add_u32_e32 v54, 58, v28
	v_add_u32_e32 v56, 60, v28
	v_add_u32_e32 v28, 62, v28
	v_lshlrev_b64 v[30:31], 13, v[30:31]
	v_ashrrev_i32_e32 v33, 31, v32
	v_ashrrev_i32_e32 v49, 31, v48
	v_ashrrev_i32_e32 v51, 31, v50
	v_ashrrev_i32_e32 v53, 31, v52
	v_ashrrev_i32_e32 v55, 31, v54
	v_ashrrev_i32_e32 v57, 31, v56
	v_ashrrev_i32_e32 v29, 31, v28
	v_lshl_add_u64 v[30:31], v[26:27], 0, v[30:31]
	v_lshlrev_b64 v[32:33], 13, v[32:33]
	v_lshlrev_b64 v[48:49], 13, v[48:49]
	v_lshlrev_b64 v[50:51], 13, v[50:51]
	v_lshlrev_b64 v[52:53], 13, v[52:53]
	v_lshlrev_b64 v[54:55], 13, v[54:55]
	v_lshlrev_b64 v[56:57], 13, v[56:57]
	v_lshlrev_b64 v[28:29], 13, v[28:29]
	v_lshl_add_u64 v[32:33], v[26:27], 0, v[32:33]
	v_lshl_add_u64 v[48:49], v[26:27], 0, v[48:49]
	v_lshl_add_u64 v[50:51], v[26:27], 0, v[50:51]
	v_lshl_add_u64 v[52:53], v[26:27], 0, v[52:53]
	v_lshl_add_u64 v[54:55], v[26:27], 0, v[54:55]
	v_lshl_add_u64 v[56:57], v[26:27], 0, v[56:57]
	v_lshl_add_u64 v[26:27], v[26:27], 0, v[28:29]
	global_load_dword v28, v[30:31], off nt
	global_load_dword v29, v[32:33], off nt
	global_load_dword v58, v[48:49], off nt
	global_load_dword v59, v[50:51], off nt
	global_load_dword v84, v[52:53], off nt
	global_load_dword v85, v[54:55], off nt
	global_load_dword v86, v[56:57], off nt
	global_load_dword v87, v[26:27], off nt
	s_waitcnt vmcnt(0)
; #define LAS __attribute__((address_space(3)))
; __device__ __forceinline__ unsigned pk2(float lo, float hi) { const f32x2_t v = {lo, hi}; const bf16x2_t b = __builtin_convertvector(v, bf16x2_t); return __builtin_bit_cast(unsigned, b); }
; template <bool QKPERM, bool BIAS>
; __device__ __forceinline__ void transpose_item(const float* W, int K, int N, bf16* WT, int row_off, LAS float* scr, int item, int lane, const float* sh2 = nullptr, float* bias2 = nullptr) {
;     ...
;     for (int i = 0; i < 32; ++i) scr[(2 * i + (lane >> 5)) * 33 + (lane & 31)] = wv[i];
;     if (BIAS) {
;         float a0 = 0.f, a1 = 0.f, a2 = 0.f, a3 = 0.f;
; #pragma unroll
;         for (int i = 0; i < 32; ++i) { const int k = k0 + 2 * i + (lane >> 5); const float w = wv[i];
;             a0 += w * sh2[0 * IN_COLS + k]; a1 += w * sh2[1 * IN_COLS + k]; a2 += w * sh2[2 * IN_COLS + k]; a3 += w * sh2[3 * IN_COLS + k]; }
;         a0 = half_swap_sum(a0); a1 = half_swap_sum(a1); a2 = half_swap_sum(a2); a3 = half_swap_sum(a3);
;         if (lane < 32) { float* bp = bias2 + row_off + n0 + lane; atomicAdd(bp, a0); atomicAdd(bp + 2 * FFN, a1); atomicAdd(bp + 4 * FFN, a2); atomicAdd(bp + 6 * FFN, a3); }
;     }
;     asm volatile("s_waitcnt lgkmcnt(0)" ::: "memory");
;     const int c = lane & 7;
; #pragma unroll
;     for (int j = 0; j < 4; ++j) { const int n = (lane >> 3) + 8 * j; const LAS float* s = scr + (8 * c) * 33 + n;
;         u32x4 o; o.x = pk2(s[0 * 33], s[1 * 33]); o.y = pk2(s[2 * 33], s[3 * 33]); o.z = pk2(s[4 * 33], s[5 * 33]); o.w = pk2(s[6 * 33], s[7 * 33]);
;         int cdst = n0 + n;
;         if (QKPERM && cdst >= 5 * WA && cdst < 7 * WA) cdst = (cdst & ~0x30) | ((cdst & 0x10) << 1) | ((cdst & 0x20) >> 1);
;         *(u32x4*)(WT + (size_t)(row_off + cdst) * K + k0 + 8 * c) = o; }
; __device__ __forceinline__ void phase_wconv_rest(const Params& p, LAS unsigned char* lds, int gw, int NGW) {
;     ...
;     for (int it = gw; it < NITEMS; it += NGW) {
	ds_write2_b32 v39, v60, v61 offset1:66
	ds_write2_b32 v39, v62, v63 offset0:132 offset1:198
	ds_write2_b32 v40, v64, v65 offset0:8 offset1:74
	ds_write2_b32 v40, v66, v67 offset0:140 offset1:206
	ds_write2_b32 v41, v68, v69 offset0:16 offset1:82
	ds_write2_b32 v41, v70, v71 offset0:148 offset1:214
	ds_write2_b32 v42, v72, v73 offset0:24 offset1:90
	ds_write2_b32 v42, v74, v75 offset0:156 offset1:222
	ds_write2_b32 v43, v76, v77 offset0:32 offset1:98
	ds_write2_b32 v43, v78, v79 offset0:164 offset1:230
	ds_write2_b32 v44, v80, v81 offset0:40 offset1:106
	ds_write2_b32 v44, v82, v83 offset0:172 offset1:238
	ds_write2_b32 v45, v28, v29 offset0:48 offset1:114
	ds_write2_b32 v45, v58, v59 offset0:180 offset1:246
	ds_write2_b32 v46, v84, v85 offset0:56 offset1:122
	ds_write2_b32 v46, v86, v87 offset0:188 offset1:254
	s_waitcnt lgkmcnt(0)
	ds_read2_b32 v[30:31], v47 offset0:33 offset1:41
	ds_read2_b32 v[32:33], v47 offset1:8
	ds_read2_b32 v[48:49], v47 offset0:66 offset1:74
	ds_read2_b32 v[50:51], v47 offset0:99 offset1:107
	ds_read2_b32 v[52:53], v47 offset0:132 offset1:140
	ds_read2_b32 v[54:55], v47 offset0:165 offset1:173
	ds_read2_b32 v[56:57], v47 offset0:198 offset1:206
	ds_read2_b32 v[58:59], v47 offset0:231 offset1:239
	v_add_u32_e32 v62, s8, v35
	s_ashr_i32 s11, s10, 31
	v_ashrrev_i32_e32 v63, 31, v62
	v_lshl_add_u64 v[60:61], s[10:11], 1, v[10:11]
	v_lshlrev_b64 v[64:65], 11, v[62:63]
	s_waitcnt lgkmcnt(6)
	v_cvt_pk_bf16_f32 v26, v32, v30
	s_waitcnt lgkmcnt(4)
	v_cvt_pk_bf16_f32 v27, v48, v50
	s_waitcnt lgkmcnt(2)
	v_cvt_pk_bf16_f32 v28, v52, v54
	s_waitcnt lgkmcnt(0)
	v_cvt_pk_bf16_f32 v29, v56, v58
	v_lshl_add_u64 v[64:65], v[60:61], 0, v[64:65]
	v_add_u32_e32 v30, 8, v62
	global_store_dwordx4 v[64:65], v[26:29], off sc1
	s_nop 1
	v_cvt_pk_bf16_f32 v26, v33, v31
	v_ashrrev_i32_e32 v31, 31, v30
	v_cvt_pk_bf16_f32 v27, v49, v51
	v_cvt_pk_bf16_f32 v28, v53, v55
	v_cvt_pk_bf16_f32 v29, v57, v59
	v_lshlrev_b64 v[30:31], 11, v[30:31]
	ds_read2_b32 v[32:33], v47 offset0:49 offset1:57
	ds_read2_b32 v[48:49], v47 offset0:16 offset1:24
	ds_read2_b32 v[50:51], v47 offset0:82 offset1:90
	ds_read2_b32 v[52:53], v47 offset0:115 offset1:123
	ds_read2_b32 v[54:55], v47 offset0:148 offset1:156
	ds_read2_b32 v[56:57], v47 offset0:181 offset1:189
	ds_read2_b32 v[58:59], v47 offset0:214 offset1:222
	ds_read2_b32 v[64:65], v47 offset0:247 offset1:255
	v_lshl_add_u64 v[30:31], v[60:61], 0, v[30:31]
	global_store_dwordx4 v[30:31], v[26:29], off sc1
	v_add_u32_e32 v30, 16, v62
	v_ashrrev_i32_e32 v31, 31, v30
	v_lshlrev_b64 v[30:31], 11, v[30:31]
	s_waitcnt lgkmcnt(6)
	v_cvt_pk_bf16_f32 v26, v48, v32
	s_waitcnt lgkmcnt(4)
	v_cvt_pk_bf16_f32 v27, v50, v52
	s_waitcnt lgkmcnt(2)
	v_cvt_pk_bf16_f32 v28, v54, v56
	s_waitcnt lgkmcnt(0)
	v_cvt_pk_bf16_f32 v29, v58, v64
	v_lshl_add_u64 v[30:31], v[60:61], 0, v[30:31]
	global_store_dwordx4 v[30:31], v[26:29], off sc1
	v_add_u32_e32 v30, 24, v62
	v_ashrrev_i32_e32 v31, 31, v30
	v_lshlrev_b64 v[30:31], 11, v[30:31]
	v_cvt_pk_bf16_f32 v26, v49, v33
	v_cvt_pk_bf16_f32 v27, v51, v53
	v_cvt_pk_bf16_f32 v28, v55, v57
	v_cvt_pk_bf16_f32 v29, v59, v65
	v_lshl_add_u64 v[30:31], v[60:61], 0, v[30:31]
	global_store_dwordx4 v[30:31], v[26:29], off sc1
	s_waitcnt lgkmcnt(0)
	s_branch .LBB0_243

; #define LAS __attribute__((address_space(3)))
; __device__ __forceinline__ void hgrn_prep(const Params& p, LAS unsigned char* lds, int vb, int nb) {
;     ...
;         unsigned char* img = p.ws + WS_HIMG + (size_t)idx * HIMG_BYTES;
; #pragma unroll
;         for (int e = 0; e < 2; ++e) { const int id = tid + 512 * e; const int kr = id >> 3, part = id & 7;
;             if (lat) *(u32x4*)(img + HIMG_QD + id * 16) = *(const LAS u32x4*)(lds + H_QD + kr * HP + 16 * part);
;             *(u32x4*)(img + HIMG_KD + id * 16) = *(const LAS u32x4*)(lds + H_KD + kr * HP + 16 * part); }
;         if (lat) *(u32x4*)(img + HIMG_P + tid * 16) = *(const LAS u32x4*)(lds + H_P + (tid >> 3) * PP + 16 * (tid & 7));
;         if (tid < 32) *(u32x4*)(img + HIMG_D + tid * 16) = *(const LAS u32x4*)(lds + H_D + 16 * tid);
.LBB0_374:
	s_mul_i32 s41, s74, 0xa200
	s_mul_hi_i32 s40, s74, 0xa200
	s_add_u32 s68, s43, s41
	s_addc_u32 s69, s44, s40
	s_add_u32 s66, s68, 0x4000
	s_addc_u32 s67, s69, 0
	s_mov_b64 s[70:71], -1
	s_and_b64 vcc, exec, s[64:65]
	v_add_u32_e32 v29, v79, v88
	v_lshl_add_u64 v[40:41], s[66:67], 0, v[32:33]
	s_cbranch_vccz .LBB0_376
	ds_read_b128 v[42:45], v29
	s_mov_b64 s[70:71], 0
	s_waitcnt lgkmcnt(0)
	global_store_dwordx4 v[40:41], v[42:45], off sc1
.LBB0_376:
	s_andn2_b64 vcc, exec, s[70:71]
	v_lshl_add_u64 v[38:39], s[68:69], 0, v[32:33]
	s_cbranch_vccnz .LBB0_378
	v_add_u32_e32 v30, v80, v88
	ds_read_b128 v[42:45], v29
	ds_read_b128 v[106:109], v30 offset:61440
	v_add_u32_e32 v29, v80, v89
	ds_read_b128 v[110:113], v29 offset:61440
	s_waitcnt lgkmcnt(2)
	global_store_dwordx4 v[40:41], v[42:45], off sc1
	s_waitcnt lgkmcnt(1)
	global_store_dwordx4 v[38:39], v[106:109], off sc1
	v_lshl_add_u64 v[40:41], s[68:69], 0, v[34:35]
	s_waitcnt lgkmcnt(0)
	global_store_dwordx4 v[40:41], v[110:113], off sc1
.LBB0_378:
	v_add_u32_e32 v29, v79, v89
	ds_read_b128 v[40:43], v29
	v_lshl_add_u64 v[44:45], s[66:67], 0, v[34:35]
	s_andn2_b64 vcc, exec, s[36:37]
	s_waitcnt lgkmcnt(0)
	global_store_dwordx4 v[44:45], v[40:43], off sc1
	s_cbranch_vccnz .LBB0_380
	ds_read_b128 v[40:43], v104
	v_add_co_u32_e32 v44, vcc, 0x8000, v38
	s_nop 1
	v_addc_co_u32_e32 v45, vcc, 0, v39, vcc
	s_waitcnt lgkmcnt(0)
	global_store_dwordx4 v[44:45], v[40:43], off sc1
.LBB0_380:
	s_and_saveexec_b64 s[36:37], s[22:23]
	s_cbranch_execz .LBB0_341
	v_add_u32_e32 v29, 0, v32
	v_add_u32_e32 v29, 0x1ec00, v29
	ds_read_b128 v[40:43], v29
	v_add_co_u32_e32 v38, vcc, 0xa000, v38
	s_nop 1
	v_addc_co_u32_e32 v39, vcc, 0, v39, vcc
	s_waitcnt lgkmcnt(0)
	global_store_dwordx4 v[38:39], v[40:43], off sc1
	s_branch .LBB0_341

; __device__ __forceinline__ unsigned pk2(float lo, float hi) { const f32x2_t v = {lo, hi}; const bf16x2_t b = __builtin_convertvector(v, bf16x2_t); return __builtin_bit_cast(unsigned, b); }
; __device__ __forceinline__ float siluf_(float x) { return x * __builtin_amdgcn_rcpf(1.0f + __expf(-x)); }
; __device__ __forceinline__ float oct_sum(float v) { v += dppf<0xB1>(v); v += dppf<0x4E>(v); v += dppf<0x141>(v); return v; }
; __device__ __forceinline__ void phase_readout(const Params& p, int vb, int nb) {
;     ...
;         for (int u = 0; u < 2; ++u) { const int row = row0 + u * NGW; if (row < ML) { const size_t off = (size_t)row * WA + 16 * lane;
;             float o[16]; float ss = 0.f;
; #pragma unroll
;             for (int q = 0; q < 8; ++q) { const unsigned wa = a[u][q >> 2][q & 3], wb = b[u][q >> 2][q & 3]; o[2 * q] = bflo(wa) + bflo(wb); o[2 * q + 1] = bfhi(wa) + bfhi(wb); ss += o[2 * q] * o[2 * q] + o[2 * q + 1] * o[2 * q + 1]; }
;             ss = oct_sum(ss);
;             const float rstd = __builtin_amdgcn_rsqf(ss * (1.0f / HD) + EPS);
;             u32x4 w[2];
; #pragma unroll
;             for (int q = 0; q < 8; ++q) { const unsigned wg = gg[u][q >> 2][q & 3];
;                 w[q >> 2][q & 3] = pk2(o[2 * q] * rstd * ng[q >> 1][(2 * q) & 3] * siluf_(bflo(wg)), o[2 * q + 1] * rstd * ng[q >> 1][(2 * q + 1) & 3] * siluf_(bfhi(wg))); }
.LBB0_564:
	s_waitcnt vmcnt(5)
	v_lshlrev_b32_e32 v68, 16, v59
	v_and_b32_e32 v69, 0xffff0000, v59
	s_waitcnt vmcnt(3)
	v_lshlrev_b32_e32 v70, 16, v63
	v_and_b32_e32 v71, 0xffff0000, v63
	v_pk_add_f32 v[68:69], v[68:69], v[70:71]
	v_lshlrev_b32_e32 v70, 16, v58
	v_and_b32_e32 v71, 0xffff0000, v58
	v_lshlrev_b32_e32 v58, 16, v62
	v_and_b32_e32 v59, 0xffff0000, v62
	v_pk_add_f32 v[58:59], v[70:71], v[58:59]
	s_waitcnt vmcnt(1)
	v_lshlrev_b32_e32 v70, 16, v42
	v_and_b32_e32 v71, 0xffff0000, v42
	v_mul_f32_e32 v42, 0xbfb8aa3b, v70
	v_exp_f32_e32 v42, v42
	v_mul_f32_e32 v72, 0xbfb8aa3b, v71
	v_exp_f32_e32 v73, v72
	v_mov_b32_e32 v62, v68
	v_mov_b32_e32 v63, v58
	v_pk_mul_f32 v[62:63], v[62:63], v[62:63]
	v_mov_b32_e32 v74, v69
	v_mov_b32_e32 v75, v59
	v_add_f32_e32 v42, 1.0, v42
	v_pk_fma_f32 v[62:63], v[74:75], v[74:75], v[62:63]
	v_lshlrev_b32_e32 v74, 16, v41
	v_rcp_f32_e32 v72, v42
	v_add_f32_e32 v42, 1.0, v73
	v_and_b32_e32 v75, 0xffff0000, v41
	v_mul_f32_e32 v41, 0xbfb8aa3b, v74
	v_rcp_f32_e32 v73, v42
	v_exp_f32_e32 v41, v41
	v_mul_f32_e32 v42, 0xbfb8aa3b, v75
	v_exp_f32_e32 v42, v42
	v_pk_mul_f32 v[70:71], v[72:73], v[70:71]
	v_add_f32_e32 v41, 1.0, v41
	v_rcp_f32_e32 v76, v41
	v_add_f32_e32 v41, 1.0, v42
	v_rcp_f32_e32 v77, v41
	v_lshlrev_b32_e32 v72, 16, v57
	v_and_b32_e32 v73, 0xffff0000, v57
	v_and_b32_e32 v57, 0xffff0000, v60
	v_pk_mul_f32 v[74:75], v[76:77], v[74:75]
	v_lshlrev_b32_e32 v76, 16, v56
	v_and_b32_e32 v77, 0xffff0000, v56
	v_lshlrev_b32_e32 v56, 16, v60
	v_pk_add_f32 v[56:57], v[76:77], v[56:57]
	v_lshlrev_b32_e32 v76, 16, v40
	v_and_b32_e32 v77, 0xffff0000, v40
	v_mul_f32_e32 v40, 0xbfb8aa3b, v76
	v_lshlrev_b32_e32 v78, 16, v61
	v_and_b32_e32 v79, 0xffff0000, v61
	v_exp_f32_e32 v42, v40
	v_mul_f32_e32 v40, 0xbfb8aa3b, v77
	v_pk_add_f32 v[72:73], v[72:73], v[78:79]
	v_exp_f32_e32 v78, v40
	v_mov_b32_e32 v60, v72
	v_mov_b32_e32 v61, v56
	v_add_f32_e32 v42, 1.0, v42
	v_pk_mul_f32 v[40:41], v[60:61], v[60:61]
	v_rcp_f32_e32 v60, v42
	v_add_f32_e32 v42, 1.0, v78
	v_mov_b32_e32 v78, v73
	v_mov_b32_e32 v79, v57
	v_pk_fma_f32 v[40:41], v[78:79], v[78:79], v[40:41]
	s_waitcnt vmcnt(0)
	v_lshlrev_b32_e32 v78, 16, v47
	v_rcp_f32_e32 v61, v42
	v_and_b32_e32 v79, 0xffff0000, v47
	v_mul_f32_e32 v42, 0xbfb8aa3b, v78
	v_exp_f32_e32 v42, v42
	v_mul_f32_e32 v47, 0xbfb8aa3b, v79
	v_exp_f32_e32 v47, v47
	v_pk_mul_f32 v[60:61], v[60:61], v[76:77]
	v_add_f32_e32 v42, 1.0, v42
	v_rcp_f32_e32 v80, v42
	v_add_f32_e32 v42, 1.0, v47
	v_lshlrev_b32_e32 v76, 16, v51
	v_and_b32_e32 v77, 0xffff0000, v51
	v_rcp_f32_e32 v81, v42
	v_lshlrev_b32_e32 v82, 16, v55
	v_and_b32_e32 v83, 0xffff0000, v55
	v_pk_add_f32 v[76:77], v[76:77], v[82:83]
	v_lshlrev_b32_e32 v82, 16, v46
	v_and_b32_e32 v83, 0xffff0000, v46
	v_mul_f32_e32 v42, 0xbfb8aa3b, v82
	v_exp_f32_e32 v42, v42
	v_mul_f32_e32 v46, 0xbfb8aa3b, v83
	v_pk_mul_f32 v[78:79], v[80:81], v[78:79]
	v_lshlrev_b32_e32 v80, 16, v50
	v_and_b32_e32 v81, 0xffff0000, v50
	v_lshlrev_b32_e32 v50, 16, v54
	v_and_b32_e32 v51, 0xffff0000, v54
	v_exp_f32_e32 v84, v46
	v_pk_add_f32 v[50:51], v[80:81], v[50:51]
	v_mov_b32_e32 v54, v76
	v_mov_b32_e32 v55, v50
	v_pk_mul_f32 v[54:55], v[54:55], v[54:55]
	v_mov_b32_e32 v80, v77
	v_mov_b32_e32 v81, v51
	v_add_f32_e32 v42, 1.0, v42
	v_pk_fma_f32 v[46:47], v[80:81], v[80:81], v[54:55]
	v_rcp_f32_e32 v54, v42
	v_add_f32_e32 v42, 1.0, v84
	v_lshlrev_b32_e32 v80, 16, v49
	v_and_b32_e32 v81, 0xffff0000, v49
	v_lshlrev_b32_e32 v84, 16, v53
	v_and_b32_e32 v85, 0xffff0000, v53
	v_pk_add_f32 v[80:81], v[80:81], v[84:85]
	v_lshlrev_b32_e32 v84, 16, v45
	v_rcp_f32_e32 v55, v42
	v_and_b32_e32 v85, 0xffff0000, v45
	v_mul_f32_e32 v42, 0xbfb8aa3b, v84
	v_exp_f32_e32 v42, v42
	v_mul_f32_e32 v45, 0xbfb8aa3b, v85
	v_exp_f32_e32 v45, v45
	v_lshlrev_b32_e32 v90, 16, v48
	v_add_f32_e32 v42, 1.0, v42
	v_rcp_f32_e32 v88, v42
	v_add_f32_e32 v42, 1.0, v45
	v_and_b32_e32 v91, 0xffff0000, v48
	v_lshlrev_b32_e32 v48, 16, v52
	v_and_b32_e32 v49, 0xffff0000, v52
	v_lshlrev_b32_e32 v52, 16, v44
	v_rcp_f32_e32 v89, v42
	v_and_b32_e32 v53, 0xffff0000, v44
	v_mul_f32_e32 v42, 0xbfb8aa3b, v52
	v_exp_f32_e32 v42, v42
	v_mul_f32_e32 v44, 0xbfb8aa3b, v53
	v_pk_add_f32 v[48:49], v[90:91], v[48:49]
	v_exp_f32_e32 v91, v44
	v_add_f32_e32 v42, 1.0, v42
	v_pk_mul_f32 v[86:87], v[80:81], v[80:81]
	v_pk_mul_f32 v[44:45], v[48:49], v[48:49]
	v_rcp_f32_e32 v90, v42
	v_add_f32_e32 v42, 1.0, v91
	v_rcp_f32_e32 v91, v42
	v_add_f32_e32 v42, v87, v86
	v_add_f32_e32 v44, v45, v44
	v_add_f32_e32 v42, v44, v42
	v_add_f32_e32 v42, v47, v42
	v_add_f32_e32 v42, v46, v42
	v_add_f32_e32 v41, v41, v42
	v_add_f32_e32 v40, v40, v41
	v_add_f32_e32 v40, v63, v40
	v_add_f32_e32 v40, v62, v40
	v_pk_mul_f32 v[44:45], v[90:91], v[52:53]
	v_pk_mul_f32 v[46:47], v[88:89], v[84:85]
	v_add_f32_dpp v40, v40, v40 quad_perm:[1,0,3,2] row_mask:0xf bank_mask:0xf bound_ctrl:1
	s_andn2_b64 vcc, exec, s[14:15]
	s_nop 0
	v_add_f32_dpp v40, v40, v40 quad_perm:[2,3,0,1] row_mask:0xf bank_mask:0xf bound_ctrl:1
	s_nop 1
	v_add_f32_dpp v40, v40, v40 row_half_mirror row_mask:0xf bank_mask:0xf bound_ctrl:1
	v_fmamk_f32 v40, v40, 0x3c000000, v65
	v_rsq_f32_e32 v62, v40
	v_pk_mul_f32 v[40:41], v[54:55], v[82:83]
	v_pk_mul_f32 v[48:49], v[48:49], v[62:63] op_sel_hi:[1,0]
	s_nop 0
	v_pk_mul_f32 v[48:49], v[0:1], v[48:49]
	s_nop 0
	v_pk_mul_f32 v[44:45], v[44:45], v[48:49]
	v_pk_mul_f32 v[48:49], v[80:81], v[62:63] op_sel_hi:[1,0]
	v_cvt_pk_bf16_f32 v44, v44, v45
	v_pk_mul_f32 v[48:49], v[2:3], v[48:49]
	s_nop 0
	v_pk_mul_f32 v[46:47], v[46:47], v[48:49]
	v_pk_mul_f32 v[48:49], v[72:73], v[62:63] op_sel_hi:[1,0]
	v_cvt_pk_bf16_f32 v45, v46, v47
; __device__ __forceinline__ unsigned pk2(float lo, float hi) { const f32x2_t v = {lo, hi}; const bf16x2_t b = __builtin_convertvector(v, bf16x2_t); return __builtin_bit_cast(unsigned, b); }
; __device__ __forceinline__ float siluf_(float x) { return x * __builtin_amdgcn_rcpf(1.0f + __expf(-x)); }
; __device__ __forceinline__ void phase_readout(const Params& p, int vb, int nb) {
;     ...
;             for (int q = 0; q < 8; ++q) { const unsigned wg = gg[u][q >> 2][q & 3];
;                 w[q >> 2][q & 3] = pk2(o[2 * q] * rstd * ng[q >> 1][(2 * q) & 3] * siluf_(bflo(wg)), o[2 * q + 1] * rstd * ng[q >> 1][(2 * q + 1) & 3] * siluf_(bfhi(wg))); }
;             *(u32x4*)(YA + off) = w[0]; *(u32x4*)(YA + off + 8) = w[1]; } }
	v_pk_mul_f32 v[46:47], v[50:51], v[62:63] op_sel_hi:[1,0]
	v_lshlrev_b32_e32 v50, 16, v43
	v_pk_mul_f32 v[46:47], v[4:5], v[46:47]
	v_and_b32_e32 v51, 0xffff0000, v43
	v_pk_mul_f32 v[40:41], v[40:41], v[46:47]
	v_mul_f32_e32 v42, 0xbfb8aa3b, v50
	v_cvt_pk_bf16_f32 v46, v40, v41
	v_pk_mul_f32 v[40:41], v[76:77], v[62:63] op_sel_hi:[1,0]
	v_exp_f32_e32 v52, v42
	v_pk_mul_f32 v[40:41], v[6:7], v[40:41]
	v_mul_f32_e32 v42, 0xbfb8aa3b, v51
	v_pk_mul_f32 v[40:41], v[78:79], v[40:41]
	v_pk_mul_f32 v[48:49], v[10:11], v[48:49]
	v_cvt_pk_bf16_f32 v47, v40, v41
	v_pk_mul_f32 v[40:41], v[56:57], v[62:63] op_sel_hi:[1,0]
	v_exp_f32_e32 v53, v42
	v_pk_mul_f32 v[40:41], v[8:9], v[40:41]
	v_pk_mul_f32 v[48:49], v[74:75], v[48:49]
	v_pk_mul_f32 v[40:41], v[60:61], v[40:41]
	s_nop 0
	v_cvt_pk_bf16_f32 v40, v40, v41
	v_cvt_pk_bf16_f32 v41, v48, v49
	v_pk_mul_f32 v[48:49], v[58:59], v[62:63] op_sel_hi:[1,0]
	s_nop 0
	v_pk_mul_f32 v[48:49], v[12:13], v[48:49]
	s_nop 0
	v_pk_mul_f32 v[42:43], v[70:71], v[48:49]
	v_add_f32_e32 v48, 1.0, v52
	v_add_f32_e32 v49, 1.0, v53
	v_rcp_f32_e32 v48, v48
	v_rcp_f32_e32 v49, v49
	v_pk_mul_f32 v[52:53], v[68:69], v[62:63] op_sel_hi:[1,0]
	v_cvt_pk_bf16_f32 v42, v42, v43
	v_pk_mul_f32 v[52:53], v[14:15], v[52:53]
	v_pk_mul_f32 v[48:49], v[48:49], v[50:51]
	s_nop 0
	v_pk_mul_f32 v[48:49], v[48:49], v[52:53]
	s_nop 0
	v_cvt_pk_bf16_f32 v43, v48, v49
	v_lshl_add_u64 v[48:49], v[66:67], 0, s[12:13]
	global_store_dwordx4 v[48:49], v[44:47], off sc1
	global_store_dwordx4 v[48:49], v[40:43], off offset:16 sc1
	s_cbranch_vccnz .LBB0_561
; __device__ __forceinline__ unsigned pk2(float lo, float hi) { const f32x2_t v = {lo, hi}; const bf16x2_t b = __builtin_convertvector(v, bf16x2_t); return __builtin_bit_cast(unsigned, b); }
; __device__ __forceinline__ float siluf_(float x) { return x * __builtin_amdgcn_rcpf(1.0f + __expf(-x)); }
; __device__ __forceinline__ float oct_sum(float v) { v += dppf<0xB1>(v); v += dppf<0x4E>(v); v += dppf<0x141>(v); return v; }
; __device__ __forceinline__ void phase_readout(const Params& p, int vb, int nb) {
;     ...
;         for (int u = 0; u < 2; ++u) { const int row = row0 + u * NGW; if (row < ML) { const size_t off = (size_t)row * WA + 16 * lane;
;             float o[16]; float ss = 0.f;
; #pragma unroll
;             for (int q = 0; q < 8; ++q) { const unsigned wa = a[u][q >> 2][q & 3], wb = b[u][q >> 2][q & 3]; o[2 * q] = bflo(wa) + bflo(wb); o[2 * q + 1] = bfhi(wa) + bfhi(wb); ss += o[2 * q] * o[2 * q] + o[2 * q + 1] * o[2 * q + 1]; }
;             ss = oct_sum(ss);
;             const float rstd = __builtin_amdgcn_rsqf(ss * (1.0f / HD) + EPS);
;             u32x4 w[2];
; #pragma unroll
;             for (int q = 0; q < 8; ++q) { const unsigned wg = gg[u][q >> 2][q & 3];
;                 w[q >> 2][q & 3] = pk2(o[2 * q] * rstd * ng[q >> 1][(2 * q) & 3] * siluf_(bflo(wg)), o[2 * q + 1] * rstd * ng[q >> 1][(2 * q + 1) & 3] * siluf_(bfhi(wg))); }
;             *(u32x4*)(YA + off) = w[0]; *(u32x4*)(YA + off + 8) = w[1]; } }
	v_lshlrev_b32_e32 v46, 16, v34
	v_and_b32_e32 v47, 0xffff0000, v34
	v_mul_f32_e32 v48, 0xbfb8aa3b, v46
	v_mul_f32_e32 v49, 0xbfb8aa3b, v47
	v_exp_f32_e32 v48, v48
	v_exp_f32_e32 v49, v49
	v_lshlrev_b32_e32 v40, 16, v19
	v_and_b32_e32 v41, 0xffff0000, v19
	v_lshlrev_b32_e32 v42, 16, v27
	v_and_b32_e32 v43, 0xffff0000, v27
	v_add_f32_e32 v48, 1.0, v48
	v_add_f32_e32 v49, 1.0, v49
	v_pk_add_f32 v[40:41], v[40:41], v[42:43]
	v_lshlrev_b32_e32 v42, 16, v18
	v_and_b32_e32 v43, 0xffff0000, v18
	v_lshlrev_b32_e32 v44, 16, v26
	v_and_b32_e32 v45, 0xffff0000, v26
	v_rcp_f32_e32 v48, v48
	v_rcp_f32_e32 v49, v49
	v_pk_add_f32 v[42:43], v[42:43], v[44:45]
	v_mov_b32_e32 v44, v40
	v_mov_b32_e32 v45, v42
	v_pk_mul_f32 v[44:45], v[44:45], v[44:45]
	v_mov_b32_e32 v50, v41
	v_mov_b32_e32 v51, v43
	v_pk_fma_f32 v[44:45], v[50:51], v[50:51], v[44:45]
	v_pk_mul_f32 v[50:51], v[48:49], v[46:47]
	v_lshlrev_b32_e32 v48, 16, v33
	v_and_b32_e32 v49, 0xffff0000, v33
	v_mul_f32_e32 v47, 0xbfb8aa3b, v48
	v_exp_f32_e32 v52, v47
	v_mul_f32_e32 v47, 0xbfb8aa3b, v49
	v_exp_f32_e32 v53, v47
	v_lshlrev_b32_e32 v56, 16, v32
	v_and_b32_e32 v57, 0xffff0000, v32
	v_add_f32_e32 v52, 1.0, v52
	v_add_f32_e32 v53, 1.0, v53
	v_mul_f32_e32 v58, 0xbfb8aa3b, v56
	v_mul_f32_e32 v59, 0xbfb8aa3b, v57
	v_rcp_f32_e32 v52, v52
	v_rcp_f32_e32 v53, v53
	v_exp_f32_e32 v58, v58
	v_exp_f32_e32 v59, v59
	v_lshlrev_b32_e32 v46, 16, v17
	v_and_b32_e32 v47, 0xffff0000, v17
	v_lshlrev_b32_e32 v54, 16, v25
	v_and_b32_e32 v55, 0xffff0000, v25
	v_pk_add_f32 v[54:55], v[46:47], v[54:55]
	v_pk_mul_f32 v[52:53], v[52:53], v[48:49]
	v_lshlrev_b32_e32 v46, 16, v16
	v_and_b32_e32 v47, 0xffff0000, v16
	v_lshlrev_b32_e32 v48, 16, v24
	v_and_b32_e32 v49, 0xffff0000, v24
	v_add_f32_e32 v58, 1.0, v58
	v_add_f32_e32 v59, 1.0, v59
	v_pk_add_f32 v[48:49], v[46:47], v[48:49]
	v_rcp_f32_e32 v58, v58
	v_rcp_f32_e32 v59, v59
	v_mov_b32_e32 v46, v54
	v_mov_b32_e32 v47, v48
	v_pk_mul_f32 v[46:47], v[46:47], v[46:47]
	v_mov_b32_e32 v60, v55
	v_mov_b32_e32 v61, v49
	v_pk_fma_f32 v[46:47], v[60:61], v[60:61], v[46:47]
	v_lshlrev_b32_e32 v60, 16, v39
	v_pk_mul_f32 v[56:57], v[58:59], v[56:57]
	v_and_b32_e32 v61, 0xffff0000, v39
	v_mul_f32_e32 v59, 0xbfb8aa3b, v60
	v_exp_f32_e32 v62, v59
	v_mul_f32_e32 v59, 0xbfb8aa3b, v61
	v_exp_f32_e32 v63, v59
	v_lshlrev_b32_e32 v72, 16, v38
	v_add_f32_e32 v62, 1.0, v62
	v_rcp_f32_e32 v62, v62
	v_add_f32_e32 v63, 1.0, v63
	v_rcp_f32_e32 v63, v63
	v_and_b32_e32 v73, 0xffff0000, v38
	v_lshlrev_b32_e32 v58, 16, v23
	v_and_b32_e32 v59, 0xffff0000, v23
	v_lshlrev_b32_e32 v68, 16, v31
	v_and_b32_e32 v69, 0xffff0000, v31
	v_mul_f32_e32 v74, 0xbfb8aa3b, v72
	v_mul_f32_e32 v75, 0xbfb8aa3b, v73
	v_pk_add_f32 v[58:59], v[58:59], v[68:69]
	v_pk_mul_f32 v[60:61], v[62:63], v[60:61]
	v_lshlrev_b32_e32 v62, 16, v22
	v_and_b32_e32 v63, 0xffff0000, v22
	v_lshlrev_b32_e32 v68, 16, v30
	v_and_b32_e32 v69, 0xffff0000, v30
	v_exp_f32_e32 v74, v74
	v_exp_f32_e32 v75, v75
	v_pk_add_f32 v[62:63], v[62:63], v[68:69]
	v_mov_b32_e32 v68, v58
	v_mov_b32_e32 v69, v62
	v_pk_mul_f32 v[68:69], v[68:69], v[68:69]
	v_mov_b32_e32 v70, v59
	v_mov_b32_e32 v71, v63
	v_pk_fma_f32 v[68:69], v[70:71], v[70:71], v[68:69]
	v_add_f32_e32 v70, 1.0, v74
	v_add_f32_e32 v71, 1.0, v75
	v_lshlrev_b32_e32 v74, 16, v21
	v_and_b32_e32 v75, 0xffff0000, v21
	v_lshlrev_b32_e32 v76, 16, v29
	v_and_b32_e32 v77, 0xffff0000, v29
	v_lshlrev_b32_e32 v82, 16, v20
	v_and_b32_e32 v83, 0xffff0000, v20
	v_lshlrev_b32_e32 v84, 16, v28
	v_and_b32_e32 v85, 0xffff0000, v28
	v_pk_add_f32 v[74:75], v[74:75], v[76:77]
	v_lshlrev_b32_e32 v76, 16, v37
	v_pk_add_f32 v[82:83], v[82:83], v[84:85]
	v_lshlrev_b32_e32 v84, 16, v36
	v_and_b32_e32 v77, 0xffff0000, v37
	v_mul_f32_e32 v78, 0xbfb8aa3b, v76
	v_and_b32_e32 v85, 0xffff0000, v36
	v_mul_f32_e32 v86, 0xbfb8aa3b, v84
	v_exp_f32_e32 v80, v78
	v_mul_f32_e32 v78, 0xbfb8aa3b, v77
	v_exp_f32_e32 v88, v86
	v_mul_f32_e32 v86, 0xbfb8aa3b, v85
	v_exp_f32_e32 v81, v78
	v_pk_mul_f32 v[78:79], v[74:75], v[74:75]
	v_exp_f32_e32 v89, v86
	v_pk_mul_f32 v[86:87], v[82:83], v[82:83]
	v_add_f32_e32 v78, v79, v78
	v_add_f32_e32 v79, v87, v86
	v_add_f32_e32 v78, v79, v78
	v_add_f32_e32 v69, v69, v78
	v_add_f32_e32 v68, v68, v69
	v_add_f32_e32 v47, v47, v68
	v_add_f32_e32 v46, v46, v47
	v_add_f32_e32 v45, v45, v46
	v_add_f32_e32 v44, v44, v45
	v_rcp_f32_e32 v70, v70
	v_rcp_f32_e32 v71, v71
	v_add_f32_dpp v44, v44, v44 quad_perm:[1,0,3,2] row_mask:0xf bank_mask:0xf bound_ctrl:1
	v_add_f32_e32 v88, 1.0, v88
	v_add_f32_e32 v89, 1.0, v89
	v_add_f32_dpp v44, v44, v44 quad_perm:[2,3,0,1] row_mask:0xf bank_mask:0xf bound_ctrl:1
	v_rcp_f32_e32 v88, v88
	v_rcp_f32_e32 v89, v89
	v_add_f32_dpp v44, v44, v44 row_half_mirror row_mask:0xf bank_mask:0xf bound_ctrl:1
	v_fmamk_f32 v44, v44, 0x3c000000, v65
	v_rsq_f32_e32 v68, v44
	v_add_f32_e32 v80, 1.0, v80
	v_add_f32_e32 v81, 1.0, v81
	v_rcp_f32_e32 v80, v80
	v_pk_mul_f32 v[48:49], v[48:49], v[68:69] op_sel_hi:[1,0]
	v_pk_mul_f32 v[54:55], v[54:55], v[68:69] op_sel_hi:[1,0]
	v_pk_mul_f32 v[48:49], v[8:9], v[48:49]
	v_pk_mul_f32 v[54:55], v[10:11], v[54:55]
	v_pk_mul_f32 v[48:49], v[56:57], v[48:49]
	v_pk_mul_f32 v[52:53], v[52:53], v[54:55]
	v_cvt_pk_bf16_f32 v48, v48, v49
	v_cvt_pk_bf16_f32 v49, v52, v53
	v_lshlrev_b32_e32 v52, 16, v35
	v_and_b32_e32 v53, 0xffff0000, v35
	v_mul_f32_e32 v54, 0xbfb8aa3b, v52
	v_exp_f32_e32 v54, v54
	v_mul_f32_e32 v55, 0xbfb8aa3b, v53
	v_exp_f32_e32 v55, v55
	v_pk_mul_f32 v[42:43], v[42:43], v[68:69] op_sel_hi:[1,0]
	v_rcp_f32_e32 v81, v81
	v_pk_mul_f32 v[42:43], v[12:13], v[42:43]
	v_pk_mul_f32 v[46:47], v[70:71], v[72:73]
	v_pk_mul_f32 v[42:43], v[50:51], v[42:43]
	v_add_f32_e32 v50, 1.0, v54
	v_rcp_f32_e32 v54, v50
	v_add_f32_e32 v50, 1.0, v55
	v_rcp_f32_e32 v55, v50
	v_pk_mul_f32 v[72:73], v[82:83], v[68:69] op_sel_hi:[1,0]
	v_pk_mul_f32 v[44:45], v[88:89], v[84:85]
	v_pk_mul_f32 v[72:73], v[0:1], v[72:73]
	v_pk_mul_f32 v[62:63], v[62:63], v[68:69] op_sel_hi:[1,0]
	v_pk_mul_f32 v[44:45], v[44:45], v[72:73]
	v_pk_mul_f32 v[72:73], v[74:75], v[68:69] op_sel_hi:[1,0]
	v_pk_mul_f32 v[58:59], v[58:59], v[68:69] op_sel_hi:[1,0]
	v_pk_mul_f32 v[40:41], v[40:41], v[68:69] op_sel_hi:[1,0]
	v_pk_mul_f32 v[70:71], v[80:81], v[76:77]
	v_pk_mul_f32 v[72:73], v[2:3], v[72:73]
	v_pk_mul_f32 v[62:63], v[4:5], v[62:63]
	v_pk_mul_f32 v[58:59], v[6:7], v[58:59]
	v_cvt_pk_bf16_f32 v50, v42, v43
	v_pk_mul_f32 v[40:41], v[14:15], v[40:41]
	v_pk_mul_f32 v[42:43], v[54:55], v[52:53]
	s_ashr_i32 s11, s10, 31
	v_pk_mul_f32 v[70:71], v[70:71], v[72:73]
	v_pk_mul_f32 v[46:47], v[46:47], v[62:63]
	v_pk_mul_f32 v[58:59], v[60:61], v[58:59]
	v_pk_mul_f32 v[40:41], v[42:43], v[40:41]
	s_lshl_b64 s[12:13], s[10:11], 11
	v_cvt_pk_bf16_f32 v44, v44, v45
	v_cvt_pk_bf16_f32 v45, v70, v71
	v_cvt_pk_bf16_f32 v46, v46, v47
	v_cvt_pk_bf16_f32 v47, v58, v59
	v_cvt_pk_bf16_f32 v51, v40, v41
	v_lshl_add_u64 v[40:41], v[66:67], 0, s[12:13]
	global_store_dwordx4 v[40:41], v[44:47], off sc1
	global_store_dwordx4 v[40:41], v[48:51], off offset:16 sc1
	s_branch .LBB0_561

; __device__ __forceinline__ unsigned pk2(float lo, float hi) { const f32x2_t v = {lo, hi}; const bf16x2_t b = __builtin_convertvector(v, bf16x2_t); return __builtin_bit_cast(unsigned, b); }
; #define EPI_WVEC_LOOP _Pragma("unroll") for (int m2 = 0; m2 < 2; ++m2) _Pragma("unroll") for (int bj = 0; bj < 2; ++bj)
; #define MRG_G(B_) __builtin_amdgcn_rcpf(B_)
;     __device__ __forceinline__ void operator()(const f32x4 (&acc_c)[2][2][4][2], const pg8::Unit& u, int wr, int wc, int fr, int fq) const {
;     ...
;             bf16* Z = (bf16*)(ws + WS_Z);
;             u32x4 gv[4][4];
; #pragma unroll
;             for (int b = 0; b < 4; ++b) { EPI_PIPE_IDX(b); EPI_WVEC_LOOP { EPI_WVEC_IDX; gv[b][wi] = *(const u32x4*)((const char*)GB + off * 2u); } }
; #pragma unroll
;             for (int b = 0; b < 4; ++b) { EPI_PIPE_IDX(b); EPI_WVEC_LOOP { EPI_WVEC_IDX; const u32x4 g = gv[b][wi]; const f32x4 v0 = acc[ai][bj][m][0], v1 = acc[ai][bj][m][1];
;     ...
;                     u32x4 o; o.x = pk2(MRG_G(bflo(g.x)) * v0.x, MRG_G(bfhi(g.x)) * v0.y); o.y = pk2(MRG_G(bflo(g.y)) * v0.z, MRG_G(bfhi(g.y)) * v0.w);
;                     o.z = pk2(MRG_G(bflo(g.z)) * v1.x, MRG_G(bfhi(g.z)) * v1.y); o.w = pk2(MRG_G(bflo(g.w)) * v1.z, MRG_G(bfhi(g.w)) * v1.w);
;     ...
;                     *(u32x4*)((char*)Z + off * 2u) = o; } }
.LBB0_602:
	s_or_b32 s27, s25, s62
	v_or_b32_e32 v128, s59, v128
	v_add_u32_e32 v184, s27, v183
	s_lshl_b32 s27, s36, 20
	v_lshl_add_u32 v128, v128, 12, s27
	v_add_u32_e32 v219, v128, v184
	global_load_dwordx4 v[186:189], v219, s[20:21]
	v_add_u32_e32 v129, 0x100, v219
	global_load_dwordx4 v[190:193], v129, s[20:21]
	v_add_u32_e32 v129, 0x10000, v219
	global_load_dwordx4 v[194:197], v129, s[20:21]
	v_add_u32_e32 v185, 0x100, v184
	v_add_u32_e32 v129, 0x10100, v219
	v_add_u32_e32 v130, 0x20000, v219
	v_add_u32_e32 v131, 0x20100, v219
	v_add_u32_e32 v132, 0x30000, v219
	v_add_u32_e32 v133, 0x30100, v219
	v_add_u32_e32 v134, 0x80000, v219
	v_add_u32_e32 v135, 0x80100, v219
	v_add_u32_e32 v136, 0x90000, v219
	v_add_u32_e32 v137, 0x90100, v219
	v_add_u32_e32 v138, 0xa0000, v219
	v_add_u32_e32 v139, 0xa0100, v219
	v_add_u32_e32 v210, 0xb0000, v219
	v_add_u32_e32 v211, 0xb0100, v219
	v_add_u32_e32 v220, v185, v128
	global_load_dwordx4 v[198:201], v129, s[20:21]
	global_load_dwordx4 v[202:205], v130, s[20:21]
	global_load_dwordx4 v[206:209], v131, s[20:21]
	global_load_dwordx4 v[164:167], v132, s[20:21]
	global_load_dwordx4 v[160:163], v133, s[20:21]
	global_load_dwordx4 v[156:159], v134, s[20:21]
	global_load_dwordx4 v[152:155], v135, s[20:21]
	global_load_dwordx4 v[148:151], v136, s[20:21]
	global_load_dwordx4 v[144:147], v137, s[20:21]
	global_load_dwordx4 v[140:143], v138, s[20:21]
	s_nop 0
	global_load_dwordx4 v[136:139], v139, s[20:21]
	s_nop 0
	global_load_dwordx4 v[132:135], v210, s[20:21]
	global_load_dwordx4 v[128:131], v211, s[20:21]
	s_waitcnt vmcnt(0)
	v_lshlrev_b32_e32 v210, 16, v186
	v_and_b32_e32 v211, 0xffff0000, v186
	v_lshlrev_b32_e32 v212, 16, v187
	v_and_b32_e32 v213, 0xffff0000, v187
	v_lshlrev_b32_e32 v214, 16, v188
	v_and_b32_e32 v215, 0xffff0000, v188
	v_lshlrev_b32_e32 v216, 16, v189
	v_and_b32_e32 v217, 0xffff0000, v189
	v_rcp_f32_e32 v186, v210
	v_rcp_f32_e32 v187, v211
	v_rcp_f32_e32 v188, v212
	v_rcp_f32_e32 v189, v213
	v_rcp_f32_e32 v210, v214
	v_rcp_f32_e32 v211, v215
	v_rcp_f32_e32 v212, v216
	v_rcp_f32_e32 v213, v217
	v_lshlrev_b32_e32 v214, 16, v190
	v_and_b32_e32 v215, 0xffff0000, v190
	v_lshlrev_b32_e32 v216, 16, v191
	v_and_b32_e32 v217, 0xffff0000, v191
	v_rcp_f32_e32 v190, v214
	v_rcp_f32_e32 v191, v215
	v_lshlrev_b32_e32 v218, 16, v192
	v_and_b32_e32 v221, 0xffff0000, v192
	v_lshlrev_b32_e32 v222, 16, v193
	v_and_b32_e32 v223, 0xffff0000, v193
	v_rcp_f32_e32 v192, v216
	v_rcp_f32_e32 v193, v217
	v_rcp_f32_e32 v214, v218
	v_rcp_f32_e32 v215, v221
	v_rcp_f32_e32 v216, v222
	v_rcp_f32_e32 v217, v223
	v_pk_mul_f32 v[186:187], v[124:125], v[186:187]
	v_pk_mul_f32 v[188:189], v[126:127], v[188:189]
	v_pk_mul_f32 v[210:211], v[120:121], v[210:211]
	v_pk_mul_f32 v[212:213], v[122:123], v[212:213]
	v_lshlrev_b32_e32 v224, 16, v194
	v_and_b32_e32 v194, 0xffff0000, v194
	v_cvt_pk_bf16_f32 v186, v186, v187
	v_cvt_pk_bf16_f32 v187, v188, v189
	v_cvt_pk_bf16_f32 v188, v210, v211
	v_cvt_pk_bf16_f32 v189, v212, v213
	v_pk_mul_f32 v[190:191], v[92:93], v[190:191]
	v_rcp_f32_e32 v218, v224
	global_store_dwordx4 v219, v[186:189], s[22:23] sc1
	v_rcp_f32_e32 v219, v194
	v_pk_mul_f32 v[192:193], v[94:95], v[192:193]
	v_cvt_pk_bf16_f32 v186, v190, v191
	v_lshlrev_b32_e32 v190, 16, v195
	v_and_b32_e32 v191, 0xffff0000, v195
	v_rcp_f32_e32 v190, v190
	v_rcp_f32_e32 v191, v191
	v_pk_mul_f32 v[210:211], v[88:89], v[214:215]
	v_pk_mul_f32 v[212:213], v[90:91], v[216:217]
	v_cvt_pk_bf16_f32 v187, v192, v193
	v_cvt_pk_bf16_f32 v188, v210, v211
	v_cvt_pk_bf16_f32 v189, v212, v213
	global_store_dwordx4 v220, v[186:189], s[22:23] sc1
	v_lshlrev_b32_e32 v194, 16, v199
	v_and_b32_e32 v195, 0xffff0000, v199
	v_pk_mul_f32 v[186:187], v[116:117], v[218:219]
	v_lshlrev_b32_e32 v189, 16, v196
	v_cvt_pk_bf16_f32 v188, v186, v187
	v_pk_mul_f32 v[186:187], v[118:119], v[190:191]
	v_rcp_f32_e32 v190, v189
	v_and_b32_e32 v189, 0xffff0000, v196
	v_rcp_f32_e32 v191, v189
	v_lshlrev_b32_e32 v189, 16, v197
	v_rcp_f32_e32 v192, v189
	v_and_b32_e32 v189, 0xffff0000, v197
	v_rcp_f32_e32 v193, v189
	v_cvt_pk_bf16_f32 v189, v186, v187
	v_pk_mul_f32 v[186:187], v[112:113], v[190:191]
	v_rcp_f32_e32 v194, v194
	v_cvt_pk_bf16_f32 v190, v186, v187
	v_pk_mul_f32 v[186:187], v[114:115], v[192:193]
	v_lshlrev_b32_e32 v192, 16, v198
	v_and_b32_e32 v193, 0xffff0000, v198
	v_rcp_f32_e32 v192, v192
	v_rcp_f32_e32 v193, v193
	v_cvt_pk_bf16_f32 v191, v186, v187
	v_add_u32_e32 v186, s27, v182
	v_add_u32_e32 v187, 0x10000, v186
	v_add_u32_e32 v196, v187, v184
	v_rcp_f32_e32 v195, v195
	global_store_dwordx4 v196, v[188:191], s[22:23] sc1
	v_add_u32_e32 v187, v187, v185
	s_nop 0
	v_pk_mul_f32 v[188:189], v[84:85], v[192:193]
	v_pk_mul_f32 v[190:191], v[86:87], v[194:195]
	v_cvt_pk_bf16_f32 v188, v188, v189
	v_lshlrev_b32_e32 v189, 16, v200
	v_rcp_f32_e32 v192, v189
	v_and_b32_e32 v189, 0xffff0000, v200
	v_rcp_f32_e32 v193, v189
	v_lshlrev_b32_e32 v189, 16, v201
	v_rcp_f32_e32 v194, v189
	v_and_b32_e32 v189, 0xffff0000, v201
	v_rcp_f32_e32 v195, v189
	v_cvt_pk_bf16_f32 v189, v190, v191
	v_pk_mul_f32 v[190:191], v[80:81], v[192:193]
	v_pk_mul_f32 v[192:193], v[82:83], v[194:195]
	v_cvt_pk_bf16_f32 v190, v190, v191
	v_cvt_pk_bf16_f32 v191, v192, v193
	v_lshlrev_b32_e32 v192, 16, v202
	v_and_b32_e32 v193, 0xffff0000, v202
	v_rcp_f32_e32 v192, v192
	v_rcp_f32_e32 v193, v193
	v_lshlrev_b32_e32 v194, 16, v203
	v_and_b32_e32 v195, 0xffff0000, v203
	v_rcp_f32_e32 v194, v194
	v_rcp_f32_e32 v195, v195
	global_store_dwordx4 v187, v[188:191], s[22:23] sc1
	v_lshlrev_b32_e32 v187, 16, v204
	s_nop 0
	v_pk_mul_f32 v[188:189], v[108:109], v[192:193]
	v_rcp_f32_e32 v192, v187
; __device__ __forceinline__ unsigned pk2(float lo, float hi) { const f32x2_t v = {lo, hi}; const bf16x2_t b = __builtin_convertvector(v, bf16x2_t); return __builtin_bit_cast(unsigned, b); }
; #define EPI_WVEC_LOOP _Pragma("unroll") for (int m2 = 0; m2 < 2; ++m2) _Pragma("unroll") for (int bj = 0; bj < 2; ++bj)
; #define MRG_G(B_) __builtin_amdgcn_rcpf(B_)
;     __device__ __forceinline__ void operator()(const f32x4 (&acc_c)[2][2][4][2], const pg8::Unit& u, int wr, int wc, int fr, int fq) const {
;     ...
;             for (int b = 0; b < 4; ++b) { EPI_PIPE_IDX(b); EPI_WVEC_LOOP { EPI_WVEC_IDX; const u32x4 g = gv[b][wi]; const f32x4 v0 = acc[ai][bj][m][0], v1 = acc[ai][bj][m][1];
;     ...
;                     u32x4 o; o.x = pk2(MRG_G(bflo(g.x)) * v0.x, MRG_G(bfhi(g.x)) * v0.y); o.y = pk2(MRG_G(bflo(g.y)) * v0.z, MRG_G(bfhi(g.y)) * v0.w);
;                     o.z = pk2(MRG_G(bflo(g.z)) * v1.x, MRG_G(bfhi(g.z)) * v1.y); o.w = pk2(MRG_G(bflo(g.w)) * v1.z, MRG_G(bfhi(g.w)) * v1.w);
;     ...
;                     *(u32x4*)((char*)Z + off * 2u) = o; } }
	v_and_b32_e32 v187, 0xffff0000, v204
	v_rcp_f32_e32 v193, v187
	v_lshlrev_b32_e32 v187, 16, v205
	v_pk_mul_f32 v[190:191], v[110:111], v[194:195]
	v_rcp_f32_e32 v194, v187
	v_and_b32_e32 v187, 0xffff0000, v205
	v_rcp_f32_e32 v195, v187
	v_cvt_pk_bf16_f32 v188, v188, v189
	v_cvt_pk_bf16_f32 v189, v190, v191
	v_pk_mul_f32 v[190:191], v[104:105], v[192:193]
	v_pk_mul_f32 v[192:193], v[106:107], v[194:195]
	v_cvt_pk_bf16_f32 v190, v190, v191
	v_cvt_pk_bf16_f32 v191, v192, v193
	v_lshlrev_b32_e32 v192, 16, v206
	v_and_b32_e32 v193, 0xffff0000, v206
	v_rcp_f32_e32 v192, v192
	v_rcp_f32_e32 v193, v193
	v_add_u32_e32 v187, 0x20000, v186
	v_add_u32_e32 v196, v187, v184
	v_lshlrev_b32_e32 v194, 16, v207
	v_and_b32_e32 v195, 0xffff0000, v207
	v_rcp_f32_e32 v194, v194
	v_rcp_f32_e32 v195, v195
	global_store_dwordx4 v196, v[188:191], s[22:23] sc1
	v_add_u32_e32 v187, v187, v185
	s_nop 0
	v_pk_mul_f32 v[188:189], v[76:77], v[192:193]
	v_pk_mul_f32 v[190:191], v[78:79], v[194:195]
	v_cvt_pk_bf16_f32 v188, v188, v189
	v_lshlrev_b32_e32 v189, 16, v208
	v_rcp_f32_e32 v192, v189
	v_and_b32_e32 v189, 0xffff0000, v208
	v_rcp_f32_e32 v193, v189
	v_lshlrev_b32_e32 v189, 16, v209
	v_rcp_f32_e32 v194, v189
	v_and_b32_e32 v189, 0xffff0000, v209
	v_rcp_f32_e32 v195, v189
	v_cvt_pk_bf16_f32 v189, v190, v191
	v_pk_mul_f32 v[190:191], v[72:73], v[192:193]
	v_pk_mul_f32 v[192:193], v[74:75], v[194:195]
	v_cvt_pk_bf16_f32 v190, v190, v191
	v_cvt_pk_bf16_f32 v191, v192, v193
	v_lshlrev_b32_e32 v192, 16, v164
	v_and_b32_e32 v164, 0xffff0000, v164
	v_rcp_f32_e32 v192, v192
	v_rcp_f32_e32 v193, v164
	v_lshlrev_b32_e32 v164, 16, v165
	v_rcp_f32_e32 v194, v164
	v_and_b32_e32 v164, 0xffff0000, v165
	v_rcp_f32_e32 v195, v164
	v_pk_mul_f32 v[164:165], v[100:101], v[192:193]
	global_store_dwordx4 v187, v[188:191], s[22:23] sc1
	v_cvt_pk_bf16_f32 v164, v164, v165
	v_lshlrev_b32_e32 v165, 16, v166
	v_rcp_f32_e32 v190, v165
	v_and_b32_e32 v165, 0xffff0000, v166
	v_rcp_f32_e32 v191, v165
	v_lshlrev_b32_e32 v165, 16, v167
	v_rcp_f32_e32 v192, v165
	v_and_b32_e32 v165, 0xffff0000, v167
	v_rcp_f32_e32 v193, v165
	v_pk_mul_f32 v[188:189], v[102:103], v[194:195]
	v_pk_mul_f32 v[166:167], v[96:97], v[190:191]
	v_cvt_pk_bf16_f32 v165, v188, v189
	v_pk_mul_f32 v[188:189], v[98:99], v[192:193]
	v_cvt_pk_bf16_f32 v166, v166, v167
	v_cvt_pk_bf16_f32 v167, v188, v189
	v_lshlrev_b32_e32 v188, 16, v160
	v_and_b32_e32 v160, 0xffff0000, v160
	v_rcp_f32_e32 v188, v188
	v_rcp_f32_e32 v189, v160
	v_lshlrev_b32_e32 v160, 16, v161
	v_rcp_f32_e32 v190, v160
	v_and_b32_e32 v160, 0xffff0000, v161
	v_add_u32_e32 v187, 0x30000, v186
	v_rcp_f32_e32 v191, v160
	v_pk_mul_f32 v[160:161], v[68:69], v[188:189]
	v_add_u32_e32 v192, v187, v184
	v_cvt_pk_bf16_f32 v160, v160, v161
	v_lshlrev_b32_e32 v161, 16, v162
	global_store_dwordx4 v192, v[164:167], s[22:23] sc1
	v_add_u32_e32 v187, v187, v185
	s_nop 0
	v_rcp_f32_e32 v166, v161
	v_and_b32_e32 v161, 0xffff0000, v162
	v_rcp_f32_e32 v167, v161
	v_lshlrev_b32_e32 v161, 16, v163
	v_rcp_f32_e32 v188, v161
	v_and_b32_e32 v161, 0xffff0000, v163
	v_rcp_f32_e32 v189, v161
	v_pk_mul_f32 v[164:165], v[70:71], v[190:191]
	v_pk_mul_f32 v[162:163], v[64:65], v[166:167]
	v_cvt_pk_bf16_f32 v161, v164, v165
	v_pk_mul_f32 v[164:165], v[66:67], v[188:189]
	v_cvt_pk_bf16_f32 v162, v162, v163
	v_cvt_pk_bf16_f32 v163, v164, v165
	v_lshlrev_b32_e32 v164, 16, v156
	v_and_b32_e32 v156, 0xffff0000, v156
	v_rcp_f32_e32 v164, v164
	v_rcp_f32_e32 v165, v156
	v_lshlrev_b32_e32 v156, 16, v157
	v_rcp_f32_e32 v166, v156
	v_and_b32_e32 v156, 0xffff0000, v157
	v_rcp_f32_e32 v167, v156
	v_pk_mul_f32 v[156:157], v[60:61], v[164:165]
	global_store_dwordx4 v187, v[160:163], s[22:23] sc1
	v_cvt_pk_bf16_f32 v156, v156, v157
	v_lshlrev_b32_e32 v157, 16, v158
	v_rcp_f32_e32 v162, v157
	v_and_b32_e32 v157, 0xffff0000, v158
	v_rcp_f32_e32 v163, v157
	v_lshlrev_b32_e32 v157, 16, v159
	v_rcp_f32_e32 v164, v157
	v_and_b32_e32 v157, 0xffff0000, v159
	v_rcp_f32_e32 v165, v157
	v_pk_mul_f32 v[160:161], v[62:63], v[166:167]
	v_pk_mul_f32 v[158:159], v[56:57], v[162:163]
	v_cvt_pk_bf16_f32 v157, v160, v161
	v_pk_mul_f32 v[160:161], v[58:59], v[164:165]
	v_cvt_pk_bf16_f32 v158, v158, v159
	v_cvt_pk_bf16_f32 v159, v160, v161
	v_lshlrev_b32_e32 v160, 16, v152
	v_and_b32_e32 v152, 0xffff0000, v152
	v_rcp_f32_e32 v160, v160
	v_rcp_f32_e32 v161, v152
	v_lshlrev_b32_e32 v152, 16, v153
	v_rcp_f32_e32 v162, v152
	v_and_b32_e32 v152, 0xffff0000, v153
	v_add_u32_e32 v164, 0x80000, v186
	v_rcp_f32_e32 v163, v152
	v_pk_mul_f32 v[152:153], v[28:29], v[160:161]
	v_add_u32_e32 v165, v164, v184
	v_cvt_pk_bf16_f32 v152, v152, v153
	v_lshlrev_b32_e32 v153, 16, v154
	global_store_dwordx4 v165, v[156:159], s[22:23] sc1
	s_nop 1
	v_rcp_f32_e32 v158, v153
	v_and_b32_e32 v153, 0xffff0000, v154
	v_rcp_f32_e32 v159, v153
	v_lshlrev_b32_e32 v153, 16, v155
	v_rcp_f32_e32 v160, v153
	v_and_b32_e32 v153, 0xffff0000, v155
	v_rcp_f32_e32 v161, v153
	v_pk_mul_f32 v[156:157], v[30:31], v[162:163]
	v_pk_mul_f32 v[154:155], v[24:25], v[158:159]
	v_cvt_pk_bf16_f32 v153, v156, v157
	v_pk_mul_f32 v[156:157], v[26:27], v[160:161]
	v_cvt_pk_bf16_f32 v154, v154, v155
	v_cvt_pk_bf16_f32 v155, v156, v157
	v_lshlrev_b32_e32 v156, 16, v148
	v_and_b32_e32 v148, 0xffff0000, v148
	v_rcp_f32_e32 v156, v156
	v_rcp_f32_e32 v157, v148
	v_lshlrev_b32_e32 v148, 16, v149
	v_rcp_f32_e32 v158, v148
	v_and_b32_e32 v148, 0xffff0000, v149
	v_rcp_f32_e32 v159, v148
	v_pk_mul_f32 v[148:149], v[52:53], v[156:157]
; __device__ __forceinline__ unsigned pk2(float lo, float hi) { const f32x2_t v = {lo, hi}; const bf16x2_t b = __builtin_convertvector(v, bf16x2_t); return __builtin_bit_cast(unsigned, b); }
; #define EPI_WVEC_LOOP _Pragma("unroll") for (int m2 = 0; m2 < 2; ++m2) _Pragma("unroll") for (int bj = 0; bj < 2; ++bj)
; #define MRG_G(B_) __builtin_amdgcn_rcpf(B_)
;     __device__ __forceinline__ void operator()(const f32x4 (&acc_c)[2][2][4][2], const pg8::Unit& u, int wr, int wc, int fr, int fq) const {
;     ...
;             for (int b = 0; b < 4; ++b) { EPI_PIPE_IDX(b); EPI_WVEC_LOOP { EPI_WVEC_IDX; const u32x4 g = gv[b][wi]; const f32x4 v0 = acc[ai][bj][m][0], v1 = acc[ai][bj][m][1];
;     ...
;                     u32x4 o; o.x = pk2(MRG_G(bflo(g.x)) * v0.x, MRG_G(bfhi(g.x)) * v0.y); o.y = pk2(MRG_G(bflo(g.y)) * v0.z, MRG_G(bfhi(g.y)) * v0.w);
;                     o.z = pk2(MRG_G(bflo(g.z)) * v1.x, MRG_G(bfhi(g.z)) * v1.y); o.w = pk2(MRG_G(bflo(g.w)) * v1.z, MRG_G(bfhi(g.w)) * v1.w);
;     ...
;                     *(u32x4*)((char*)Z + off * 2u) = o; } }
	v_add_u32_e32 v160, v164, v185
	v_cvt_pk_bf16_f32 v148, v148, v149
	v_lshlrev_b32_e32 v149, 16, v150
	global_store_dwordx4 v160, v[152:155], s[22:23] sc1
	s_nop 1
	v_rcp_f32_e32 v154, v149
	v_and_b32_e32 v149, 0xffff0000, v150
	v_rcp_f32_e32 v155, v149
	v_lshlrev_b32_e32 v149, 16, v151
	v_rcp_f32_e32 v156, v149
	v_and_b32_e32 v149, 0xffff0000, v151
	v_rcp_f32_e32 v157, v149
	v_pk_mul_f32 v[152:153], v[54:55], v[158:159]
	v_pk_mul_f32 v[150:151], v[48:49], v[154:155]
	v_cvt_pk_bf16_f32 v149, v152, v153
	v_pk_mul_f32 v[152:153], v[50:51], v[156:157]
	v_cvt_pk_bf16_f32 v150, v150, v151
	v_cvt_pk_bf16_f32 v151, v152, v153
	v_lshlrev_b32_e32 v152, 16, v144
	v_and_b32_e32 v144, 0xffff0000, v144
	v_rcp_f32_e32 v152, v152
	v_rcp_f32_e32 v153, v144
	v_lshlrev_b32_e32 v144, 16, v145
	v_rcp_f32_e32 v154, v144
	v_and_b32_e32 v144, 0xffff0000, v145
	v_add_u32_e32 v156, 0x90000, v186
	v_rcp_f32_e32 v155, v144
	v_pk_mul_f32 v[144:145], v[20:21], v[152:153]
	v_add_u32_e32 v157, v156, v184
	v_cvt_pk_bf16_f32 v144, v144, v145
	v_lshlrev_b32_e32 v145, 16, v146
	global_store_dwordx4 v157, v[148:151], s[22:23] sc1
	s_nop 1
	v_rcp_f32_e32 v150, v145
	v_and_b32_e32 v145, 0xffff0000, v146
	v_rcp_f32_e32 v151, v145
	v_lshlrev_b32_e32 v145, 16, v147
	v_rcp_f32_e32 v152, v145
	v_and_b32_e32 v145, 0xffff0000, v147
	v_rcp_f32_e32 v153, v145
	v_pk_mul_f32 v[148:149], v[22:23], v[154:155]
	v_pk_mul_f32 v[146:147], v[16:17], v[150:151]
	v_cvt_pk_bf16_f32 v145, v148, v149
	v_pk_mul_f32 v[148:149], v[18:19], v[152:153]
	v_cvt_pk_bf16_f32 v146, v146, v147
	v_cvt_pk_bf16_f32 v147, v148, v149
	v_lshlrev_b32_e32 v148, 16, v140
	v_and_b32_e32 v140, 0xffff0000, v140
	v_rcp_f32_e32 v148, v148
	v_rcp_f32_e32 v149, v140
	v_lshlrev_b32_e32 v140, 16, v141
	v_rcp_f32_e32 v150, v140
	v_and_b32_e32 v140, 0xffff0000, v141
	v_rcp_f32_e32 v151, v140
	v_pk_mul_f32 v[140:141], v[44:45], v[148:149]
	v_add_u32_e32 v152, v156, v185
	v_cvt_pk_bf16_f32 v140, v140, v141
	v_lshlrev_b32_e32 v141, 16, v142
	global_store_dwordx4 v152, v[144:147], s[22:23] sc1
	s_nop 1
	v_rcp_f32_e32 v146, v141
	v_and_b32_e32 v141, 0xffff0000, v142
	v_rcp_f32_e32 v147, v141
	v_lshlrev_b32_e32 v141, 16, v143
	v_rcp_f32_e32 v148, v141
	v_and_b32_e32 v141, 0xffff0000, v143
	v_rcp_f32_e32 v149, v141
	v_pk_mul_f32 v[144:145], v[46:47], v[150:151]
	v_pk_mul_f32 v[142:143], v[40:41], v[146:147]
	v_cvt_pk_bf16_f32 v141, v144, v145
	v_pk_mul_f32 v[144:145], v[42:43], v[148:149]
	v_cvt_pk_bf16_f32 v142, v142, v143
	v_cvt_pk_bf16_f32 v143, v144, v145
	v_lshlrev_b32_e32 v144, 16, v136
	v_and_b32_e32 v136, 0xffff0000, v136
	v_rcp_f32_e32 v144, v144
	v_rcp_f32_e32 v145, v136
	v_lshlrev_b32_e32 v136, 16, v137
	v_rcp_f32_e32 v146, v136
	v_and_b32_e32 v136, 0xffff0000, v137
	v_add_u32_e32 v148, 0xa0000, v186
	v_rcp_f32_e32 v147, v136
	v_pk_mul_f32 v[136:137], v[12:13], v[144:145]
	v_add_u32_e32 v149, v148, v184
	v_cvt_pk_bf16_f32 v136, v136, v137
	v_lshlrev_b32_e32 v137, 16, v138
	global_store_dwordx4 v149, v[140:143], s[22:23] sc1
	s_nop 1
	v_rcp_f32_e32 v142, v137
	v_and_b32_e32 v137, 0xffff0000, v138
	v_rcp_f32_e32 v143, v137
	v_lshlrev_b32_e32 v137, 16, v139
	v_rcp_f32_e32 v144, v137
	v_and_b32_e32 v137, 0xffff0000, v139
	v_rcp_f32_e32 v145, v137
	v_pk_mul_f32 v[140:141], v[14:15], v[146:147]
	v_pk_mul_f32 v[138:139], v[8:9], v[142:143]
	v_cvt_pk_bf16_f32 v137, v140, v141
	v_pk_mul_f32 v[140:141], v[10:11], v[144:145]
	v_cvt_pk_bf16_f32 v138, v138, v139
	v_cvt_pk_bf16_f32 v139, v140, v141
	v_lshlrev_b32_e32 v140, 16, v132
	v_and_b32_e32 v132, 0xffff0000, v132
	v_rcp_f32_e32 v140, v140
	v_rcp_f32_e32 v141, v132
	v_lshlrev_b32_e32 v132, 16, v133
	v_rcp_f32_e32 v142, v132
	v_and_b32_e32 v132, 0xffff0000, v133
	v_rcp_f32_e32 v143, v132
	v_pk_mul_f32 v[132:133], v[36:37], v[140:141]
	v_add_u32_e32 v144, v148, v185
	v_cvt_pk_bf16_f32 v132, v132, v133
	v_lshlrev_b32_e32 v133, 16, v134
	global_store_dwordx4 v144, v[136:139], s[22:23] sc1
	s_nop 1
	v_rcp_f32_e32 v138, v133
	v_and_b32_e32 v133, 0xffff0000, v134
	v_rcp_f32_e32 v139, v133
	v_lshlrev_b32_e32 v133, 16, v135
	v_rcp_f32_e32 v140, v133
	v_and_b32_e32 v133, 0xffff0000, v135
	v_rcp_f32_e32 v141, v133
	v_pk_mul_f32 v[136:137], v[38:39], v[142:143]
	v_pk_mul_f32 v[134:135], v[32:33], v[138:139]
	v_cvt_pk_bf16_f32 v133, v136, v137
	v_pk_mul_f32 v[136:137], v[34:35], v[140:141]
	v_cvt_pk_bf16_f32 v134, v134, v135
	v_cvt_pk_bf16_f32 v135, v136, v137
	v_lshlrev_b32_e32 v136, 16, v128
	v_and_b32_e32 v128, 0xffff0000, v128
	v_rcp_f32_e32 v136, v136
	v_rcp_f32_e32 v137, v128
	v_lshlrev_b32_e32 v128, 16, v129
	v_rcp_f32_e32 v138, v128
	v_and_b32_e32 v128, 0xffff0000, v129
	v_add_u32_e32 v140, 0xb0000, v186
	v_rcp_f32_e32 v139, v128
	v_pk_mul_f32 v[128:129], v[4:5], v[136:137]
	v_add_u32_e32 v141, v140, v184
	v_cvt_pk_bf16_f32 v128, v128, v129
	v_lshlrev_b32_e32 v129, 16, v130
	global_store_dwordx4 v141, v[132:135], s[22:23] sc1
	s_nop 1
	v_rcp_f32_e32 v134, v129
	v_and_b32_e32 v129, 0xffff0000, v130
	v_rcp_f32_e32 v135, v129
	v_lshlrev_b32_e32 v129, 16, v131
	v_rcp_f32_e32 v136, v129
	v_and_b32_e32 v129, 0xffff0000, v131
	v_rcp_f32_e32 v137, v129
	v_pk_mul_f32 v[132:133], v[6:7], v[138:139]
	v_pk_mul_f32 v[130:131], v[0:1], v[134:135]
	v_cvt_pk_bf16_f32 v129, v132, v133
	v_pk_mul_f32 v[132:133], v[2:3], v[136:137]
	v_cvt_pk_bf16_f32 v130, v130, v131
	v_cvt_pk_bf16_f32 v131, v132, v133
	v_add_u32_e32 v132, v140, v185
	global_store_dwordx4 v132, v[128:131], s[22:23] sc1
	s_cbranch_execnz .LBB0_601

;     __device__ __forceinline__ void operator()(const f32x4 (&acc)[2][2][4][2], const pg8::Unit& u, int wr, int wc, int fr, int fq) const {
;     ...
;         const float* mod = (const float*)(ws + WS_MOD); bf16* XMG = (bf16*)(ws + WS_XMG); bf16* XM = (bf16*)(ws + WS_XM16); float* rowsq = (float*)(ws + WS_ROWSQ);
;         const int bb = (u.pm * 256) / SEQ;
;         const float* g1 = mod + (size_t)bb * IN_COLS + 2 * D_MODEL, *sc2 = mod + (size_t)bb * IN_COLS + 4 * D_MODEL;
;         float ss[2][4];
; #pragma unroll
;         for (int ai = 0; ai < 2; ++ai)
; #pragma unroll
;             for (int m = 0; m < 4; ++m) ss[ai][m] = 0.f;
; #pragma unroll
;         for (int bj = 0; bj < 2; ++bj) {
;             const int col = u.pn * 256 + bj * 128 + wc * 32 + fq * 8;
;             const f32x4 cg0 = *(const f32x4*)(g1 + col), cg1 = *(const f32x4*)(g1 + col + 4), ch0 = *(const f32x4*)(sc2 + col), ch1 = *(const f32x4*)(sc2 + col + 4);
;             f32x4 xv[2][4][2];
; #pragma unroll
;             for (int ai = 0; ai < 2; ++ai)
; #pragma unroll
;                 for (int m = 0; m < 4; ++m) { const unsigned off = (unsigned)((u.pm * 256 + ai * 128 + wr * 64 + m * 16 + fr) * D_MODEL + col); xv[ai][m][0] = *(const f32x4*)((const char*)x + off * 4u); xv[ai][m][1] = *(const f32x4*)((const char*)x + off * 4u + 16); }
; #pragma unroll
;             for (int ai = 0; ai < 2; ++ai)
; #pragma unroll
;                 for (int m = 0; m < 4; ++m) { const unsigned off = (unsigned)((u.pm * 256 + ai * 128 + wr * 64 + m * 16 + fr) * D_MODEL + col);
;                     const f32x4 xm0 = xv[ai][m][0] + cg0 * acc[ai][bj][m][0], xm1 = xv[ai][m][1] + cg1 * acc[ai][bj][m][1];
;                     { u32x4 o; o.x = pk2(xm0.x, xm0.y); o.y = pk2(xm0.z, xm0.w); o.z = pk2(xm1.x, xm1.y); o.w = pk2(xm1.z, xm1.w); *(u32x4*)((char*)XM + off * 2u) = o; }
;                     ss[ai][m] += ((xm0.x * xm0.x + xm0.y * xm0.y) + (xm0.z * xm0.z + xm0.w * xm0.w)) + ((xm1.x * xm1.x + xm1.y * xm1.y) + (xm1.z * xm1.z + xm1.w * xm1.w));
;                     const f32x4 h0 = xm0 * ch0, h1 = xm1 * ch1;
;                     u32x4 o; o.x = pk2(h0.x, h0.y); o.y = pk2(h0.z, h0.w); o.z = pk2(h1.x, h1.y); o.w = pk2(h1.z, h1.w);
;                     *(u32x4*)((char*)XMG + off * 2u) = o; }
.LBB0_683:
	s_ashr_i32 s23, s30, 31
	s_lshr_b32 s23, s23, 29
	s_add_i32 s23, s30, s23
	s_ashr_i32 s23, s23, 3
	s_mul_hi_i32 s25, s23, 0xc000
	s_mul_i32 s23, s23, 0xc000
	s_add_u32 s23, s55, s23
	s_addc_u32 s25, s56, s25
	s_add_u32 s36, s23, 0x4000
	s_addc_u32 s37, s25, 0
	s_add_u32 s46, s23, 0x8000
	v_mbcnt_lo_u32_b32 v220, -1, 0
	v_mbcnt_hi_u32_b32 v220, -1, v220
	s_addc_u32 s47, s25, 0
	s_lshl_b32 s23, s34, 8
	v_ashrrev_i32_e32 v128, 1, v220
	v_and_b32_e32 v128, -8, v128
	s_or_b32 s23, s23, s52
	v_add_u32_e32 v208, s23, v128
	s_lshl_b32 s23, s30, 8
	s_add_i32 s23, s23, s51
	v_and_or_b32 v228, v220, 15, s23
	v_ashrrev_i32_e32 v209, 31, v208
	v_lshlrev_b64 v[128:129], 2, v[208:209]
	v_lshlrev_b32_e32 v144, 2, v208
	v_lshlrev_b32_e32 v227, 13, v228
	v_lshl_add_u64 v[130:131], s[36:37], 0, v[128:129]
	v_lshl_add_u64 v[132:133], s[46:47], 0, v[128:129]
	v_add_u32_e32 v145, v144, v227
	global_load_dwordx4 v[136:139], v[130:131], off offset:16
	global_load_dwordx4 v[140:143], v[130:131], off
	s_nop 0
	global_load_dwordx4 v[128:131], v[132:133], off offset:16
	s_nop 0
	global_load_dwordx4 v[132:135], v[132:133], off
	s_nop 0
	global_load_dwordx4 v[232:235], v145, s[8:9] offset:16
	global_load_dwordx4 v[236:239], v145, s[8:9]
	v_or_b32_e32 v225, 0x20000, v227
	v_add_u32_e32 v145, v225, v144
	global_load_dwordx4 v[240:243], v145, s[8:9] offset:16
	global_load_dwordx4 v[244:247], v145, s[8:9]
	v_or_b32_e32 v226, 0x40000, v227
	v_add_u32_e32 v145, v226, v144
	global_load_dwordx4 v[184:187], v145, s[8:9] offset:16
	global_load_dwordx4 v[188:191], v145, s[8:9]
	v_or_b32_e32 v209, 0x60000, v227
	v_add_u32_e32 v145, v209, v144
	global_load_dwordx4 v[176:179], v145, s[8:9] offset:16
	global_load_dwordx4 v[180:183], v145, s[8:9]
	v_add_u32_e32 v221, 0x100000, v227
	v_add_u32_e32 v145, v221, v144
	global_load_dwordx4 v[168:171], v145, s[8:9] offset:16
	global_load_dwordx4 v[172:175], v145, s[8:9]
	v_add_u32_e32 v222, 0x120000, v227
	v_add_u32_e32 v145, v222, v144
	global_load_dwordx4 v[160:163], v145, s[8:9] offset:16
	global_load_dwordx4 v[164:167], v145, s[8:9]
	v_add_u32_e32 v223, 0x140000, v227
	v_add_u32_e32 v145, v223, v144
	global_load_dwordx4 v[152:155], v145, s[8:9] offset:16
	global_load_dwordx4 v[156:159], v145, s[8:9]
	v_add_u32_e32 v224, 0x160000, v227
	v_add_u32_e32 v148, v224, v144
	global_load_dwordx4 v[144:147], v148, s[8:9] offset:16
	s_nop 0
	global_load_dwordx4 v[148:151], v148, s[8:9]
	v_lshlrev_b32_e32 v231, 1, v208
	v_lshlrev_b32_e32 v228, 12, v228
	v_add_u32_e32 v230, v231, v228
	v_cmp_gt_u32_e32 vcc, 16, v220
	s_waitcnt vmcnt(0)
	v_pk_fma_f32 v[234:235], v[122:123], v[138:139], v[234:235]
	v_pk_fma_f32 v[126:127], v[126:127], v[142:143], v[238:239]
	v_pk_fma_f32 v[124:125], v[124:125], v[140:141], v[236:237]
	v_pk_fma_f32 v[232:233], v[120:121], v[136:137], v[232:233]
	v_cvt_pk_bf16_f32 v120, v124, v125
	v_cvt_pk_bf16_f32 v121, v126, v127
	v_cvt_pk_bf16_f32 v122, v232, v233
	v_cvt_pk_bf16_f32 v123, v234, v235
	global_store_dwordx4 v230, v[120:123], s[16:17] sc1
	v_pk_fma_f32 v[118:119], v[118:119], v[142:143], v[246:247]
	v_pk_fma_f32 v[116:117], v[116:117], v[140:141], v[244:245]
	v_mul_f32_e32 v120, v125, v125
	v_mul_f32_e32 v121, v127, v127
	v_fmac_f32_e32 v120, v124, v124
	v_fmac_f32_e32 v121, v126, v126
	v_add_f32_e32 v120, v120, v121
	v_mul_f32_e32 v121, v233, v233
	v_mul_f32_e32 v122, v235, v235
	v_fmac_f32_e32 v121, v232, v232
	v_fmac_f32_e32 v122, v234, v234
	v_add_f32_e32 v121, v121, v122
	v_add_f32_e32 v229, v120, v121
	v_pk_mul_f32 v[122:123], v[134:135], v[126:127]
	v_pk_mul_f32 v[120:121], v[132:133], v[124:125]
	v_pk_mul_f32 v[124:125], v[130:131], v[234:235]
	v_pk_mul_f32 v[126:127], v[128:129], v[232:233]
	v_cvt_pk_bf16_f32 v120, v120, v121
	v_cvt_pk_bf16_f32 v121, v122, v123
	v_cvt_pk_bf16_f32 v122, v126, v127
	v_cvt_pk_bf16_f32 v123, v124, v125
	global_store_dwordx4 v230, v[120:123], s[18:19] sc1
	v_pk_fma_f32 v[114:115], v[114:115], v[138:139], v[242:243]
	v_pk_fma_f32 v[112:113], v[112:113], v[136:137], v[240:241]
	v_or_b32_e32 v230, 0x10000, v228
	v_cvt_pk_bf16_f32 v120, v116, v117
	v_cvt_pk_bf16_f32 v121, v118, v119
	v_cvt_pk_bf16_f32 v122, v112, v113
	v_cvt_pk_bf16_f32 v123, v114, v115
	v_add_u32_e32 v232, v230, v231
	global_store_dwordx4 v232, v[120:123], s[16:17] sc1
	v_pk_mul_f32 v[124:125], v[130:131], v[114:115]
	v_pk_mul_f32 v[126:127], v[128:129], v[112:113]
	v_pk_mul_f32 v[122:123], v[134:135], v[118:119]
	v_pk_mul_f32 v[120:121], v[132:133], v[116:117]
	v_pk_fma_f32 v[190:191], v[110:111], v[142:143], v[190:191]
	v_cvt_pk_bf16_f32 v120, v120, v121
	v_cvt_pk_bf16_f32 v121, v122, v123
	v_cvt_pk_bf16_f32 v122, v126, v127
	v_cvt_pk_bf16_f32 v123, v124, v125
	v_pk_fma_f32 v[188:189], v[108:109], v[140:141], v[188:189]
	v_pk_fma_f32 v[186:187], v[106:107], v[138:139], v[186:187]
	v_pk_fma_f32 v[184:185], v[104:105], v[136:137], v[184:185]
	v_or_b32_e32 v242, 0x20000, v228
	global_store_dwordx4 v232, v[120:123], s[18:19] sc1
	v_cvt_pk_bf16_f32 v104, v188, v189
	v_cvt_pk_bf16_f32 v105, v190, v191
	v_cvt_pk_bf16_f32 v106, v184, v185
	v_cvt_pk_bf16_f32 v107, v186, v187
	v_add_u32_e32 v120, v242, v231
	global_store_dwordx4 v120, v[104:107], s[16:17] sc1
	v_pk_mul_f32 v[108:109], v[130:131], v[186:187]
	v_pk_mul_f32 v[110:111], v[128:129], v[184:185]
	v_pk_mul_f32 v[106:107], v[134:135], v[190:191]
	v_pk_mul_f32 v[104:105], v[132:133], v[188:189]
	v_pk_fma_f32 v[182:183], v[102:103], v[142:143], v[182:183]
	v_cvt_pk_bf16_f32 v104, v104, v105
	v_cvt_pk_bf16_f32 v105, v106, v107
	v_cvt_pk_bf16_f32 v106, v110, v111
	v_cvt_pk_bf16_f32 v107, v108, v109
	v_pk_fma_f32 v[180:181], v[100:101], v[140:141], v[180:181]
; __device__ __forceinline__ unsigned pk2(float lo, float hi) { const f32x2_t v = {lo, hi}; const bf16x2_t b = __builtin_convertvector(v, bf16x2_t); return __builtin_bit_cast(unsigned, b); }
;     __device__ __forceinline__ void operator()(const f32x4 (&acc)[2][2][4][2], const pg8::Unit& u, int wr, int wc, int fr, int fq) const {
;     ...
;                 for (int m = 0; m < 4; ++m) { const unsigned off = (unsigned)((u.pm * 256 + ai * 128 + wr * 64 + m * 16 + fr) * D_MODEL + col); xv[ai][m][0] = *(const f32x4*)((const char*)x + off * 4u); xv[ai][m][1] = *(const f32x4*)((const char*)x + off * 4u + 16); }
; #pragma unroll
;             for (int ai = 0; ai < 2; ++ai)
; #pragma unroll
;                 for (int m = 0; m < 4; ++m) { const unsigned off = (unsigned)((u.pm * 256 + ai * 128 + wr * 64 + m * 16 + fr) * D_MODEL + col);
;                     const f32x4 xm0 = xv[ai][m][0] + cg0 * acc[ai][bj][m][0], xm1 = xv[ai][m][1] + cg1 * acc[ai][bj][m][1];
;                     { u32x4 o; o.x = pk2(xm0.x, xm0.y); o.y = pk2(xm0.z, xm0.w); o.z = pk2(xm1.x, xm1.y); o.w = pk2(xm1.z, xm1.w); *(u32x4*)((char*)XM + off * 2u) = o; }
;                     ss[ai][m] += ((xm0.x * xm0.x + xm0.y * xm0.y) + (xm0.z * xm0.z + xm0.w * xm0.w)) + ((xm1.x * xm1.x + xm1.y * xm1.y) + (xm1.z * xm1.z + xm1.w * xm1.w));
;                     const f32x4 h0 = xm0 * ch0, h1 = xm1 * ch1;
;                     u32x4 o; o.x = pk2(h0.x, h0.y); o.y = pk2(h0.z, h0.w); o.z = pk2(h1.x, h1.y); o.w = pk2(h1.z, h1.w);
;                     *(u32x4*)((char*)XMG + off * 2u) = o; }
	v_pk_fma_f32 v[178:179], v[98:99], v[138:139], v[178:179]
	v_pk_fma_f32 v[176:177], v[96:97], v[136:137], v[176:177]
	v_or_b32_e32 v243, 0x30000, v228
	global_store_dwordx4 v120, v[104:107], s[18:19] sc1
	v_cvt_pk_bf16_f32 v96, v180, v181
	v_cvt_pk_bf16_f32 v97, v182, v183
	v_cvt_pk_bf16_f32 v98, v176, v177
	v_cvt_pk_bf16_f32 v99, v178, v179
	v_add_u32_e32 v104, v243, v231
	global_store_dwordx4 v104, v[96:99], s[16:17] sc1
	v_pk_mul_f32 v[100:101], v[130:131], v[178:179]
	v_pk_mul_f32 v[102:103], v[128:129], v[176:177]
	v_pk_mul_f32 v[98:99], v[134:135], v[182:183]
	v_pk_mul_f32 v[96:97], v[132:133], v[180:181]
	v_pk_fma_f32 v[122:123], v[94:95], v[142:143], v[174:175]
	v_cvt_pk_bf16_f32 v96, v96, v97
	v_cvt_pk_bf16_f32 v97, v98, v99
	v_cvt_pk_bf16_f32 v98, v102, v103
	v_cvt_pk_bf16_f32 v99, v100, v101
	v_pk_fma_f32 v[126:127], v[92:93], v[140:141], v[172:173]
	v_pk_fma_f32 v[120:121], v[90:91], v[138:139], v[170:171]
	v_pk_fma_f32 v[124:125], v[88:89], v[136:137], v[168:169]
	v_add_u32_e32 v244, 0x80000, v228
	global_store_dwordx4 v104, v[96:99], s[18:19] sc1
	v_cvt_pk_bf16_f32 v88, v126, v127
	v_cvt_pk_bf16_f32 v89, v122, v123
	v_cvt_pk_bf16_f32 v90, v124, v125
	v_cvt_pk_bf16_f32 v91, v120, v121
	v_add_u32_e32 v96, v244, v231
	global_store_dwordx4 v96, v[88:91], s[16:17] sc1
	v_pk_mul_f32 v[92:93], v[130:131], v[120:121]
	v_pk_mul_f32 v[94:95], v[128:129], v[124:125]
	v_pk_mul_f32 v[90:91], v[134:135], v[122:123]
	v_pk_mul_f32 v[88:89], v[132:133], v[126:127]
	v_pk_fma_f32 v[106:107], v[86:87], v[142:143], v[166:167]
	v_cvt_pk_bf16_f32 v88, v88, v89
	v_cvt_pk_bf16_f32 v89, v90, v91
	v_cvt_pk_bf16_f32 v90, v94, v95
	v_cvt_pk_bf16_f32 v91, v92, v93
	v_pk_fma_f32 v[110:111], v[84:85], v[140:141], v[164:165]
	v_pk_fma_f32 v[104:105], v[82:83], v[138:139], v[162:163]
	v_pk_fma_f32 v[108:109], v[80:81], v[136:137], v[160:161]
	v_add_u32_e32 v245, 0x90000, v228
	global_store_dwordx4 v96, v[88:91], s[18:19] sc1
	v_cvt_pk_bf16_f32 v80, v110, v111
	v_cvt_pk_bf16_f32 v81, v106, v107
	v_cvt_pk_bf16_f32 v82, v108, v109
	v_cvt_pk_bf16_f32 v83, v104, v105
	v_add_u32_e32 v88, v245, v231
	global_store_dwordx4 v88, v[80:83], s[16:17] sc1
	v_pk_mul_f32 v[84:85], v[130:131], v[104:105]
	v_pk_mul_f32 v[86:87], v[128:129], v[108:109]
	v_pk_mul_f32 v[82:83], v[134:135], v[106:107]
	v_pk_mul_f32 v[80:81], v[132:133], v[110:111]
	v_pk_fma_f32 v[98:99], v[78:79], v[142:143], v[158:159]
	v_cvt_pk_bf16_f32 v80, v80, v81
	v_cvt_pk_bf16_f32 v81, v82, v83
	v_cvt_pk_bf16_f32 v82, v86, v87
	v_cvt_pk_bf16_f32 v83, v84, v85
	v_pk_fma_f32 v[102:103], v[76:77], v[140:141], v[156:157]
	v_pk_fma_f32 v[96:97], v[74:75], v[138:139], v[154:155]
	v_pk_fma_f32 v[100:101], v[72:73], v[136:137], v[152:153]
	v_add_u32_e32 v246, 0xa0000, v228
	global_store_dwordx4 v88, v[80:83], s[18:19] sc1
	v_cvt_pk_bf16_f32 v72, v102, v103
	v_cvt_pk_bf16_f32 v73, v98, v99
	v_cvt_pk_bf16_f32 v74, v100, v101
	v_cvt_pk_bf16_f32 v75, v96, v97
	v_add_u32_e32 v80, v246, v231
	global_store_dwordx4 v80, v[72:75], s[16:17] sc1
	v_pk_mul_f32 v[76:77], v[130:131], v[96:97]
	v_pk_mul_f32 v[78:79], v[128:129], v[100:101]
	v_pk_mul_f32 v[74:75], v[134:135], v[98:99]
	v_pk_mul_f32 v[72:73], v[132:133], v[102:103]
	v_pk_fma_f32 v[90:91], v[70:71], v[142:143], v[150:151]
	v_cvt_pk_bf16_f32 v72, v72, v73
	v_cvt_pk_bf16_f32 v73, v74, v75
	v_cvt_pk_bf16_f32 v74, v78, v79
	v_cvt_pk_bf16_f32 v75, v76, v77
	v_pk_fma_f32 v[94:95], v[68:69], v[140:141], v[148:149]
	v_pk_fma_f32 v[88:89], v[66:67], v[138:139], v[146:147]
	v_pk_fma_f32 v[92:93], v[64:65], v[136:137], v[144:145]
	v_add_u32_e32 v247, 0xb0000, v228
	global_store_dwordx4 v80, v[72:75], s[18:19] sc1
	v_cvt_pk_bf16_f32 v64, v94, v95
	v_cvt_pk_bf16_f32 v65, v90, v91
	v_cvt_pk_bf16_f32 v66, v92, v93
	v_cvt_pk_bf16_f32 v67, v88, v89
	v_add_u32_e32 v72, v247, v231
	global_store_dwordx4 v72, v[64:67], s[16:17] sc1
	v_pk_mul_f32 v[68:69], v[130:131], v[88:89]
	v_pk_mul_f32 v[70:71], v[128:129], v[92:93]
	v_pk_mul_f32 v[66:67], v[134:135], v[90:91]
	v_pk_mul_f32 v[64:65], v[132:133], v[94:95]
	v_add_u32_e32 v240, 0x80, v208
	v_cvt_pk_bf16_f32 v64, v64, v65
	v_cvt_pk_bf16_f32 v65, v66, v67
	v_cvt_pk_bf16_f32 v66, v70, v71
	v_cvt_pk_bf16_f32 v67, v68, v69
	v_ashrrev_i32_e32 v241, 31, v240
	global_store_dwordx4 v72, v[64:67], s[18:19] sc1
	v_lshlrev_b32_e32 v80, 2, v240
	v_add_u32_e32 v81, v80, v227
	v_lshlrev_b64 v[64:65], 2, v[240:241]
	v_lshl_add_u64 v[66:67], s[36:37], 0, v[64:65]
	v_lshl_add_u64 v[68:69], s[46:47], 0, v[64:65]
	global_load_dwordx4 v[72:75], v[66:67], off offset:16
	global_load_dwordx4 v[76:79], v[66:67], off
	s_nop 0
	global_load_dwordx4 v[64:67], v[68:69], off offset:16
	s_nop 0
	global_load_dwordx4 v[68:71], v[68:69], off
	s_nop 0
	global_load_dwordx4 v[128:131], v81, s[8:9] offset:16
	global_load_dwordx4 v[132:135], v81, s[8:9]
	v_add_u32_e32 v81, v80, v225
	global_load_dwordx4 v[136:139], v81, s[8:9] offset:16
	global_load_dwordx4 v[140:143], v81, s[8:9]
	v_add_u32_e32 v81, v80, v226
	global_load_dwordx4 v[144:147], v81, s[8:9] offset:16
	global_load_dwordx4 v[148:151], v81, s[8:9]
	v_add_u32_e32 v81, v80, v209
	global_load_dwordx4 v[152:155], v81, s[8:9] offset:16
	global_load_dwordx4 v[156:159], v81, s[8:9]
	v_add_u32_e32 v81, v80, v221
	global_load_dwordx4 v[160:163], v81, s[8:9] offset:16
	global_load_dwordx4 v[164:167], v81, s[8:9]
	v_add_u32_e32 v81, v80, v222
	global_load_dwordx4 v[168:171], v81, s[8:9] offset:16
	global_load_dwordx4 v[172:175], v81, s[8:9]
	v_add_u32_e32 v81, v80, v223
	global_load_dwordx4 v[232:235], v81, s[8:9] offset:16
	global_load_dwordx4 v[236:239], v81, s[8:9]
	v_add_u32_e32 v84, v80, v224
	global_load_dwordx4 v[80:83], v84, s[8:9] offset:16
	s_nop 0
	global_load_dwordx4 v[84:87], v84, s[8:9]
	v_lshlrev_b32_e32 v208, 1, v240
	s_waitcnt vmcnt(15)
; __device__ __forceinline__ unsigned pk2(float lo, float hi) { const f32x2_t v = {lo, hi}; const bf16x2_t b = __builtin_convertvector(v, bf16x2_t); return __builtin_bit_cast(unsigned, b); }
;     __device__ __forceinline__ void operator()(const f32x4 (&acc)[2][2][4][2], const pg8::Unit& u, int wr, int wc, int fr, int fq) const {
;     ...
;             for (int ai = 0; ai < 2; ++ai)
; #pragma unroll
;                 for (int m = 0; m < 4; ++m) { const unsigned off = (unsigned)((u.pm * 256 + ai * 128 + wr * 64 + m * 16 + fr) * D_MODEL + col);
;                     const f32x4 xm0 = xv[ai][m][0] + cg0 * acc[ai][bj][m][0], xm1 = xv[ai][m][1] + cg1 * acc[ai][bj][m][1];
;                     { u32x4 o; o.x = pk2(xm0.x, xm0.y); o.y = pk2(xm0.z, xm0.w); o.z = pk2(xm1.x, xm1.y); o.w = pk2(xm1.z, xm1.w); *(u32x4*)((char*)XM + off * 2u) = o; }
;                     ss[ai][m] += ((xm0.x * xm0.x + xm0.y * xm0.y) + (xm0.z * xm0.z + xm0.w * xm0.w)) + ((xm1.x * xm1.x + xm1.y * xm1.y) + (xm1.z * xm1.z + xm1.w * xm1.w));
;                     const f32x4 h0 = xm0 * ch0, h1 = xm1 * ch1;
;                     u32x4 o; o.x = pk2(h0.x, h0.y); o.y = pk2(h0.z, h0.w); o.z = pk2(h1.x, h1.y); o.w = pk2(h1.z, h1.w);
;                     *(u32x4*)((char*)XMG + off * 2u) = o; }
	v_pk_fma_f32 v[130:131], v[58:59], v[74:75], v[130:131]
	s_waitcnt vmcnt(14)
	v_pk_fma_f32 v[62:63], v[62:63], v[78:79], v[134:135]
	v_pk_fma_f32 v[60:61], v[60:61], v[76:77], v[132:133]
	v_pk_fma_f32 v[128:129], v[56:57], v[72:73], v[128:129]
	v_cvt_pk_bf16_f32 v56, v60, v61
	v_cvt_pk_bf16_f32 v57, v62, v63
	v_cvt_pk_bf16_f32 v58, v128, v129
	v_cvt_pk_bf16_f32 v59, v130, v131
	v_add_u32_e32 v132, v208, v228
	global_store_dwordx4 v132, v[56:59], s[16:17] sc1
	s_waitcnt vmcnt(13)
	v_pk_fma_f32 v[54:55], v[54:55], v[78:79], v[142:143]
	v_pk_fma_f32 v[52:53], v[52:53], v[76:77], v[140:141]
	v_mul_f32_e32 v56, v61, v61
	v_mul_f32_e32 v57, v63, v63
	v_fmac_f32_e32 v56, v60, v60
	v_fmac_f32_e32 v57, v62, v62
	v_add_f32_e32 v56, v56, v57
	v_mul_f32_e32 v57, v129, v129
	v_mul_f32_e32 v58, v131, v131
	v_fmac_f32_e32 v57, v128, v128
	v_fmac_f32_e32 v58, v130, v130
	v_add_f32_e32 v57, v57, v58
	v_add_f32_e32 v56, v56, v57
	v_add_f32_e32 v133, v229, v56
	v_pk_mul_f32 v[58:59], v[70:71], v[62:63]
	v_pk_mul_f32 v[56:57], v[68:69], v[60:61]
	v_pk_mul_f32 v[60:61], v[66:67], v[130:131]
	v_pk_mul_f32 v[62:63], v[64:65], v[128:129]
	v_cvt_pk_bf16_f32 v56, v56, v57
	v_cvt_pk_bf16_f32 v57, v58, v59
	v_cvt_pk_bf16_f32 v58, v62, v63
	v_cvt_pk_bf16_f32 v59, v60, v61
	v_pk_fma_f32 v[50:51], v[50:51], v[74:75], v[138:139]
	v_pk_fma_f32 v[48:49], v[48:49], v[72:73], v[136:137]
	global_store_dwordx4 v132, v[56:59], s[18:19] sc1
	v_add_u32_e32 v128, v208, v230
	v_pk_mul_f32 v[60:61], v[66:67], v[50:51]
	v_cvt_pk_bf16_f32 v56, v52, v53
	v_cvt_pk_bf16_f32 v57, v54, v55
	v_cvt_pk_bf16_f32 v58, v48, v49
	v_cvt_pk_bf16_f32 v59, v50, v51
	global_store_dwordx4 v128, v[56:59], s[16:17] sc1
	v_pk_mul_f32 v[62:63], v[64:65], v[48:49]
	s_waitcnt vmcnt(13)
	v_pk_fma_f32 v[46:47], v[46:47], v[78:79], v[150:151]
	v_pk_mul_f32 v[58:59], v[70:71], v[54:55]
	v_pk_mul_f32 v[56:57], v[68:69], v[52:53]
	v_pk_fma_f32 v[44:45], v[44:45], v[76:77], v[148:149]
	v_cvt_pk_bf16_f32 v56, v56, v57
	v_cvt_pk_bf16_f32 v57, v58, v59
	v_cvt_pk_bf16_f32 v58, v62, v63
	v_cvt_pk_bf16_f32 v59, v60, v61
	v_pk_fma_f32 v[42:43], v[42:43], v[74:75], v[146:147]
	v_pk_fma_f32 v[40:41], v[40:41], v[72:73], v[144:145]
	global_store_dwordx4 v128, v[56:59], s[18:19] sc1
	v_add_u32_e32 v128, v208, v242
	v_pk_mul_f32 v[60:61], v[66:67], v[42:43]
	v_cvt_pk_bf16_f32 v56, v44, v45
	v_cvt_pk_bf16_f32 v57, v46, v47
	v_cvt_pk_bf16_f32 v58, v40, v41
	v_cvt_pk_bf16_f32 v59, v42, v43
	global_store_dwordx4 v128, v[56:59], s[16:17] sc1
	v_pk_mul_f32 v[62:63], v[64:65], v[40:41]
	s_waitcnt vmcnt(13)
	v_pk_fma_f32 v[38:39], v[38:39], v[78:79], v[158:159]
	v_pk_mul_f32 v[58:59], v[70:71], v[46:47]
	v_pk_mul_f32 v[56:57], v[68:69], v[44:45]
	v_pk_fma_f32 v[36:37], v[36:37], v[76:77], v[156:157]
	v_cvt_pk_bf16_f32 v56, v56, v57
	v_cvt_pk_bf16_f32 v57, v58, v59
	v_cvt_pk_bf16_f32 v58, v62, v63
	v_cvt_pk_bf16_f32 v59, v60, v61
	v_pk_fma_f32 v[34:35], v[34:35], v[74:75], v[154:155]
	v_pk_fma_f32 v[32:33], v[32:33], v[72:73], v[152:153]
	global_store_dwordx4 v128, v[56:59], s[18:19] sc1
	v_add_u32_e32 v128, v208, v243
	v_pk_mul_f32 v[60:61], v[66:67], v[34:35]
	v_cvt_pk_bf16_f32 v56, v36, v37
	v_cvt_pk_bf16_f32 v57, v38, v39
	v_cvt_pk_bf16_f32 v58, v32, v33
	v_cvt_pk_bf16_f32 v59, v34, v35
	global_store_dwordx4 v128, v[56:59], s[16:17] sc1
	v_pk_mul_f32 v[62:63], v[64:65], v[32:33]
	s_waitcnt vmcnt(13)
; __device__ __forceinline__ unsigned pk2(float lo, float hi) { const f32x2_t v = {lo, hi}; const bf16x2_t b = __builtin_convertvector(v, bf16x2_t); return __builtin_bit_cast(unsigned, b); }
;     __device__ __forceinline__ void operator()(const f32x4 (&acc)[2][2][4][2], const pg8::Unit& u, int wr, int wc, int fr, int fq) const {
;     ...
;             for (int ai = 0; ai < 2; ++ai)
; #pragma unroll
;                 for (int m = 0; m < 4; ++m) { const unsigned off = (unsigned)((u.pm * 256 + ai * 128 + wr * 64 + m * 16 + fr) * D_MODEL + col);
;                     const f32x4 xm0 = xv[ai][m][0] + cg0 * acc[ai][bj][m][0], xm1 = xv[ai][m][1] + cg1 * acc[ai][bj][m][1];
;                     { u32x4 o; o.x = pk2(xm0.x, xm0.y); o.y = pk2(xm0.z, xm0.w); o.z = pk2(xm1.x, xm1.y); o.w = pk2(xm1.z, xm1.w); *(u32x4*)((char*)XM + off * 2u) = o; }
;                     ss[ai][m] += ((xm0.x * xm0.x + xm0.y * xm0.y) + (xm0.z * xm0.z + xm0.w * xm0.w)) + ((xm1.x * xm1.x + xm1.y * xm1.y) + (xm1.z * xm1.z + xm1.w * xm1.w));
;                     const f32x4 h0 = xm0 * ch0, h1 = xm1 * ch1;
;                     u32x4 o; o.x = pk2(h0.x, h0.y); o.y = pk2(h0.z, h0.w); o.z = pk2(h1.x, h1.y); o.w = pk2(h1.z, h1.w);
;                     *(u32x4*)((char*)XMG + off * 2u) = o; }
;         }
; #pragma unroll
;         for (int ai = 0; ai < 2; ++ai)
; #pragma unroll
;             for (int m = 0; m < 4; ++m) { const float t = rows_sum(ss[ai][m]);
;                 if (fq == 0) atomicAdd((float*)((char*)rowsq + (unsigned)(u.pm * 256 + ai * 128 + wr * 64 + m * 16 + fr) * 4u), t); }
	v_pk_fma_f32 v[30:31], v[30:31], v[78:79], v[166:167]
	v_pk_mul_f32 v[58:59], v[70:71], v[38:39]
	v_pk_mul_f32 v[56:57], v[68:69], v[36:37]
	v_pk_fma_f32 v[28:29], v[28:29], v[76:77], v[164:165]
	v_cvt_pk_bf16_f32 v56, v56, v57
	v_cvt_pk_bf16_f32 v57, v58, v59
	v_cvt_pk_bf16_f32 v58, v62, v63
	v_cvt_pk_bf16_f32 v59, v60, v61
	v_pk_fma_f32 v[26:27], v[26:27], v[74:75], v[162:163]
	v_pk_fma_f32 v[24:25], v[24:25], v[72:73], v[160:161]
	global_store_dwordx4 v128, v[56:59], s[18:19] sc1
	v_add_u32_e32 v128, v208, v244
	v_pk_mul_f32 v[60:61], v[66:67], v[26:27]
	v_cvt_pk_bf16_f32 v56, v28, v29
	v_cvt_pk_bf16_f32 v57, v30, v31
	v_cvt_pk_bf16_f32 v58, v24, v25
	v_cvt_pk_bf16_f32 v59, v26, v27
	global_store_dwordx4 v128, v[56:59], s[16:17] sc1
	v_pk_mul_f32 v[62:63], v[64:65], v[24:25]
	s_waitcnt vmcnt(13)
	v_pk_fma_f32 v[22:23], v[22:23], v[78:79], v[174:175]
	v_pk_mul_f32 v[58:59], v[70:71], v[30:31]
	v_pk_mul_f32 v[56:57], v[68:69], v[28:29]
	v_pk_fma_f32 v[20:21], v[20:21], v[76:77], v[172:173]
	v_cvt_pk_bf16_f32 v56, v56, v57
	v_cvt_pk_bf16_f32 v57, v58, v59
	v_cvt_pk_bf16_f32 v58, v62, v63
	v_cvt_pk_bf16_f32 v59, v60, v61
	v_pk_fma_f32 v[18:19], v[18:19], v[74:75], v[170:171]
	v_pk_fma_f32 v[16:17], v[16:17], v[72:73], v[168:169]
	global_store_dwordx4 v128, v[56:59], s[18:19] sc1
	v_add_u32_e32 v128, v208, v245
	v_pk_mul_f32 v[60:61], v[66:67], v[18:19]
	v_cvt_pk_bf16_f32 v56, v20, v21
	v_cvt_pk_bf16_f32 v57, v22, v23
	v_cvt_pk_bf16_f32 v58, v16, v17
	v_cvt_pk_bf16_f32 v59, v18, v19
	global_store_dwordx4 v128, v[56:59], s[16:17] sc1
	v_pk_mul_f32 v[62:63], v[64:65], v[16:17]
	s_waitcnt vmcnt(13)
	v_pk_fma_f32 v[14:15], v[14:15], v[78:79], v[238:239]
	v_pk_mul_f32 v[58:59], v[70:71], v[22:23]
	v_pk_mul_f32 v[56:57], v[68:69], v[20:21]
	v_pk_fma_f32 v[12:13], v[12:13], v[76:77], v[236:237]
	v_cvt_pk_bf16_f32 v56, v56, v57
	v_cvt_pk_bf16_f32 v57, v58, v59
	v_cvt_pk_bf16_f32 v58, v62, v63
	v_cvt_pk_bf16_f32 v59, v60, v61
	v_pk_fma_f32 v[10:11], v[10:11], v[74:75], v[234:235]
	v_pk_fma_f32 v[8:9], v[8:9], v[72:73], v[232:233]
	global_store_dwordx4 v128, v[56:59], s[18:19] sc1
	v_add_u32_e32 v128, v208, v246
	v_pk_mul_f32 v[60:61], v[66:67], v[10:11]
	v_cvt_pk_bf16_f32 v56, v12, v13
	v_cvt_pk_bf16_f32 v57, v14, v15
	v_cvt_pk_bf16_f32 v58, v8, v9
	v_cvt_pk_bf16_f32 v59, v10, v11
	global_store_dwordx4 v128, v[56:59], s[16:17] sc1
	v_pk_mul_f32 v[62:63], v[64:65], v[8:9]
	s_waitcnt vmcnt(13)
	v_pk_fma_f32 v[6:7], v[6:7], v[78:79], v[86:87]
	v_pk_mul_f32 v[58:59], v[70:71], v[14:15]
	v_pk_mul_f32 v[56:57], v[68:69], v[12:13]
	v_pk_fma_f32 v[4:5], v[4:5], v[76:77], v[84:85]
	v_cvt_pk_bf16_f32 v56, v56, v57
	v_cvt_pk_bf16_f32 v57, v58, v59
	v_cvt_pk_bf16_f32 v58, v62, v63
	v_cvt_pk_bf16_f32 v59, v60, v61
	v_pk_fma_f32 v[2:3], v[2:3], v[74:75], v[82:83]
	v_pk_fma_f32 v[0:1], v[0:1], v[72:73], v[80:81]
	global_store_dwordx4 v128, v[56:59], s[18:19] sc1
	v_add_u32_e32 v72, v208, v247
	v_pk_mul_f32 v[60:61], v[66:67], v[2:3]
	v_cvt_pk_bf16_f32 v56, v4, v5
	v_cvt_pk_bf16_f32 v57, v6, v7
	v_cvt_pk_bf16_f32 v58, v0, v1
	v_cvt_pk_bf16_f32 v59, v2, v3
	global_store_dwordx4 v72, v[56:59], s[16:17] sc1
	v_pk_mul_f32 v[62:63], v[64:65], v[0:1]
	s_nop 0
	v_pk_mul_f32 v[58:59], v[70:71], v[6:7]
	v_pk_mul_f32 v[56:57], v[68:69], v[4:5]
	s_nop 0
	v_cvt_pk_bf16_f32 v56, v56, v57
	v_cvt_pk_bf16_f32 v57, v58, v59
	v_cvt_pk_bf16_f32 v58, v62, v63
	v_cvt_pk_bf16_f32 v59, v60, v61
	global_store_dwordx4 v72, v[56:59], s[18:19] sc1
	s_nop 1
	v_mov_b32_e32 v57, v133
	s_nop 1
	v_permlane32_swap_b32_e32 v133, v57
	v_add_f32_e32 v57, v133, v57
	v_mov_b32_e32 v58, v57
	v_add_u32_e32 v56, s23, v220
	s_nop 0
	v_permlane16_swap_b32_e32 v57, v58
	s_and_saveexec_b64 s[30:31], vcc
	s_cbranch_execz .LBB0_685
	v_add_f32_e32 v57, v57, v58
	v_lshlrev_b32_e32 v58, 2, v56
	global_atomic_add_f32 v58, v57, s[20:21]

;     __host__ __device__ bool next(int i, Unit& u) const { const long L = (long)i * G + c; if (L >= maxL) return false; return unit_of(L, u); }
; #define LAS __attribute__((address_space(3)))
; __device__ __forceinline__ unsigned pk2(float lo, float hi) { const f32x2_t v = {lo, hi}; const bf16x2_t b = __builtin_convertvector(v, bf16x2_t); return __builtin_bit_cast(unsigned, b); }
; __device__ __forceinline__ float siluf_(float x) { return x * __builtin_amdgcn_rcpf(1.0f + __expf(-x)); }
;     __device__ bool next(int i, pg8::Unit& u) const { if (!pg8::StaticOrder::next(i >> 1, u)) return false; u.br = i & 1; return true; }
; __device__ __forceinline__ f32x4 ror1_4(const f32x4 v) { return (f32x4){dpp_ror1(v.x), dpp_ror1(v.y), dpp_ror1(v.z), dpp_ror1(v.w)}; }
; __device__ __forceinline__ f32x4 rol1_4(const f32x4 v) { return (f32x4){dpp_rol1(v.x), dpp_rol1(v.y), dpp_rol1(v.z), dpp_rol1(v.w)}; }
;     __device__ __forceinline__ void operator()(const f32x4 (&acc_c)[2][2][4][2], const pg8::Unit& u, int wr, int wc, int fr, int fq) const {
;     ...
;             for (int m = 0; m < 4; ++m) { u32x4 o;
; #pragma unroll
;                 for (int n = 0; n < 2; ++n) { const f32x4 cur = acc[0][0][m][n];
;                     f32x4 pu, nd;
;                     if (m > 0) pu = ror1_4(acc[0][0][m > 0 ? m - 1 : 0][n]); else pu = (bi > 0) ? *(const LAS f32x4*)(X + ((bi - 1) * 2 + 1) * 128 + cl + 4 * n) : (f32x4){0.f, 0.f, 0.f, 0.f};
;                     if (m < 3) nd = rol1_4(acc[0][0][m < 3 ? m + 1 : 3][n]); else nd = (bi < 1) ? *(const LAS f32x4*)(X + ((bi + 1) * 2 + 0) * 128 + cl + 4 * n) : (f32x4){0.f, 0.f, 0.f, 0.f};
;                     const f32x4 ps = ror1_4(cur), ns = rol1_4(cur);
;                     const f32x4 prev = (fr > 0) ? ps : pu, next = (fr < 15) ? ns : nd;
;                     const f32x4 uu = w0[n] * prev + w1[n] * cur + w2[n] * next + cbv[n]; const f32x4 gt = acc[0][1][m][n];
;                     f32x4 r; r.x = siluf_(uu.x) * gt.x; r.y = siluf_(uu.y) * gt.y; r.z = siluf_(uu.z) * gt.z; r.w = siluf_(uu.w) * gt.w;
;                     if (n == 0) { o.x = pk2(r.x, r.y); o.y = pk2(r.z, r.w); } else { o.z = pk2(r.x, r.y); o.w = pk2(r.z, r.w); } }
;                 const int rh = wr * 64 + m * 16 + fr;
;                 if (rh != 0 && rh != 127) *(u32x4*)(ACT + (size_t)(u.pm * 256 + half * 128 + rh) * FFN + ch0) = o; } }
.LBB0_780:
	v_mov_b32_e32 v146, v128
	v_mov_b32_e32 v147, v128
	v_pk_fma_f32 v[40:41], v[40:41], v[128:129], v[92:93]
	v_pk_fma_f32 v[48:49], v[48:49], v[128:129], v[88:89]
	v_mov_b32_e32 v128, v130
	v_mov_b32_e32 v129, v130
	v_pk_fma_f32 v[42:43], v[42:43], v[146:147], v[94:95]
	v_or_b32_e32 v127, s25, v132
	v_lshl_add_u64 v[100:101], v[120:121], 1, s[14:15]
	s_mov_b64 s[10:11], 0x14342000
	v_pk_fma_f32 v[50:51], v[50:51], v[146:147], v[90:91]
	v_pk_fma_f32 v[98:99], v[98:99], v[128:129], v[106:107]
	v_pk_fma_f32 v[128:129], v[96:97], v[130:131], v[104:105]
	s_lshl_b32 s25, s4, 7
	v_lshl_add_u64 v[100:101], v[100:101], 0, s[10:11]
	v_mov_b32_dpp v96, v128 row_ror:15 row_mask:0xf bank_mask:0xf
	v_mov_b32_dpp v146, v129 row_ror:15 row_mask:0xf bank_mask:0xf
	v_mov_b32_dpp v147, v98 row_ror:15 row_mask:0xf bank_mask:0xf
	v_mov_b32_dpp v148, v99 row_ror:15 row_mask:0xf bank_mask:0xf
	v_mov_b32_dpp v152, v16 row_ror:1 row_mask:0xf bank_mask:0xf
	v_mov_b32_dpp v153, v17 row_ror:1 row_mask:0xf bank_mask:0xf
	v_mov_b32_dpp v154, v18 row_ror:1 row_mask:0xf bank_mask:0xf
	v_mov_b32_dpp v155, v19 row_ror:1 row_mask:0xf bank_mask:0xf
	v_mov_b32_dpp v149, v16 row_ror:15 row_mask:0xf bank_mask:0xf
	v_mov_b32_dpp v150, v17 row_ror:15 row_mask:0xf bank_mask:0xf
	v_mov_b32_dpp v151, v18 row_ror:15 row_mask:0xf bank_mask:0xf
	v_mov_b32_dpp v97, v19 row_ror:15 row_mask:0xf bank_mask:0xf
	v_cmp_ne_u32_e32 vcc, 0, v127
	s_and_saveexec_b64 s[10:11], vcc
	s_xor_b64 s[10:11], exec, s[10:11]
	s_cbranch_execz .LBB0_782
	s_waitcnt lgkmcnt(0)
	v_cndmask_b32_e64 v119, v145, v119, s[8:9]
	v_cndmask_b32_e64 v118, v143, v118, s[8:9]
	s_waitcnt vmcnt(0)
	v_pk_mul_f32 v[118:119], v[58:59], v[118:119]
	v_cndmask_b32_e64 v143, v140, v136, s[6:7]
	v_pk_fma_f32 v[118:119], v[22:23], v[66:67], v[118:119]
	v_cndmask_b32_e64 v137, v141, v137, s[6:7]
	v_cndmask_b32_e64 v136, v139, v135, s[6:7]
	v_pk_fma_f32 v[118:119], v[54:55], v[136:137], v[118:119]
	v_cndmask_b32_e64 v116, v142, v116, s[8:9]
	v_pk_add_f32 v[118:119], v[46:47], v[118:119]
	v_cndmask_b32_e64 v142, v138, v134, s[6:7]
	v_mul_f32_e32 v134, 0xbfb8aa3b, v119
	v_cndmask_b32_e64 v117, v144, v117, s[8:9]
	v_exp_f32_e32 v134, v134
	v_mul_f32_e32 v135, 0xbfb8aa3b, v118
	v_pk_mul_f32 v[116:117], v[56:57], v[116:117]
	v_exp_f32_e32 v136, v135
	v_pk_fma_f32 v[116:117], v[20:21], v[64:65], v[116:117]
	v_add_f32_e32 v134, 1.0, v134
	v_pk_fma_f32 v[116:117], v[52:53], v[142:143], v[116:117]
	v_rcp_f32_e32 v135, v134
	v_pk_add_f32 v[116:117], v[44:45], v[116:117]
	v_add_f32_e32 v134, 1.0, v136
	v_mul_f32_e32 v136, 0xbfb8aa3b, v117
	v_exp_f32_e32 v136, v136
	v_mul_f32_e32 v137, 0xbfb8aa3b, v116
	v_exp_f32_e32 v138, v137
	v_rcp_f32_e32 v134, v134
	v_add_f32_e32 v136, 1.0, v136
	v_rcp_f32_e32 v137, v136
	v_add_f32_e32 v136, 1.0, v138
	v_rcp_f32_e32 v136, v136
	v_pk_mul_f32 v[118:119], v[118:119], v[134:135]
	v_cndmask_b32_e64 v113, v153, v113, s[8:9]
	v_cndmask_b32_e64 v112, v152, v112, s[8:9]
	v_pk_mul_f32 v[116:117], v[116:117], v[136:137]
	v_pk_mul_f32 v[118:119], v[42:43], v[118:119]
	v_pk_mul_f32 v[116:117], v[40:41], v[116:117]
	v_cndmask_b32_e64 v115, v155, v115, s[8:9]
	v_cndmask_b32_e64 v114, v154, v114, s[8:9]
	v_pk_mul_f32 v[112:113], v[32:33], v[112:113]
	v_cvt_pk_bf16_f32 v116, v116, v117
	v_cvt_pk_bf16_f32 v117, v118, v119
	v_pk_mul_f32 v[114:115], v[34:35], v[114:115]
	v_pk_fma_f32 v[112:113], v[16:17], v[36:37], v[112:113]
	v_cndmask_b32_e64 v119, v97, v148, s[6:7]
	v_cndmask_b32_e64 v97, v150, v146, s[6:7]
	v_cndmask_b32_e64 v96, v149, v96, s[6:7]
	v_pk_fma_f32 v[114:115], v[18:19], v[38:39], v[114:115]
	v_cndmask_b32_e64 v118, v151, v147, s[6:7]
	v_pk_fma_f32 v[96:97], v[28:29], v[96:97], v[112:113]
	v_pk_fma_f32 v[112:113], v[30:31], v[118:119], v[114:115]
	v_pk_add_f32 v[96:97], v[24:25], v[96:97]
	v_pk_add_f32 v[112:113], v[26:27], v[112:113]
	v_mul_f32_e32 v114, 0xbfb8aa3b, v96
	v_mul_f32_e32 v115, 0xbfb8aa3b, v97
	v_exp_f32_e32 v114, v114
	v_exp_f32_e32 v115, v115
	v_mul_f32_e32 v118, 0xbfb8aa3b, v112
	v_exp_f32_e32 v118, v118
	v_mul_f32_e32 v119, 0xbfb8aa3b, v113
	v_exp_f32_e32 v119, v119
	v_add_f32_e32 v114, 1.0, v114
	v_add_f32_e32 v115, 1.0, v115
	v_rcp_f32_e32 v114, v114
	v_rcp_f32_e32 v115, v115
	v_add_f32_e32 v118, 1.0, v118
	v_rcp_f32_e32 v134, v118
	v_add_f32_e32 v118, 1.0, v119
	v_rcp_f32_e32 v135, v118
	v_pk_mul_f32 v[96:97], v[96:97], v[114:115]
	s_lshl_b32 s31, s12, 8
	v_pk_mul_f32 v[96:97], v[48:49], v[96:97]
	s_or_b32 s31, s31, s25
	v_cvt_pk_bf16_f32 v118, v96, v97
	v_pk_mul_f32 v[96:97], v[112:113], v[134:135]
	s_movk_i32 s34, 0x2c00
	v_pk_mul_f32 v[96:97], v[50:51], v[96:97]
	s_nop 0
	v_cvt_pk_bf16_f32 v119, v96, v97
	v_add_u32_e32 v96, s31, v127
	v_mad_i64_i32 v[96:97], s[34:35], v96, s34, v[100:101]
	global_store_dwordx4 v[96:97], v[116:119], off sc1
;     __device__ __forceinline__ void operator()(const f32x4 (&acc_c)[2][2][4][2], const pg8::Unit& u, int wr, int wc, int fr, int fq) const {
;     ...
;         for (int m = 0; m < 4; ++m) { const int rl = half * 128 + wr * 64 + m * 16 + fr;
;             const float rstd = __builtin_amdgcn_rsqf(rsq[rl] * (1.0f / D_MODEL) + EPS);
; #pragma unroll
;             for (int bj = 0; bj < 2; ++bj)
; #pragma unroll
;                 for (int n = 0; n < 2; ++n) acc[0][bj][m][n] = acc[0][bj][m][n] * rstd + *(const LAS f32x4*)(bias2 + bj * 128 + cl + 4 * n); }
;         f32x4 w0[2], w1[2], w2[2], cbv[2];
; #pragma unroll
;         for (int n = 0; n < 2; ++n) { w0[n] = *(const f32x4*)(cw + ch0 + 4 * n); w1[n] = *(const f32x4*)(cw + FFN + ch0 + 4 * n); w2[n] = *(const f32x4*)(cw + 2 * FFN + ch0 + 4 * n); cbv[n] = *(const f32x4*)(cb + ch0 + 4 * n); }
;         { const int bi = wr;
;             if (fr == 0) {
; #pragma unroll
;                 for (int n = 0; n < 2; ++n) *(LAS f32x4*)(X + (bi * 2 + 0) * 128 + cl + 4 * n) = acc[0][0][0][n]; }
;             if (fr == 15) {
; #pragma unroll
;                 for (int n = 0; n < 2; ++n) *(LAS f32x4*)(X + (bi * 2 + 1) * 128 + cl + 4 * n) = acc[0][0][3][n]; } }
;         asm volatile("s_waitcnt lgkmcnt(0)" ::: "memory"); __builtin_amdgcn_s_barrier(); asm volatile("" ::: "memory");
;         { const int bi = wr;
; #pragma unroll
;             for (int m = 0; m < 4; ++m) { u32x4 o;
; #pragma unroll
;                 for (int n = 0; n < 2; ++n) { const f32x4 cur = acc[0][0][m][n];
;                     f32x4 pu, nd;
;                     if (m > 0) pu = ror1_4(acc[0][0][m > 0 ? m - 1 : 0][n]); else pu = (bi > 0) ? *(const LAS f32x4*)(X + ((bi - 1) * 2 + 1) * 128 + cl + 4 * n) : (f32x4){0.f, 0.f, 0.f, 0.f};
;                     if (m < 3) nd = rol1_4(acc[0][0][m < 3 ? m + 1 : 3][n]); else nd = (bi < 1) ? *(const LAS f32x4*)(X + ((bi + 1) * 2 + 0) * 128 + cl + 4 * n) : (f32x4){0.f, 0.f, 0.f, 0.f};
;                     const f32x4 ps = ror1_4(cur), ns = rol1_4(cur);
;                     const f32x4 prev = (fr > 0) ? ps : pu, next = (fr < 15) ? ns : nd;
;                     const f32x4 uu = w0[n] * prev + w1[n] * cur + w2[n] * next + cbv[n]; const f32x4 gt = acc[0][1][m][n];
;                     f32x4 r; r.x = siluf_(uu.x) * gt.x; r.y = siluf_(uu.y) * gt.y; r.z = siluf_(uu.z) * gt.z; r.w = siluf_(uu.w) * gt.w;
.LBB0_782:
	s_or_saveexec_b64 s[10:11], s[10:11]
	s_add_i32 s30, s30, 0x20000
	s_waitcnt lgkmcnt(0)
	v_mov_b32_e32 v112, s31
	s_xor_b64 exec, exec, s[10:11]
	s_lshl_b32 s31, s12, 8
	s_or_b32 s25, s25, s31
	v_mov_b32_e32 v112, s25
	s_or_b64 exec, exec, s[10:11]
	v_mov_b32_e32 v114, v130
	v_mov_b32_e32 v115, v130
	v_pk_fma_f32 v[116:117], v[78:79], v[114:115], v[94:95]
	v_mov_b32_e32 v78, 0x358637bd
	v_fmac_f32_e32 v78, 0x3a000000, v126
	v_rsq_f32_e32 v118, v78
	v_pk_fma_f32 v[134:135], v[76:77], v[130:131], v[92:93]
	v_pk_fma_f32 v[130:131], v[72:73], v[130:131], v[88:89]
	v_pk_fma_f32 v[114:115], v[74:75], v[114:115], v[90:91]
	v_pk_fma_f32 v[78:79], v[84:85], v[118:119], v[108:109] op_sel_hi:[1,0,1]
	v_pk_fma_f32 v[72:73], v[82:83], v[118:119], v[106:107] op_sel_hi:[1,0,1]
	v_mov_b32_dpp v82, v20 row_ror:1 row_mask:0xf bank_mask:0xf
	v_mov_b32_dpp v83, v21 row_ror:1 row_mask:0xf bank_mask:0xf
	v_mov_b32_dpp v107, v124 row_ror:1 row_mask:0xf bank_mask:0xf
	v_mov_b32_dpp v108, v125 row_ror:1 row_mask:0xf bank_mask:0xf
	v_pk_fma_f32 v[76:77], v[86:87], v[118:119], v[110:111] op_sel_hi:[1,0,1]
	v_pk_fma_f32 v[74:75], v[80:81], v[118:119], v[104:105] op_sel_hi:[1,0,1]
	v_cndmask_b32_e64 v83, v108, v83, s[8:9]
	v_cndmask_b32_e64 v82, v107, v82, s[8:9]
	v_mov_b32_dpp v80, v22 row_ror:1 row_mask:0xf bank_mask:0xf
	v_mov_b32_dpp v81, v23 row_ror:1 row_mask:0xf bank_mask:0xf
	v_mov_b32_dpp v97, v78 row_ror:15 row_mask:0xf bank_mask:0xf
	v_mov_b32_dpp v104, v79 row_ror:15 row_mask:0xf bank_mask:0xf
	v_mov_b32_dpp v109, v102 row_ror:1 row_mask:0xf bank_mask:0xf
	v_mov_b32_dpp v110, v103 row_ror:1 row_mask:0xf bank_mask:0xf
	v_mov_b32_dpp v86, v124 row_ror:15 row_mask:0xf bank_mask:0xf
	v_mov_b32_dpp v87, v125 row_ror:15 row_mask:0xf bank_mask:0xf
	s_waitcnt vmcnt(0)
	v_pk_mul_f32 v[82:83], v[56:57], v[82:83]
	v_cndmask_b32_e64 v81, v110, v81, s[8:9]
	v_cndmask_b32_e64 v80, v109, v80, s[8:9]
	v_pk_fma_f32 v[82:83], v[64:65], v[124:125], v[82:83]
	v_cndmask_b32_e64 v87, v87, v104, s[6:7]
	v_cndmask_b32_e64 v86, v86, v97, s[6:7]
	v_mov_b32_dpp v105, v76 row_ror:15 row_mask:0xf bank_mask:0xf
	v_mov_b32_dpp v106, v77 row_ror:15 row_mask:0xf bank_mask:0xf
	v_mov_b32_dpp v84, v102 row_ror:15 row_mask:0xf bank_mask:0xf
	v_mov_b32_dpp v85, v103 row_ror:15 row_mask:0xf bank_mask:0xf
	v_pk_mul_f32 v[80:81], v[58:59], v[80:81]
	v_pk_fma_f32 v[82:83], v[52:53], v[86:87], v[82:83]
	v_pk_fma_f32 v[80:81], v[66:67], v[102:103], v[80:81]
	v_cndmask_b32_e64 v85, v85, v106, s[6:7]
	v_cndmask_b32_e64 v84, v84, v105, s[6:7]
	v_pk_add_f32 v[82:83], v[44:45], v[82:83]
	v_pk_fma_f32 v[80:81], v[54:55], v[84:85], v[80:81]
	v_mul_f32_e32 v84, 0xbfb8aa3b, v82
	v_exp_f32_e32 v86, v84
	v_mul_f32_e32 v84, 0xbfb8aa3b, v83
	v_exp_f32_e32 v87, v84
	v_pk_add_f32 v[84:85], v[46:47], v[80:81]
	v_add_f32_e32 v80, 1.0, v86
	v_mul_f32_e32 v86, 0xbfb8aa3b, v84
	v_add_f32_e32 v81, 1.0, v87
	v_mul_f32_e32 v87, 0xbfb8aa3b, v85
	v_exp_f32_e32 v86, v86
	v_exp_f32_e32 v87, v87
	v_rcp_f32_e32 v80, v80
	v_rcp_f32_e32 v81, v81
	v_add_f32_e32 v86, 1.0, v86
	v_add_f32_e32 v87, 1.0, v87
	v_rcp_f32_e32 v86, v86
	v_rcp_f32_e32 v87, v87
	v_lshl_add_u32 v113, v123, 2, s30
	v_pk_fma_f32 v[70:71], v[70:71], v[118:119], v[94:95] op_sel_hi:[1,0,1]
	v_pk_fma_f32 v[68:69], v[68:69], v[118:119], v[92:93] op_sel_hi:[1,0,1]
	v_pk_fma_f32 v[62:63], v[62:63], v[118:119], v[90:91] op_sel_hi:[1,0,1]
	v_pk_fma_f32 v[60:61], v[60:61], v[118:119], v[88:89] op_sel_hi:[1,0,1]
	v_pk_mul_f32 v[80:81], v[82:83], v[80:81]
	v_pk_mul_f32 v[82:83], v[84:85], v[86:87]
	v_mov_b32_dpp v111, v16 row_ror:1 row_mask:0xf bank_mask:0xf
	v_mov_b32_dpp v118, v17 row_ror:1 row_mask:0xf bank_mask:0xf
	v_mov_b32_dpp v119, v18 row_ror:1 row_mask:0xf bank_mask:0xf
	v_mov_b32_dpp v123, v19 row_ror:1 row_mask:0xf bank_mask:0xf
	v_mov_b32_dpp v139, v128 row_ror:1 row_mask:0xf bank_mask:0xf
	v_mov_b32_dpp v140, v129 row_ror:1 row_mask:0xf bank_mask:0xf
	v_mov_b32_dpp v141, v98 row_ror:1 row_mask:0xf bank_mask:0xf
	v_mov_b32_dpp v142, v99 row_ror:1 row_mask:0xf bank_mask:0xf
	v_pk_mul_f32 v[80:81], v[134:135], v[80:81]
	v_pk_mul_f32 v[82:83], v[116:117], v[82:83]
	v_cvt_pk_bf16_f32 v80, v80, v81
	v_cvt_pk_bf16_f32 v81, v82, v83
	v_cndmask_b32_e64 v83, v142, v123, s[8:9]
	v_cndmask_b32_e64 v82, v141, v119, s[8:9]
	v_cndmask_b32_e64 v85, v140, v118, s[8:9]
	v_cndmask_b32_e64 v84, v139, v111, s[8:9]
	v_mov_b32_dpp v126, v74 row_ror:15 row_mask:0xf bank_mask:0xf
	v_mov_b32_dpp v136, v75 row_ror:15 row_mask:0xf bank_mask:0xf
	v_mov_b32_dpp v143, v128 row_ror:15 row_mask:0xf bank_mask:0xf
	v_mov_b32_dpp v144, v129 row_ror:15 row_mask:0xf bank_mask:0xf
	v_pk_mul_f32 v[84:85], v[32:33], v[84:85]
	v_pk_mul_f32 v[82:83], v[34:35], v[82:83]
	v_mov_b32_dpp v145, v98 row_ror:15 row_mask:0xf bank_mask:0xf
	v_mov_b32_dpp v146, v99 row_ror:15 row_mask:0xf bank_mask:0xf
	v_pk_fma_f32 v[82:83], v[98:99], v[38:39], v[82:83]
	v_pk_fma_f32 v[84:85], v[128:129], v[36:37], v[84:85]
	v_cndmask_b32_e64 v99, v144, v136, s[6:7]
	v_cndmask_b32_e64 v98, v143, v126, s[6:7]
	v_mov_b32_dpp v137, v72 row_ror:15 row_mask:0xf bank_mask:0xf
	v_mov_b32_dpp v138, v73 row_ror:15 row_mask:0xf bank_mask:0xf
	v_pk_fma_f32 v[84:85], v[28:29], v[98:99], v[84:85]
	v_cndmask_b32_e64 v87, v146, v138, s[6:7]
;     __host__ __device__ bool next(int i, Unit& u) const { const long L = (long)i * G + c; if (L >= maxL) return false; return unit_of(L, u); }
; #define LAS __attribute__((address_space(3)))
; __device__ __forceinline__ unsigned pk2(float lo, float hi) { const f32x2_t v = {lo, hi}; const bf16x2_t b = __builtin_convertvector(v, bf16x2_t); return __builtin_bit_cast(unsigned, b); }
; __device__ __forceinline__ float siluf_(float x) { return x * __builtin_amdgcn_rcpf(1.0f + __expf(-x)); }
;     __device__ bool next(int i, pg8::Unit& u) const { if (!pg8::StaticOrder::next(i >> 1, u)) return false; u.br = i & 1; return true; }
; __device__ __forceinline__ f32x4 ror1_4(const f32x4 v) { return (f32x4){dpp_ror1(v.x), dpp_ror1(v.y), dpp_ror1(v.z), dpp_ror1(v.w)}; }
; __device__ __forceinline__ f32x4 rol1_4(const f32x4 v) { return (f32x4){dpp_rol1(v.x), dpp_rol1(v.y), dpp_rol1(v.z), dpp_rol1(v.w)}; }
;     __device__ __forceinline__ void operator()(const f32x4 (&acc_c)[2][2][4][2], const pg8::Unit& u, int wr, int wc, int fr, int fq) const {
;     ...
;             for (int m = 0; m < 4; ++m) { u32x4 o;
; #pragma unroll
;                 for (int n = 0; n < 2; ++n) { const f32x4 cur = acc[0][0][m][n];
;                     f32x4 pu, nd;
;                     if (m > 0) pu = ror1_4(acc[0][0][m > 0 ? m - 1 : 0][n]); else pu = (bi > 0) ? *(const LAS f32x4*)(X + ((bi - 1) * 2 + 1) * 128 + cl + 4 * n) : (f32x4){0.f, 0.f, 0.f, 0.f};
;                     if (m < 3) nd = rol1_4(acc[0][0][m < 3 ? m + 1 : 3][n]); else nd = (bi < 1) ? *(const LAS f32x4*)(X + ((bi + 1) * 2 + 0) * 128 + cl + 4 * n) : (f32x4){0.f, 0.f, 0.f, 0.f};
;                     const f32x4 ps = ror1_4(cur), ns = rol1_4(cur);
;                     const f32x4 prev = (fr > 0) ? ps : pu, next = (fr < 15) ? ns : nd;
;                     const f32x4 uu = w0[n] * prev + w1[n] * cur + w2[n] * next + cbv[n]; const f32x4 gt = acc[0][1][m][n];
;                     f32x4 r; r.x = siluf_(uu.x) * gt.x; r.y = siluf_(uu.y) * gt.y; r.z = siluf_(uu.z) * gt.z; r.w = siluf_(uu.w) * gt.w;
;                     if (n == 0) { o.x = pk2(r.x, r.y); o.y = pk2(r.z, r.w); } else { o.z = pk2(r.x, r.y); o.w = pk2(r.z, r.w); } }
;                 const int rh = wr * 64 + m * 16 + fr;
;                 if (rh != 0 && rh != 127) *(u32x4*)(ACT + (size_t)(u.pm * 256 + half * 128 + rh) * FFN + ch0) = o; } }
	v_cndmask_b32_e64 v86, v145, v137, s[6:7]
	v_pk_add_f32 v[84:85], v[24:25], v[84:85]
	v_pk_fma_f32 v[82:83], v[30:31], v[86:87], v[82:83]
	v_mul_f32_e32 v86, 0xbfb8aa3b, v84
	v_exp_f32_e32 v98, v86
	v_mul_f32_e32 v86, 0xbfb8aa3b, v85
	v_exp_f32_e32 v99, v86
	v_pk_add_f32 v[86:87], v[26:27], v[82:83]
	v_add_f32_e32 v82, 1.0, v98
	v_mul_f32_e32 v98, 0xbfb8aa3b, v86
	v_add_f32_e32 v83, 1.0, v99
	v_mul_f32_e32 v99, 0xbfb8aa3b, v87
	v_exp_f32_e32 v98, v98
	v_exp_f32_e32 v99, v99
	v_rcp_f32_e32 v82, v82
	v_rcp_f32_e32 v83, v83
	v_add_f32_e32 v98, 1.0, v98
	v_add_f32_e32 v99, 1.0, v99
	v_rcp_f32_e32 v98, v98
	v_rcp_f32_e32 v99, v99
	v_pk_mul_f32 v[82:83], v[84:85], v[82:83]
	s_movk_i32 s25, 0x2c00
	v_pk_mul_f32 v[82:83], v[130:131], v[82:83]
	v_pk_mul_f32 v[84:85], v[86:87], v[98:99]
	v_add_u32_e32 v98, v112, v127
	v_pk_mul_f32 v[84:85], v[114:115], v[84:85]
	v_cvt_pk_bf16_f32 v82, v82, v83
	v_cvt_pk_bf16_f32 v83, v84, v85
	v_add_u32_e32 v84, 16, v98
	v_mad_i64_i32 v[84:85], s[30:31], v84, s25, v[100:101]
	global_store_dwordx4 v[84:85], v[80:83], off sc1
	s_nop 1
	v_mov_b32_dpp v81, v76 row_ror:1 row_mask:0xf bank_mask:0xf
	v_mov_b32_dpp v83, v77 row_ror:1 row_mask:0xf bank_mask:0xf
	v_mov_b32_dpp v80, v78 row_ror:1 row_mask:0xf bank_mask:0xf
	v_mov_b32_dpp v82, v79 row_ror:1 row_mask:0xf bank_mask:0xf
	v_cndmask_b32_e64 v85, v83, v110, s[8:9]
	v_cndmask_b32_e64 v84, v81, v109, s[8:9]
	v_mov_b32_dpp v103, v14 row_ror:15 row_mask:0xf bank_mask:0xf
	v_mov_b32_dpp v111, v15 row_ror:15 row_mask:0xf bank_mask:0xf
	v_cndmask_b32_e64 v87, v82, v108, s[8:9]
	v_cndmask_b32_e64 v86, v80, v107, s[8:9]
	v_pk_mul_f32 v[84:85], v[58:59], v[84:85]
	v_mov_b32_dpp v99, v12 row_ror:15 row_mask:0xf bank_mask:0xf
	v_mov_b32_dpp v102, v13 row_ror:15 row_mask:0xf bank_mask:0xf
	v_pk_mul_f32 v[86:87], v[56:57], v[86:87]
	v_pk_fma_f32 v[76:77], v[66:67], v[76:77], v[84:85]
	v_cndmask_b32_e64 v85, v106, v111, s[6:7]
	v_cndmask_b32_e64 v84, v105, v103, s[6:7]
	v_pk_fma_f32 v[78:79], v[64:65], v[78:79], v[86:87]
	v_cndmask_b32_e64 v87, v104, v102, s[6:7]
	v_cndmask_b32_e64 v86, v97, v99, s[6:7]
	v_pk_fma_f32 v[76:77], v[54:55], v[84:85], v[76:77]
	v_pk_fma_f32 v[78:79], v[52:53], v[86:87], v[78:79]
	v_pk_add_f32 v[76:77], v[46:47], v[76:77]
	v_pk_add_f32 v[78:79], v[44:45], v[78:79]
	v_mul_f32_e32 v86, 0xbfb8aa3b, v76
	v_mul_f32_e32 v87, 0xbfb8aa3b, v77
	v_mul_f32_e32 v84, 0xbfb8aa3b, v78
	v_mul_f32_e32 v85, 0xbfb8aa3b, v79
	v_exp_f32_e32 v86, v86
	v_exp_f32_e32 v87, v87
	v_exp_f32_e32 v84, v84
	v_exp_f32_e32 v85, v85
	v_add_f32_e32 v86, 1.0, v86
	v_add_f32_e32 v87, 1.0, v87
	v_add_f32_e32 v84, 1.0, v84
	v_add_f32_e32 v85, 1.0, v85
	v_rcp_f32_e32 v86, v86
	v_rcp_f32_e32 v87, v87
	v_rcp_f32_e32 v84, v84
	v_rcp_f32_e32 v85, v85
	v_pk_mul_f32 v[76:77], v[76:77], v[86:87]
	v_mov_b32_dpp v118, v74 row_ror:1 row_mask:0xf bank_mask:0xf
	v_mov_b32_dpp v119, v75 row_ror:1 row_mask:0xf bank_mask:0xf
	v_pk_mul_f32 v[78:79], v[78:79], v[84:85]
	v_pk_mul_f32 v[70:71], v[70:71], v[76:77]
	v_cndmask_b32_e64 v77, v119, v140, s[8:9]
	v_cndmask_b32_e64 v76, v118, v139, s[8:9]
	v_mov_b32_dpp v114, v8 row_ror:15 row_mask:0xf bank_mask:0xf
	v_mov_b32_dpp v115, v9 row_ror:15 row_mask:0xf bank_mask:0xf
	v_mov_b32_dpp v123, v72 row_ror:1 row_mask:0xf bank_mask:0xf
	v_mov_b32_dpp v124, v73 row_ror:1 row_mask:0xf bank_mask:0xf
	v_pk_mul_f32 v[68:69], v[68:69], v[78:79]
	v_pk_mul_f32 v[76:77], v[32:33], v[76:77]
	v_cvt_pk_bf16_f32 v68, v68, v69
	v_cvt_pk_bf16_f32 v69, v70, v71
	v_cndmask_b32_e64 v71, v124, v142, s[8:9]
	v_cndmask_b32_e64 v70, v123, v141, s[8:9]
	v_pk_fma_f32 v[76:77], v[36:37], v[74:75], v[76:77]
	v_cndmask_b32_e64 v85, v136, v115, s[6:7]
	v_cndmask_b32_e64 v84, v126, v114, s[6:7]
	v_mov_b32_dpp v116, v10 row_ror:15 row_mask:0xf bank_mask:0xf
	v_mov_b32_dpp v117, v11 row_ror:15 row_mask:0xf bank_mask:0xf
	v_pk_mul_f32 v[70:71], v[34:35], v[70:71]
	v_pk_fma_f32 v[76:77], v[28:29], v[84:85], v[76:77]
	v_pk_fma_f32 v[70:71], v[38:39], v[72:73], v[70:71]
	v_cndmask_b32_e64 v79, v138, v117, s[6:7]
	v_cndmask_b32_e64 v78, v137, v116, s[6:7]
	v_pk_add_f32 v[76:77], v[24:25], v[76:77]
	v_pk_fma_f32 v[70:71], v[30:31], v[78:79], v[70:71]
	v_mul_f32_e32 v78, 0xbfb8aa3b, v76
	v_exp_f32_e32 v84, v78
	v_mul_f32_e32 v78, 0xbfb8aa3b, v77
	v_exp_f32_e32 v85, v78
	v_pk_add_f32 v[78:79], v[26:27], v[70:71]
	v_add_f32_e32 v70, 1.0, v84
	v_mul_f32_e32 v84, 0xbfb8aa3b, v78
	v_add_f32_e32 v71, 1.0, v85
	v_mul_f32_e32 v85, 0xbfb8aa3b, v79
	v_exp_f32_e32 v84, v84
	v_exp_f32_e32 v85, v85
	v_rcp_f32_e32 v70, v70
	v_rcp_f32_e32 v71, v71
	v_add_f32_e32 v84, 1.0, v84
	v_add_f32_e32 v85, 1.0, v85
	v_rcp_f32_e32 v84, v84
	v_rcp_f32_e32 v85, v85
	v_pk_mul_f32 v[70:71], v[76:77], v[70:71]
	s_cmp_lt_i32 s5, 1
	v_pk_mul_f32 v[60:61], v[60:61], v[70:71]
	s_cselect_b64 s[10:11], -1, 0
	v_cvt_pk_bf16_f32 v70, v60, v61
	v_pk_mul_f32 v[60:61], v[78:79], v[84:85]
	v_mov_b32_e32 v96, 0
	v_pk_mul_f32 v[60:61], v[62:63], v[60:61]
	s_cmp_gt_i32 s5, 0
	v_cvt_pk_bf16_f32 v71, v60, v61
	v_add_u32_e32 v60, 32, v98
	v_mad_i64_i32 v[60:61], s[30:31], v60, s25, v[100:101]
	global_store_dwordx4 v[60:61], v[68:71], off sc1
	v_mov_b32_e32 v60, 0
	v_mov_b32_e32 v61, 0
	v_mov_b32_e32 v62, 0
	v_mov_b32_e32 v63, 0
	s_cbranch_scc1 .LBB0_786
	ds_read_b128 v[60:63], v113 offset:1024

;     __host__ __device__ bool next(int i, Unit& u) const { const long L = (long)i * G + c; if (L >= maxL) return false; return unit_of(L, u); }
; #define LAS __attribute__((address_space(3)))
; __device__ __forceinline__ unsigned pk2(float lo, float hi) { const f32x2_t v = {lo, hi}; const bf16x2_t b = __builtin_convertvector(v, bf16x2_t); return __builtin_bit_cast(unsigned, b); }
; __device__ __forceinline__ float siluf_(float x) { return x * __builtin_amdgcn_rcpf(1.0f + __expf(-x)); }
;     __device__ bool next(int i, pg8::Unit& u) const { if (!pg8::StaticOrder::next(i >> 1, u)) return false; u.br = i & 1; return true; }
; __device__ __forceinline__ f32x4 ror1_4(const f32x4 v) { return (f32x4){dpp_ror1(v.x), dpp_ror1(v.y), dpp_ror1(v.z), dpp_ror1(v.w)}; }
; __device__ __forceinline__ f32x4 rol1_4(const f32x4 v) { return (f32x4){dpp_rol1(v.x), dpp_rol1(v.y), dpp_rol1(v.z), dpp_rol1(v.w)}; }
;     __device__ __forceinline__ void operator()(const f32x4 (&acc_c)[2][2][4][2], const pg8::Unit& u, int wr, int wc, int fr, int fq) const {
;     ...
;             for (int m = 0; m < 4; ++m) { u32x4 o;
; #pragma unroll
;                 for (int n = 0; n < 2; ++n) { const f32x4 cur = acc[0][0][m][n];
;                     f32x4 pu, nd;
;                     if (m > 0) pu = ror1_4(acc[0][0][m > 0 ? m - 1 : 0][n]); else pu = (bi > 0) ? *(const LAS f32x4*)(X + ((bi - 1) * 2 + 1) * 128 + cl + 4 * n) : (f32x4){0.f, 0.f, 0.f, 0.f};
;                     if (m < 3) nd = rol1_4(acc[0][0][m < 3 ? m + 1 : 3][n]); else nd = (bi < 1) ? *(const LAS f32x4*)(X + ((bi + 1) * 2 + 0) * 128 + cl + 4 * n) : (f32x4){0.f, 0.f, 0.f, 0.f};
;                     const f32x4 ps = ror1_4(cur), ns = rol1_4(cur);
;                     const f32x4 prev = (fr > 0) ? ps : pu, next = (fr < 15) ? ns : nd;
;                     const f32x4 uu = w0[n] * prev + w1[n] * cur + w2[n] * next + cbv[n]; const f32x4 gt = acc[0][1][m][n];
;                     f32x4 r; r.x = siluf_(uu.x) * gt.x; r.y = siluf_(uu.y) * gt.y; r.z = siluf_(uu.z) * gt.z; r.w = siluf_(uu.w) * gt.w;
;                     if (n == 0) { o.x = pk2(r.x, r.y); o.y = pk2(r.z, r.w); } else { o.z = pk2(r.x, r.y); o.w = pk2(r.z, r.w); } }
;                 const int rh = wr * 64 + m * 16 + fr;
;                 if (rh != 0 && rh != 127) *(u32x4*)(ACT + (size_t)(u.pm * 256 + half * 128 + rh) * FFN + ch0) = o; } }
.LBB0_788:
	v_mov_b32_e32 v72, v122
	v_mov_b32_e32 v73, v122
	v_pk_fma_f32 v[6:7], v[6:7], v[72:73], v[94:95]
	v_pk_fma_f32 v[2:3], v[2:3], v[72:73], v[90:91]
	v_pk_fma_f32 v[0:1], v[0:1], v[122:123], v[88:89]
	s_movk_i32 s10, 0x4f
	v_pk_fma_f32 v[4:5], v[4:5], v[122:123], v[92:93]
	v_mov_b32_dpp v84, v8 row_ror:1 row_mask:0xf bank_mask:0xf
	v_mov_b32_dpp v87, v9 row_ror:1 row_mask:0xf bank_mask:0xf
	v_mov_b32_dpp v88, v10 row_ror:1 row_mask:0xf bank_mask:0xf
	v_mov_b32_dpp v89, v11 row_ror:1 row_mask:0xf bank_mask:0xf
	v_mov_b32_dpp v73, v8 row_ror:15 row_mask:0xf bank_mask:0xf
	v_mov_b32_dpp v74, v9 row_ror:15 row_mask:0xf bank_mask:0xf
	v_mov_b32_dpp v75, v10 row_ror:15 row_mask:0xf bank_mask:0xf
	v_mov_b32_dpp v72, v11 row_ror:15 row_mask:0xf bank_mask:0xf
	v_cmp_ne_u32_e32 vcc, s10, v127
	s_and_saveexec_b64 s[10:11], vcc
	s_cbranch_execz .LBB0_790
	v_cndmask_b32_e64 v91, v102, v82, s[8:9]
	v_cndmask_b32_e64 v83, v103, v83, s[8:9]
	v_cndmask_b32_e64 v82, v86, v81, s[8:9]
	v_pk_mul_f32 v[58:59], v[58:59], v[82:83]
	s_waitcnt lgkmcnt(0)
	v_cndmask_b32_e64 v63, v79, v63, s[6:7]
	v_pk_fma_f32 v[58:59], v[66:67], v[14:15], v[58:59]
	v_cndmask_b32_e64 v62, v77, v62, s[6:7]
	v_pk_fma_f32 v[54:55], v[54:55], v[62:63], v[58:59]
	v_cndmask_b32_e64 v90, v85, v80, s[8:9]
	v_pk_add_f32 v[46:47], v[46:47], v[54:55]
	v_pk_mul_f32 v[56:57], v[56:57], v[90:91]
	v_mul_f32_e32 v54, 0xbfb8aa3b, v47
	v_exp_f32_e32 v54, v54
	v_mul_f32_e32 v55, 0xbfb8aa3b, v46
	v_pk_fma_f32 v[56:57], v[64:65], v[12:13], v[56:57]
	v_cndmask_b32_e64 v61, v78, v61, s[6:7]
	v_cndmask_b32_e64 v60, v76, v60, s[6:7]
	v_exp_f32_e32 v55, v55
	v_pk_fma_f32 v[52:53], v[52:53], v[60:61], v[56:57]
	s_nop 0
	v_pk_add_f32 v[44:45], v[44:45], v[52:53]
	v_add_f32_e32 v52, 1.0, v54
	v_mul_f32_e32 v54, 0xbfb8aa3b, v45
	v_rcp_f32_e32 v53, v52
	v_add_f32_e32 v52, 1.0, v55
	v_exp_f32_e32 v54, v54
	v_mul_f32_e32 v55, 0xbfb8aa3b, v44
	v_exp_f32_e32 v56, v55
	v_rcp_f32_e32 v52, v52
	v_add_f32_e32 v54, 1.0, v54
	v_rcp_f32_e32 v55, v54
	v_add_f32_e32 v54, 1.0, v56
	v_rcp_f32_e32 v54, v54
	v_pk_mul_f32 v[46:47], v[46:47], v[52:53]
	v_cndmask_b32_e64 v53, v87, v69, s[8:9]
	v_pk_mul_f32 v[46:47], v[6:7], v[46:47]
	v_pk_mul_f32 v[44:45], v[44:45], v[54:55]
	v_cndmask_b32_e64 v52, v84, v68, s[8:9]
	v_pk_mul_f32 v[44:45], v[4:5], v[44:45]
	v_pk_mul_f32 v[32:33], v[32:33], v[52:53]
	v_cvt_pk_bf16_f32 v44, v44, v45
	v_cvt_pk_bf16_f32 v45, v46, v47
	v_cndmask_b32_e64 v47, v89, v71, s[8:9]
	v_cndmask_b32_e64 v46, v88, v70, s[8:9]
	v_pk_mul_f32 v[34:35], v[34:35], v[46:47]
	v_pk_fma_f32 v[32:33], v[36:37], v[8:9], v[32:33]
	v_pk_fma_f32 v[34:35], v[38:39], v[10:11], v[34:35]
	v_cndmask_b32_e64 v39, v74, v97, s[6:7]
	v_cndmask_b32_e64 v38, v73, v96, s[6:7]
	v_pk_fma_f32 v[28:29], v[28:29], v[38:39], v[32:33]
	v_cndmask_b32_e64 v37, v72, v99, s[6:7]
	v_cndmask_b32_e64 v36, v75, v98, s[6:7]
	v_pk_add_f32 v[24:25], v[24:25], v[28:29]
	v_pk_fma_f32 v[30:31], v[30:31], v[36:37], v[34:35]
	v_mul_f32_e32 v28, 0xbfb8aa3b, v24
	v_mul_f32_e32 v29, 0xbfb8aa3b, v25
	v_exp_f32_e32 v28, v28
	v_exp_f32_e32 v29, v29
	v_pk_add_f32 v[26:27], v[26:27], v[30:31]
	v_add_f32_e32 v28, 1.0, v28
	v_mul_f32_e32 v30, 0xbfb8aa3b, v26
	v_mul_f32_e32 v31, 0xbfb8aa3b, v27
	v_exp_f32_e32 v30, v30
	v_exp_f32_e32 v31, v31
	v_add_f32_e32 v29, 1.0, v29
	v_rcp_f32_e32 v28, v28
	v_rcp_f32_e32 v29, v29
	v_add_f32_e32 v30, 1.0, v30
	v_add_f32_e32 v31, 1.0, v31
	v_rcp_f32_e32 v30, v30
	v_rcp_f32_e32 v31, v31
	v_pk_mul_f32 v[24:25], v[24:25], v[28:29]
	s_nop 0
	v_pk_mul_f32 v[24:25], v[0:1], v[24:25]
	s_nop 0
	v_cvt_pk_bf16_f32 v46, v24, v25
	v_pk_mul_f32 v[24:25], v[26:27], v[30:31]
	s_nop 0
	v_pk_mul_f32 v[24:25], v[2:3], v[24:25]
	s_nop 0
	v_cvt_pk_bf16_f32 v47, v24, v25
	v_add3_u32 v24, v112, v127, 48
	v_mad_i64_i32 v[24:25], s[30:31], v24, s25, v[100:101]
	global_store_dwordx4 v[24:25], v[44:47], off sc1

;     __device__ __forceinline__ void operator()(const f32x4 (&acc_c)[2][2][4][2], const pg8::Unit& u, int wr, int wc, int fr, int fq) const {
;     ...
;         if (wr == 0 && fr < 2) { float* dst = half ? HALO2 + (size_t)(3 + fr) * FFN : HALO + (size_t)fr * FFN; float* gd = half ? HALO2 + (size_t)5 * FFN : HALO + (size_t)4 * FFN;
; #pragma unroll
;             for (int n = 0; n < 2; ++n) { *(f32x4*)(dst + ch0 + 4 * n) = acc[0][0][0][n]; if (fr == 0) *(f32x4*)(gd + ch0 + 4 * n) = acc[0][1][0][n]; } }
;         if (wr == 1 && fr >= 14) { float* dst = half ? HALO + (size_t)(fr - 12) * FFN : HALO2 + (size_t)(fr - 14) * FFN; float* gd = half ? HALO + (size_t)5 * FFN : HALO2 + (size_t)2 * FFN;
; #pragma unroll
;             for (int n = 0; n < 2; ++n) { *(f32x4*)(dst + ch0 + 4 * n) = acc[0][0][3][n]; if (fr == 15) *(f32x4*)(gd + ch0 + 4 * n) = acc[0][1][3][n]; } }
.LBB0_792:
	s_or_b64 exec, exec, s[10:11]
	s_mul_i32 s10, s12, 0x21000
	s_mul_hi_i32 s5, s12, 0x21000
	s_add_u32 s12, s14, s10
	s_addc_u32 s5, s15, s5
	s_add_u32 s10, s12, 0x5342000
	s_addc_u32 s11, s5, 0
	s_add_u32 s12, s12, 0x5b42000
	v_cmp_gt_u32_e32 vcc, 2, v132
	s_addc_u32 s13, s5, 0
	s_and_b64 s[28:29], s[28:29], vcc
	s_and_saveexec_b64 s[24:25], s[28:29]
	s_cbranch_execz .LBB0_796
	v_mul_u32_u24_e32 v24, 0x1600, v132
	v_lshlrev_b32_e32 v24, 2, v24
	v_mov_b32_e32 v25, 0
	s_cmp_eq_u32 s4, 0
	v_lshl_add_u64 v[26:27], s[12:13], 0, v[24:25]
	s_mov_b64 s[28:29], 0x10800
	v_lshl_add_u64 v[26:27], v[26:27], 0, s[28:29]
	v_lshl_add_u64 v[24:25], s[10:11], 0, v[24:25]
	s_cselect_b64 vcc, -1, 0
	v_cndmask_b32_e32 v25, v27, v25, vcc
	v_cndmask_b32_e32 v24, v26, v24, vcc
	v_lshl_add_u64 v[26:27], v[120:121], 2, v[24:25]
	global_store_dwordx4 v[26:27], v[20:23], off sc1
	s_and_saveexec_b64 s[28:29], s[8:9]
	s_cbranch_execz .LBB0_795
	s_add_u32 s5, s10, 0x16000
	s_addc_u32 s30, s11, 0
	s_add_u32 s31, s12, 0x1b800
	s_addc_u32 s34, s13, 0
	s_and_b64 s[8:9], vcc, exec
	s_cselect_b32 s9, s30, s34
	s_cselect_b32 s8, s5, s31
	v_lshl_add_u64 v[20:21], v[120:121], 2, s[8:9]
	global_store_dwordx4 v[20:21], v[40:43], off sc1
	global_store_dwordx4 v[26:27], v[16:19], off offset:16 sc1
	v_mov_b64_e32 v[24:25], s[8:9]
	s_nop 0
	v_mov_b64_e32 v[16:17], v[48:49]
	v_mov_b64_e32 v[18:19], v[50:51]
.LBB0_795:
	s_or_b64 exec, exec, s[28:29]
	v_lshl_add_u64 v[20:21], v[120:121], 2, v[24:25]
	global_store_dwordx4 v[20:21], v[16:19], off offset:16 sc1
.LBB0_796:
	s_or_b64 exec, exec, s[24:25]
	v_cmp_lt_u32_e32 vcc, 13, v132
	s_and_b64 s[24:25], s[26:27], vcc
	s_and_saveexec_b64 s[8:9], s[24:25]
	s_cbranch_execz .LBB0_800
	s_cmp_eq_u32 s4, 0
	s_cselect_b64 s[24:25], -1, 0
	s_and_b64 s[4:5], s[24:25], exec
	s_cselect_b32 s4, -14, -12
	s_cselect_b32 s5, s13, s11
	s_cselect_b32 s26, s12, s10
	v_mov_b32_e32 v16, s26
	v_mov_b32_e32 v17, s5
	v_add_u32_e32 v18, s4, v132
	s_movk_i32 s4, 0x5800
	v_mad_u64_u32 v[18:19], s[4:5], v18, s4, v[16:17]
	v_lshl_add_u64 v[16:17], v[120:121], 2, v[18:19]
	global_store_dwordx4 v[16:17], v[12:15], off sc1
	s_and_saveexec_b64 s[26:27], s[6:7]
	s_cbranch_execz .LBB0_799
	s_add_u32 s6, s12, 0xb000
	s_addc_u32 s7, s13, 0
	s_add_u32 s10, s10, 0x1b800
	s_addc_u32 s11, s11, 0
	s_and_b64 s[4:5], s[24:25], exec
	s_cselect_b32 s5, s7, s11
	s_cselect_b32 s4, s6, s10
	v_lshl_add_u64 v[12:13], v[120:121], 2, s[4:5]
	global_store_dwordx4 v[12:13], v[4:7], off sc1
	global_store_dwordx4 v[16:17], v[8:11], off offset:16 sc1
	v_mov_b64_e32 v[18:19], s[4:5]
	s_nop 0
	v_mov_b64_e32 v[10:11], v[2:3]
	v_mov_b64_e32 v[8:9], v[0:1]
.LBB0_799:
	s_or_b64 exec, exec, s[26:27]
	v_lshl_add_u64 v[0:1], v[120:121], 2, v[18:19]
	global_store_dwordx4 v[0:1], v[8:11], off offset:16 sc1

;     __host__ __device__ bool next(int i, Unit& u) const { const long L = (long)i * G + c; if (L >= maxL) return false; return unit_of(L, u); }
; #define LAS __attribute__((address_space(3)))
; __device__ __forceinline__ unsigned pk2(float lo, float hi) { const f32x2_t v = {lo, hi}; const bf16x2_t b = __builtin_convertvector(v, bf16x2_t); return __builtin_bit_cast(unsigned, b); }
; __device__ __forceinline__ float siluf_(float x) { return x * __builtin_amdgcn_rcpf(1.0f + __expf(-x)); }
;     __device__ bool next(int i, pg8::Unit& u) const { if (!pg8::StaticOrder::next(i >> 1, u)) return false; u.br = i & 1; return true; }
; __device__ __forceinline__ f32x4 ror1_4(const f32x4 v) { return (f32x4){dpp_ror1(v.x), dpp_ror1(v.y), dpp_ror1(v.z), dpp_ror1(v.w)}; }
;     __device__ __forceinline__ void operator()(const f32x4 (&acc_c)[2][2][4][2], const pg8::Unit& u, int wr, int wc, int fr, int fq) const {
;     ...
;         for (int ai = 0; ai < 2; ++ai) { const int bi = 2 * ai + wr;
; #pragma unroll
;             for (int m = 0; m < 4; ++m) { u32x4 o;
; #pragma unroll
;                 for (int n = 0; n < 2; ++n) { const f32x4 cur = acc[ai][0][m][n];
;                     f32x4 pu, nd;
;                     if (m > 0) pu = ror1_4(acc[ai][0][m > 0 ? m - 1 : 0][n]); else pu = (bi > 0) ? *(const LAS f32x4*)(X + ((bi - 1) * 2 + 1) * 128 + cl + 4 * n) : (f32x4){0.f, 0.f, 0.f, 0.f};
;                     if (m < 3) nd = rol1_4(acc[ai][0][m < 3 ? m + 1 : 3][n]); else nd = (bi < 3) ? *(const LAS f32x4*)(X + ((bi + 1) * 2 + 0) * 128 + cl + 4 * n) : (f32x4){0.f, 0.f, 0.f, 0.f};
;                     const f32x4 ps = ror1_4(cur), ns = rol1_4(cur);
;                     const f32x4 prev = (fr > 0) ? ps : pu, next = (fr < 15) ? ns : nd;
;                     const f32x4 uu = w0[n] * prev + w1[n] * cur + w2[n] * next + cbv[n]; const f32x4 gt = acc[ai][1][m][n];
;                     f32x4 r; r.x = siluf_(uu.x) * gt.x; r.y = siluf_(uu.y) * gt.y; r.z = siluf_(uu.z) * gt.z; r.w = siluf_(uu.w) * gt.w;
;                     if (n == 0) { o.x = pk2(r.x, r.y); o.y = pk2(r.z, r.w); } else { o.z = pk2(r.x, r.y); o.w = pk2(r.z, r.w); } }
;                 const int rl = ai * 128 + wr * 64 + m * 16 + fr;
;                 if (rl != 0 && rl != 255) *(u32x4*)(ACT + (size_t)(u.pm * 256 + rl) * FFN + ch0) = o; } }
.LBB0_841:
	v_mov_b32_e32 v219, v218
	v_mov_b32_e32 v240, v216
	v_mov_b32_e32 v241, v216
	v_pk_fma_f32 v[104:105], v[104:105], v[216:217], v[96:97]
	v_pk_fma_f32 v[108:109], v[108:109], v[216:217], v[92:93]
	v_mov_b32_e32 v216, v218
	v_mov_b32_e32 v217, v218
	v_pk_fma_f32 v[106:107], v[106:107], v[240:241], v[98:99]
	v_or_b32_e32 v192, s85, v225
	s_lshl_b32 s27, s26, 8
	v_pk_fma_f32 v[110:111], v[110:111], v[240:241], v[94:95]
	v_pk_fma_f32 v[166:167], v[166:167], v[216:217], v[122:123]
	v_pk_fma_f32 v[164:165], v[164:165], v[218:219], v[120:121]
	v_cmp_eq_u32_e64 s[10:11], 0, v225
	v_cmp_eq_u32_e64 s[8:9], 15, v225
	v_lshl_add_u64 v[172:173], v[200:201], 1, s[56:57]
	v_mov_b32_dpp v237, v164 row_ror:15 row_mask:0xf bank_mask:0xf
	v_mov_b32_dpp v239, v165 row_ror:15 row_mask:0xf bank_mask:0xf
	v_mov_b32_dpp v240, v166 row_ror:15 row_mask:0xf bank_mask:0xf
	v_mov_b32_dpp v241, v167 row_ror:15 row_mask:0xf bank_mask:0xf
	v_mov_b32_dpp v246, v36 row_ror:1 row_mask:0xf bank_mask:0xf
	v_mov_b32_dpp v247, v37 row_ror:1 row_mask:0xf bank_mask:0xf
	v_mov_b32_dpp v248, v38 row_ror:1 row_mask:0xf bank_mask:0xf
	v_mov_b32_dpp v249, v39 row_ror:1 row_mask:0xf bank_mask:0xf
	v_mov_b32_dpp v242, v36 row_ror:15 row_mask:0xf bank_mask:0xf
	v_mov_b32_dpp v243, v37 row_ror:15 row_mask:0xf bank_mask:0xf
	v_mov_b32_dpp v244, v38 row_ror:15 row_mask:0xf bank_mask:0xf
	v_mov_b32_dpp v245, v39 row_ror:15 row_mask:0xf bank_mask:0xf
	v_cmp_ne_u32_e32 vcc, 0, v192
	v_mov_b32_e32 v205, s27
	s_and_saveexec_b64 s[12:13], vcc
	s_cbranch_execz .LBB0_843
	s_waitcnt lgkmcnt(0)
	v_cndmask_b32_e64 v183, v238, v183, s[10:11]
	v_cndmask_b32_e64 v182, v235, v182, s[10:11]
	s_waitcnt vmcnt(0)
	v_pk_mul_f32 v[182:183], v[86:87], v[182:183]
	v_cndmask_b32_e64 v229, v233, v229, s[8:9]
	v_pk_fma_f32 v[182:183], v[42:43], v[78:79], v[182:183]
	v_cndmask_b32_e64 v228, v231, v228, s[8:9]
	v_pk_fma_f32 v[182:183], v[74:75], v[228:229], v[182:183]
	v_cndmask_b32_e64 v181, v236, v181, s[10:11]
	v_pk_add_f32 v[182:183], v[70:71], v[182:183]
	v_cndmask_b32_e64 v180, v234, v180, s[10:11]
	v_mul_f32_e32 v205, 0xbfb8aa3b, v183
	v_cndmask_b32_e64 v234, v230, v208, s[8:9]
	v_exp_f32_e32 v205, v205
	v_mul_f32_e32 v208, 0xbfb8aa3b, v182
	v_pk_mul_f32 v[180:181], v[84:85], v[180:181]
	v_exp_f32_e32 v208, v208
	v_pk_fma_f32 v[180:181], v[40:41], v[76:77], v[180:181]
	v_cndmask_b32_e64 v235, v232, v227, s[8:9]
	v_pk_fma_f32 v[180:181], v[72:73], v[234:235], v[180:181]
	v_add_f32_e32 v205, 1.0, v205
	v_pk_add_f32 v[180:181], v[68:69], v[180:181]
	v_rcp_f32_e32 v229, v205
	v_add_f32_e32 v205, 1.0, v208
	v_mul_f32_e32 v208, 0xbfb8aa3b, v181
	v_exp_f32_e32 v208, v208
	v_mul_f32_e32 v227, 0xbfb8aa3b, v180
	v_exp_f32_e32 v227, v227
	v_rcp_f32_e32 v228, v205
	v_add_f32_e32 v205, 1.0, v208
	v_rcp_f32_e32 v231, v205
	v_add_f32_e32 v205, 1.0, v227
	v_rcp_f32_e32 v230, v205
	v_cndmask_b32_e64 v177, v247, v177, s[10:11]
	v_cndmask_b32_e64 v176, v246, v176, s[10:11]
	v_pk_mul_f32 v[182:183], v[182:183], v[228:229]
	v_pk_mul_f32 v[180:181], v[180:181], v[230:231]
	v_cndmask_b32_e64 v179, v249, v179, s[10:11]
	v_cndmask_b32_e64 v178, v248, v178, s[10:11]
	v_pk_mul_f32 v[176:177], v[60:61], v[176:177]
	v_pk_mul_f32 v[182:183], v[106:107], v[182:183]
	v_pk_mul_f32 v[180:181], v[104:105], v[180:181]
	v_pk_mul_f32 v[178:179], v[62:63], v[178:179]
	v_pk_fma_f32 v[176:177], v[36:37], v[56:57], v[176:177]
	v_cndmask_b32_e64 v229, v243, v239, s[8:9]
	v_cndmask_b32_e64 v228, v242, v237, s[8:9]
	v_cvt_pk_bf16_f32 v180, v180, v181
	v_cvt_pk_bf16_f32 v181, v182, v183
	v_pk_fma_f32 v[178:179], v[38:39], v[58:59], v[178:179]
	v_cndmask_b32_e64 v183, v245, v241, s[8:9]
	v_cndmask_b32_e64 v182, v244, v240, s[8:9]
	v_pk_fma_f32 v[176:177], v[48:49], v[228:229], v[176:177]
	v_pk_fma_f32 v[178:179], v[50:51], v[182:183], v[178:179]
	v_pk_add_f32 v[176:177], v[44:45], v[176:177]
	v_pk_add_f32 v[178:179], v[46:47], v[178:179]
	v_mul_f32_e32 v182, 0xbfb8aa3b, v176
	v_mul_f32_e32 v183, 0xbfb8aa3b, v177
	v_exp_f32_e32 v182, v182
	v_exp_f32_e32 v183, v183
	v_mul_f32_e32 v205, 0xbfb8aa3b, v178
	v_exp_f32_e32 v205, v205
	v_mul_f32_e32 v208, 0xbfb8aa3b, v179
	v_exp_f32_e32 v208, v208
	v_add_f32_e32 v182, 1.0, v182
	v_add_f32_e32 v183, 1.0, v183
	v_rcp_f32_e32 v182, v182
	v_rcp_f32_e32 v183, v183
	v_add_f32_e32 v205, 1.0, v205
	v_rcp_f32_e32 v228, v205
	v_add_f32_e32 v205, 1.0, v208
	v_rcp_f32_e32 v229, v205
	v_pk_mul_f32 v[176:177], v[176:177], v[182:183]
	v_add_u32_e32 v205, s27, v192
	v_pk_mul_f32 v[176:177], v[108:109], v[176:177]
	s_nop 0
	v_cvt_pk_bf16_f32 v182, v176, v177
	v_pk_mul_f32 v[176:177], v[178:179], v[228:229]
	s_nop 0
	v_pk_mul_f32 v[176:177], v[110:111], v[176:177]
	s_nop 0
	v_cvt_pk_bf16_f32 v183, v176, v177
	v_mad_i64_i32 v[176:177], s[40:41], v205, s38, v[172:173]
	global_store_dwordx4 v[176:177], v[180:183], off sc1
;     __device__ __forceinline__ void operator()(const f32x4 (&acc_c)[2][2][4][2], const pg8::Unit& u, int wr, int wc, int fr, int fq) const {
;     ...
;             for (int m = 0; m < 4; ++m) { const int rl = ai * 128 + wr * 64 + m * 16 + fr;
;                 const float rstd = __builtin_amdgcn_rsqf(rsq[rl] * (1.0f / D_MODEL) + EPS);
; #pragma unroll
;                 for (int bj = 0; bj < 2; ++bj)
; #pragma unroll
;                     for (int n = 0; n < 2; ++n) acc[ai][bj][m][n] = acc[ai][bj][m][n] * rstd + *(const LAS f32x4*)(bias2 + bj * 128 + cl + 4 * n); }
;         f32x4 w0[2], w1[2], w2[2], cbv[2];
; #pragma unroll
;         for (int n = 0; n < 2; ++n) { w0[n] = *(const f32x4*)(cw + ch0 + 4 * n); w1[n] = *(const f32x4*)(cw + FFN + ch0 + 4 * n); w2[n] = *(const f32x4*)(cw + 2 * FFN + ch0 + 4 * n); cbv[n] = *(const f32x4*)(cb + ch0 + 4 * n); }
; #pragma unroll
;         for (int ai = 0; ai < 2; ++ai) { const int bi = 2 * ai + wr;
;             if (fr == 0) {
; #pragma unroll
;                 for (int n = 0; n < 2; ++n) *(LAS f32x4*)(X + (bi * 2 + 0) * 128 + cl + 4 * n) = acc[ai][0][0][n]; }
;             if (fr == 15) {
; #pragma unroll
;                 for (int n = 0; n < 2; ++n) *(LAS f32x4*)(X + (bi * 2 + 1) * 128 + cl + 4 * n) = acc[ai][0][3][n]; } }
;         asm volatile("s_waitcnt lgkmcnt(0)" ::: "memory"); __builtin_amdgcn_s_barrier(); asm volatile("" ::: "memory");
; #pragma unroll
;         for (int ai = 0; ai < 2; ++ai) { const int bi = 2 * ai + wr;
; #pragma unroll
;             for (int m = 0; m < 4; ++m) { u32x4 o;
; #pragma unroll
;                 for (int n = 0; n < 2; ++n) { const f32x4 cur = acc[ai][0][m][n];
;                     f32x4 pu, nd;
;                     if (m > 0) pu = ror1_4(acc[ai][0][m > 0 ? m - 1 : 0][n]); else pu = (bi > 0) ? *(const LAS f32x4*)(X + ((bi - 1) * 2 + 1) * 128 + cl + 4 * n) : (f32x4){0.f, 0.f, 0.f, 0.f};
;                     if (m < 3) nd = rol1_4(acc[ai][0][m < 3 ? m + 1 : 3][n]); else nd = (bi < 3) ? *(const LAS f32x4*)(X + ((bi + 1) * 2 + 0) * 128 + cl + 4 * n) : (f32x4){0.f, 0.f, 0.f, 0.f};
;                     const f32x4 ps = ror1_4(cur), ns = rol1_4(cur);
;                     const f32x4 prev = (fr > 0) ? ps : pu, next = (fr < 15) ? ns : nd;
;                     const f32x4 uu = w0[n] * prev + w1[n] * cur + w2[n] * next + cbv[n]; const f32x4 gt = acc[ai][1][m][n];
.LBB0_843:
	s_or_b64 exec, exec, s[12:13]
	s_waitcnt lgkmcnt(0)
	v_pk_fma_f32 v[176:177], v[150:151], v[216:217], v[98:99]
	v_fmamk_f32 v150, v212, 0x3a000000, v224
	v_rsq_f32_e32 v178, v150
	v_pk_fma_f32 v[180:181], v[148:149], v[218:219], v[96:97]
	v_pk_fma_f32 v[182:183], v[146:147], v[216:217], v[94:95]
	v_pk_fma_f32 v[216:217], v[144:145], v[218:219], v[92:93]
	v_pk_fma_f32 v[144:145], v[154:155], v[178:179], v[122:123] op_sel_hi:[1,0,1]
	v_mov_b32_dpp v154, v40 row_ror:1 row_mask:0xf bank_mask:0xf
	v_mov_b32_dpp v155, v41 row_ror:1 row_mask:0xf bank_mask:0xf
	v_mov_b32_dpp v218, v214 row_ror:1 row_mask:0xf bank_mask:0xf
	v_mov_b32_dpp v219, v215 row_ror:1 row_mask:0xf bank_mask:0xf
	v_pk_fma_f32 v[148:149], v[158:159], v[178:179], v[126:127] op_sel_hi:[1,0,1]
	v_pk_fma_f32 v[150:151], v[156:157], v[178:179], v[124:125] op_sel_hi:[1,0,1]
	v_pk_fma_f32 v[146:147], v[152:153], v[178:179], v[120:121] op_sel_hi:[1,0,1]
	v_pk_fma_f32 v[142:143], v[142:143], v[178:179], v[98:99] op_sel_hi:[1,0,1]
	v_pk_fma_f32 v[140:141], v[140:141], v[178:179], v[96:97] op_sel_hi:[1,0,1]
	v_pk_fma_f32 v[138:139], v[138:139], v[178:179], v[94:95] op_sel_hi:[1,0,1]
	v_pk_fma_f32 v[136:137], v[136:137], v[178:179], v[92:93] op_sel_hi:[1,0,1]
	v_cndmask_b32_e64 v155, v219, v155, s[10:11]
	v_cndmask_b32_e64 v154, v218, v154, s[10:11]
	v_mov_b32_dpp v152, v42 row_ror:1 row_mask:0xf bank_mask:0xf
	v_mov_b32_dpp v153, v43 row_ror:1 row_mask:0xf bank_mask:0xf
	v_mov_b32_dpp v178, v150 row_ror:15 row_mask:0xf bank_mask:0xf
	v_mov_b32_dpp v179, v151 row_ror:15 row_mask:0xf bank_mask:0xf
	v_mov_b32_dpp v227, v174 row_ror:1 row_mask:0xf bank_mask:0xf
	v_mov_b32_dpp v228, v175 row_ror:1 row_mask:0xf bank_mask:0xf
	v_mov_b32_dpp v158, v214 row_ror:15 row_mask:0xf bank_mask:0xf
	v_mov_b32_dpp v159, v215 row_ror:15 row_mask:0xf bank_mask:0xf
	s_waitcnt vmcnt(0)
	v_pk_mul_f32 v[154:155], v[84:85], v[154:155]
	v_cndmask_b32_e64 v153, v228, v153, s[10:11]
	v_cndmask_b32_e64 v152, v227, v152, s[10:11]
	v_pk_fma_f32 v[154:155], v[214:215], v[76:77], v[154:155]
	v_cndmask_b32_e64 v159, v159, v179, s[8:9]
	v_cndmask_b32_e64 v158, v158, v178, s[8:9]
	v_mov_b32_dpp v208, v148 row_ror:15 row_mask:0xf bank_mask:0xf
	v_mov_b32_dpp v212, v149 row_ror:15 row_mask:0xf bank_mask:0xf
	v_mov_b32_dpp v156, v174 row_ror:15 row_mask:0xf bank_mask:0xf
	v_mov_b32_dpp v157, v175 row_ror:15 row_mask:0xf bank_mask:0xf
	v_pk_mul_f32 v[152:153], v[86:87], v[152:153]
	v_pk_fma_f32 v[154:155], v[72:73], v[158:159], v[154:155]
	v_pk_fma_f32 v[152:153], v[174:175], v[78:79], v[152:153]
	v_cndmask_b32_e64 v157, v157, v212, s[8:9]
	v_cndmask_b32_e64 v156, v156, v208, s[8:9]
	v_pk_add_f32 v[154:155], v[68:69], v[154:155]
	v_pk_fma_f32 v[152:153], v[74:75], v[156:157], v[152:153]
	v_mul_f32_e32 v156, 0xbfb8aa3b, v154
	v_exp_f32_e32 v158, v156
	v_mul_f32_e32 v156, 0xbfb8aa3b, v155
	v_exp_f32_e32 v159, v156
	v_pk_add_f32 v[156:157], v[70:71], v[152:153]
	v_add_f32_e32 v152, 1.0, v158
	v_mul_f32_e32 v158, 0xbfb8aa3b, v156
	v_add_f32_e32 v153, 1.0, v159
	v_mul_f32_e32 v159, 0xbfb8aa3b, v157
	v_exp_f32_e32 v158, v158
	v_exp_f32_e32 v159, v159
	v_rcp_f32_e32 v152, v152
	v_rcp_f32_e32 v153, v153
	v_add_f32_e32 v158, 1.0, v158
	v_add_f32_e32 v159, 1.0, v159
	v_rcp_f32_e32 v158, v158
	v_rcp_f32_e32 v159, v159
	v_mov_b32_dpp v229, v36 row_ror:1 row_mask:0xf bank_mask:0xf
	v_mov_b32_dpp v230, v37 row_ror:1 row_mask:0xf bank_mask:0xf
	v_mov_b32_dpp v237, v164 row_ror:1 row_mask:0xf bank_mask:0xf
	v_mov_b32_dpp v238, v165 row_ror:1 row_mask:0xf bank_mask:0xf
	v_pk_mul_f32 v[152:153], v[154:155], v[152:153]
	v_pk_mul_f32 v[154:155], v[156:157], v[158:159]
	v_cndmask_b32_e64 v157, v238, v230, s[10:11]
	v_cndmask_b32_e64 v156, v237, v229, s[10:11]
	v_mov_b32_dpp v231, v38 row_ror:1 row_mask:0xf bank_mask:0xf
	v_mov_b32_dpp v232, v39 row_ror:1 row_mask:0xf bank_mask:0xf
	v_mov_b32_dpp v233, v146 row_ror:15 row_mask:0xf bank_mask:0xf
	v_mov_b32_dpp v234, v147 row_ror:15 row_mask:0xf bank_mask:0xf
	v_mov_b32_dpp v239, v166 row_ror:1 row_mask:0xf bank_mask:0xf
	v_mov_b32_dpp v240, v167 row_ror:1 row_mask:0xf bank_mask:0xf
	v_mov_b32_dpp v241, v164 row_ror:15 row_mask:0xf bank_mask:0xf
	v_mov_b32_dpp v242, v165 row_ror:15 row_mask:0xf bank_mask:0xf
	v_pk_mul_f32 v[152:153], v[180:181], v[152:153]
	v_pk_mul_f32 v[154:155], v[176:177], v[154:155]
	v_pk_mul_f32 v[156:157], v[60:61], v[156:157]
	v_cvt_pk_bf16_f32 v152, v152, v153
	v_cvt_pk_bf16_f32 v153, v154, v155
	v_cndmask_b32_e64 v155, v240, v232, s[10:11]
	v_cndmask_b32_e64 v154, v239, v231, s[10:11]
	v_pk_fma_f32 v[156:157], v[164:165], v[56:57], v[156:157]
	v_cndmask_b32_e64 v165, v242, v234, s[8:9]
	v_cndmask_b32_e64 v164, v241, v233, s[8:9]
	v_mov_b32_dpp v235, v144 row_ror:15 row_mask:0xf bank_mask:0xf
	v_mov_b32_dpp v236, v145 row_ror:15 row_mask:0xf bank_mask:0xf
	v_mov_b32_dpp v243, v166 row_ror:15 row_mask:0xf bank_mask:0xf
	v_mov_b32_dpp v244, v167 row_ror:15 row_mask:0xf bank_mask:0xf
	v_pk_mul_f32 v[154:155], v[62:63], v[154:155]
	v_pk_fma_f32 v[156:157], v[48:49], v[164:165], v[156:157]
	v_pk_fma_f32 v[154:155], v[166:167], v[58:59], v[154:155]
	v_cndmask_b32_e64 v159, v244, v236, s[8:9]
	v_cndmask_b32_e64 v158, v243, v235, s[8:9]
	v_pk_add_f32 v[156:157], v[44:45], v[156:157]
	v_pk_fma_f32 v[154:155], v[50:51], v[158:159], v[154:155]
	v_mul_f32_e32 v158, 0xbfb8aa3b, v156
	v_exp_f32_e32 v164, v158
	v_mul_f32_e32 v158, 0xbfb8aa3b, v157
;     __host__ __device__ bool next(int i, Unit& u) const { const long L = (long)i * G + c; if (L >= maxL) return false; return unit_of(L, u); }
; #define LAS __attribute__((address_space(3)))
; __device__ __forceinline__ unsigned pk2(float lo, float hi) { const f32x2_t v = {lo, hi}; const bf16x2_t b = __builtin_convertvector(v, bf16x2_t); return __builtin_bit_cast(unsigned, b); }
; __device__ __forceinline__ float siluf_(float x) { return x * __builtin_amdgcn_rcpf(1.0f + __expf(-x)); }
;     __device__ bool next(int i, pg8::Unit& u) const { if (!pg8::StaticOrder::next(i >> 1, u)) return false; u.br = i & 1; return true; }
; __device__ __forceinline__ f32x4 ror1_4(const f32x4 v) { return (f32x4){dpp_ror1(v.x), dpp_ror1(v.y), dpp_ror1(v.z), dpp_ror1(v.w)}; }
; __device__ __forceinline__ f32x4 rol1_4(const f32x4 v) { return (f32x4){dpp_rol1(v.x), dpp_rol1(v.y), dpp_rol1(v.z), dpp_rol1(v.w)}; }
;     __device__ __forceinline__ void operator()(const f32x4 (&acc_c)[2][2][4][2], const pg8::Unit& u, int wr, int wc, int fr, int fq) const {
;     ...
;             for (int m = 0; m < 4; ++m) { u32x4 o;
; #pragma unroll
;                 for (int n = 0; n < 2; ++n) { const f32x4 cur = acc[ai][0][m][n];
;                     f32x4 pu, nd;
;                     if (m > 0) pu = ror1_4(acc[ai][0][m > 0 ? m - 1 : 0][n]); else pu = (bi > 0) ? *(const LAS f32x4*)(X + ((bi - 1) * 2 + 1) * 128 + cl + 4 * n) : (f32x4){0.f, 0.f, 0.f, 0.f};
;                     if (m < 3) nd = rol1_4(acc[ai][0][m < 3 ? m + 1 : 3][n]); else nd = (bi < 3) ? *(const LAS f32x4*)(X + ((bi + 1) * 2 + 0) * 128 + cl + 4 * n) : (f32x4){0.f, 0.f, 0.f, 0.f};
;                     const f32x4 ps = ror1_4(cur), ns = rol1_4(cur);
;                     const f32x4 prev = (fr > 0) ? ps : pu, next = (fr < 15) ? ns : nd;
;                     const f32x4 uu = w0[n] * prev + w1[n] * cur + w2[n] * next + cbv[n]; const f32x4 gt = acc[ai][1][m][n];
;                     f32x4 r; r.x = siluf_(uu.x) * gt.x; r.y = siluf_(uu.y) * gt.y; r.z = siluf_(uu.z) * gt.z; r.w = siluf_(uu.w) * gt.w;
;                     if (n == 0) { o.x = pk2(r.x, r.y); o.y = pk2(r.z, r.w); } else { o.z = pk2(r.x, r.y); o.w = pk2(r.z, r.w); } }
;                 const int rl = ai * 128 + wr * 64 + m * 16 + fr;
;                 if (rl != 0 && rl != 255) *(u32x4*)(ACT + (size_t)(u.pm * 256 + rl) * FFN + ch0) = o; } }
	v_exp_f32_e32 v165, v158
	v_pk_add_f32 v[158:159], v[46:47], v[154:155]
	v_add_f32_e32 v154, 1.0, v164
	v_mul_f32_e32 v164, 0xbfb8aa3b, v158
	v_add_f32_e32 v155, 1.0, v165
	v_mul_f32_e32 v165, 0xbfb8aa3b, v159
	v_exp_f32_e32 v164, v164
	v_exp_f32_e32 v165, v165
	v_rcp_f32_e32 v154, v154
	v_rcp_f32_e32 v155, v155
	v_add_f32_e32 v164, 1.0, v164
	v_add_f32_e32 v165, 1.0, v165
	v_rcp_f32_e32 v164, v164
	v_rcp_f32_e32 v165, v165
	v_pk_mul_f32 v[154:155], v[156:157], v[154:155]
	v_pk_mul_f32 v[154:155], v[216:217], v[154:155]
	v_pk_mul_f32 v[156:157], v[158:159], v[164:165]
	v_cvt_pk_bf16_f32 v154, v154, v155
	v_pk_mul_f32 v[156:157], v[182:183], v[156:157]
	v_cvt_pk_bf16_f32 v155, v156, v157
	v_or_b32_e32 v156, 16, v205
	v_mad_i64_i32 v[156:157], s[12:13], v156, s38, v[172:173]
	global_store_dwordx4 v[156:157], v[152:155], off sc1
	s_nop 1
	v_mov_b32_dpp v153, v148 row_ror:1 row_mask:0xf bank_mask:0xf
	v_mov_b32_dpp v155, v149 row_ror:1 row_mask:0xf bank_mask:0xf
	v_mov_b32_dpp v152, v150 row_ror:1 row_mask:0xf bank_mask:0xf
	v_mov_b32_dpp v154, v151 row_ror:1 row_mask:0xf bank_mask:0xf
	v_cndmask_b32_e64 v157, v155, v228, s[10:11]
	v_cndmask_b32_e64 v156, v153, v227, s[10:11]
	v_mov_b32_dpp v166, v170 row_ror:15 row_mask:0xf bank_mask:0xf
	v_mov_b32_dpp v167, v171 row_ror:15 row_mask:0xf bank_mask:0xf
	v_cndmask_b32_e64 v159, v154, v219, s[10:11]
	v_cndmask_b32_e64 v158, v152, v218, s[10:11]
	v_pk_mul_f32 v[156:157], v[86:87], v[156:157]
	v_mov_b32_dpp v164, v168 row_ror:15 row_mask:0xf bank_mask:0xf
	v_mov_b32_dpp v165, v169 row_ror:15 row_mask:0xf bank_mask:0xf
	v_pk_mul_f32 v[158:159], v[84:85], v[158:159]
	v_pk_fma_f32 v[148:149], v[78:79], v[148:149], v[156:157]
	v_cndmask_b32_e64 v157, v212, v167, s[8:9]
	v_cndmask_b32_e64 v156, v208, v166, s[8:9]
	v_pk_fma_f32 v[150:151], v[76:77], v[150:151], v[158:159]
	v_cndmask_b32_e64 v159, v179, v165, s[8:9]
	v_cndmask_b32_e64 v158, v178, v164, s[8:9]
	v_pk_fma_f32 v[148:149], v[74:75], v[156:157], v[148:149]
	v_pk_fma_f32 v[150:151], v[72:73], v[158:159], v[150:151]
	v_pk_add_f32 v[148:149], v[70:71], v[148:149]
	v_pk_add_f32 v[150:151], v[68:69], v[150:151]
	v_mul_f32_e32 v158, 0xbfb8aa3b, v148
	v_mul_f32_e32 v159, 0xbfb8aa3b, v149
	v_mul_f32_e32 v156, 0xbfb8aa3b, v150
	v_mul_f32_e32 v157, 0xbfb8aa3b, v151
	v_exp_f32_e32 v158, v158
	v_exp_f32_e32 v159, v159
	v_exp_f32_e32 v156, v156
	v_exp_f32_e32 v157, v157
	v_add_f32_e32 v158, 1.0, v158
	v_add_f32_e32 v159, 1.0, v159
	v_add_f32_e32 v156, 1.0, v156
	v_add_f32_e32 v157, 1.0, v157
	v_rcp_f32_e32 v158, v158
	v_rcp_f32_e32 v159, v159
	v_rcp_f32_e32 v156, v156
	v_rcp_f32_e32 v157, v157
	v_pk_mul_f32 v[148:149], v[148:149], v[158:159]
	v_mov_b32_dpp v180, v146 row_ror:1 row_mask:0xf bank_mask:0xf
	v_mov_b32_dpp v181, v147 row_ror:1 row_mask:0xf bank_mask:0xf
	v_pk_mul_f32 v[150:151], v[150:151], v[156:157]
	v_pk_mul_f32 v[142:143], v[142:143], v[148:149]
	v_cndmask_b32_e64 v149, v181, v238, s[10:11]
	v_cndmask_b32_e64 v148, v180, v237, s[10:11]
	v_mov_b32_dpp v174, v160 row_ror:15 row_mask:0xf bank_mask:0xf
	v_mov_b32_dpp v175, v161 row_ror:15 row_mask:0xf bank_mask:0xf
	v_mov_b32_dpp v182, v144 row_ror:1 row_mask:0xf bank_mask:0xf
	v_mov_b32_dpp v183, v145 row_ror:1 row_mask:0xf bank_mask:0xf
	v_pk_mul_f32 v[140:141], v[140:141], v[150:151]
	v_pk_mul_f32 v[148:149], v[60:61], v[148:149]
	v_cvt_pk_bf16_f32 v140, v140, v141
	v_cvt_pk_bf16_f32 v141, v142, v143
	v_cndmask_b32_e64 v143, v183, v240, s[10:11]
	v_cndmask_b32_e64 v142, v182, v239, s[10:11]
	v_pk_fma_f32 v[148:149], v[146:147], v[56:57], v[148:149]
	v_cndmask_b32_e64 v157, v234, v175, s[8:9]
	v_cndmask_b32_e64 v156, v233, v174, s[8:9]
	v_mov_b32_dpp v176, v162 row_ror:15 row_mask:0xf bank_mask:0xf
	v_mov_b32_dpp v177, v163 row_ror:15 row_mask:0xf bank_mask:0xf
	v_pk_mul_f32 v[142:143], v[62:63], v[142:143]
	v_pk_fma_f32 v[148:149], v[48:49], v[156:157], v[148:149]
	v_pk_fma_f32 v[142:143], v[144:145], v[58:59], v[142:143]
	v_cndmask_b32_e64 v151, v236, v177, s[8:9]
	v_cndmask_b32_e64 v150, v235, v176, s[8:9]
	v_pk_add_f32 v[148:149], v[44:45], v[148:149]
	v_pk_fma_f32 v[142:143], v[50:51], v[150:151], v[142:143]
	v_mul_f32_e32 v150, 0xbfb8aa3b, v148
	v_exp_f32_e32 v156, v150
	v_mul_f32_e32 v150, 0xbfb8aa3b, v149
	v_exp_f32_e32 v157, v150
	v_pk_add_f32 v[150:151], v[46:47], v[142:143]
	v_add_f32_e32 v142, 1.0, v156
	v_mul_f32_e32 v156, 0xbfb8aa3b, v150
	v_add_f32_e32 v143, 1.0, v157
	v_mul_f32_e32 v157, 0xbfb8aa3b, v151
	v_exp_f32_e32 v156, v156
	v_exp_f32_e32 v157, v157
	v_rcp_f32_e32 v142, v142
	v_rcp_f32_e32 v143, v143
	v_add_f32_e32 v156, 1.0, v156
	v_add_f32_e32 v157, 1.0, v157
	v_rcp_f32_e32 v156, v156
	v_rcp_f32_e32 v157, v157
	v_pk_mul_f32 v[142:143], v[148:149], v[142:143]
	s_andn2_b64 vcc, exec, s[48:49]
	v_pk_mul_f32 v[136:137], v[136:137], v[142:143]
	s_nop 0
	v_cvt_pk_bf16_f32 v142, v136, v137
	v_pk_mul_f32 v[136:137], v[150:151], v[156:157]
	s_nop 0
	v_pk_mul_f32 v[136:137], v[138:139], v[136:137]
	s_nop 0
	v_cvt_pk_bf16_f32 v143, v136, v137
	v_or_b32_e32 v136, 32, v205
	v_mad_i64_i32 v[136:137], s[12:13], v136, s38, v[172:173]
	global_store_dwordx4 v[136:137], v[140:143], off sc1
	v_cndmask_b32_e64 v137, 0, 1, s[48:49]
	v_mov_b32_e32 v136, 0
	v_cmp_ne_u32_e64 s[12:13], 1, v137
	v_mov_b32_e32 v140, 0
	v_mov_b32_e32 v141, 0
	v_mov_b32_e32 v142, 0
	v_mov_b32_e32 v143, 0
	s_cbranch_vccnz .LBB0_845
	ds_read_b128 v[140:143], v213 offset:1024

;     __host__ __device__ bool next(int i, Unit& u) const { const long L = (long)i * G + c; if (L >= maxL) return false; return unit_of(L, u); }
; #define LAS __attribute__((address_space(3)))
; __device__ __forceinline__ unsigned pk2(float lo, float hi) { const f32x2_t v = {lo, hi}; const bf16x2_t b = __builtin_convertvector(v, bf16x2_t); return __builtin_bit_cast(unsigned, b); }
; __device__ __forceinline__ float siluf_(float x) { return x * __builtin_amdgcn_rcpf(1.0f + __expf(-x)); }
;     __device__ bool next(int i, pg8::Unit& u) const { if (!pg8::StaticOrder::next(i >> 1, u)) return false; u.br = i & 1; return true; }
; __device__ __forceinline__ f32x4 ror1_4(const f32x4 v) { return (f32x4){dpp_ror1(v.x), dpp_ror1(v.y), dpp_ror1(v.z), dpp_ror1(v.w)}; }
; __device__ __forceinline__ f32x4 rol1_4(const f32x4 v) { return (f32x4){dpp_rol1(v.x), dpp_rol1(v.y), dpp_rol1(v.z), dpp_rol1(v.w)}; }
;     __device__ __forceinline__ void operator()(const f32x4 (&acc_c)[2][2][4][2], const pg8::Unit& u, int wr, int wc, int fr, int fq) const {
;     ...
;             for (int m = 0; m < 4; ++m) { u32x4 o;
; #pragma unroll
;                 for (int n = 0; n < 2; ++n) { const f32x4 cur = acc[ai][0][m][n];
;                     f32x4 pu, nd;
;                     if (m > 0) pu = ror1_4(acc[ai][0][m > 0 ? m - 1 : 0][n]); else pu = (bi > 0) ? *(const LAS f32x4*)(X + ((bi - 1) * 2 + 1) * 128 + cl + 4 * n) : (f32x4){0.f, 0.f, 0.f, 0.f};
;                     if (m < 3) nd = rol1_4(acc[ai][0][m < 3 ? m + 1 : 3][n]); else nd = (bi < 3) ? *(const LAS f32x4*)(X + ((bi + 1) * 2 + 0) * 128 + cl + 4 * n) : (f32x4){0.f, 0.f, 0.f, 0.f};
;                     const f32x4 ps = ror1_4(cur), ns = rol1_4(cur);
;                     const f32x4 prev = (fr > 0) ? ps : pu, next = (fr < 15) ? ns : nd;
;                     const f32x4 uu = w0[n] * prev + w1[n] * cur + w2[n] * next + cbv[n]; const f32x4 gt = acc[ai][1][m][n];
;                     f32x4 r; r.x = siluf_(uu.x) * gt.x; r.y = siluf_(uu.y) * gt.y; r.z = siluf_(uu.z) * gt.z; r.w = siluf_(uu.w) * gt.w;
;                     if (n == 0) { o.x = pk2(r.x, r.y); o.y = pk2(r.z, r.w); } else { o.z = pk2(r.x, r.y); o.w = pk2(r.z, r.w); } }
;                 const int rl = ai * 128 + wr * 64 + m * 16 + fr;
;                 if (rl != 0 && rl != 255) *(u32x4*)(ACT + (size_t)(u.pm * 256 + rl) * FFN + ch0) = o; } }
.LBB0_847:
	s_movk_i32 s12, 0xcf
	v_mov_b32_dpp v156, v160 row_ror:1 row_mask:0xf bank_mask:0xf
	v_mov_b32_dpp v157, v161 row_ror:1 row_mask:0xf bank_mask:0xf
	v_mov_b32_dpp v158, v162 row_ror:1 row_mask:0xf bank_mask:0xf
	v_mov_b32_dpp v159, v163 row_ror:1 row_mask:0xf bank_mask:0xf
	v_mov_b32_dpp v145, v160 row_ror:15 row_mask:0xf bank_mask:0xf
	v_mov_b32_dpp v149, v161 row_ror:15 row_mask:0xf bank_mask:0xf
	v_mov_b32_dpp v150, v162 row_ror:15 row_mask:0xf bank_mask:0xf
	v_mov_b32_dpp v151, v163 row_ror:15 row_mask:0xf bank_mask:0xf
	v_cmp_ne_u32_e32 vcc, s12, v192
	s_and_saveexec_b64 s[12:13], vcc
	s_cbranch_execz .LBB0_849
	v_cndmask_b32_e64 v181, v176, v154, s[10:11]
	v_cndmask_b32_e64 v155, v177, v155, s[10:11]
	v_cndmask_b32_e64 v154, v175, v153, s[10:11]
	v_cndmask_b32_e64 v180, v174, v152, s[10:11]
	v_pk_mul_f32 v[152:153], v[86:87], v[154:155]
	s_waitcnt lgkmcnt(0)
	v_cndmask_b32_e64 v143, v167, v143, s[8:9]
	v_pk_fma_f32 v[152:153], v[78:79], v[170:171], v[152:153]
	v_cndmask_b32_e64 v142, v165, v142, s[8:9]
	v_pk_fma_f32 v[142:143], v[74:75], v[142:143], v[152:153]
	v_pk_mul_f32 v[154:155], v[84:85], v[180:181]
	v_pk_add_f32 v[142:143], v[70:71], v[142:143]
	v_pk_fma_f32 v[154:155], v[76:77], v[168:169], v[154:155]
	v_mul_f32_e32 v152, 0xbfb8aa3b, v143
	v_exp_f32_e32 v152, v152
	v_cndmask_b32_e64 v141, v166, v141, s[8:9]
	v_cndmask_b32_e64 v140, v164, v140, s[8:9]
	v_mov_b32_e32 v178, v210
	v_add_f32_e32 v152, 1.0, v152
	v_rcp_f32_e32 v153, v152
	v_mul_f32_e32 v152, 0xbfb8aa3b, v142
	v_exp_f32_e32 v152, v152
	v_mov_b32_e32 v179, v210
	v_pk_fma_f32 v[140:141], v[72:73], v[140:141], v[154:155]
	v_pk_fma_f32 v[118:119], v[118:119], v[178:179], v[98:99]
	v_add_f32_e32 v152, 1.0, v152
	v_rcp_f32_e32 v152, v152
	v_pk_add_f32 v[140:141], v[68:69], v[140:141]
	v_pk_fma_f32 v[116:117], v[116:117], v[210:211], v[96:97]
	v_cndmask_b32_e64 v139, v151, v139, s[8:9]
	v_pk_mul_f32 v[142:143], v[142:143], v[152:153]
	v_cndmask_b32_e64 v138, v150, v138, s[8:9]
	v_pk_mul_f32 v[118:119], v[118:119], v[142:143]
	v_mul_f32_e32 v142, 0xbfb8aa3b, v141
	v_exp_f32_e32 v142, v142
	v_cndmask_b32_e64 v137, v149, v137, s[8:9]
	v_cndmask_b32_e64 v136, v145, v136, s[8:9]
	v_pk_fma_f32 v[112:113], v[112:113], v[210:211], v[92:93]
	v_add_f32_e32 v142, 1.0, v142
	v_rcp_f32_e32 v143, v142
	v_mul_f32_e32 v142, 0xbfb8aa3b, v140
	v_exp_f32_e32 v142, v142
	v_pk_fma_f32 v[114:115], v[114:115], v[178:179], v[94:95]
	v_add_f32_e32 v142, 1.0, v142
	v_rcp_f32_e32 v142, v142
	s_nop 0
	v_pk_mul_f32 v[140:141], v[140:141], v[142:143]
	s_nop 0
	v_pk_mul_f32 v[116:117], v[116:117], v[140:141]
	v_cndmask_b32_e64 v141, v157, v146, s[10:11]
	v_cvt_pk_bf16_f32 v116, v116, v117
	v_cvt_pk_bf16_f32 v117, v118, v119
	v_cndmask_b32_e64 v119, v159, v144, s[10:11]
	v_cndmask_b32_e64 v118, v158, v147, s[10:11]
	v_cndmask_b32_e64 v140, v156, v148, s[10:11]
	v_pk_mul_f32 v[140:141], v[60:61], v[140:141]
	v_pk_mul_f32 v[118:119], v[62:63], v[118:119]
	v_pk_fma_f32 v[140:141], v[160:161], v[56:57], v[140:141]
	v_pk_fma_f32 v[118:119], v[162:163], v[58:59], v[118:119]
	v_pk_fma_f32 v[136:137], v[48:49], v[136:137], v[140:141]
	v_pk_fma_f32 v[118:119], v[50:51], v[138:139], v[118:119]
	s_nop 0
	v_pk_add_f32 v[138:139], v[46:47], v[118:119]
	v_pk_add_f32 v[118:119], v[44:45], v[136:137]
	s_nop 0
	v_mul_f32_e32 v136, 0xbfb8aa3b, v118
	v_mul_f32_e32 v137, 0xbfb8aa3b, v119
	v_exp_f32_e32 v136, v136
	v_exp_f32_e32 v137, v137
	v_add_f32_e32 v136, 1.0, v136
	v_add_f32_e32 v137, 1.0, v137
	v_rcp_f32_e32 v136, v136
	v_rcp_f32_e32 v137, v137
	s_nop 0
	v_pk_mul_f32 v[118:119], v[118:119], v[136:137]
	s_nop 0
	v_pk_mul_f32 v[112:113], v[112:113], v[118:119]
	s_nop 0
	v_cvt_pk_bf16_f32 v118, v112, v113
	v_mul_f32_e32 v112, 0xbfb8aa3b, v138
	v_mul_f32_e32 v113, 0xbfb8aa3b, v139
	v_exp_f32_e32 v112, v112
	v_exp_f32_e32 v113, v113
	v_add_f32_e32 v112, 1.0, v112
	v_add_f32_e32 v113, 1.0, v113
	v_rcp_f32_e32 v112, v112
	v_rcp_f32_e32 v113, v113
	s_nop 0
	v_pk_mul_f32 v[112:113], v[138:139], v[112:113]
	s_nop 0
	v_pk_mul_f32 v[112:113], v[114:115], v[112:113]
	s_nop 0
	v_cvt_pk_bf16_f32 v119, v112, v113
	v_or_b32_e32 v112, 48, v205
	v_mad_i64_i32 v[112:113], s[40:41], v112, s38, v[172:173]
	global_store_dwordx4 v[112:113], v[116:119], off sc1

;     __host__ __device__ bool next(int i, Unit& u) const { const long L = (long)i * G + c; if (L >= maxL) return false; return unit_of(L, u); }
; #define LAS __attribute__((address_space(3)))
; __device__ __forceinline__ unsigned pk2(float lo, float hi) { const f32x2_t v = {lo, hi}; const bf16x2_t b = __builtin_convertvector(v, bf16x2_t); return __builtin_bit_cast(unsigned, b); }
; __device__ __forceinline__ float siluf_(float x) { return x * __builtin_amdgcn_rcpf(1.0f + __expf(-x)); }
;     __device__ __forceinline__ void operator()(const f32x4 (&acc_c)[2][2][4][2], const pg8::Unit& u, int wr, int wc, int fr, int fq) const {
;     ...
;             for (int m = 0; m < 4; ++m) { const int rl = ai * 128 + wr * 64 + m * 16 + fr;
;                 const float rstd = __builtin_amdgcn_rsqf(rsq[rl] * (1.0f / D_MODEL) + EPS);
; #pragma unroll
;                 for (int bj = 0; bj < 2; ++bj)
; #pragma unroll
;                     for (int n = 0; n < 2; ++n) acc[ai][bj][m][n] = acc[ai][bj][m][n] * rstd + *(const LAS f32x4*)(bias2 + bj * 128 + cl + 4 * n); }
;     ...
;             for (int m = 0; m < 4; ++m) { u32x4 o;
; #pragma unroll
;                 for (int n = 0; n < 2; ++n) { const f32x4 cur = acc[ai][0][m][n];
;                     f32x4 pu, nd;
;                     if (m > 0) pu = ror1_4(acc[ai][0][m > 0 ? m - 1 : 0][n]); else pu = (bi > 0) ? *(const LAS f32x4*)(X + ((bi - 1) * 2 + 1) * 128 + cl + 4 * n) : (f32x4){0.f, 0.f, 0.f, 0.f};
;                     if (m < 3) nd = rol1_4(acc[ai][0][m < 3 ? m + 1 : 3][n]); else nd = (bi < 3) ? *(const LAS f32x4*)(X + ((bi + 1) * 2 + 0) * 128 + cl + 4 * n) : (f32x4){0.f, 0.f, 0.f, 0.f};
;                     const f32x4 ps = ror1_4(cur), ns = rol1_4(cur);
;                     const f32x4 prev = (fr > 0) ? ps : pu, next = (fr < 15) ? ns : nd;
;                     const f32x4 uu = w0[n] * prev + w1[n] * cur + w2[n] * next + cbv[n]; const f32x4 gt = acc[ai][1][m][n];
;                     f32x4 r; r.x = siluf_(uu.x) * gt.x; r.y = siluf_(uu.y) * gt.y; r.z = siluf_(uu.z) * gt.z; r.w = siluf_(uu.w) * gt.w;
;                     if (n == 0) { o.x = pk2(r.x, r.y); o.y = pk2(r.z, r.w); } else { o.z = pk2(r.x, r.y); o.w = pk2(r.z, r.w); } }
;                 const int rl = ai * 128 + wr * 64 + m * 16 + fr;
;                 if (rl != 0 && rl != 255) *(u32x4*)(ACT + (size_t)(u.pm * 256 + rl) * FFN + ch0) = o; } }
.LBB0_853:
	v_mov_b32_e32 v137, v136
	v_mov_b32_e32 v138, v136
	v_mov_b32_e32 v139, v136
	v_pk_fma_f32 v[90:91], v[90:91], v[138:139], v[122:123]
	v_pk_fma_f32 v[88:89], v[88:89], v[136:137], v[120:121]
	s_movk_i32 s12, 0xff80
	s_nop 0
	v_mov_b32_dpp v140, v88 row_ror:15 row_mask:0xf bank_mask:0xf
	v_mov_b32_dpp v141, v89 row_ror:15 row_mask:0xf bank_mask:0xf
	v_mov_b32_dpp v142, v90 row_ror:15 row_mask:0xf bank_mask:0xf
	v_mov_b32_dpp v143, v91 row_ror:15 row_mask:0xf bank_mask:0xf
	v_mov_b32_dpp v148, v128 row_ror:1 row_mask:0xf bank_mask:0xf
	v_mov_b32_dpp v149, v129 row_ror:1 row_mask:0xf bank_mask:0xf
	v_mov_b32_dpp v150, v130 row_ror:1 row_mask:0xf bank_mask:0xf
	v_mov_b32_dpp v151, v131 row_ror:1 row_mask:0xf bank_mask:0xf
	v_mov_b32_dpp v144, v128 row_ror:15 row_mask:0xf bank_mask:0xf
	v_mov_b32_dpp v145, v129 row_ror:15 row_mask:0xf bank_mask:0xf
	v_mov_b32_dpp v146, v130 row_ror:15 row_mask:0xf bank_mask:0xf
	v_mov_b32_dpp v147, v131 row_ror:15 row_mask:0xf bank_mask:0xf
	v_cmp_ne_u32_e32 vcc, s12, v192
	s_and_saveexec_b64 s[12:13], vcc
	s_cbranch_execz .LBB0_855
	s_waitcnt lgkmcnt(0)
	v_cndmask_b32_e64 v119, v163, v119, s[10:11]
	v_cndmask_b32_e64 v118, v161, v118, s[10:11]
	v_pk_mul_f32 v[118:119], v[86:87], v[118:119]
	v_cndmask_b32_e64 v117, v162, v117, s[10:11]
	v_cndmask_b32_e64 v116, v160, v116, s[10:11]
	v_pk_fma_f32 v[118:119], v[78:79], v[134:135], v[118:119]
	v_cndmask_b32_e64 v155, v159, v155, s[8:9]
	v_cndmask_b32_e64 v154, v157, v154, s[8:9]
	v_pk_mul_f32 v[116:117], v[84:85], v[116:117]
	v_pk_fma_f32 v[118:119], v[74:75], v[154:155], v[118:119]
	v_pk_fma_f32 v[116:117], v[76:77], v[132:133], v[116:117]
	v_cndmask_b32_e64 v153, v158, v153, s[8:9]
	v_cndmask_b32_e64 v152, v156, v152, s[8:9]
	v_pk_add_f32 v[118:119], v[70:71], v[118:119]
	v_pk_fma_f32 v[116:117], v[72:73], v[152:153], v[116:117]
	v_mul_f32_e32 v152, 0xbfb8aa3b, v119
	v_exp_f32_e32 v152, v152
	v_mov_b32_e32 v164, v206
	v_mov_b32_e32 v165, v206
	v_pk_fma_f32 v[82:83], v[82:83], v[164:165], v[98:99]
	v_add_f32_e32 v152, 1.0, v152
	v_rcp_f32_e32 v153, v152
	v_mul_f32_e32 v152, 0xbfb8aa3b, v118
	v_exp_f32_e32 v152, v152
	v_pk_add_f32 v[116:117], v[68:69], v[116:117]
	v_pk_fma_f32 v[80:81], v[80:81], v[206:207], v[96:97]
	v_cndmask_b32_e64 v113, v149, v113, s[10:11]
	v_add_f32_e32 v152, 1.0, v152
	v_rcp_f32_e32 v152, v152
	v_cndmask_b32_e64 v112, v148, v112, s[10:11]
	v_pk_mul_f32 v[112:113], v[60:61], v[112:113]
	v_pk_fma_f32 v[32:33], v[32:33], v[206:207], v[92:93]
	v_pk_mul_f32 v[118:119], v[118:119], v[152:153]
	v_pk_fma_f32 v[112:113], v[128:129], v[56:57], v[112:113]
	v_pk_mul_f32 v[82:83], v[82:83], v[118:119]
	v_mul_f32_e32 v118, 0xbfb8aa3b, v117
	v_exp_f32_e32 v118, v118
	v_pk_fma_f32 v[34:35], v[34:35], v[164:165], v[94:95]
	v_add_f32_e32 v118, 1.0, v118
	v_rcp_f32_e32 v119, v118
	v_mul_f32_e32 v118, 0xbfb8aa3b, v116
	v_exp_f32_e32 v118, v118
	s_nop 0
	v_add_f32_e32 v118, 1.0, v118
	v_rcp_f32_e32 v118, v118
	s_nop 0
	v_pk_mul_f32 v[116:117], v[116:117], v[118:119]
	s_nop 0
	v_pk_mul_f32 v[80:81], v[80:81], v[116:117]
	v_cndmask_b32_e64 v117, v145, v141, s[8:9]
	v_cvt_pk_bf16_f32 v80, v80, v81
	v_cvt_pk_bf16_f32 v81, v82, v83
	v_cndmask_b32_e64 v83, v151, v115, s[10:11]
	v_cndmask_b32_e64 v82, v150, v114, s[10:11]
	v_pk_mul_f32 v[82:83], v[62:63], v[82:83]
	v_cndmask_b32_e64 v115, v147, v143, s[8:9]
	v_pk_fma_f32 v[82:83], v[130:131], v[58:59], v[82:83]
	v_cndmask_b32_e64 v114, v146, v142, s[8:9]
	v_cndmask_b32_e64 v116, v144, v140, s[8:9]
	v_pk_fma_f32 v[112:113], v[48:49], v[116:117], v[112:113]
	v_pk_fma_f32 v[82:83], v[50:51], v[114:115], v[82:83]
	s_nop 0
	v_pk_add_f32 v[114:115], v[46:47], v[82:83]
	v_pk_add_f32 v[82:83], v[44:45], v[112:113]
	s_nop 0
	v_mul_f32_e32 v112, 0xbfb8aa3b, v82
	v_mul_f32_e32 v113, 0xbfb8aa3b, v83
	v_exp_f32_e32 v112, v112
	v_exp_f32_e32 v113, v113
	v_add_f32_e32 v112, 1.0, v112
	v_add_f32_e32 v113, 1.0, v113
	v_rcp_f32_e32 v112, v112
	v_rcp_f32_e32 v113, v113
	s_nop 0
	v_pk_mul_f32 v[82:83], v[82:83], v[112:113]
	s_nop 0
	v_pk_mul_f32 v[32:33], v[32:33], v[82:83]
	s_nop 0
	v_cvt_pk_bf16_f32 v82, v32, v33
	v_mul_f32_e32 v32, 0xbfb8aa3b, v114
	v_mul_f32_e32 v33, 0xbfb8aa3b, v115
	v_exp_f32_e32 v32, v32
	v_exp_f32_e32 v33, v33
	v_add_f32_e32 v32, 1.0, v32
	v_add_f32_e32 v33, 1.0, v33
	v_rcp_f32_e32 v32, v32
	v_rcp_f32_e32 v33, v33
	s_nop 0
	v_pk_mul_f32 v[32:33], v[114:115], v[32:33]
	s_nop 0
	v_pk_mul_f32 v[32:33], v[34:35], v[32:33]
	s_nop 0
	v_cvt_pk_bf16_f32 v83, v32, v33
	v_add_u32_e32 v32, 0x80, v205
	v_mad_i64_i32 v[32:33], s[40:41], v32, s38, v[172:173]
	global_store_dwordx4 v[32:33], v[80:83], off sc1
;     __host__ __device__ bool next(int i, Unit& u) const { const long L = (long)i * G + c; if (L >= maxL) return false; return unit_of(L, u); }
; #define LAS __attribute__((address_space(3)))
; __device__ __forceinline__ unsigned pk2(float lo, float hi) { const f32x2_t v = {lo, hi}; const bf16x2_t b = __builtin_convertvector(v, bf16x2_t); return __builtin_bit_cast(unsigned, b); }
; __device__ __forceinline__ float siluf_(float x) { return x * __builtin_amdgcn_rcpf(1.0f + __expf(-x)); }
;     __device__ __forceinline__ void operator()(const f32x4 (&acc_c)[2][2][4][2], const pg8::Unit& u, int wr, int wc, int fr, int fq) const {
;     ...
;             for (int m = 0; m < 4; ++m) { const int rl = ai * 128 + wr * 64 + m * 16 + fr;
;                 const float rstd = __builtin_amdgcn_rsqf(rsq[rl] * (1.0f / D_MODEL) + EPS);
; #pragma unroll
;                 for (int bj = 0; bj < 2; ++bj)
; #pragma unroll
;                     for (int n = 0; n < 2; ++n) acc[ai][bj][m][n] = acc[ai][bj][m][n] * rstd + *(const LAS f32x4*)(bias2 + bj * 128 + cl + 4 * n); }
;     ...
;             for (int m = 0; m < 4; ++m) { u32x4 o;
; #pragma unroll
;                 for (int n = 0; n < 2; ++n) { const f32x4 cur = acc[ai][0][m][n];
;                     f32x4 pu, nd;
;                     if (m > 0) pu = ror1_4(acc[ai][0][m > 0 ? m - 1 : 0][n]); else pu = (bi > 0) ? *(const LAS f32x4*)(X + ((bi - 1) * 2 + 1) * 128 + cl + 4 * n) : (f32x4){0.f, 0.f, 0.f, 0.f};
;                     if (m < 3) nd = rol1_4(acc[ai][0][m < 3 ? m + 1 : 3][n]); else nd = (bi < 3) ? *(const LAS f32x4*)(X + ((bi + 1) * 2 + 0) * 128 + cl + 4 * n) : (f32x4){0.f, 0.f, 0.f, 0.f};
;                     const f32x4 ps = ror1_4(cur), ns = rol1_4(cur);
;                     const f32x4 prev = (fr > 0) ? ps : pu, next = (fr < 15) ? ns : nd;
;                     const f32x4 uu = w0[n] * prev + w1[n] * cur + w2[n] * next + cbv[n]; const f32x4 gt = acc[ai][1][m][n];
;                     f32x4 r; r.x = siluf_(uu.x) * gt.x; r.y = siluf_(uu.y) * gt.y; r.z = siluf_(uu.z) * gt.z; r.w = siluf_(uu.w) * gt.w;
;                     if (n == 0) { o.x = pk2(r.x, r.y); o.y = pk2(r.z, r.w); } else { o.z = pk2(r.x, r.y); o.w = pk2(r.z, r.w); } }
;                 const int rl = ai * 128 + wr * 64 + m * 16 + fr;
;                 if (rl != 0 && rl != 255) *(u32x4*)(ACT + (size_t)(u.pm * 256 + rl) * FFN + ch0) = o; } }
.LBB0_855:
	s_or_b64 exec, exec, s[12:13]
	v_fmamk_f32 v33, v204, 0x3a000000, v224
	v_rsq_f32_e32 v34, v33
	v_pk_fma_f32 v[82:83], v[16:17], v[136:137], v[92:93]
	s_waitcnt lgkmcnt(0)
	v_pk_fma_f32 v[16:17], v[26:27], v[34:35], v[122:123] op_sel_hi:[1,0,1]
	v_mov_b32_dpp v117, v102 row_ror:1 row_mask:0xf bank_mask:0xf
	v_mov_b32_dpp v26, v134 row_ror:1 row_mask:0xf bank_mask:0xf
	v_mov_b32_dpp v27, v135 row_ror:1 row_mask:0xf bank_mask:0xf
	v_mov_b32_dpp v118, v103 row_ror:1 row_mask:0xf bank_mask:0xf
	v_pk_fma_f32 v[80:81], v[18:19], v[138:139], v[94:95]
	v_pk_fma_f32 v[30:31], v[30:31], v[34:35], v[126:127] op_sel_hi:[1,0,1]
	v_pk_fma_f32 v[18:19], v[24:25], v[34:35], v[120:121] op_sel_hi:[1,0,1]
	v_cndmask_b32_e64 v27, v118, v27, s[10:11]
	v_cndmask_b32_e64 v26, v117, v26, s[10:11]
	v_mov_b32_dpp v113, v30 row_ror:15 row_mask:0xf bank_mask:0xf
	v_mov_b32_dpp v114, v31 row_ror:15 row_mask:0xf bank_mask:0xf
	v_mov_b32_dpp v120, v102 row_ror:15 row_mask:0xf bank_mask:0xf
	v_mov_b32_dpp v121, v103 row_ror:15 row_mask:0xf bank_mask:0xf
	v_pk_mul_f32 v[26:27], v[86:87], v[26:27]
	v_mov_b32_dpp v24, v132 row_ror:1 row_mask:0xf bank_mask:0xf
	v_mov_b32_dpp v25, v133 row_ror:1 row_mask:0xf bank_mask:0xf
	v_mov_b32_dpp v115, v100 row_ror:1 row_mask:0xf bank_mask:0xf
	v_mov_b32_dpp v116, v101 row_ror:1 row_mask:0xf bank_mask:0xf
	v_pk_fma_f32 v[26:27], v[78:79], v[102:103], v[26:27]
	v_cndmask_b32_e64 v103, v121, v114, s[8:9]
	v_cndmask_b32_e64 v102, v120, v113, s[8:9]
	v_pk_fma_f32 v[28:29], v[28:29], v[34:35], v[124:125] op_sel_hi:[1,0,1]
	v_pk_fma_f32 v[12:13], v[12:13], v[34:35], v[96:97] op_sel_hi:[1,0,1]
	v_pk_fma_f32 v[14:15], v[14:15], v[34:35], v[98:99] op_sel_hi:[1,0,1]
	v_pk_fma_f32 v[8:9], v[8:9], v[34:35], v[92:93] op_sel_hi:[1,0,1]
	v_cndmask_b32_e64 v25, v116, v25, s[10:11]
	v_cndmask_b32_e64 v24, v115, v24, s[10:11]
	v_pk_fma_f32 v[26:27], v[74:75], v[102:103], v[26:27]
	v_mov_b32_dpp v33, v28 row_ror:15 row_mask:0xf bank_mask:0xf
	v_mov_b32_dpp v112, v29 row_ror:15 row_mask:0xf bank_mask:0xf
	v_mov_b32_dpp v35, v100 row_ror:15 row_mask:0xf bank_mask:0xf
	v_mov_b32_dpp v119, v101 row_ror:15 row_mask:0xf bank_mask:0xf
	v_pk_mul_f32 v[24:25], v[84:85], v[24:25]
	v_pk_add_f32 v[26:27], v[70:71], v[26:27]
	v_pk_fma_f32 v[24:25], v[76:77], v[100:101], v[24:25]
	v_cndmask_b32_e64 v101, v119, v112, s[8:9]
	v_cndmask_b32_e64 v100, v35, v33, s[8:9]
	v_mul_f32_e32 v35, 0xbfb8aa3b, v27
	v_pk_fma_f32 v[24:25], v[72:73], v[100:101], v[24:25]
	v_exp_f32_e32 v35, v35
	v_mul_f32_e32 v100, 0xbfb8aa3b, v26
	v_exp_f32_e32 v100, v100
	v_pk_add_f32 v[24:25], v[68:69], v[24:25]
	v_add_f32_e32 v35, 1.0, v35
	v_rcp_f32_e32 v101, v35
	v_add_f32_e32 v35, 1.0, v100
	v_mul_f32_e32 v100, 0xbfb8aa3b, v25
	v_exp_f32_e32 v102, v100
	v_mul_f32_e32 v100, 0xbfb8aa3b, v24
	v_exp_f32_e32 v119, v100
	v_rcp_f32_e32 v100, v35
	v_add_f32_e32 v35, 1.0, v102
	v_rcp_f32_e32 v103, v35
	v_add_f32_e32 v35, 1.0, v119
	v_rcp_f32_e32 v102, v35
	v_pk_fma_f32 v[20:21], v[20:21], v[136:137], v[96:97]
	v_pk_fma_f32 v[22:23], v[22:23], v[138:139], v[98:99]
	v_pk_mul_f32 v[26:27], v[26:27], v[100:101]
	v_pk_mul_f32 v[24:25], v[24:25], v[102:103]
	v_pk_mul_f32 v[22:23], v[22:23], v[26:27]
	v_pk_mul_f32 v[20:21], v[20:21], v[24:25]
	v_cvt_pk_bf16_f32 v24, v20, v21
	s_nop 0
	v_mov_b32_dpp v20, v128 row_ror:1 row_mask:0xf bank_mask:0xf
	v_mov_b32_dpp v21, v129 row_ror:1 row_mask:0xf bank_mask:0xf
	v_mov_b32_dpp v25, v130 row_ror:1 row_mask:0xf bank_mask:0xf
	v_mov_b32_dpp v26, v131 row_ror:1 row_mask:0xf bank_mask:0xf
	v_mov_b32_dpp v119, v88 row_ror:1 row_mask:0xf bank_mask:0xf
	v_mov_b32_dpp v120, v89 row_ror:1 row_mask:0xf bank_mask:0xf
	v_mov_b32_dpp v121, v90 row_ror:1 row_mask:0xf bank_mask:0xf
	v_mov_b32_dpp v122, v91 row_ror:1 row_mask:0xf bank_mask:0xf
	v_cndmask_b32_e64 v21, v120, v21, s[10:11]
	v_cndmask_b32_e64 v20, v119, v20, s[10:11]
	v_cndmask_b32_e64 v27, v122, v26, s[10:11]
	v_cndmask_b32_e64 v26, v121, v25, s[10:11]
	v_pk_fma_f32 v[10:11], v[10:11], v[34:35], v[94:95] op_sel_hi:[1,0,1]
	v_mov_b32_dpp v102, v16 row_ror:15 row_mask:0xf bank_mask:0xf
	v_mov_b32_dpp v103, v17 row_ror:15 row_mask:0xf bank_mask:0xf
	v_mov_b32_dpp v123, v90 row_ror:15 row_mask:0xf bank_mask:0xf
	v_mov_b32_dpp v124, v91 row_ror:15 row_mask:0xf bank_mask:0xf
	v_pk_mul_f32 v[26:27], v[62:63], v[26:27]
	v_pk_mul_f32 v[20:21], v[60:61], v[20:21]
	v_mov_b32_dpp v34, v88 row_ror:15 row_mask:0xf bank_mask:0xf
	v_mov_b32_dpp v35, v89 row_ror:15 row_mask:0xf bank_mask:0xf
	v_pk_fma_f32 v[20:21], v[88:89], v[56:57], v[20:21]
	v_pk_fma_f32 v[26:27], v[90:91], v[58:59], v[26:27]
	v_cndmask_b32_e64 v89, v124, v103, s[8:9]
	v_cndmask_b32_e64 v88, v123, v102, s[8:9]
	v_pk_fma_f32 v[26:27], v[50:51], v[88:89], v[26:27]
	v_mov_b32_dpp v100, v18 row_ror:15 row_mask:0xf bank_mask:0xf
	v_mov_b32_dpp v101, v19 row_ror:15 row_mask:0xf bank_mask:0xf
	v_pk_add_f32 v[26:27], v[46:47], v[26:27]
	v_cndmask_b32_e64 v35, v35, v101, s[8:9]
	v_cndmask_b32_e64 v34, v34, v100, s[8:9]
	v_mul_f32_e32 v25, 0xbfb8aa3b, v27
	v_pk_fma_f32 v[20:21], v[48:49], v[34:35], v[20:21]
	v_exp_f32_e32 v25, v25
;     __host__ __device__ bool next(int i, Unit& u) const { const long L = (long)i * G + c; if (L >= maxL) return false; return unit_of(L, u); }
; #define LAS __attribute__((address_space(3)))
; __device__ __forceinline__ unsigned pk2(float lo, float hi) { const f32x2_t v = {lo, hi}; const bf16x2_t b = __builtin_convertvector(v, bf16x2_t); return __builtin_bit_cast(unsigned, b); }
; __device__ __forceinline__ float siluf_(float x) { return x * __builtin_amdgcn_rcpf(1.0f + __expf(-x)); }
;     __device__ __forceinline__ void operator()(const f32x4 (&acc_c)[2][2][4][2], const pg8::Unit& u, int wr, int wc, int fr, int fq) const {
;     ...
;             for (int m = 0; m < 4; ++m) { const int rl = ai * 128 + wr * 64 + m * 16 + fr;
;                 const float rstd = __builtin_amdgcn_rsqf(rsq[rl] * (1.0f / D_MODEL) + EPS);
; #pragma unroll
;                 for (int bj = 0; bj < 2; ++bj)
; #pragma unroll
;                     for (int n = 0; n < 2; ++n) acc[ai][bj][m][n] = acc[ai][bj][m][n] * rstd + *(const LAS f32x4*)(bias2 + bj * 128 + cl + 4 * n); }
;     ...
;             for (int m = 0; m < 4; ++m) { u32x4 o;
; #pragma unroll
;                 for (int n = 0; n < 2; ++n) { const f32x4 cur = acc[ai][0][m][n];
;                     f32x4 pu, nd;
;                     if (m > 0) pu = ror1_4(acc[ai][0][m > 0 ? m - 1 : 0][n]); else pu = (bi > 0) ? *(const LAS f32x4*)(X + ((bi - 1) * 2 + 1) * 128 + cl + 4 * n) : (f32x4){0.f, 0.f, 0.f, 0.f};
;                     if (m < 3) nd = rol1_4(acc[ai][0][m < 3 ? m + 1 : 3][n]); else nd = (bi < 3) ? *(const LAS f32x4*)(X + ((bi + 1) * 2 + 0) * 128 + cl + 4 * n) : (f32x4){0.f, 0.f, 0.f, 0.f};
;                     const f32x4 ps = ror1_4(cur), ns = rol1_4(cur);
;                     const f32x4 prev = (fr > 0) ? ps : pu, next = (fr < 15) ? ns : nd;
;                     const f32x4 uu = w0[n] * prev + w1[n] * cur + w2[n] * next + cbv[n]; const f32x4 gt = acc[ai][1][m][n];
;                     f32x4 r; r.x = siluf_(uu.x) * gt.x; r.y = siluf_(uu.y) * gt.y; r.z = siluf_(uu.z) * gt.z; r.w = siluf_(uu.w) * gt.w;
;                     if (n == 0) { o.x = pk2(r.x, r.y); o.y = pk2(r.z, r.w); } else { o.z = pk2(r.x, r.y); o.w = pk2(r.z, r.w); } }
;                 const int rl = ai * 128 + wr * 64 + m * 16 + fr;
;                 if (rl != 0 && rl != 255) *(u32x4*)(ACT + (size_t)(u.pm * 256 + rl) * FFN + ch0) = o; } }
	v_mul_f32_e32 v34, 0xbfb8aa3b, v26
	v_exp_f32_e32 v34, v34
	v_pk_add_f32 v[20:21], v[44:45], v[20:21]
	v_add_f32_e32 v25, 1.0, v25
	v_rcp_f32_e32 v35, v25
	v_add_f32_e32 v25, 1.0, v34
	v_mul_f32_e32 v34, 0xbfb8aa3b, v21
	v_exp_f32_e32 v88, v34
	v_mul_f32_e32 v34, 0xbfb8aa3b, v20
	v_exp_f32_e32 v90, v34
	v_rcp_f32_e32 v34, v25
	v_add_f32_e32 v25, 1.0, v88
	v_rcp_f32_e32 v89, v25
	v_add_f32_e32 v25, 1.0, v90
	v_rcp_f32_e32 v88, v25
	v_cvt_pk_bf16_f32 v25, v22, v23
	v_pk_mul_f32 v[22:23], v[26:27], v[34:35]
	v_pk_mul_f32 v[20:21], v[20:21], v[88:89]
	v_pk_mul_f32 v[22:23], v[80:81], v[22:23]
	v_pk_mul_f32 v[20:21], v[82:83], v[20:21]
	v_cvt_pk_bf16_f32 v27, v22, v23
	v_cvt_pk_bf16_f32 v26, v20, v21
	v_add_u32_e32 v20, 0x90, v205
	v_mov_b32_dpp v21, v30 row_ror:1 row_mask:0xf bank_mask:0xf
	v_mov_b32_dpp v23, v31 row_ror:1 row_mask:0xf bank_mask:0xf
	v_cndmask_b32_e64 v83, v23, v118, s[10:11]
	v_cndmask_b32_e64 v82, v21, v117, s[10:11]
	v_mad_i64_i32 v[34:35], s[12:13], v20, s38, v[172:173]
	v_mov_b32_dpp v90, v66 row_ror:15 row_mask:0xf bank_mask:0xf
	v_mov_b32_dpp v91, v67 row_ror:15 row_mask:0xf bank_mask:0xf
	v_pk_mul_f32 v[82:83], v[86:87], v[82:83]
	v_mov_b32_dpp v20, v28 row_ror:1 row_mask:0xf bank_mask:0xf
	v_mov_b32_dpp v22, v29 row_ror:1 row_mask:0xf bank_mask:0xf
	v_pk_fma_f32 v[30:31], v[78:79], v[30:31], v[82:83]
	v_cndmask_b32_e64 v83, v114, v91, s[8:9]
	v_cndmask_b32_e64 v82, v113, v90, s[8:9]
	v_cndmask_b32_e64 v81, v22, v116, s[10:11]
	v_cndmask_b32_e64 v80, v20, v115, s[10:11]
	v_pk_fma_f32 v[30:31], v[74:75], v[82:83], v[30:31]
	v_mov_b32_dpp v88, v64 row_ror:15 row_mask:0xf bank_mask:0xf
	v_mov_b32_dpp v89, v65 row_ror:15 row_mask:0xf bank_mask:0xf
	v_pk_mul_f32 v[80:81], v[84:85], v[80:81]
	v_pk_add_f32 v[30:31], v[70:71], v[30:31]
	v_pk_fma_f32 v[28:29], v[76:77], v[28:29], v[80:81]
	v_cndmask_b32_e64 v81, v112, v89, s[8:9]
	v_cndmask_b32_e64 v80, v33, v88, s[8:9]
	v_mul_f32_e32 v33, 0xbfb8aa3b, v31
	v_pk_fma_f32 v[28:29], v[72:73], v[80:81], v[28:29]
	v_exp_f32_e32 v33, v33
	v_mul_f32_e32 v80, 0xbfb8aa3b, v30
	v_exp_f32_e32 v80, v80
	v_pk_add_f32 v[28:29], v[68:69], v[28:29]
	v_add_f32_e32 v33, 1.0, v33
	v_rcp_f32_e32 v81, v33
	v_add_f32_e32 v33, 1.0, v80
	v_mul_f32_e32 v80, 0xbfb8aa3b, v29
	v_exp_f32_e32 v82, v80
	v_mul_f32_e32 v80, 0xbfb8aa3b, v28
	v_exp_f32_e32 v88, v80
	v_rcp_f32_e32 v80, v33
	v_add_f32_e32 v33, 1.0, v82
	v_rcp_f32_e32 v83, v33
	v_add_f32_e32 v33, 1.0, v88
	v_rcp_f32_e32 v82, v33
	global_store_dwordx4 v[34:35], v[24:27], off sc1
	v_lshl_add_u32 v32, v226, 2, s96
	s_andn2_b64 vcc, exec, s[52:53]
	v_pk_mul_f32 v[24:25], v[30:31], v[80:81]
	v_mov_b32_dpp v26, v16 row_ror:1 row_mask:0xf bank_mask:0xf
	v_mov_b32_dpp v27, v17 row_ror:1 row_mask:0xf bank_mask:0xf
	v_pk_mul_f32 v[14:15], v[14:15], v[24:25]
	v_pk_mul_f32 v[24:25], v[28:29], v[82:83]
	v_cndmask_b32_e64 v27, v27, v122, s[10:11]
	v_cndmask_b32_e64 v26, v26, v121, s[10:11]
	v_pk_mul_f32 v[12:13], v[12:13], v[24:25]
	v_mov_b32_dpp v30, v54 row_ror:15 row_mask:0xf bank_mask:0xf
	v_mov_b32_dpp v31, v55 row_ror:15 row_mask:0xf bank_mask:0xf
	v_pk_mul_f32 v[26:27], v[62:63], v[26:27]
	v_mov_b32_dpp v24, v18 row_ror:1 row_mask:0xf bank_mask:0xf
	v_mov_b32_dpp v25, v19 row_ror:1 row_mask:0xf bank_mask:0xf
	v_pk_fma_f32 v[26:27], v[58:59], v[16:17], v[26:27]
	v_cndmask_b32_e64 v31, v103, v31, s[8:9]
	v_cndmask_b32_e64 v30, v102, v30, s[8:9]
	v_cvt_pk_bf16_f32 v12, v12, v13
	v_cndmask_b32_e64 v25, v25, v120, s[10:11]
	v_cndmask_b32_e64 v24, v24, v119, s[10:11]
	v_pk_fma_f32 v[26:27], v[50:51], v[30:31], v[26:27]
	v_mov_b32_dpp v13, v52 row_ror:15 row_mask:0xf bank_mask:0xf
	v_mov_b32_dpp v28, v53 row_ror:15 row_mask:0xf bank_mask:0xf
	v_pk_mul_f32 v[24:25], v[60:61], v[24:25]
	v_pk_add_f32 v[26:27], v[46:47], v[26:27]
	v_pk_fma_f32 v[24:25], v[56:57], v[18:19], v[24:25]
	v_cndmask_b32_e64 v29, v101, v28, s[8:9]
	v_cndmask_b32_e64 v28, v100, v13, s[8:9]
	v_mul_f32_e32 v13, 0xbfb8aa3b, v27
	v_pk_fma_f32 v[24:25], v[48:49], v[28:29], v[24:25]
	v_exp_f32_e32 v13, v13
	v_mul_f32_e32 v28, 0xbfb8aa3b, v26
	v_exp_f32_e32 v28, v28
	v_pk_add_f32 v[24:25], v[44:45], v[24:25]
	v_add_f32_e32 v13, 1.0, v13
	v_rcp_f32_e32 v29, v13
	v_add_f32_e32 v13, 1.0, v28
	v_mul_f32_e32 v28, 0xbfb8aa3b, v25
	v_exp_f32_e32 v30, v28
	v_mul_f32_e32 v28, 0xbfb8aa3b, v24
	v_exp_f32_e32 v33, v28
	v_rcp_f32_e32 v28, v13
	v_add_f32_e32 v13, 1.0, v30
	v_rcp_f32_e32 v31, v13
	v_add_f32_e32 v13, 1.0, v33
	v_rcp_f32_e32 v30, v13
	v_cvt_pk_bf16_f32 v13, v14, v15
	v_pk_mul_f32 v[14:15], v[26:27], v[28:29]
	s_nop 0
	v_pk_mul_f32 v[10:11], v[10:11], v[14:15]
	v_pk_mul_f32 v[14:15], v[24:25], v[30:31]
	s_nop 0
	v_pk_mul_f32 v[8:9], v[8:9], v[14:15]
	v_cvt_pk_bf16_f32 v15, v10, v11
	v_cvt_pk_bf16_f32 v14, v8, v9
	v_add_u32_e32 v8, 0xa0, v205
	v_mad_i64_i32 v[8:9], s[12:13], v8, s38, v[172:173]
	global_store_dwordx4 v[8:9], v[12:15], off sc1
	v_cndmask_b32_e64 v9, 0, 1, s[52:53]
	v_mov_b32_e32 v8, 0
	v_cmp_ne_u32_e64 s[12:13], 1, v9
	v_mov_b32_e32 v12, 0
	v_mov_b32_e32 v13, 0
	v_mov_b32_e32 v14, 0
	v_mov_b32_e32 v15, 0
	s_cbranch_vccnz .LBB0_857
	ds_read_b128 v[12:15], v32 offset:1024

;     __host__ __device__ bool next(int i, Unit& u) const { const long L = (long)i * G + c; if (L >= maxL) return false; return unit_of(L, u); }
; #define LAS __attribute__((address_space(3)))
; __device__ __forceinline__ unsigned pk2(float lo, float hi) { const f32x2_t v = {lo, hi}; const bf16x2_t b = __builtin_convertvector(v, bf16x2_t); return __builtin_bit_cast(unsigned, b); }
;     __device__ __forceinline__ void operator()(const f32x4 (&acc_c)[2][2][4][2], const pg8::Unit& u, int wr, int wc, int fr, int fq) const {
;     ...
;             for (int m = 0; m < 4; ++m) { u32x4 o;
; #pragma unroll
;                 for (int n = 0; n < 2; ++n) { const f32x4 cur = acc[ai][0][m][n];
;                     f32x4 pu, nd;
;                     if (m > 0) pu = ror1_4(acc[ai][0][m > 0 ? m - 1 : 0][n]); else pu = (bi > 0) ? *(const LAS f32x4*)(X + ((bi - 1) * 2 + 1) * 128 + cl + 4 * n) : (f32x4){0.f, 0.f, 0.f, 0.f};
;                     if (m < 3) nd = rol1_4(acc[ai][0][m < 3 ? m + 1 : 3][n]); else nd = (bi < 3) ? *(const LAS f32x4*)(X + ((bi + 1) * 2 + 0) * 128 + cl + 4 * n) : (f32x4){0.f, 0.f, 0.f, 0.f};
;                     const f32x4 ps = ror1_4(cur), ns = rol1_4(cur);
;                     const f32x4 prev = (fr > 0) ? ps : pu, next = (fr < 15) ? ns : nd;
;                     const f32x4 uu = w0[n] * prev + w1[n] * cur + w2[n] * next + cbv[n]; const f32x4 gt = acc[ai][1][m][n];
;                     f32x4 r; r.x = siluf_(uu.x) * gt.x; r.y = siluf_(uu.y) * gt.y; r.z = siluf_(uu.z) * gt.z; r.w = siluf_(uu.w) * gt.w;
;                     if (n == 0) { o.x = pk2(r.x, r.y); o.y = pk2(r.z, r.w); } else { o.z = pk2(r.x, r.y); o.w = pk2(r.z, r.w); } }
;                 const int rl = ai * 128 + wr * 64 + m * 16 + fr;
;                 if (rl != 0 && rl != 255) *(u32x4*)(ACT + (size_t)(u.pm * 256 + rl) * FFN + ch0) = o; } }
;         if (wr == 0 && fr < 2) {
; #pragma unroll
;             for (int n = 0; n < 2; ++n) { *(f32x4*)(HALO + (size_t)fr * FFN + ch0 + 4 * n) = acc[0][0][0][n]; if (fr == 0) *(f32x4*)(HALO + (size_t)4 * FFN + ch0 + 4 * n) = acc[0][1][0][n]; } }
;         if (wr == 1 && fr >= 14) {
; #pragma unroll
;             for (int n = 0; n < 2; ++n) { *(f32x4*)(HALO + (size_t)(fr - 12) * FFN + ch0 + 4 * n) = acc[1][0][3][n]; if (fr == 15) *(f32x4*)(HALO + (size_t)5 * FFN + ch0 + 4 * n) = acc[1][1][3][n]; } }
.LBB0_859:
	v_mov_b32_e32 v32, v202
	v_mov_b32_e32 v33, v202
	v_pk_fma_f32 v[6:7], v[6:7], v[32:33], v[98:99]
	v_pk_fma_f32 v[2:3], v[2:3], v[32:33], v[94:95]
	s_movk_i32 s12, 0x4f
	v_pk_fma_f32 v[4:5], v[4:5], v[202:203], v[96:97]
	v_pk_fma_f32 v[0:1], v[0:1], v[202:203], v[92:93]
	v_mov_b32_dpp v32, v52 row_ror:1 row_mask:0xf bank_mask:0xf
	v_mov_b32_dpp v33, v53 row_ror:1 row_mask:0xf bank_mask:0xf
	v_mov_b32_dpp v80, v54 row_ror:1 row_mask:0xf bank_mask:0xf
	v_mov_b32_dpp v83, v55 row_ror:1 row_mask:0xf bank_mask:0xf
	v_mov_b32_dpp v17, v52 row_ror:15 row_mask:0xf bank_mask:0xf
	v_mov_b32_dpp v25, v53 row_ror:15 row_mask:0xf bank_mask:0xf
	v_mov_b32_dpp v28, v54 row_ror:15 row_mask:0xf bank_mask:0xf
	v_mov_b32_dpp v31, v55 row_ror:15 row_mask:0xf bank_mask:0xf
	v_cmp_ne_u32_e32 vcc, s12, v192
	s_and_saveexec_b64 s[12:13], vcc
	s_cbranch_execz .LBB0_861
	v_cndmask_b32_e64 v89, v81, v22, s[10:11]
	v_cndmask_b32_e64 v23, v82, v23, s[10:11]
	v_cndmask_b32_e64 v22, v35, v21, s[10:11]
	v_cndmask_b32_e64 v88, v34, v20, s[10:11]
	v_pk_mul_f32 v[20:21], v[86:87], v[22:23]
	s_waitcnt lgkmcnt(0)
	v_cndmask_b32_e64 v15, v30, v15, s[8:9]
	v_pk_fma_f32 v[20:21], v[78:79], v[66:67], v[20:21]
	v_cndmask_b32_e64 v14, v27, v14, s[8:9]
	v_pk_fma_f32 v[14:15], v[74:75], v[14:15], v[20:21]
	v_pk_mul_f32 v[22:23], v[84:85], v[88:89]
	v_pk_add_f32 v[14:15], v[70:71], v[14:15]
	v_pk_fma_f32 v[22:23], v[76:77], v[64:65], v[22:23]
	v_mul_f32_e32 v20, 0xbfb8aa3b, v15
	v_cndmask_b32_e64 v13, v29, v13, s[8:9]
	v_cndmask_b32_e64 v12, v26, v12, s[8:9]
	v_exp_f32_e32 v20, v20
	v_mul_f32_e32 v21, 0xbfb8aa3b, v14
	v_pk_fma_f32 v[12:13], v[72:73], v[12:13], v[22:23]
	v_exp_f32_e32 v22, v21
	v_pk_add_f32 v[12:13], v[68:69], v[12:13]
	v_add_f32_e32 v20, 1.0, v20
	v_rcp_f32_e32 v21, v20
	v_add_f32_e32 v20, 1.0, v22
	v_mul_f32_e32 v22, 0xbfb8aa3b, v13
	v_exp_f32_e32 v22, v22
	v_mul_f32_e32 v23, 0xbfb8aa3b, v12
	v_exp_f32_e32 v26, v23
	v_rcp_f32_e32 v20, v20
	v_add_f32_e32 v22, 1.0, v22
	v_rcp_f32_e32 v23, v22
	v_add_f32_e32 v22, 1.0, v26
	v_rcp_f32_e32 v22, v22
	v_pk_mul_f32 v[14:15], v[14:15], v[20:21]
	v_cndmask_b32_e64 v9, v25, v9, s[8:9]
	v_pk_mul_f32 v[14:15], v[6:7], v[14:15]
	v_pk_mul_f32 v[12:13], v[12:13], v[22:23]
	v_cndmask_b32_e64 v8, v17, v8, s[8:9]
	v_pk_mul_f32 v[12:13], v[4:5], v[12:13]
	v_cndmask_b32_e64 v11, v31, v11, s[8:9]
	v_cvt_pk_bf16_f32 v12, v12, v13
	v_cvt_pk_bf16_f32 v13, v14, v15
	v_cndmask_b32_e64 v14, v80, v19, s[10:11]
	v_cndmask_b32_e64 v19, v33, v18, s[10:11]
	v_cndmask_b32_e64 v18, v32, v24, s[10:11]
	v_pk_mul_f32 v[18:19], v[60:61], v[18:19]
	v_cndmask_b32_e64 v15, v83, v16, s[10:11]
	v_pk_fma_f32 v[18:19], v[56:57], v[52:53], v[18:19]
	v_pk_mul_f32 v[14:15], v[62:63], v[14:15]
	v_pk_fma_f32 v[8:9], v[48:49], v[8:9], v[18:19]
	v_pk_fma_f32 v[14:15], v[58:59], v[54:55], v[14:15]
	v_cndmask_b32_e64 v10, v28, v10, s[8:9]
	v_pk_add_f32 v[8:9], v[44:45], v[8:9]
	v_pk_fma_f32 v[10:11], v[50:51], v[10:11], v[14:15]
	v_mul_f32_e32 v14, 0xbfb8aa3b, v8
	v_mul_f32_e32 v15, 0xbfb8aa3b, v9
	v_exp_f32_e32 v14, v14
	v_exp_f32_e32 v15, v15
	v_pk_add_f32 v[10:11], v[46:47], v[10:11]
	v_add_f32_e32 v14, 1.0, v14
	v_mul_f32_e32 v16, 0xbfb8aa3b, v10
	v_mul_f32_e32 v17, 0xbfb8aa3b, v11
	v_exp_f32_e32 v16, v16
	v_exp_f32_e32 v17, v17
	v_add_f32_e32 v15, 1.0, v15
	v_rcp_f32_e32 v14, v14
	v_rcp_f32_e32 v15, v15
	v_add_f32_e32 v16, 1.0, v16
	v_add_f32_e32 v17, 1.0, v17
	v_rcp_f32_e32 v16, v16
	v_rcp_f32_e32 v17, v17
	v_pk_mul_f32 v[8:9], v[8:9], v[14:15]
	s_nop 0
	v_pk_mul_f32 v[8:9], v[0:1], v[8:9]
	s_nop 0
	v_cvt_pk_bf16_f32 v14, v8, v9
	v_pk_mul_f32 v[8:9], v[10:11], v[16:17]
	s_nop 0
	v_pk_mul_f32 v[8:9], v[2:3], v[8:9]
	s_nop 0
	v_cvt_pk_bf16_f32 v15, v8, v9
	v_add_u32_e32 v8, 0xb0, v205
	v_mad_i64_i32 v[8:9], s[40:41], v8, s38, v[172:173]
	global_store_dwordx4 v[8:9], v[12:15], off sc1
.LBB0_861:
	s_or_b64 exec, exec, s[12:13]
	s_mul_i32 s12, s26, 0x21000
	s_mul_hi_i32 s13, s26, 0x21000
	s_add_u32 s12, s93, s12
	v_cmp_gt_u32_e32 vcc, 2, v225
	s_addc_u32 s13, s94, s13
	s_and_b64 s[40:41], s[36:37], vcc
	s_and_saveexec_b64 s[26:27], s[40:41]
	s_cbranch_execz .LBB0_865
	s_waitcnt lgkmcnt(0)
	v_mul_u32_u24_e32 v8, 0x1600, v225
	v_lshlrev_b32_e32 v192, 2, v8
	v_lshl_add_u64 v[8:9], s[12:13], 0, v[192:193]
	v_lshl_add_u64 v[10:11], v[200:201], 2, v[8:9]
	global_store_dwordx4 v[10:11], v[40:43], off sc1
	s_and_saveexec_b64 s[72:73], s[10:11]
	s_cbranch_execz .LBB0_864
	s_add_u32 s10, s12, 0x16000
	s_addc_u32 s11, s13, 0
	v_lshl_add_u64 v[12:13], v[200:201], 2, s[10:11]
	global_store_dwordx4 v[12:13], v[104:107], off sc1
	global_store_dwordx4 v[10:11], v[36:39], off offset:16 sc1
	v_mov_b64_e32 v[8:9], s[10:11]
	s_nop 0
	v_mov_b64_e32 v[36:37], v[108:109]
	v_mov_b64_e32 v[38:39], v[110:111]
.LBB0_864:
	s_or_b64 exec, exec, s[72:73]
	v_lshl_add_u64 v[8:9], v[200:201], 2, v[8:9]
	global_store_dwordx4 v[8:9], v[36:39], off offset:16 sc1
.LBB0_865:
	s_or_b64 exec, exec, s[26:27]
	v_cmp_lt_u32_e32 vcc, 13, v225
	s_and_b64 s[26:27], s[30:31], vcc
	s_and_saveexec_b64 s[10:11], s[26:27]
	s_cbranch_execz .LBB0_869
	s_waitcnt lgkmcnt(0)
	v_add_u32_e32 v12, -12, v225
	v_mov_b64_e32 v[10:11], s[12:13]
	v_mad_u64_u32 v[10:11], s[26:27], v12, s39, v[10:11]
	v_mad_u64_u32 v[8:9], s[26:27], v12, s39, 0
	v_lshl_add_u64 v[10:11], v[200:201], 2, v[10:11]
	global_store_dwordx4 v[10:11], v[64:67], off sc1
	s_and_saveexec_b64 s[26:27], s[8:9]
	s_cbranch_execz .LBB0_868
	v_lshl_add_u64 v[8:9], v[200:201], 2, s[12:13]
	v_add_co_u32_e32 v8, vcc, 0x1b000, v8
	s_nop 1
	v_addc_co_u32_e32 v9, vcc, 0, v9, vcc
	global_store_dwordx4 v[8:9], v[4:7], off offset:2048 sc1
	global_store_dwordx4 v[10:11], v[52:55], off offset:16 sc1
	v_mov_b64_e32 v[8:9], 0x1b800
	s_nop 0
	v_mov_b64_e32 v[54:55], v[2:3]
	v_mov_b64_e32 v[52:53], v[0:1]
.LBB0_868:
	s_or_b64 exec, exec, s[26:27]
	v_lshl_add_u64 v[0:1], s[12:13], 0, v[8:9]
	v_lshl_add_u64 v[0:1], v[200:201], 2, v[0:1]
	global_store_dwordx4 v[0:1], v[52:55], off offset:16 sc1

;     __host__ __device__ bool next(int i, Unit& u) const { const long L = (long)i * G + c; if (L >= maxL) return false; return unit_of(L, u); }
; #define LAS __attribute__((address_space(3)))
; __device__ __forceinline__ unsigned pk2(float lo, float hi) { const f32x2_t v = {lo, hi}; const bf16x2_t b = __builtin_convertvector(v, bf16x2_t); return __builtin_bit_cast(unsigned, b); }
;     __device__ __forceinline__ void operator()(const f32x4 (&acc_c)[2][2][4][2], const pg8::Unit& u, int wr, int wc, int fr, int fq) const {
;     ...
; #pragma unroll
;         for (int m = 0; m < 4; ++m) { const int rl = half * 128 + wr * 64 + m * 16 + fr;
;             const float rstd = __builtin_amdgcn_rsqf(rsq[rl] * (1.0f / D_MODEL) + EPS);
; #pragma unroll
;             for (int bj = 0; bj < 2; ++bj)
; #pragma unroll
;                 for (int n = 0; n < 2; ++n) acc[0][bj][m][n] = acc[0][bj][m][n] * rstd + *(const LAS f32x4*)(bias2 + bj * 128 + cl + 4 * n); }
;     ...
;         { const int bi = wr;
; #pragma unroll
;             for (int m = 0; m < 4; ++m) { u32x4 o;
; #pragma unroll
;                 for (int n = 0; n < 2; ++n) { const f32x4 cur = acc[0][0][m][n];
;                     f32x4 pu, nd;
;                     if (m > 0) pu = ror1_4(acc[0][0][m > 0 ? m - 1 : 0][n]); else pu = (bi > 0) ? *(const LAS f32x4*)(X + ((bi - 1) * 2 + 1) * 128 + cl + 4 * n) : (f32x4){0.f, 0.f, 0.f, 0.f};
;                     if (m < 3) nd = rol1_4(acc[0][0][m < 3 ? m + 1 : 3][n]); else nd = (bi < 1) ? *(const LAS f32x4*)(X + ((bi + 1) * 2 + 0) * 128 + cl + 4 * n) : (f32x4){0.f, 0.f, 0.f, 0.f};
;                     const f32x4 ps = ror1_4(cur), ns = rol1_4(cur);
;                     const f32x4 prev = (fr > 0) ? ps : pu, next = (fr < 15) ? ns : nd;
;                     const f32x4 uu = w0[n] * prev + w1[n] * cur + w2[n] * next + cbv[n]; const f32x4 gt = acc[0][1][m][n];
;                     f32x4 r; r.x = siluf_(uu.x) * gt.x; r.y = siluf_(uu.y) * gt.y; r.z = siluf_(uu.z) * gt.z; r.w = siluf_(uu.w) * gt.w;
;                     if (n == 0) { o.x = pk2(r.x, r.y); o.y = pk2(r.z, r.w); } else { o.z = pk2(r.x, r.y); o.w = pk2(r.z, r.w); } }
;                 const int rh = wr * 64 + m * 16 + fr;
;                 if (rh != 0 && rh != 127) *(u32x4*)(ACT + (size_t)(u.pm * 256 + half * 128 + rh) * FFN + ch0) = o; } }
.LBB0_899:
	v_mov_b32_e32 v146, v128
	v_mov_b32_e32 v147, v128
	v_pk_fma_f32 v[40:41], v[40:41], v[128:129], v[92:93]
	v_pk_fma_f32 v[48:49], v[48:49], v[128:129], v[88:89]
	v_mov_b32_e32 v128, v130
	v_mov_b32_e32 v129, v130
	v_pk_fma_f32 v[42:43], v[42:43], v[146:147], v[94:95]
	v_or_b32_e32 v127, s13, v132
	v_lshl_add_u64 v[100:101], v[120:121], 1, s[14:15]
	s_mov_b64 s[10:11], 0x14342000
	v_pk_fma_f32 v[50:51], v[50:51], v[146:147], v[90:91]
	v_pk_fma_f32 v[98:99], v[98:99], v[128:129], v[106:107]
	v_pk_fma_f32 v[128:129], v[96:97], v[130:131], v[104:105]
	s_lshl_b32 s13, s3, 7
	v_lshl_add_u64 v[100:101], v[100:101], 0, s[10:11]
	v_mov_b32_dpp v96, v128 row_ror:15 row_mask:0xf bank_mask:0xf
	v_mov_b32_dpp v146, v129 row_ror:15 row_mask:0xf bank_mask:0xf
	v_mov_b32_dpp v147, v98 row_ror:15 row_mask:0xf bank_mask:0xf
	v_mov_b32_dpp v148, v99 row_ror:15 row_mask:0xf bank_mask:0xf
	v_mov_b32_dpp v152, v16 row_ror:1 row_mask:0xf bank_mask:0xf
	v_mov_b32_dpp v153, v17 row_ror:1 row_mask:0xf bank_mask:0xf
	v_mov_b32_dpp v154, v18 row_ror:1 row_mask:0xf bank_mask:0xf
	v_mov_b32_dpp v155, v19 row_ror:1 row_mask:0xf bank_mask:0xf
	v_mov_b32_dpp v149, v16 row_ror:15 row_mask:0xf bank_mask:0xf
	v_mov_b32_dpp v150, v17 row_ror:15 row_mask:0xf bank_mask:0xf
	v_mov_b32_dpp v151, v18 row_ror:15 row_mask:0xf bank_mask:0xf
	v_mov_b32_dpp v97, v19 row_ror:15 row_mask:0xf bank_mask:0xf
	v_cmp_ne_u32_e32 vcc, 0, v127
	s_and_saveexec_b64 s[10:11], vcc
	s_xor_b64 s[10:11], exec, s[10:11]
	s_cbranch_execz .LBB0_901
	s_waitcnt lgkmcnt(0)
	v_cndmask_b32_e64 v119, v145, v119, s[8:9]
	v_cndmask_b32_e64 v118, v143, v118, s[8:9]
	s_waitcnt vmcnt(0)
	v_pk_mul_f32 v[118:119], v[58:59], v[118:119]
	v_cndmask_b32_e64 v143, v140, v136, s[6:7]
	v_pk_fma_f32 v[118:119], v[22:23], v[66:67], v[118:119]
	v_cndmask_b32_e64 v137, v141, v137, s[6:7]
	v_cndmask_b32_e64 v136, v139, v135, s[6:7]
	v_pk_fma_f32 v[118:119], v[54:55], v[136:137], v[118:119]
	v_cndmask_b32_e64 v116, v142, v116, s[8:9]
	v_pk_add_f32 v[118:119], v[46:47], v[118:119]
	v_cndmask_b32_e64 v142, v138, v134, s[6:7]
	v_mul_f32_e32 v134, 0xbfb8aa3b, v119
	v_cndmask_b32_e64 v117, v144, v117, s[8:9]
	v_exp_f32_e32 v134, v134
	v_mul_f32_e32 v135, 0xbfb8aa3b, v118
	v_pk_mul_f32 v[116:117], v[56:57], v[116:117]
	v_exp_f32_e32 v136, v135
	v_pk_fma_f32 v[116:117], v[20:21], v[64:65], v[116:117]
	v_add_f32_e32 v134, 1.0, v134
	v_pk_fma_f32 v[116:117], v[52:53], v[142:143], v[116:117]
	v_rcp_f32_e32 v135, v134
	v_pk_add_f32 v[116:117], v[44:45], v[116:117]
	v_add_f32_e32 v134, 1.0, v136
	v_mul_f32_e32 v136, 0xbfb8aa3b, v117
	v_exp_f32_e32 v136, v136
	v_mul_f32_e32 v137, 0xbfb8aa3b, v116
	v_exp_f32_e32 v138, v137
	v_rcp_f32_e32 v134, v134
	v_add_f32_e32 v136, 1.0, v136
	v_rcp_f32_e32 v137, v136
	v_add_f32_e32 v136, 1.0, v138
	v_rcp_f32_e32 v136, v136
	v_pk_mul_f32 v[118:119], v[118:119], v[134:135]
	v_cndmask_b32_e64 v113, v153, v113, s[8:9]
	v_cndmask_b32_e64 v112, v152, v112, s[8:9]
	v_pk_mul_f32 v[116:117], v[116:117], v[136:137]
	v_pk_mul_f32 v[118:119], v[42:43], v[118:119]
	v_pk_mul_f32 v[116:117], v[40:41], v[116:117]
	v_cndmask_b32_e64 v115, v155, v115, s[8:9]
	v_cndmask_b32_e64 v114, v154, v114, s[8:9]
	v_pk_mul_f32 v[112:113], v[32:33], v[112:113]
	v_cvt_pk_bf16_f32 v116, v116, v117
	v_cvt_pk_bf16_f32 v117, v118, v119
	v_pk_mul_f32 v[114:115], v[34:35], v[114:115]
	v_pk_fma_f32 v[112:113], v[16:17], v[36:37], v[112:113]
	v_cndmask_b32_e64 v119, v97, v148, s[6:7]
	v_cndmask_b32_e64 v97, v150, v146, s[6:7]
	v_cndmask_b32_e64 v96, v149, v96, s[6:7]
	v_pk_fma_f32 v[114:115], v[18:19], v[38:39], v[114:115]
	v_cndmask_b32_e64 v118, v151, v147, s[6:7]
	v_pk_fma_f32 v[96:97], v[28:29], v[96:97], v[112:113]
	v_pk_fma_f32 v[112:113], v[30:31], v[118:119], v[114:115]
	v_pk_add_f32 v[96:97], v[24:25], v[96:97]
	v_pk_add_f32 v[112:113], v[26:27], v[112:113]
	v_mul_f32_e32 v114, 0xbfb8aa3b, v96
	v_mul_f32_e32 v115, 0xbfb8aa3b, v97
	v_exp_f32_e32 v114, v114
	v_exp_f32_e32 v115, v115
	v_mul_f32_e32 v118, 0xbfb8aa3b, v112
	v_exp_f32_e32 v118, v118
	v_mul_f32_e32 v119, 0xbfb8aa3b, v113
	v_exp_f32_e32 v119, v119
	v_add_f32_e32 v114, 1.0, v114
	v_add_f32_e32 v115, 1.0, v115
	v_rcp_f32_e32 v114, v114
	v_rcp_f32_e32 v115, v115
	v_add_f32_e32 v118, 1.0, v118
	v_rcp_f32_e32 v134, v118
	v_add_f32_e32 v118, 1.0, v119
	v_rcp_f32_e32 v135, v118
	v_pk_mul_f32 v[96:97], v[96:97], v[114:115]
	s_lshl_b32 s17, s12, 8
	v_pk_mul_f32 v[96:97], v[48:49], v[96:97]
	s_or_b32 s17, s17, s13
	v_cvt_pk_bf16_f32 v118, v96, v97
	v_pk_mul_f32 v[96:97], v[112:113], v[134:135]
	s_movk_i32 s18, 0x2c00
	v_pk_mul_f32 v[96:97], v[50:51], v[96:97]
	s_nop 0
	v_cvt_pk_bf16_f32 v119, v96, v97
	v_add_u32_e32 v96, s17, v127
	v_mad_i64_i32 v[96:97], s[18:19], v96, s18, v[100:101]
	global_store_dwordx4 v[96:97], v[116:119], off sc1
;     __host__ __device__ bool next(int i, Unit& u) const { const long L = (long)i * G + c; if (L >= maxL) return false; return unit_of(L, u); }
; #define LAS __attribute__((address_space(3)))
; __device__ __forceinline__ unsigned pk2(float lo, float hi) { const f32x2_t v = {lo, hi}; const bf16x2_t b = __builtin_convertvector(v, bf16x2_t); return __builtin_bit_cast(unsigned, b); }
; __device__ __forceinline__ float siluf_(float x) { return x * __builtin_amdgcn_rcpf(1.0f + __expf(-x)); }
;     __device__ __forceinline__ void operator()(const f32x4 (&acc_c)[2][2][4][2], const pg8::Unit& u, int wr, int wc, int fr, int fq) const {
;     ...
;         for (int m = 0; m < 4; ++m) { const int rl = half * 128 + wr * 64 + m * 16 + fr;
;             const float rstd = __builtin_amdgcn_rsqf(rsq[rl] * (1.0f / D_MODEL) + EPS);
; #pragma unroll
;             for (int bj = 0; bj < 2; ++bj)
; #pragma unroll
;                 for (int n = 0; n < 2; ++n) acc[0][bj][m][n] = acc[0][bj][m][n] * rstd + *(const LAS f32x4*)(bias2 + bj * 128 + cl + 4 * n); }
;     ...
;         { const int bi = wr;
; #pragma unroll
;             for (int m = 0; m < 4; ++m) { u32x4 o;
; #pragma unroll
;                 for (int n = 0; n < 2; ++n) { const f32x4 cur = acc[0][0][m][n];
;                     f32x4 pu, nd;
;                     if (m > 0) pu = ror1_4(acc[0][0][m > 0 ? m - 1 : 0][n]); else pu = (bi > 0) ? *(const LAS f32x4*)(X + ((bi - 1) * 2 + 1) * 128 + cl + 4 * n) : (f32x4){0.f, 0.f, 0.f, 0.f};
;                     if (m < 3) nd = rol1_4(acc[0][0][m < 3 ? m + 1 : 3][n]); else nd = (bi < 1) ? *(const LAS f32x4*)(X + ((bi + 1) * 2 + 0) * 128 + cl + 4 * n) : (f32x4){0.f, 0.f, 0.f, 0.f};
;                     const f32x4 ps = ror1_4(cur), ns = rol1_4(cur);
;                     const f32x4 prev = (fr > 0) ? ps : pu, next = (fr < 15) ? ns : nd;
;                     const f32x4 uu = w0[n] * prev + w1[n] * cur + w2[n] * next + cbv[n]; const f32x4 gt = acc[0][1][m][n];
;                     f32x4 r; r.x = siluf_(uu.x) * gt.x; r.y = siluf_(uu.y) * gt.y; r.z = siluf_(uu.z) * gt.z; r.w = siluf_(uu.w) * gt.w;
;                     if (n == 0) { o.x = pk2(r.x, r.y); o.y = pk2(r.z, r.w); } else { o.z = pk2(r.x, r.y); o.w = pk2(r.z, r.w); } }
;                 const int rh = wr * 64 + m * 16 + fr;
;                 if (rh != 0 && rh != 127) *(u32x4*)(ACT + (size_t)(u.pm * 256 + half * 128 + rh) * FFN + ch0) = o; } }
.LBB0_901:
	s_or_saveexec_b64 s[10:11], s[10:11]
	s_add_i32 s16, s16, 0x20000
	s_waitcnt lgkmcnt(0)
	v_mov_b32_e32 v112, s17
	s_xor_b64 exec, exec, s[10:11]
	s_lshl_b32 s17, s12, 8
	s_or_b32 s13, s13, s17
	v_mov_b32_e32 v112, s13
	s_or_b64 exec, exec, s[10:11]
	v_mov_b32_e32 v114, v130
	v_mov_b32_e32 v115, v130
	v_pk_fma_f32 v[116:117], v[78:79], v[114:115], v[94:95]
	v_mov_b32_e32 v78, 0x358637bd
	v_fmac_f32_e32 v78, 0x3a000000, v126
	v_rsq_f32_e32 v118, v78
	v_pk_fma_f32 v[134:135], v[76:77], v[130:131], v[92:93]
	v_pk_fma_f32 v[130:131], v[72:73], v[130:131], v[88:89]
	v_pk_fma_f32 v[114:115], v[74:75], v[114:115], v[90:91]
	v_pk_fma_f32 v[78:79], v[84:85], v[118:119], v[108:109] op_sel_hi:[1,0,1]
	v_pk_fma_f32 v[72:73], v[82:83], v[118:119], v[106:107] op_sel_hi:[1,0,1]
	v_mov_b32_dpp v82, v20 row_ror:1 row_mask:0xf bank_mask:0xf
	v_mov_b32_dpp v83, v21 row_ror:1 row_mask:0xf bank_mask:0xf
	v_mov_b32_dpp v107, v124 row_ror:1 row_mask:0xf bank_mask:0xf
	v_mov_b32_dpp v108, v125 row_ror:1 row_mask:0xf bank_mask:0xf
	v_pk_fma_f32 v[76:77], v[86:87], v[118:119], v[110:111] op_sel_hi:[1,0,1]
	v_pk_fma_f32 v[74:75], v[80:81], v[118:119], v[104:105] op_sel_hi:[1,0,1]
	v_cndmask_b32_e64 v83, v108, v83, s[8:9]
	v_cndmask_b32_e64 v82, v107, v82, s[8:9]
	v_mov_b32_dpp v80, v22 row_ror:1 row_mask:0xf bank_mask:0xf
	v_mov_b32_dpp v81, v23 row_ror:1 row_mask:0xf bank_mask:0xf
	v_mov_b32_dpp v97, v78 row_ror:15 row_mask:0xf bank_mask:0xf
	v_mov_b32_dpp v104, v79 row_ror:15 row_mask:0xf bank_mask:0xf
	v_mov_b32_dpp v109, v102 row_ror:1 row_mask:0xf bank_mask:0xf
	v_mov_b32_dpp v110, v103 row_ror:1 row_mask:0xf bank_mask:0xf
	v_mov_b32_dpp v86, v124 row_ror:15 row_mask:0xf bank_mask:0xf
	v_mov_b32_dpp v87, v125 row_ror:15 row_mask:0xf bank_mask:0xf
	s_waitcnt vmcnt(0)
	v_pk_mul_f32 v[82:83], v[56:57], v[82:83]
	v_cndmask_b32_e64 v81, v110, v81, s[8:9]
	v_cndmask_b32_e64 v80, v109, v80, s[8:9]
	v_pk_fma_f32 v[82:83], v[64:65], v[124:125], v[82:83]
	v_cndmask_b32_e64 v87, v87, v104, s[6:7]
	v_cndmask_b32_e64 v86, v86, v97, s[6:7]
	v_mov_b32_dpp v105, v76 row_ror:15 row_mask:0xf bank_mask:0xf
	v_mov_b32_dpp v106, v77 row_ror:15 row_mask:0xf bank_mask:0xf
	v_mov_b32_dpp v84, v102 row_ror:15 row_mask:0xf bank_mask:0xf
	v_mov_b32_dpp v85, v103 row_ror:15 row_mask:0xf bank_mask:0xf
	v_pk_mul_f32 v[80:81], v[58:59], v[80:81]
	v_pk_fma_f32 v[82:83], v[52:53], v[86:87], v[82:83]
	v_pk_fma_f32 v[80:81], v[66:67], v[102:103], v[80:81]
	v_cndmask_b32_e64 v85, v85, v106, s[6:7]
	v_cndmask_b32_e64 v84, v84, v105, s[6:7]
	v_pk_add_f32 v[82:83], v[44:45], v[82:83]
	v_pk_fma_f32 v[80:81], v[54:55], v[84:85], v[80:81]
	v_mul_f32_e32 v84, 0xbfb8aa3b, v82
	v_exp_f32_e32 v86, v84
	v_mul_f32_e32 v84, 0xbfb8aa3b, v83
	v_exp_f32_e32 v87, v84
	v_pk_add_f32 v[84:85], v[46:47], v[80:81]
	v_add_f32_e32 v80, 1.0, v86
	v_mul_f32_e32 v86, 0xbfb8aa3b, v84
	v_add_f32_e32 v81, 1.0, v87
	v_mul_f32_e32 v87, 0xbfb8aa3b, v85
	v_exp_f32_e32 v86, v86
	v_exp_f32_e32 v87, v87
	v_rcp_f32_e32 v80, v80
	v_rcp_f32_e32 v81, v81
	v_add_f32_e32 v86, 1.0, v86
	v_add_f32_e32 v87, 1.0, v87
	v_rcp_f32_e32 v86, v86
	v_rcp_f32_e32 v87, v87
	v_lshl_add_u32 v113, v123, 2, s16
	v_pk_fma_f32 v[70:71], v[70:71], v[118:119], v[94:95] op_sel_hi:[1,0,1]
	v_pk_fma_f32 v[68:69], v[68:69], v[118:119], v[92:93] op_sel_hi:[1,0,1]
	v_pk_fma_f32 v[62:63], v[62:63], v[118:119], v[90:91] op_sel_hi:[1,0,1]
	v_pk_fma_f32 v[60:61], v[60:61], v[118:119], v[88:89] op_sel_hi:[1,0,1]
	v_pk_mul_f32 v[80:81], v[82:83], v[80:81]
	v_pk_mul_f32 v[82:83], v[84:85], v[86:87]
	v_mov_b32_dpp v111, v16 row_ror:1 row_mask:0xf bank_mask:0xf
	v_mov_b32_dpp v118, v17 row_ror:1 row_mask:0xf bank_mask:0xf
	v_mov_b32_dpp v119, v18 row_ror:1 row_mask:0xf bank_mask:0xf
	v_mov_b32_dpp v123, v19 row_ror:1 row_mask:0xf bank_mask:0xf
	v_mov_b32_dpp v139, v128 row_ror:1 row_mask:0xf bank_mask:0xf
	v_mov_b32_dpp v140, v129 row_ror:1 row_mask:0xf bank_mask:0xf
	v_mov_b32_dpp v141, v98 row_ror:1 row_mask:0xf bank_mask:0xf
	v_mov_b32_dpp v142, v99 row_ror:1 row_mask:0xf bank_mask:0xf
	v_pk_mul_f32 v[80:81], v[134:135], v[80:81]
	v_pk_mul_f32 v[82:83], v[116:117], v[82:83]
	v_cvt_pk_bf16_f32 v80, v80, v81
	v_cvt_pk_bf16_f32 v81, v82, v83
	v_cndmask_b32_e64 v83, v142, v123, s[8:9]
	v_cndmask_b32_e64 v82, v141, v119, s[8:9]
	v_cndmask_b32_e64 v85, v140, v118, s[8:9]
	v_cndmask_b32_e64 v84, v139, v111, s[8:9]
	v_mov_b32_dpp v126, v74 row_ror:15 row_mask:0xf bank_mask:0xf
	v_mov_b32_dpp v136, v75 row_ror:15 row_mask:0xf bank_mask:0xf
	v_mov_b32_dpp v143, v128 row_ror:15 row_mask:0xf bank_mask:0xf
	v_mov_b32_dpp v144, v129 row_ror:15 row_mask:0xf bank_mask:0xf
	v_pk_mul_f32 v[84:85], v[32:33], v[84:85]
	v_pk_mul_f32 v[82:83], v[34:35], v[82:83]
	v_mov_b32_dpp v145, v98 row_ror:15 row_mask:0xf bank_mask:0xf
	v_mov_b32_dpp v146, v99 row_ror:15 row_mask:0xf bank_mask:0xf
	v_pk_fma_f32 v[82:83], v[98:99], v[38:39], v[82:83]
	v_pk_fma_f32 v[84:85], v[128:129], v[36:37], v[84:85]
	v_cndmask_b32_e64 v99, v144, v136, s[6:7]
	v_cndmask_b32_e64 v98, v143, v126, s[6:7]
	v_mov_b32_dpp v137, v72 row_ror:15 row_mask:0xf bank_mask:0xf
	v_mov_b32_dpp v138, v73 row_ror:15 row_mask:0xf bank_mask:0xf
	v_pk_fma_f32 v[84:85], v[28:29], v[98:99], v[84:85]
	v_cndmask_b32_e64 v87, v146, v138, s[6:7]
;     __host__ __device__ bool next(int i, Unit& u) const { const long L = (long)i * G + c; if (L >= maxL) return false; return unit_of(L, u); }
; #define LAS __attribute__((address_space(3)))
; __device__ __forceinline__ unsigned pk2(float lo, float hi) { const f32x2_t v = {lo, hi}; const bf16x2_t b = __builtin_convertvector(v, bf16x2_t); return __builtin_bit_cast(unsigned, b); }
; __device__ __forceinline__ float siluf_(float x) { return x * __builtin_amdgcn_rcpf(1.0f + __expf(-x)); }
;     __device__ bool next(int i, pg8::Unit& u) const { if (!pg8::StaticOrder::next(i >> 1, u)) return false; u.br = i & 1; return true; }
; __device__ __forceinline__ f32x4 ror1_4(const f32x4 v) { return (f32x4){dpp_ror1(v.x), dpp_ror1(v.y), dpp_ror1(v.z), dpp_ror1(v.w)}; }
;     __device__ __forceinline__ void operator()(const f32x4 (&acc_c)[2][2][4][2], const pg8::Unit& u, int wr, int wc, int fr, int fq) const {
;     ...
;         { const int bi = wr;
; #pragma unroll
;             for (int m = 0; m < 4; ++m) { u32x4 o;
; #pragma unroll
;                 for (int n = 0; n < 2; ++n) { const f32x4 cur = acc[0][0][m][n];
;                     f32x4 pu, nd;
;                     if (m > 0) pu = ror1_4(acc[0][0][m > 0 ? m - 1 : 0][n]); else pu = (bi > 0) ? *(const LAS f32x4*)(X + ((bi - 1) * 2 + 1) * 128 + cl + 4 * n) : (f32x4){0.f, 0.f, 0.f, 0.f};
;                     if (m < 3) nd = rol1_4(acc[0][0][m < 3 ? m + 1 : 3][n]); else nd = (bi < 1) ? *(const LAS f32x4*)(X + ((bi + 1) * 2 + 0) * 128 + cl + 4 * n) : (f32x4){0.f, 0.f, 0.f, 0.f};
;                     const f32x4 ps = ror1_4(cur), ns = rol1_4(cur);
;                     const f32x4 prev = (fr > 0) ? ps : pu, next = (fr < 15) ? ns : nd;
;                     const f32x4 uu = w0[n] * prev + w1[n] * cur + w2[n] * next + cbv[n]; const f32x4 gt = acc[0][1][m][n];
;                     f32x4 r; r.x = siluf_(uu.x) * gt.x; r.y = siluf_(uu.y) * gt.y; r.z = siluf_(uu.z) * gt.z; r.w = siluf_(uu.w) * gt.w;
;                     if (n == 0) { o.x = pk2(r.x, r.y); o.y = pk2(r.z, r.w); } else { o.z = pk2(r.x, r.y); o.w = pk2(r.z, r.w); } }
;                 const int rh = wr * 64 + m * 16 + fr;
;                 if (rh != 0 && rh != 127) *(u32x4*)(ACT + (size_t)(u.pm * 256 + half * 128 + rh) * FFN + ch0) = o; } }
	v_cndmask_b32_e64 v86, v145, v137, s[6:7]
	v_pk_add_f32 v[84:85], v[24:25], v[84:85]
	v_pk_fma_f32 v[82:83], v[30:31], v[86:87], v[82:83]
	v_mul_f32_e32 v86, 0xbfb8aa3b, v84
	v_exp_f32_e32 v98, v86
	v_mul_f32_e32 v86, 0xbfb8aa3b, v85
	v_exp_f32_e32 v99, v86
	v_pk_add_f32 v[86:87], v[26:27], v[82:83]
	v_add_f32_e32 v82, 1.0, v98
	v_mul_f32_e32 v98, 0xbfb8aa3b, v86
	v_add_f32_e32 v83, 1.0, v99
	v_mul_f32_e32 v99, 0xbfb8aa3b, v87
	v_exp_f32_e32 v98, v98
	v_exp_f32_e32 v99, v99
	v_rcp_f32_e32 v82, v82
	v_rcp_f32_e32 v83, v83
	v_add_f32_e32 v98, 1.0, v98
	v_add_f32_e32 v99, 1.0, v99
	v_rcp_f32_e32 v98, v98
	v_rcp_f32_e32 v99, v99
	v_pk_mul_f32 v[82:83], v[84:85], v[82:83]
	s_movk_i32 s13, 0x2c00
	v_pk_mul_f32 v[82:83], v[130:131], v[82:83]
	v_pk_mul_f32 v[84:85], v[86:87], v[98:99]
	v_add_u32_e32 v98, v112, v127
	v_pk_mul_f32 v[84:85], v[114:115], v[84:85]
	v_cvt_pk_bf16_f32 v82, v82, v83
	v_cvt_pk_bf16_f32 v83, v84, v85
	v_add_u32_e32 v84, 16, v98
	v_mad_i64_i32 v[84:85], s[16:17], v84, s13, v[100:101]
	global_store_dwordx4 v[84:85], v[80:83], off sc1
	s_nop 1
	v_mov_b32_dpp v81, v76 row_ror:1 row_mask:0xf bank_mask:0xf
	v_mov_b32_dpp v83, v77 row_ror:1 row_mask:0xf bank_mask:0xf
	v_mov_b32_dpp v80, v78 row_ror:1 row_mask:0xf bank_mask:0xf
	v_mov_b32_dpp v82, v79 row_ror:1 row_mask:0xf bank_mask:0xf
	v_cndmask_b32_e64 v85, v83, v110, s[8:9]
	v_cndmask_b32_e64 v84, v81, v109, s[8:9]
	v_mov_b32_dpp v103, v14 row_ror:15 row_mask:0xf bank_mask:0xf
	v_mov_b32_dpp v111, v15 row_ror:15 row_mask:0xf bank_mask:0xf
	v_cndmask_b32_e64 v87, v82, v108, s[8:9]
	v_cndmask_b32_e64 v86, v80, v107, s[8:9]
	v_pk_mul_f32 v[84:85], v[58:59], v[84:85]
	v_mov_b32_dpp v99, v12 row_ror:15 row_mask:0xf bank_mask:0xf
	v_mov_b32_dpp v102, v13 row_ror:15 row_mask:0xf bank_mask:0xf
	v_pk_mul_f32 v[86:87], v[56:57], v[86:87]
	v_pk_fma_f32 v[76:77], v[66:67], v[76:77], v[84:85]
	v_cndmask_b32_e64 v85, v106, v111, s[6:7]
	v_cndmask_b32_e64 v84, v105, v103, s[6:7]
	v_pk_fma_f32 v[78:79], v[64:65], v[78:79], v[86:87]
	v_cndmask_b32_e64 v87, v104, v102, s[6:7]
	v_cndmask_b32_e64 v86, v97, v99, s[6:7]
	v_pk_fma_f32 v[76:77], v[54:55], v[84:85], v[76:77]
	v_pk_fma_f32 v[78:79], v[52:53], v[86:87], v[78:79]
	v_pk_add_f32 v[76:77], v[46:47], v[76:77]
	v_pk_add_f32 v[78:79], v[44:45], v[78:79]
	v_mul_f32_e32 v86, 0xbfb8aa3b, v76
	v_mul_f32_e32 v87, 0xbfb8aa3b, v77
	v_mul_f32_e32 v84, 0xbfb8aa3b, v78
	v_mul_f32_e32 v85, 0xbfb8aa3b, v79
	v_exp_f32_e32 v86, v86
	v_exp_f32_e32 v87, v87
	v_exp_f32_e32 v84, v84
	v_exp_f32_e32 v85, v85
	v_add_f32_e32 v86, 1.0, v86
	v_add_f32_e32 v87, 1.0, v87
	v_add_f32_e32 v84, 1.0, v84
	v_add_f32_e32 v85, 1.0, v85
	v_rcp_f32_e32 v86, v86
	v_rcp_f32_e32 v87, v87
	v_rcp_f32_e32 v84, v84
	v_rcp_f32_e32 v85, v85
	v_pk_mul_f32 v[76:77], v[76:77], v[86:87]
	v_mov_b32_dpp v118, v74 row_ror:1 row_mask:0xf bank_mask:0xf
	v_mov_b32_dpp v119, v75 row_ror:1 row_mask:0xf bank_mask:0xf
	v_pk_mul_f32 v[78:79], v[78:79], v[84:85]
	v_pk_mul_f32 v[70:71], v[70:71], v[76:77]
	v_cndmask_b32_e64 v77, v119, v140, s[8:9]
	v_cndmask_b32_e64 v76, v118, v139, s[8:9]
	v_mov_b32_dpp v114, v8 row_ror:15 row_mask:0xf bank_mask:0xf
	v_mov_b32_dpp v115, v9 row_ror:15 row_mask:0xf bank_mask:0xf
	v_mov_b32_dpp v123, v72 row_ror:1 row_mask:0xf bank_mask:0xf
	v_mov_b32_dpp v124, v73 row_ror:1 row_mask:0xf bank_mask:0xf
	v_pk_mul_f32 v[68:69], v[68:69], v[78:79]
	v_pk_mul_f32 v[76:77], v[32:33], v[76:77]
	v_cvt_pk_bf16_f32 v68, v68, v69
	v_cvt_pk_bf16_f32 v69, v70, v71
	v_cndmask_b32_e64 v71, v124, v142, s[8:9]
	v_cndmask_b32_e64 v70, v123, v141, s[8:9]
	v_pk_fma_f32 v[76:77], v[36:37], v[74:75], v[76:77]
	v_cndmask_b32_e64 v85, v136, v115, s[6:7]
	v_cndmask_b32_e64 v84, v126, v114, s[6:7]
	v_mov_b32_dpp v116, v10 row_ror:15 row_mask:0xf bank_mask:0xf
	v_mov_b32_dpp v117, v11 row_ror:15 row_mask:0xf bank_mask:0xf
	v_pk_mul_f32 v[70:71], v[34:35], v[70:71]
	v_pk_fma_f32 v[76:77], v[28:29], v[84:85], v[76:77]
	v_pk_fma_f32 v[70:71], v[38:39], v[72:73], v[70:71]
	v_cndmask_b32_e64 v79, v138, v117, s[6:7]
	v_cndmask_b32_e64 v78, v137, v116, s[6:7]
	v_pk_add_f32 v[76:77], v[24:25], v[76:77]
	v_pk_fma_f32 v[70:71], v[30:31], v[78:79], v[70:71]
	v_mul_f32_e32 v78, 0xbfb8aa3b, v76
	v_exp_f32_e32 v84, v78
	v_mul_f32_e32 v78, 0xbfb8aa3b, v77
	v_exp_f32_e32 v85, v78
	v_pk_add_f32 v[78:79], v[26:27], v[70:71]
	v_add_f32_e32 v70, 1.0, v84
	v_mul_f32_e32 v84, 0xbfb8aa3b, v78
	v_add_f32_e32 v71, 1.0, v85
	v_mul_f32_e32 v85, 0xbfb8aa3b, v79
	v_exp_f32_e32 v84, v84
	v_exp_f32_e32 v85, v85
	v_rcp_f32_e32 v70, v70
	v_rcp_f32_e32 v71, v71
	v_add_f32_e32 v84, 1.0, v84
	v_add_f32_e32 v85, 1.0, v85
	v_rcp_f32_e32 v84, v84
	v_rcp_f32_e32 v85, v85
	v_pk_mul_f32 v[70:71], v[76:77], v[70:71]
	s_cmp_lt_i32 s4, 1
	v_pk_mul_f32 v[60:61], v[60:61], v[70:71]
	s_cselect_b64 s[10:11], -1, 0
	v_cvt_pk_bf16_f32 v70, v60, v61
	v_pk_mul_f32 v[60:61], v[78:79], v[84:85]
	v_mov_b32_e32 v96, 0
	v_pk_mul_f32 v[60:61], v[62:63], v[60:61]
	s_cmp_gt_i32 s4, 0
	v_cvt_pk_bf16_f32 v71, v60, v61
	v_add_u32_e32 v60, 32, v98
	v_mad_i64_i32 v[60:61], s[16:17], v60, s13, v[100:101]
	global_store_dwordx4 v[60:61], v[68:71], off sc1
	v_mov_b32_e32 v60, 0
	v_mov_b32_e32 v61, 0
	v_mov_b32_e32 v62, 0
	v_mov_b32_e32 v63, 0
	s_cbranch_scc1 .LBB0_905
	ds_read_b128 v[60:63], v113 offset:1024

;     __host__ __device__ bool next(int i, Unit& u) const { const long L = (long)i * G + c; if (L >= maxL) return false; return unit_of(L, u); }
; #define LAS __attribute__((address_space(3)))
; __device__ __forceinline__ unsigned pk2(float lo, float hi) { const f32x2_t v = {lo, hi}; const bf16x2_t b = __builtin_convertvector(v, bf16x2_t); return __builtin_bit_cast(unsigned, b); }
; __device__ __forceinline__ float siluf_(float x) { return x * __builtin_amdgcn_rcpf(1.0f + __expf(-x)); }
;     __device__ bool next(int i, pg8::Unit& u) const { if (!pg8::StaticOrder::next(i >> 1, u)) return false; u.br = i & 1; return true; }
; __device__ __forceinline__ f32x4 ror1_4(const f32x4 v) { return (f32x4){dpp_ror1(v.x), dpp_ror1(v.y), dpp_ror1(v.z), dpp_ror1(v.w)}; }
;     __device__ __forceinline__ void operator()(const f32x4 (&acc_c)[2][2][4][2], const pg8::Unit& u, int wr, int wc, int fr, int fq) const {
;     ...
;         { const int bi = wr;
; #pragma unroll
;             for (int m = 0; m < 4; ++m) { u32x4 o;
; #pragma unroll
;                 for (int n = 0; n < 2; ++n) { const f32x4 cur = acc[0][0][m][n];
;                     f32x4 pu, nd;
;                     if (m > 0) pu = ror1_4(acc[0][0][m > 0 ? m - 1 : 0][n]); else pu = (bi > 0) ? *(const LAS f32x4*)(X + ((bi - 1) * 2 + 1) * 128 + cl + 4 * n) : (f32x4){0.f, 0.f, 0.f, 0.f};
;                     if (m < 3) nd = rol1_4(acc[0][0][m < 3 ? m + 1 : 3][n]); else nd = (bi < 1) ? *(const LAS f32x4*)(X + ((bi + 1) * 2 + 0) * 128 + cl + 4 * n) : (f32x4){0.f, 0.f, 0.f, 0.f};
;                     const f32x4 ps = ror1_4(cur), ns = rol1_4(cur);
;                     const f32x4 prev = (fr > 0) ? ps : pu, next = (fr < 15) ? ns : nd;
;                     const f32x4 uu = w0[n] * prev + w1[n] * cur + w2[n] * next + cbv[n]; const f32x4 gt = acc[0][1][m][n];
;                     f32x4 r; r.x = siluf_(uu.x) * gt.x; r.y = siluf_(uu.y) * gt.y; r.z = siluf_(uu.z) * gt.z; r.w = siluf_(uu.w) * gt.w;
;                     if (n == 0) { o.x = pk2(r.x, r.y); o.y = pk2(r.z, r.w); } else { o.z = pk2(r.x, r.y); o.w = pk2(r.z, r.w); } }
;                 const int rh = wr * 64 + m * 16 + fr;
;                 if (rh != 0 && rh != 127) *(u32x4*)(ACT + (size_t)(u.pm * 256 + half * 128 + rh) * FFN + ch0) = o; } }
.LBB0_907:
	v_mov_b32_e32 v72, v122
	v_mov_b32_e32 v73, v122
	v_pk_fma_f32 v[6:7], v[6:7], v[72:73], v[94:95]
	v_pk_fma_f32 v[2:3], v[2:3], v[72:73], v[90:91]
	v_pk_fma_f32 v[0:1], v[0:1], v[122:123], v[88:89]
	s_movk_i32 s10, 0x4f
	v_pk_fma_f32 v[4:5], v[4:5], v[122:123], v[92:93]
	v_mov_b32_dpp v84, v8 row_ror:1 row_mask:0xf bank_mask:0xf
	v_mov_b32_dpp v87, v9 row_ror:1 row_mask:0xf bank_mask:0xf
	v_mov_b32_dpp v88, v10 row_ror:1 row_mask:0xf bank_mask:0xf
	v_mov_b32_dpp v89, v11 row_ror:1 row_mask:0xf bank_mask:0xf
	v_mov_b32_dpp v73, v8 row_ror:15 row_mask:0xf bank_mask:0xf
	v_mov_b32_dpp v74, v9 row_ror:15 row_mask:0xf bank_mask:0xf
	v_mov_b32_dpp v75, v10 row_ror:15 row_mask:0xf bank_mask:0xf
	v_mov_b32_dpp v72, v11 row_ror:15 row_mask:0xf bank_mask:0xf
	v_cmp_ne_u32_e32 vcc, s10, v127
	s_and_saveexec_b64 s[10:11], vcc
	s_cbranch_execz .LBB0_909
	v_cndmask_b32_e64 v91, v102, v82, s[8:9]
	v_cndmask_b32_e64 v83, v103, v83, s[8:9]
	v_cndmask_b32_e64 v82, v86, v81, s[8:9]
	v_pk_mul_f32 v[58:59], v[58:59], v[82:83]
	s_waitcnt lgkmcnt(0)
	v_cndmask_b32_e64 v63, v79, v63, s[6:7]
	v_pk_fma_f32 v[58:59], v[66:67], v[14:15], v[58:59]
	v_cndmask_b32_e64 v62, v77, v62, s[6:7]
	v_pk_fma_f32 v[54:55], v[54:55], v[62:63], v[58:59]
	v_cndmask_b32_e64 v90, v85, v80, s[8:9]
	v_pk_add_f32 v[46:47], v[46:47], v[54:55]
	v_pk_mul_f32 v[56:57], v[56:57], v[90:91]
	v_mul_f32_e32 v54, 0xbfb8aa3b, v47
	v_exp_f32_e32 v54, v54
	v_mul_f32_e32 v55, 0xbfb8aa3b, v46
	v_pk_fma_f32 v[56:57], v[64:65], v[12:13], v[56:57]
	v_cndmask_b32_e64 v61, v78, v61, s[6:7]
	v_cndmask_b32_e64 v60, v76, v60, s[6:7]
	v_exp_f32_e32 v55, v55
	v_pk_fma_f32 v[52:53], v[52:53], v[60:61], v[56:57]
	s_nop 0
	v_pk_add_f32 v[44:45], v[44:45], v[52:53]
	v_add_f32_e32 v52, 1.0, v54
	v_mul_f32_e32 v54, 0xbfb8aa3b, v45
	v_rcp_f32_e32 v53, v52
	v_add_f32_e32 v52, 1.0, v55
	v_exp_f32_e32 v54, v54
	v_mul_f32_e32 v55, 0xbfb8aa3b, v44
	v_exp_f32_e32 v56, v55
	v_rcp_f32_e32 v52, v52
	v_add_f32_e32 v54, 1.0, v54
	v_rcp_f32_e32 v55, v54
	v_add_f32_e32 v54, 1.0, v56
	v_rcp_f32_e32 v54, v54
	v_pk_mul_f32 v[46:47], v[46:47], v[52:53]
	v_cndmask_b32_e64 v53, v87, v69, s[8:9]
	v_pk_mul_f32 v[46:47], v[6:7], v[46:47]
	v_pk_mul_f32 v[44:45], v[44:45], v[54:55]
	v_cndmask_b32_e64 v52, v84, v68, s[8:9]
	v_pk_mul_f32 v[44:45], v[4:5], v[44:45]
	v_pk_mul_f32 v[32:33], v[32:33], v[52:53]
	v_cvt_pk_bf16_f32 v44, v44, v45
	v_cvt_pk_bf16_f32 v45, v46, v47
	v_cndmask_b32_e64 v47, v89, v71, s[8:9]
	v_cndmask_b32_e64 v46, v88, v70, s[8:9]
	v_pk_mul_f32 v[34:35], v[34:35], v[46:47]
	v_pk_fma_f32 v[32:33], v[36:37], v[8:9], v[32:33]
	v_pk_fma_f32 v[34:35], v[38:39], v[10:11], v[34:35]
	v_cndmask_b32_e64 v39, v74, v97, s[6:7]
	v_cndmask_b32_e64 v38, v73, v96, s[6:7]
	v_pk_fma_f32 v[28:29], v[28:29], v[38:39], v[32:33]
	v_cndmask_b32_e64 v37, v72, v99, s[6:7]
	v_cndmask_b32_e64 v36, v75, v98, s[6:7]
	v_pk_add_f32 v[24:25], v[24:25], v[28:29]
	v_pk_fma_f32 v[30:31], v[30:31], v[36:37], v[34:35]
	v_mul_f32_e32 v28, 0xbfb8aa3b, v24
	v_mul_f32_e32 v29, 0xbfb8aa3b, v25
	v_exp_f32_e32 v28, v28
	v_exp_f32_e32 v29, v29
	v_pk_add_f32 v[26:27], v[26:27], v[30:31]
	v_add_f32_e32 v28, 1.0, v28
	v_mul_f32_e32 v30, 0xbfb8aa3b, v26
	v_mul_f32_e32 v31, 0xbfb8aa3b, v27
	v_exp_f32_e32 v30, v30
	v_exp_f32_e32 v31, v31
	v_add_f32_e32 v29, 1.0, v29
	v_rcp_f32_e32 v28, v28
	v_rcp_f32_e32 v29, v29
	v_add_f32_e32 v30, 1.0, v30
	v_add_f32_e32 v31, 1.0, v31
	v_rcp_f32_e32 v30, v30
	v_rcp_f32_e32 v31, v31
	v_pk_mul_f32 v[24:25], v[24:25], v[28:29]
	s_nop 0
	v_pk_mul_f32 v[24:25], v[0:1], v[24:25]
	s_nop 0
	v_cvt_pk_bf16_f32 v46, v24, v25
	v_pk_mul_f32 v[24:25], v[26:27], v[30:31]
	s_nop 0
	v_pk_mul_f32 v[24:25], v[2:3], v[24:25]
	s_nop 0
	v_cvt_pk_bf16_f32 v47, v24, v25
	v_add3_u32 v24, v112, v127, 48
	v_mad_i64_i32 v[24:25], s[16:17], v24, s13, v[100:101]
	global_store_dwordx4 v[24:25], v[44:47], off sc1

;     __device__ __forceinline__ void operator()(const f32x4 (&acc_c)[2][2][4][2], const pg8::Unit& u, int wr, int wc, int fr, int fq) const {
;     ...
;         if (wr == 0 && fr < 2) { float* dst = half ? HALO2 + (size_t)(3 + fr) * FFN : HALO + (size_t)fr * FFN; float* gd = half ? HALO2 + (size_t)5 * FFN : HALO + (size_t)4 * FFN;
; #pragma unroll
;             for (int n = 0; n < 2; ++n) { *(f32x4*)(dst + ch0 + 4 * n) = acc[0][0][0][n]; if (fr == 0) *(f32x4*)(gd + ch0 + 4 * n) = acc[0][1][0][n]; } }
;         if (wr == 1 && fr >= 14) { float* dst = half ? HALO + (size_t)(fr - 12) * FFN : HALO2 + (size_t)(fr - 14) * FFN; float* gd = half ? HALO + (size_t)5 * FFN : HALO2 + (size_t)2 * FFN;
; #pragma unroll
;             for (int n = 0; n < 2; ++n) { *(f32x4*)(dst + ch0 + 4 * n) = acc[0][0][3][n]; if (fr == 15) *(f32x4*)(gd + ch0 + 4 * n) = acc[0][1][3][n]; } }
.LBB0_911:
	s_or_b64 exec, exec, s[10:11]
	s_mul_i32 s5, s12, 0x21000
	s_mul_hi_i32 s4, s12, 0x21000
	s_add_u32 s5, s14, s5
	s_addc_u32 s4, s15, s4
	s_add_u32 s10, s5, 0x5342000
	s_addc_u32 s11, s4, 0
	s_add_u32 s12, s5, 0x5b42000
	v_cmp_gt_u32_e32 vcc, 2, v132
	s_addc_u32 s13, s4, 0
	s_and_b64 s[4:5], s[26:27], vcc
	s_and_saveexec_b64 s[14:15], s[4:5]
	s_cbranch_execz .LBB0_915
	v_mul_u32_u24_e32 v24, 0x1600, v132
	v_lshlrev_b32_e32 v24, 2, v24
	v_mov_b32_e32 v25, 0
	s_cmp_eq_u32 s3, 0
	v_lshl_add_u64 v[26:27], s[12:13], 0, v[24:25]
	s_mov_b64 s[4:5], 0x10800
	v_lshl_add_u64 v[26:27], v[26:27], 0, s[4:5]
	v_lshl_add_u64 v[24:25], s[10:11], 0, v[24:25]
	s_cselect_b64 vcc, -1, 0
	v_cndmask_b32_e32 v25, v27, v25, vcc
	v_cndmask_b32_e32 v24, v26, v24, vcc
	v_lshl_add_u64 v[26:27], v[120:121], 2, v[24:25]
	global_store_dwordx4 v[26:27], v[20:23], off sc1
	s_and_saveexec_b64 s[16:17], s[8:9]
	s_cbranch_execz .LBB0_914
	s_add_u32 s8, s10, 0x16000
	s_addc_u32 s9, s11, 0
	s_add_u32 s18, s12, 0x1b800
	s_addc_u32 s19, s13, 0
	s_and_b64 s[4:5], vcc, exec
	s_cselect_b32 s5, s9, s19
	s_cselect_b32 s4, s8, s18
	v_lshl_add_u64 v[20:21], v[120:121], 2, s[4:5]
	global_store_dwordx4 v[20:21], v[40:43], off sc1
	global_store_dwordx4 v[26:27], v[16:19], off offset:16 sc1
	v_mov_b64_e32 v[24:25], s[4:5]
	s_nop 0
	v_mov_b64_e32 v[16:17], v[48:49]
	v_mov_b64_e32 v[18:19], v[50:51]
.LBB0_914:
	s_or_b64 exec, exec, s[16:17]
	v_lshl_add_u64 v[20:21], v[120:121], 2, v[24:25]
	global_store_dwordx4 v[20:21], v[16:19], off offset:16 sc1
.LBB0_915:
	s_or_b64 exec, exec, s[14:15]
	v_cmp_lt_u32_e32 vcc, 13, v132
	s_and_b64 s[4:5], s[24:25], vcc
	s_and_saveexec_b64 s[8:9], s[4:5]
	s_cbranch_execz .LBB0_919
	s_cmp_eq_u32 s3, 0
	s_cselect_b64 s[14:15], -1, 0
	s_and_b64 s[4:5], s[14:15], exec
	s_cselect_b32 s3, -14, -12
	s_cselect_b32 s4, s13, s11
	s_cselect_b32 s5, s12, s10
	v_mov_b32_e32 v16, s5
	v_mov_b32_e32 v17, s4
	v_add_u32_e32 v18, s3, v132
	s_movk_i32 s3, 0x5800
	v_mad_u64_u32 v[18:19], s[4:5], v18, s3, v[16:17]
	v_lshl_add_u64 v[16:17], v[120:121], 2, v[18:19]
	global_store_dwordx4 v[16:17], v[12:15], off sc1
	s_and_saveexec_b64 s[16:17], s[6:7]
	s_cbranch_execz .LBB0_918
	s_add_u32 s3, s12, 0xb000
	s_addc_u32 s6, s13, 0
	s_add_u32 s7, s10, 0x1b800
	s_addc_u32 s10, s11, 0
	s_and_b64 s[4:5], s[14:15], exec
	s_cselect_b32 s5, s6, s10
	s_cselect_b32 s4, s3, s7
	v_lshl_add_u64 v[12:13], v[120:121], 2, s[4:5]
	global_store_dwordx4 v[12:13], v[4:7], off sc1
	global_store_dwordx4 v[16:17], v[8:11], off offset:16 sc1
	v_mov_b64_e32 v[18:19], s[4:5]
	s_nop 0
	v_mov_b64_e32 v[10:11], v[2:3]
	v_mov_b64_e32 v[8:9], v[0:1]
.LBB0_918:
	s_or_b64 exec, exec, s[16:17]
	v_lshl_add_u64 v[0:1], v[120:121], 2, v[18:19]
	global_store_dwordx4 v[0:1], v[8:11], off offset:16 sc1
